# k28: LDS-DMA issue, m0 write hoisted above the address add so the s_nop 0 goes (160 sites)
# baseline (speedup 1.0000x reference)
;     __host__ __device__ bool next(int i, Unit& u) const { const int L = i * G + c; if (L >= 16 * nkc) return false; u.kc = L % nkc; const int t = L / nkc; u.pn = t & 3; u.pm = 33 * (t >> 2); return true; }
; #define PG8_LDA(dst, b, h) do { _Pragma("unroll") for (int m = 0; m < 4; ++m) _Pragma("unroll") for (int k = 0; k < 2; ++k) dst[m][k] = *(const PG8_LAS bf16x8*)(lds + PG8_SA(b, h) + aoff + m * 2048 + k * 1024); } while (0)
; template <class Epi, class Sched, bool ALIGN_EPI = false, bool SP2 = false>
; __device__ __forceinline__ void gemm_phase(PG8_LAS unsigned char* lds, const Gemm g, const Sched& S, const Epi& E) {
;     ...
;         const bool has_next = S.next(ui + 1, nxt);
;         const char* nA = has_next ? (const char*)g.A + (size_t)nxt.pm * tstep + (size_t)nxt.kc * cstep : cA; const char* nB = has_next ? (const char*)g.Bt + (size_t)nxt.pn * tstep + (size_t)nxt.kc * cstep : cB;
;         for (int t = 0; t < nt; t += 2) {
;             const bool last = (t == nt - 2);
;             const char* a1 = cA + (size_t)(t + 1) * kstep;
;             const char* a2 = last ? nA : cA + (size_t)(t + 2) * kstep; const char* b2 = last ? nB : cB + (size_t)(t + 2) * kstep;
;             const char* a3 = a2 + kstep; const char* b3 = b2 + kstep;
;             if (last && has_next) S.a_ready(nxt);
;             if constexpr (SP2) {
;             PG8_LDB(B0, 0, 0); PG8_LDB(B1, 0, 1); PG8_SCHED; PG8_LDA(At, 0, 0); PG8_STAGE(PG8_SA(1, 1), a1 + hstep, voffA);
;             PG8_WAIT_V(8); PG8_WAIT_L(0); PG8_BAR; PG8_MMA(0, 0, At, B0); PG8_MMA(0, 1, At, B1); PG8_BAR; PG8_SCHED;
;             PG8_LDA(At, 0, 1); PG8_STAGE(PG8_SB(0, 0), b2, voffB); PG8_STAGE(PG8_SB(0, 1), b2 + hstep, voffB); PG8_STAGE(PG8_SA(0, 0), a2, voffA);
;             PG8_WAIT_V(8); PG8_WAIT_L(0); PG8_BAR; PG8_MMA(1, 0, At, B0); PG8_MMA(1, 1, At, B1); PG8_BAR; PG8_SCHED;
;             PG8_LDB(B0, 1, 0); PG8_LDB(B1, 1, 1); PG8_SCHED; PG8_LDA(At, 1, 0); PG8_STAGE(PG8_SA(0, 1), a2 + hstep, voffA);
;             PG8_WAIT_V(8); PG8_WAIT_L(0); PG8_BAR; PG8_MMA(0, 0, At, B0); PG8_MMA(0, 1, At, B1); PG8_BAR; PG8_SCHED;
;             PG8_LDA(At, 1, 1); PG8_STAGE(PG8_SB(1, 0), b3, voffB); PG8_STAGE(PG8_SB(1, 1), b3 + hstep, voffB); PG8_STAGE(PG8_SA(1, 0), a3, voffA);
;             PG8_WAIT_V(8); PG8_WAIT_L(0); PG8_BAR; PG8_MMA(1, 0, At, B0); PG8_MMA(1, 1, At, B1); PG8_BAR; PG8_SCHED;
.LBB0_188:
	s_ashr_i32 s51, s50, 31
	s_lshl_b64 s[52:53], s[50:51], 19
	s_add_u32 s52, s46, s52
	s_addc_u32 s53, s47, s53
	s_and_b64 s[54:55], s[4:5], exec
	s_cselect_b32 s51, s53, s59
	s_cselect_b32 s83, s52, s58
	s_ashr_i32 s49, s48, 31
	s_lshl_b64 s[54:55], s[48:49], 19
	s_add_u32 s54, s30, s54
	s_addc_u32 s55, s31, s55
	s_and_b64 s[66:67], s[4:5], exec
	s_cselect_b32 s49, s55, s65
	s_cselect_b32 s84, s54, s64
	s_add_u32 s58, s58, 0x40080
	s_addc_u32 s59, s59, 0
	s_add_u32 s85, s64, 0x100
	s_addc_u32 s86, s65, 0
	s_mov_b32 s87, -2
	ds_read_b128 v[168:171], v150
	ds_read_b128 v[172:175], v151
	ds_read_b128 v[176:179], v152
	ds_read_b128 v[180:183], v153
	ds_read_b128 v[184:187], v154
	ds_read_b128 v[188:191], v155
	ds_read_b128 v[192:195], v156
	ds_read_b128 v[196:199], v157
	s_add_u32 s64, s58, 0xfffc0080
	s_addc_u32 s65, s59, -1
	s_cmp_eq_u32 s87, 12
	s_cselect_b32 s67, s51, s65
	s_cselect_b32 s66, s83, s64
	s_cselect_b32 s65, s49, s86
	s_cselect_b32 s64, s84, s85
	s_mov_b32 m0, s79
	v_lshl_add_u64 v[146:147], s[58:59], 0, v[136:137]
	ds_read_b128 v[200:203], v148
	ds_read_b128 v[204:207], v148 offset:1024
	ds_read_b128 v[208:211], v148 offset:2048
	ds_read_b128 v[212:215], v148 offset:3072
	ds_read_b128 v[216:219], v148 offset:4096
	ds_read_b128 v[224:227], v148 offset:5120
	ds_read_b128 v[228:231], v148 offset:6144
	ds_read_b128 v[232:235], v148 offset:7168
	global_load_lds_dwordx4 v[146:147], off
	s_mov_b32 m0, s80
	v_lshl_add_u64 v[146:147], s[58:59], 0, v[138:139]
	global_load_lds_dwordx4 v[146:147], off
	s_waitcnt vmcnt(8)
	s_waitcnt lgkmcnt(0)
	s_barrier
	s_setprio 1
	s_waitcnt lgkmcnt(0)
	v_mfma_f32_16x16x32_bf16 v[124:127], v[168:171], v[200:203], 0
	v_mfma_f32_16x16x32_bf16 v[120:123], v[176:179], v[200:203], 0
	v_mfma_f32_16x16x32_bf16 v[112:115], v[168:171], v[208:211], 0
	v_mfma_f32_16x16x32_bf16 v[104:107], v[176:179], v[208:211], 0
	v_mfma_f32_16x16x32_bf16 v[96:99], v[168:171], v[216:219], 0
	v_mfma_f32_16x16x32_bf16 v[88:91], v[176:179], v[216:219], 0
	v_mfma_f32_16x16x32_bf16 v[80:83], v[168:171], v[228:231], 0
	v_mfma_f32_16x16x32_bf16 v[72:75], v[176:179], v[228:231], 0
	v_mfma_f32_16x16x32_bf16 v[124:127], v[172:175], v[204:207], v[124:127]
	v_mfma_f32_16x16x32_bf16 v[120:123], v[180:183], v[204:207], v[120:123]
	v_mfma_f32_16x16x32_bf16 v[112:115], v[172:175], v[212:215], v[112:115]
	v_mfma_f32_16x16x32_bf16 v[104:107], v[180:183], v[212:215], v[104:107]
	v_mfma_f32_16x16x32_bf16 v[96:99], v[172:175], v[224:227], v[96:99]
	v_mfma_f32_16x16x32_bf16 v[88:91], v[180:183], v[224:227], v[88:91]
	v_mfma_f32_16x16x32_bf16 v[80:83], v[172:175], v[232:235], v[80:83]
	v_mfma_f32_16x16x32_bf16 v[72:75], v[180:183], v[232:235], v[72:75]
	s_setprio 0
	s_setprio 1
	v_mfma_f32_16x16x32_bf16 v[116:119], v[184:187], v[200:203], 0
	v_mfma_f32_16x16x32_bf16 v[108:111], v[192:195], v[200:203], 0
	v_mfma_f32_16x16x32_bf16 v[100:103], v[184:187], v[208:211], 0
	v_mfma_f32_16x16x32_bf16 v[92:95], v[192:195], v[208:211], 0
	v_mfma_f32_16x16x32_bf16 v[84:87], v[184:187], v[216:219], 0
	v_mfma_f32_16x16x32_bf16 v[76:79], v[192:195], v[216:219], 0
	v_mfma_f32_16x16x32_bf16 v[68:71], v[184:187], v[228:231], 0
	v_mfma_f32_16x16x32_bf16 v[64:67], v[192:195], v[228:231], 0
	v_mfma_f32_16x16x32_bf16 v[116:119], v[188:191], v[204:207], v[116:119]
	v_mfma_f32_16x16x32_bf16 v[108:111], v[196:199], v[204:207], v[108:111]
	v_mfma_f32_16x16x32_bf16 v[100:103], v[188:191], v[212:215], v[100:103]
	v_mfma_f32_16x16x32_bf16 v[92:95], v[196:199], v[212:215], v[92:95]
	v_mfma_f32_16x16x32_bf16 v[84:87], v[188:191], v[224:227], v[84:87]
	v_mfma_f32_16x16x32_bf16 v[76:79], v[196:199], v[224:227], v[76:79]
	v_mfma_f32_16x16x32_bf16 v[68:71], v[188:191], v[232:235], v[68:71]
	v_mfma_f32_16x16x32_bf16 v[64:67], v[196:199], v[232:235], v[64:67]
	s_setprio 0
	s_barrier
	s_mov_b32 m0, s3
	v_lshl_add_u64 v[146:147], s[64:65], 0, v[130:131]
	s_add_u32 s88, s64, 0x40000
	ds_read_b128 v[200:203], v148 offset:16384
	ds_read_b128 v[204:207], v148 offset:17408
	ds_read_b128 v[208:211], v148 offset:18432
	ds_read_b128 v[212:215], v148 offset:19456
	ds_read_b128 v[216:219], v148 offset:20480
	ds_read_b128 v[224:227], v148 offset:21504
	ds_read_b128 v[228:231], v148 offset:22528
	ds_read_b128 v[232:235], v148 offset:23552
	global_load_lds_dwordx4 v[146:147], off
	v_lshl_add_u64 v[220:221], s[64:65], 0, v[134:135]
	s_mov_b32 m0, s14
	s_addc_u32 s89, s65, 0
	global_load_lds_dwordx4 v[220:221], off
	v_lshl_add_u64 v[236:237], s[88:89], 0, v[130:131]
	s_mov_b32 m0, s15
	v_lshl_add_u64 v[238:239], s[66:67], 0, v[132:133]
	global_load_lds_dwordx4 v[236:237], off
	s_mov_b32 m0, s33
	v_lshl_add_u64 v[236:237], s[88:89], 0, v[134:135]
	global_load_lds_dwordx4 v[236:237], off
	s_mov_b32 m0, s1
	v_lshl_add_u64 v[236:237], s[66:67], 0, v[128:129]
	global_load_lds_dwordx4 v[236:237], off
	s_mov_b32 m0, s39
	s_nop 0
	global_load_lds_dwordx4 v[238:239], off
	s_waitcnt vmcnt(8)
	s_waitcnt lgkmcnt(0)
	s_barrier
; #define PG8_STAGE(bufoff, gbase, voff) do { _Pragma("unroll") for (int _i = 0; _i < 2; ++_i) \
;         __builtin_amdgcn_global_load_lds((const unsigned*)((const char*)(gbase) + (voff)[_i]), (PG8_LAS unsigned*)(lds + (bufoff) + ldsw + _i * 8192), 16, 0, 0); } while (0)
; #define PG8_LDA(dst, b, h) do { _Pragma("unroll") for (int m = 0; m < 4; ++m) _Pragma("unroll") for (int k = 0; k < 2; ++k) dst[m][k] = *(const PG8_LAS bf16x8*)(lds + PG8_SA(b, h) + aoff + m * 2048 + k * 1024); } while (0)
; #define PG8_LDB(dst, b, h) do { _Pragma("unroll") for (int n = 0; n < 2; ++n) _Pragma("unroll") for (int k = 0; k < 2; ++k) dst[n][k] = *(const PG8_LAS bf16x8*)(lds + PG8_SB(b, h) + boff + n * 2048 + k * 1024); } while (0)
; #define PG8_MMA(ai, bj, At, Bt) do { __builtin_amdgcn_s_setprio(1); _Pragma("unroll") for (int m = 0; m < 4; ++m) _Pragma("unroll") for (int n = 0; n < 2; ++n) _Pragma("unroll") for (int k = 0; k < 2; ++k) \
;         acc[ai][bj][m][n] = __builtin_amdgcn_mfma_f32_16x16x32_bf16(Bt[n][k], At[m][k], acc[ai][bj][m][n], 0, 0, 0); __builtin_amdgcn_s_setprio(0); } while (0)
; #define PG8_WAIT_V(n) asm volatile("s_waitcnt vmcnt(" #n ")" ::: "memory")
; template <class Epi, class Sched, bool ALIGN_EPI = false, bool SP2 = false>
; __device__ __forceinline__ void gemm_phase(PG8_LAS unsigned char* lds, const Gemm g, const Sched& S, const Epi& E) {
;     ...
;             PG8_LDB(B0, 0, 0); PG8_LDB(B1, 0, 1); PG8_SCHED; PG8_LDA(At, 0, 0); PG8_STAGE(PG8_SA(1, 1), a1 + hstep, voffA);
;             PG8_WAIT_V(8); PG8_WAIT_L(0); PG8_BAR; PG8_MMA(0, 0, At, B0); PG8_MMA(0, 1, At, B1); PG8_BAR; PG8_SCHED;
;             PG8_LDA(At, 0, 1); PG8_STAGE(PG8_SB(0, 0), b2, voffB); PG8_STAGE(PG8_SB(0, 1), b2 + hstep, voffB); PG8_STAGE(PG8_SA(0, 0), a2, voffA);
;             PG8_WAIT_V(8); PG8_WAIT_L(0); PG8_BAR; PG8_MMA(1, 0, At, B0); PG8_MMA(1, 1, At, B1); PG8_BAR; PG8_SCHED;
;             PG8_LDB(B0, 1, 0); PG8_LDB(B1, 1, 1); PG8_SCHED; PG8_LDA(At, 1, 0); PG8_STAGE(PG8_SA(0, 1), a2 + hstep, voffA);
;             PG8_WAIT_V(8); PG8_WAIT_L(0); PG8_BAR; PG8_MMA(0, 0, At, B0); PG8_MMA(0, 1, At, B1); PG8_BAR; PG8_SCHED;
;             PG8_LDA(At, 1, 1); PG8_STAGE(PG8_SB(1, 0), b3, voffB); PG8_STAGE(PG8_SB(1, 1), b3 + hstep, voffB); PG8_STAGE(PG8_SA(1, 0), a3, voffA);
;             PG8_WAIT_V(8); PG8_WAIT_L(0); PG8_BAR; PG8_MMA(1, 0, At, B0); PG8_MMA(1, 1, At, B1); PG8_BAR; PG8_SCHED;
	s_setprio 1
	s_waitcnt lgkmcnt(0)
	v_mfma_f32_16x16x32_bf16 v[60:63], v[168:171], v[200:203], 0
	v_mfma_f32_16x16x32_bf16 v[56:59], v[176:179], v[200:203], 0
	v_mfma_f32_16x16x32_bf16 v[48:51], v[168:171], v[208:211], 0
	v_mfma_f32_16x16x32_bf16 v[40:43], v[176:179], v[208:211], 0
	v_mfma_f32_16x16x32_bf16 v[32:35], v[168:171], v[216:219], 0
	v_mfma_f32_16x16x32_bf16 v[24:27], v[176:179], v[216:219], 0
	v_mfma_f32_16x16x32_bf16 v[16:19], v[168:171], v[228:231], 0
	v_mfma_f32_16x16x32_bf16 v[8:11], v[176:179], v[228:231], 0
	v_mfma_f32_16x16x32_bf16 v[60:63], v[172:175], v[204:207], v[60:63]
	v_mfma_f32_16x16x32_bf16 v[56:59], v[180:183], v[204:207], v[56:59]
	v_mfma_f32_16x16x32_bf16 v[48:51], v[172:175], v[212:215], v[48:51]
	v_mfma_f32_16x16x32_bf16 v[40:43], v[180:183], v[212:215], v[40:43]
	v_mfma_f32_16x16x32_bf16 v[32:35], v[172:175], v[224:227], v[32:35]
	v_mfma_f32_16x16x32_bf16 v[24:27], v[180:183], v[224:227], v[24:27]
	v_mfma_f32_16x16x32_bf16 v[16:19], v[172:175], v[232:235], v[16:19]
	v_mfma_f32_16x16x32_bf16 v[8:11], v[180:183], v[232:235], v[8:11]
	s_setprio 0
	s_setprio 1
	v_mfma_f32_16x16x32_bf16 v[52:55], v[184:187], v[200:203], 0
	v_mfma_f32_16x16x32_bf16 v[44:47], v[192:195], v[200:203], 0
	v_mfma_f32_16x16x32_bf16 v[36:39], v[184:187], v[208:211], 0
	v_mfma_f32_16x16x32_bf16 v[28:31], v[192:195], v[208:211], 0
	v_mfma_f32_16x16x32_bf16 v[20:23], v[184:187], v[216:219], 0
	v_mfma_f32_16x16x32_bf16 v[12:15], v[192:195], v[216:219], 0
	v_mfma_f32_16x16x32_bf16 v[4:7], v[184:187], v[228:231], 0
	v_mfma_f32_16x16x32_bf16 v[0:3], v[192:195], v[228:231], 0
	v_mfma_f32_16x16x32_bf16 v[52:55], v[188:191], v[204:207], v[52:55]
	v_mfma_f32_16x16x32_bf16 v[44:47], v[196:199], v[204:207], v[44:47]
	v_mfma_f32_16x16x32_bf16 v[36:39], v[188:191], v[212:215], v[36:39]
	v_mfma_f32_16x16x32_bf16 v[28:31], v[196:199], v[212:215], v[28:31]
	v_mfma_f32_16x16x32_bf16 v[20:23], v[188:191], v[224:227], v[20:23]
	v_mfma_f32_16x16x32_bf16 v[12:15], v[196:199], v[224:227], v[12:15]
	v_mfma_f32_16x16x32_bf16 v[4:7], v[188:191], v[232:235], v[4:7]
	v_mfma_f32_16x16x32_bf16 v[0:3], v[196:199], v[232:235], v[0:3]
	s_setprio 0
	s_barrier
	ds_read_b128 v[168:171], v158
	ds_read_b128 v[172:175], v159
	ds_read_b128 v[176:179], v160
	ds_read_b128 v[180:183], v161
	ds_read_b128 v[184:187], v162
	ds_read_b128 v[188:191], v163
	ds_read_b128 v[192:195], v164
	ds_read_b128 v[196:199], v165
	s_add_u32 s66, s66, 0x40000
	s_addc_u32 s67, s67, 0
	s_mov_b32 m0, s43
	v_lshl_add_u64 v[240:241], s[66:67], 0, v[128:129]
	ds_read_b128 v[200:203], v148 offset:32768
	ds_read_b128 v[204:207], v148 offset:33792
	ds_read_b128 v[208:211], v148 offset:34816
	ds_read_b128 v[212:215], v148 offset:35840
	ds_read_b128 v[216:219], v148 offset:36864
	ds_read_b128 v[224:227], v148 offset:37888
	ds_read_b128 v[228:231], v148 offset:38912
	ds_read_b128 v[232:235], v148 offset:39936
	global_load_lds_dwordx4 v[240:241], off
	s_mov_b32 m0, s57
	v_lshl_add_u64 v[240:241], s[66:67], 0, v[132:133]
	global_load_lds_dwordx4 v[240:241], off
	s_waitcnt vmcnt(8)
	s_waitcnt lgkmcnt(0)
	s_barrier
	s_setprio 1
	s_waitcnt lgkmcnt(0)
	v_mfma_f32_16x16x32_bf16 v[124:127], v[168:171], v[200:203], v[124:127]
	v_mfma_f32_16x16x32_bf16 v[120:123], v[176:179], v[200:203], v[120:123]
	v_mfma_f32_16x16x32_bf16 v[112:115], v[168:171], v[208:211], v[112:115]
	v_mfma_f32_16x16x32_bf16 v[104:107], v[176:179], v[208:211], v[104:107]
	v_mfma_f32_16x16x32_bf16 v[96:99], v[168:171], v[216:219], v[96:99]
	v_mfma_f32_16x16x32_bf16 v[88:91], v[176:179], v[216:219], v[88:91]
	v_mfma_f32_16x16x32_bf16 v[80:83], v[168:171], v[228:231], v[80:83]
	v_mfma_f32_16x16x32_bf16 v[72:75], v[176:179], v[228:231], v[72:75]
	v_mfma_f32_16x16x32_bf16 v[124:127], v[172:175], v[204:207], v[124:127]
	v_mfma_f32_16x16x32_bf16 v[120:123], v[180:183], v[204:207], v[120:123]
	v_mfma_f32_16x16x32_bf16 v[112:115], v[172:175], v[212:215], v[112:115]
	v_mfma_f32_16x16x32_bf16 v[104:107], v[180:183], v[212:215], v[104:107]
	v_mfma_f32_16x16x32_bf16 v[96:99], v[172:175], v[224:227], v[96:99]
	v_mfma_f32_16x16x32_bf16 v[88:91], v[180:183], v[224:227], v[88:91]
	v_mfma_f32_16x16x32_bf16 v[80:83], v[172:175], v[232:235], v[80:83]
	v_mfma_f32_16x16x32_bf16 v[72:75], v[180:183], v[232:235], v[72:75]
	s_setprio 0
	s_setprio 1
	v_mfma_f32_16x16x32_bf16 v[116:119], v[184:187], v[200:203], v[116:119]
	v_mfma_f32_16x16x32_bf16 v[108:111], v[192:195], v[200:203], v[108:111]
	v_mfma_f32_16x16x32_bf16 v[100:103], v[184:187], v[208:211], v[100:103]
	v_mfma_f32_16x16x32_bf16 v[92:95], v[192:195], v[208:211], v[92:95]
	v_mfma_f32_16x16x32_bf16 v[84:87], v[184:187], v[216:219], v[84:87]
	v_mfma_f32_16x16x32_bf16 v[76:79], v[192:195], v[216:219], v[76:79]
	v_mfma_f32_16x16x32_bf16 v[68:71], v[184:187], v[228:231], v[68:71]
	v_mfma_f32_16x16x32_bf16 v[64:67], v[192:195], v[228:231], v[64:67]
	v_mfma_f32_16x16x32_bf16 v[116:119], v[188:191], v[204:207], v[116:119]
	v_mfma_f32_16x16x32_bf16 v[108:111], v[196:199], v[204:207], v[108:111]
	v_mfma_f32_16x16x32_bf16 v[100:103], v[188:191], v[212:215], v[100:103]
	v_mfma_f32_16x16x32_bf16 v[92:95], v[196:199], v[212:215], v[92:95]
	v_mfma_f32_16x16x32_bf16 v[84:87], v[188:191], v[224:227], v[84:87]
	v_mfma_f32_16x16x32_bf16 v[76:79], v[196:199], v[224:227], v[76:79]
	v_mfma_f32_16x16x32_bf16 v[68:71], v[188:191], v[232:235], v[68:71]
	v_mfma_f32_16x16x32_bf16 v[64:67], v[196:199], v[232:235], v[64:67]
	s_setprio 0
	s_barrier
; #define PG8_STAGE(bufoff, gbase, voff) do { _Pragma("unroll") for (int _i = 0; _i < 2; ++_i) \
;         __builtin_amdgcn_global_load_lds((const unsigned*)((const char*)(gbase) + (voff)[_i]), (PG8_LAS unsigned*)(lds + (bufoff) + ldsw + _i * 8192), 16, 0, 0); } while (0)
; #define PG8_LDA(dst, b, h) do { _Pragma("unroll") for (int m = 0; m < 4; ++m) _Pragma("unroll") for (int k = 0; k < 2; ++k) dst[m][k] = *(const PG8_LAS bf16x8*)(lds + PG8_SA(b, h) + aoff + m * 2048 + k * 1024); } while (0)
; #define PG8_LDB(dst, b, h) do { _Pragma("unroll") for (int n = 0; n < 2; ++n) _Pragma("unroll") for (int k = 0; k < 2; ++k) dst[n][k] = *(const PG8_LAS bf16x8*)(lds + PG8_SB(b, h) + boff + n * 2048 + k * 1024); } while (0)
; template <class Epi, class Sched, bool ALIGN_EPI = false, bool SP2 = false>
; __device__ __forceinline__ void gemm_phase(PG8_LAS unsigned char* lds, const Gemm g, const Sched& S, const Epi& E) {
;     ...
;         for (int t = 0; t < nt; t += 2) {
;             const bool last = (t == nt - 2);
;             const char* a1 = cA + (size_t)(t + 1) * kstep;
;             const char* a2 = last ? nA : cA + (size_t)(t + 2) * kstep; const char* b2 = last ? nB : cB + (size_t)(t + 2) * kstep;
;             const char* a3 = a2 + kstep; const char* b3 = b2 + kstep;
;             if (last && has_next) S.a_ready(nxt);
;             if constexpr (SP2) {
;             PG8_LDB(B0, 0, 0); PG8_LDB(B1, 0, 1); PG8_SCHED; PG8_LDA(At, 0, 0); PG8_STAGE(PG8_SA(1, 1), a1 + hstep, voffA);
;             PG8_WAIT_V(8); PG8_WAIT_L(0); PG8_BAR; PG8_MMA(0, 0, At, B0); PG8_MMA(0, 1, At, B1); PG8_BAR; PG8_SCHED;
;             PG8_LDA(At, 0, 1); PG8_STAGE(PG8_SB(0, 0), b2, voffB); PG8_STAGE(PG8_SB(0, 1), b2 + hstep, voffB); PG8_STAGE(PG8_SA(0, 0), a2, voffA);
;             PG8_WAIT_V(8); PG8_WAIT_L(0); PG8_BAR; PG8_MMA(1, 0, At, B0); PG8_MMA(1, 1, At, B1); PG8_BAR; PG8_SCHED;
;             PG8_LDB(B0, 1, 0); PG8_LDB(B1, 1, 1); PG8_SCHED; PG8_LDA(At, 1, 0); PG8_STAGE(PG8_SA(0, 1), a2 + hstep, voffA);
;             PG8_WAIT_V(8); PG8_WAIT_L(0); PG8_BAR; PG8_MMA(0, 0, At, B0); PG8_MMA(0, 1, At, B1); PG8_BAR; PG8_SCHED;
;             PG8_LDA(At, 1, 1); PG8_STAGE(PG8_SB(1, 0), b3, voffB); PG8_STAGE(PG8_SB(1, 1), b3 + hstep, voffB); PG8_STAGE(PG8_SA(1, 0), a3, voffA);
;             PG8_WAIT_V(8); PG8_WAIT_L(0); PG8_BAR; PG8_MMA(1, 0, At, B0); PG8_MMA(1, 1, At, B1); PG8_BAR; PG8_SCHED;
	s_mov_b32 m0, s71
	v_lshl_add_u64 v[146:147], v[146:147], 0, s[10:11]
	s_add_u32 s64, s64, 0x40080
	ds_read_b128 v[200:203], v148 offset:49152
	ds_read_b128 v[204:207], v148 offset:50176
	ds_read_b128 v[208:211], v148 offset:51200
	ds_read_b128 v[212:215], v148 offset:52224
	ds_read_b128 v[216:219], v148 offset:53248
	ds_read_b128 v[224:227], v148 offset:54272
	ds_read_b128 v[228:231], v148 offset:55296
	ds_read_b128 v[232:235], v148 offset:56320
	global_load_lds_dwordx4 v[146:147], off
	v_lshl_add_u64 v[146:147], v[220:221], 0, s[10:11]
	s_mov_b32 m0, s72
	s_addc_u32 s65, s65, 0
	global_load_lds_dwordx4 v[146:147], off
	s_mov_b32 m0, s75
	v_lshl_add_u64 v[146:147], s[64:65], 0, v[130:131]
	global_load_lds_dwordx4 v[146:147], off
	s_mov_b32 m0, s76
	v_lshl_add_u64 v[146:147], s[64:65], 0, v[134:135]
	global_load_lds_dwordx4 v[146:147], off
	s_mov_b32 m0, s73
	v_lshl_add_u64 v[146:147], v[236:237], 0, s[10:11]
	global_load_lds_dwordx4 v[146:147], off
	s_mov_b32 m0, s74
	v_lshl_add_u64 v[146:147], v[238:239], 0, s[10:11]
	global_load_lds_dwordx4 v[146:147], off
	s_waitcnt vmcnt(8)
	s_waitcnt lgkmcnt(0)
	s_barrier
	s_setprio 1
	s_waitcnt lgkmcnt(0)
	v_mfma_f32_16x16x32_bf16 v[60:63], v[168:171], v[200:203], v[60:63]
	v_mfma_f32_16x16x32_bf16 v[56:59], v[176:179], v[200:203], v[56:59]
	v_mfma_f32_16x16x32_bf16 v[48:51], v[168:171], v[208:211], v[48:51]
	v_mfma_f32_16x16x32_bf16 v[40:43], v[176:179], v[208:211], v[40:43]
	v_mfma_f32_16x16x32_bf16 v[32:35], v[168:171], v[216:219], v[32:35]
	v_mfma_f32_16x16x32_bf16 v[24:27], v[176:179], v[216:219], v[24:27]
	v_mfma_f32_16x16x32_bf16 v[16:19], v[168:171], v[228:231], v[16:19]
	v_mfma_f32_16x16x32_bf16 v[8:11], v[176:179], v[228:231], v[8:11]
	v_mfma_f32_16x16x32_bf16 v[60:63], v[172:175], v[204:207], v[60:63]
	v_mfma_f32_16x16x32_bf16 v[56:59], v[180:183], v[204:207], v[56:59]
	v_mfma_f32_16x16x32_bf16 v[48:51], v[172:175], v[212:215], v[48:51]
	v_mfma_f32_16x16x32_bf16 v[40:43], v[180:183], v[212:215], v[40:43]
	v_mfma_f32_16x16x32_bf16 v[32:35], v[172:175], v[224:227], v[32:35]
	v_mfma_f32_16x16x32_bf16 v[24:27], v[180:183], v[224:227], v[24:27]
	v_mfma_f32_16x16x32_bf16 v[16:19], v[172:175], v[232:235], v[16:19]
	v_mfma_f32_16x16x32_bf16 v[8:11], v[180:183], v[232:235], v[8:11]
	s_setprio 0
	s_setprio 1
	v_mfma_f32_16x16x32_bf16 v[52:55], v[184:187], v[200:203], v[52:55]
	v_mfma_f32_16x16x32_bf16 v[44:47], v[192:195], v[200:203], v[44:47]
	v_mfma_f32_16x16x32_bf16 v[36:39], v[184:187], v[208:211], v[36:39]
	v_mfma_f32_16x16x32_bf16 v[28:31], v[192:195], v[208:211], v[28:31]
	v_mfma_f32_16x16x32_bf16 v[20:23], v[184:187], v[216:219], v[20:23]
	v_mfma_f32_16x16x32_bf16 v[12:15], v[192:195], v[216:219], v[12:15]
	v_mfma_f32_16x16x32_bf16 v[4:7], v[184:187], v[228:231], v[4:7]
	v_mfma_f32_16x16x32_bf16 v[0:3], v[192:195], v[228:231], v[0:3]
	v_mfma_f32_16x16x32_bf16 v[52:55], v[188:191], v[204:207], v[52:55]
	v_mfma_f32_16x16x32_bf16 v[44:47], v[196:199], v[204:207], v[44:47]
	v_mfma_f32_16x16x32_bf16 v[36:39], v[188:191], v[212:215], v[36:39]
	v_mfma_f32_16x16x32_bf16 v[28:31], v[196:199], v[212:215], v[28:31]
	v_mfma_f32_16x16x32_bf16 v[20:23], v[188:191], v[224:227], v[20:23]
	v_mfma_f32_16x16x32_bf16 v[12:15], v[196:199], v[224:227], v[12:15]
	v_mfma_f32_16x16x32_bf16 v[4:7], v[188:191], v[232:235], v[4:7]
	v_mfma_f32_16x16x32_bf16 v[0:3], v[196:199], v[232:235], v[0:3]
	s_setprio 0
	s_barrier
	s_add_i32 s87, s87, 2
	s_add_u32 s58, s58, 0x100
	s_addc_u32 s59, s59, 0
	s_add_u32 s85, s85, 0x100
	s_addc_u32 s86, s86, 0
.LBB0_189:
	ds_read_b128 v[168:171], v150
	ds_read_b128 v[172:175], v151
	ds_read_b128 v[176:179], v152
	ds_read_b128 v[180:183], v153
	ds_read_b128 v[184:187], v154
	ds_read_b128 v[188:191], v155
	ds_read_b128 v[192:195], v156
	ds_read_b128 v[196:199], v157
	s_add_u32 s64, s58, 0xfffc0080
	s_addc_u32 s65, s59, -1
	s_cmp_eq_u32 s87, 12
	s_cselect_b32 s67, s51, s65
	s_cselect_b32 s66, s83, s64
	s_cselect_b32 s65, s49, s86
	s_cselect_b32 s64, s84, s85
	s_mov_b32 m0, s79
	v_lshl_add_u64 v[146:147], s[58:59], 0, v[136:137]
	ds_read_b128 v[200:203], v148
	ds_read_b128 v[204:207], v148 offset:1024
	ds_read_b128 v[208:211], v148 offset:2048
	ds_read_b128 v[212:215], v148 offset:3072
	ds_read_b128 v[216:219], v148 offset:4096
	ds_read_b128 v[224:227], v148 offset:5120
	ds_read_b128 v[228:231], v148 offset:6144
	ds_read_b128 v[232:235], v148 offset:7168
	global_load_lds_dwordx4 v[146:147], off
	s_mov_b32 m0, s80
	v_lshl_add_u64 v[146:147], s[58:59], 0, v[138:139]
	global_load_lds_dwordx4 v[146:147], off
	s_waitcnt vmcnt(8)
	s_waitcnt lgkmcnt(0)
	s_barrier
; #define PG8_STAGE(bufoff, gbase, voff) do { _Pragma("unroll") for (int _i = 0; _i < 2; ++_i) \
;         __builtin_amdgcn_global_load_lds((const unsigned*)((const char*)(gbase) + (voff)[_i]), (PG8_LAS unsigned*)(lds + (bufoff) + ldsw + _i * 8192), 16, 0, 0); } while (0)
; #define PG8_LDA(dst, b, h) do { _Pragma("unroll") for (int m = 0; m < 4; ++m) _Pragma("unroll") for (int k = 0; k < 2; ++k) dst[m][k] = *(const PG8_LAS bf16x8*)(lds + PG8_SA(b, h) + aoff + m * 2048 + k * 1024); } while (0)
; #define PG8_LDB(dst, b, h) do { _Pragma("unroll") for (int n = 0; n < 2; ++n) _Pragma("unroll") for (int k = 0; k < 2; ++k) dst[n][k] = *(const PG8_LAS bf16x8*)(lds + PG8_SB(b, h) + boff + n * 2048 + k * 1024); } while (0)
; #define PG8_MMA(ai, bj, At, Bt) do { __builtin_amdgcn_s_setprio(1); _Pragma("unroll") for (int m = 0; m < 4; ++m) _Pragma("unroll") for (int n = 0; n < 2; ++n) _Pragma("unroll") for (int k = 0; k < 2; ++k) \
;         acc[ai][bj][m][n] = __builtin_amdgcn_mfma_f32_16x16x32_bf16(Bt[n][k], At[m][k], acc[ai][bj][m][n], 0, 0, 0); __builtin_amdgcn_s_setprio(0); } while (0)
; #define PG8_WAIT_V(n) asm volatile("s_waitcnt vmcnt(" #n ")" ::: "memory")
; template <class Epi, class Sched, bool ALIGN_EPI = false, bool SP2 = false>
; __device__ __forceinline__ void gemm_phase(PG8_LAS unsigned char* lds, const Gemm g, const Sched& S, const Epi& E) {
;     ...
;             PG8_LDB(B0, 0, 0); PG8_LDB(B1, 0, 1); PG8_SCHED; PG8_LDA(At, 0, 0); PG8_STAGE(PG8_SA(1, 1), a1 + hstep, voffA);
;             PG8_WAIT_V(8); PG8_WAIT_L(0); PG8_BAR; PG8_MMA(0, 0, At, B0); PG8_MMA(0, 1, At, B1); PG8_BAR; PG8_SCHED;
;             PG8_LDA(At, 0, 1); PG8_STAGE(PG8_SB(0, 0), b2, voffB); PG8_STAGE(PG8_SB(0, 1), b2 + hstep, voffB); PG8_STAGE(PG8_SA(0, 0), a2, voffA);
;             PG8_WAIT_V(8); PG8_WAIT_L(0); PG8_BAR; PG8_MMA(1, 0, At, B0); PG8_MMA(1, 1, At, B1); PG8_BAR; PG8_SCHED;
;             PG8_LDB(B0, 1, 0); PG8_LDB(B1, 1, 1); PG8_SCHED; PG8_LDA(At, 1, 0); PG8_STAGE(PG8_SA(0, 1), a2 + hstep, voffA);
;             PG8_WAIT_V(8); PG8_WAIT_L(0); PG8_BAR; PG8_MMA(0, 0, At, B0); PG8_MMA(0, 1, At, B1); PG8_BAR; PG8_SCHED;
;             PG8_LDA(At, 1, 1); PG8_STAGE(PG8_SB(1, 0), b3, voffB); PG8_STAGE(PG8_SB(1, 1), b3 + hstep, voffB); PG8_STAGE(PG8_SA(1, 0), a3, voffA);
;             PG8_WAIT_V(8); PG8_WAIT_L(0); PG8_BAR; PG8_MMA(1, 0, At, B0); PG8_MMA(1, 1, At, B1); PG8_BAR; PG8_SCHED;
	s_setprio 1
	s_waitcnt lgkmcnt(0)
	v_mfma_f32_16x16x32_bf16 v[124:127], v[168:171], v[200:203], v[124:127]
	v_mfma_f32_16x16x32_bf16 v[120:123], v[176:179], v[200:203], v[120:123]
	v_mfma_f32_16x16x32_bf16 v[112:115], v[168:171], v[208:211], v[112:115]
	v_mfma_f32_16x16x32_bf16 v[104:107], v[176:179], v[208:211], v[104:107]
	v_mfma_f32_16x16x32_bf16 v[96:99], v[168:171], v[216:219], v[96:99]
	v_mfma_f32_16x16x32_bf16 v[88:91], v[176:179], v[216:219], v[88:91]
	v_mfma_f32_16x16x32_bf16 v[80:83], v[168:171], v[228:231], v[80:83]
	v_mfma_f32_16x16x32_bf16 v[72:75], v[176:179], v[228:231], v[72:75]
	v_mfma_f32_16x16x32_bf16 v[124:127], v[172:175], v[204:207], v[124:127]
	v_mfma_f32_16x16x32_bf16 v[120:123], v[180:183], v[204:207], v[120:123]
	v_mfma_f32_16x16x32_bf16 v[112:115], v[172:175], v[212:215], v[112:115]
	v_mfma_f32_16x16x32_bf16 v[104:107], v[180:183], v[212:215], v[104:107]
	v_mfma_f32_16x16x32_bf16 v[96:99], v[172:175], v[224:227], v[96:99]
	v_mfma_f32_16x16x32_bf16 v[88:91], v[180:183], v[224:227], v[88:91]
	v_mfma_f32_16x16x32_bf16 v[80:83], v[172:175], v[232:235], v[80:83]
	v_mfma_f32_16x16x32_bf16 v[72:75], v[180:183], v[232:235], v[72:75]
	s_setprio 0
	s_setprio 1
	v_mfma_f32_16x16x32_bf16 v[116:119], v[184:187], v[200:203], v[116:119]
	v_mfma_f32_16x16x32_bf16 v[108:111], v[192:195], v[200:203], v[108:111]
	v_mfma_f32_16x16x32_bf16 v[100:103], v[184:187], v[208:211], v[100:103]
	v_mfma_f32_16x16x32_bf16 v[92:95], v[192:195], v[208:211], v[92:95]
	v_mfma_f32_16x16x32_bf16 v[84:87], v[184:187], v[216:219], v[84:87]
	v_mfma_f32_16x16x32_bf16 v[76:79], v[192:195], v[216:219], v[76:79]
	v_mfma_f32_16x16x32_bf16 v[68:71], v[184:187], v[228:231], v[68:71]
	v_mfma_f32_16x16x32_bf16 v[64:67], v[192:195], v[228:231], v[64:67]
	v_mfma_f32_16x16x32_bf16 v[116:119], v[188:191], v[204:207], v[116:119]
	v_mfma_f32_16x16x32_bf16 v[108:111], v[196:199], v[204:207], v[108:111]
	v_mfma_f32_16x16x32_bf16 v[100:103], v[188:191], v[212:215], v[100:103]
	v_mfma_f32_16x16x32_bf16 v[92:95], v[196:199], v[212:215], v[92:95]
	v_mfma_f32_16x16x32_bf16 v[84:87], v[188:191], v[224:227], v[84:87]
	v_mfma_f32_16x16x32_bf16 v[76:79], v[196:199], v[224:227], v[76:79]
	v_mfma_f32_16x16x32_bf16 v[68:71], v[188:191], v[232:235], v[68:71]
	v_mfma_f32_16x16x32_bf16 v[64:67], v[196:199], v[232:235], v[64:67]
	s_setprio 0
	s_barrier
	s_mov_b32 m0, s3
	v_lshl_add_u64 v[146:147], s[64:65], 0, v[130:131]
	s_add_u32 s88, s64, 0x40000
	ds_read_b128 v[200:203], v148 offset:16384
	ds_read_b128 v[204:207], v148 offset:17408
	ds_read_b128 v[208:211], v148 offset:18432
	ds_read_b128 v[212:215], v148 offset:19456
	ds_read_b128 v[216:219], v148 offset:20480
	ds_read_b128 v[224:227], v148 offset:21504
	ds_read_b128 v[228:231], v148 offset:22528
	ds_read_b128 v[232:235], v148 offset:23552
	global_load_lds_dwordx4 v[146:147], off
	v_lshl_add_u64 v[220:221], s[64:65], 0, v[134:135]
	s_mov_b32 m0, s14
	s_addc_u32 s89, s65, 0
	global_load_lds_dwordx4 v[220:221], off
	v_lshl_add_u64 v[236:237], s[88:89], 0, v[130:131]
	s_mov_b32 m0, s15
	v_lshl_add_u64 v[238:239], s[66:67], 0, v[132:133]
	global_load_lds_dwordx4 v[236:237], off
	s_mov_b32 m0, s33
	v_lshl_add_u64 v[236:237], s[88:89], 0, v[134:135]
	global_load_lds_dwordx4 v[236:237], off
	s_mov_b32 m0, s1
	v_lshl_add_u64 v[236:237], s[66:67], 0, v[128:129]
	global_load_lds_dwordx4 v[236:237], off
	s_mov_b32 m0, s39
	s_nop 0
	global_load_lds_dwordx4 v[238:239], off
	s_waitcnt vmcnt(8)
	s_waitcnt lgkmcnt(0)
	s_barrier
	s_setprio 1
	s_waitcnt lgkmcnt(0)
	v_mfma_f32_16x16x32_bf16 v[60:63], v[168:171], v[200:203], v[60:63]
	v_mfma_f32_16x16x32_bf16 v[56:59], v[176:179], v[200:203], v[56:59]
	v_mfma_f32_16x16x32_bf16 v[48:51], v[168:171], v[208:211], v[48:51]
	v_mfma_f32_16x16x32_bf16 v[40:43], v[176:179], v[208:211], v[40:43]
	v_mfma_f32_16x16x32_bf16 v[32:35], v[168:171], v[216:219], v[32:35]
	v_mfma_f32_16x16x32_bf16 v[24:27], v[176:179], v[216:219], v[24:27]
	v_mfma_f32_16x16x32_bf16 v[16:19], v[168:171], v[228:231], v[16:19]
	v_mfma_f32_16x16x32_bf16 v[8:11], v[176:179], v[228:231], v[8:11]
	v_mfma_f32_16x16x32_bf16 v[60:63], v[172:175], v[204:207], v[60:63]
	v_mfma_f32_16x16x32_bf16 v[56:59], v[180:183], v[204:207], v[56:59]
	v_mfma_f32_16x16x32_bf16 v[48:51], v[172:175], v[212:215], v[48:51]
	v_mfma_f32_16x16x32_bf16 v[40:43], v[180:183], v[212:215], v[40:43]
	v_mfma_f32_16x16x32_bf16 v[32:35], v[172:175], v[224:227], v[32:35]
	v_mfma_f32_16x16x32_bf16 v[24:27], v[180:183], v[224:227], v[24:27]
	v_mfma_f32_16x16x32_bf16 v[16:19], v[172:175], v[232:235], v[16:19]
	v_mfma_f32_16x16x32_bf16 v[8:11], v[180:183], v[232:235], v[8:11]
	s_setprio 0
	s_setprio 1
	v_mfma_f32_16x16x32_bf16 v[52:55], v[184:187], v[200:203], v[52:55]
	v_mfma_f32_16x16x32_bf16 v[44:47], v[192:195], v[200:203], v[44:47]
	v_mfma_f32_16x16x32_bf16 v[36:39], v[184:187], v[208:211], v[36:39]
	v_mfma_f32_16x16x32_bf16 v[28:31], v[192:195], v[208:211], v[28:31]
	v_mfma_f32_16x16x32_bf16 v[20:23], v[184:187], v[216:219], v[20:23]
	v_mfma_f32_16x16x32_bf16 v[12:15], v[192:195], v[216:219], v[12:15]
	v_mfma_f32_16x16x32_bf16 v[4:7], v[184:187], v[228:231], v[4:7]
	v_mfma_f32_16x16x32_bf16 v[0:3], v[192:195], v[228:231], v[0:3]
	v_mfma_f32_16x16x32_bf16 v[52:55], v[188:191], v[204:207], v[52:55]
	v_mfma_f32_16x16x32_bf16 v[44:47], v[196:199], v[204:207], v[44:47]
	v_mfma_f32_16x16x32_bf16 v[36:39], v[188:191], v[212:215], v[36:39]
	v_mfma_f32_16x16x32_bf16 v[28:31], v[196:199], v[212:215], v[28:31]
	v_mfma_f32_16x16x32_bf16 v[20:23], v[188:191], v[224:227], v[20:23]
	v_mfma_f32_16x16x32_bf16 v[12:15], v[196:199], v[224:227], v[12:15]
	v_mfma_f32_16x16x32_bf16 v[4:7], v[188:191], v[232:235], v[4:7]
	v_mfma_f32_16x16x32_bf16 v[0:3], v[196:199], v[232:235], v[0:3]
	s_setprio 0
	s_barrier
; #define PG8_STAGE(bufoff, gbase, voff) do { _Pragma("unroll") for (int _i = 0; _i < 2; ++_i) \
;         __builtin_amdgcn_global_load_lds((const unsigned*)((const char*)(gbase) + (voff)[_i]), (PG8_LAS unsigned*)(lds + (bufoff) + ldsw + _i * 8192), 16, 0, 0); } while (0)
; #define PG8_LDA(dst, b, h) do { _Pragma("unroll") for (int m = 0; m < 4; ++m) _Pragma("unroll") for (int k = 0; k < 2; ++k) dst[m][k] = *(const PG8_LAS bf16x8*)(lds + PG8_SA(b, h) + aoff + m * 2048 + k * 1024); } while (0)
; #define PG8_LDB(dst, b, h) do { _Pragma("unroll") for (int n = 0; n < 2; ++n) _Pragma("unroll") for (int k = 0; k < 2; ++k) dst[n][k] = *(const PG8_LAS bf16x8*)(lds + PG8_SB(b, h) + boff + n * 2048 + k * 1024); } while (0)
; #define PG8_MMA(ai, bj, At, Bt) do { __builtin_amdgcn_s_setprio(1); _Pragma("unroll") for (int m = 0; m < 4; ++m) _Pragma("unroll") for (int n = 0; n < 2; ++n) _Pragma("unroll") for (int k = 0; k < 2; ++k) \
;         acc[ai][bj][m][n] = __builtin_amdgcn_mfma_f32_16x16x32_bf16(Bt[n][k], At[m][k], acc[ai][bj][m][n], 0, 0, 0); __builtin_amdgcn_s_setprio(0); } while (0)
; template <class Epi, class Sched, bool ALIGN_EPI = false, bool SP2 = false>
; __device__ __forceinline__ void gemm_phase(PG8_LAS unsigned char* lds, const Gemm g, const Sched& S, const Epi& E) {
;     ...
;             PG8_LDB(B0, 0, 0); PG8_LDB(B1, 0, 1); PG8_SCHED; PG8_LDA(At, 0, 0); PG8_STAGE(PG8_SA(1, 1), a1 + hstep, voffA);
;             PG8_WAIT_V(8); PG8_WAIT_L(0); PG8_BAR; PG8_MMA(0, 0, At, B0); PG8_MMA(0, 1, At, B1); PG8_BAR; PG8_SCHED;
;             PG8_LDA(At, 0, 1); PG8_STAGE(PG8_SB(0, 0), b2, voffB); PG8_STAGE(PG8_SB(0, 1), b2 + hstep, voffB); PG8_STAGE(PG8_SA(0, 0), a2, voffA);
;             PG8_WAIT_V(8); PG8_WAIT_L(0); PG8_BAR; PG8_MMA(1, 0, At, B0); PG8_MMA(1, 1, At, B1); PG8_BAR; PG8_SCHED;
;             PG8_LDB(B0, 1, 0); PG8_LDB(B1, 1, 1); PG8_SCHED; PG8_LDA(At, 1, 0); PG8_STAGE(PG8_SA(0, 1), a2 + hstep, voffA);
;             PG8_WAIT_V(8); PG8_WAIT_L(0); PG8_BAR; PG8_MMA(0, 0, At, B0); PG8_MMA(0, 1, At, B1); PG8_BAR; PG8_SCHED;
;             PG8_LDA(At, 1, 1); PG8_STAGE(PG8_SB(1, 0), b3, voffB); PG8_STAGE(PG8_SB(1, 1), b3 + hstep, voffB); PG8_STAGE(PG8_SA(1, 0), a3, voffA);
;             PG8_WAIT_V(8); PG8_WAIT_L(0); PG8_BAR; PG8_MMA(1, 0, At, B0); PG8_MMA(1, 1, At, B1); PG8_BAR; PG8_SCHED;
;     ...
;         if constexpr (ALIGN_EPI) { if (wr == 0) PG8_BAR; }
	ds_read_b128 v[168:171], v158
	ds_read_b128 v[172:175], v159
	ds_read_b128 v[176:179], v160
	ds_read_b128 v[180:183], v161
	ds_read_b128 v[184:187], v162
	ds_read_b128 v[188:191], v163
	ds_read_b128 v[192:195], v164
	ds_read_b128 v[196:199], v165
	s_add_u32 s66, s66, 0x40000
	s_addc_u32 s67, s67, 0
	s_mov_b32 m0, s43
	v_lshl_add_u64 v[240:241], s[66:67], 0, v[128:129]
	ds_read_b128 v[200:203], v148 offset:32768
	ds_read_b128 v[204:207], v148 offset:33792
	ds_read_b128 v[208:211], v148 offset:34816
	ds_read_b128 v[212:215], v148 offset:35840
	ds_read_b128 v[216:219], v148 offset:36864
	ds_read_b128 v[224:227], v148 offset:37888
	ds_read_b128 v[228:231], v148 offset:38912
	ds_read_b128 v[232:235], v148 offset:39936
	global_load_lds_dwordx4 v[240:241], off
	s_mov_b32 m0, s57
	v_lshl_add_u64 v[240:241], s[66:67], 0, v[132:133]
	global_load_lds_dwordx4 v[240:241], off
	s_waitcnt vmcnt(8)
	s_waitcnt lgkmcnt(0)
	s_barrier
	s_setprio 1
	s_waitcnt lgkmcnt(0)
	v_mfma_f32_16x16x32_bf16 v[124:127], v[168:171], v[200:203], v[124:127]
	v_mfma_f32_16x16x32_bf16 v[120:123], v[176:179], v[200:203], v[120:123]
	v_mfma_f32_16x16x32_bf16 v[112:115], v[168:171], v[208:211], v[112:115]
	v_mfma_f32_16x16x32_bf16 v[104:107], v[176:179], v[208:211], v[104:107]
	v_mfma_f32_16x16x32_bf16 v[96:99], v[168:171], v[216:219], v[96:99]
	v_mfma_f32_16x16x32_bf16 v[88:91], v[176:179], v[216:219], v[88:91]
	v_mfma_f32_16x16x32_bf16 v[80:83], v[168:171], v[228:231], v[80:83]
	v_mfma_f32_16x16x32_bf16 v[72:75], v[176:179], v[228:231], v[72:75]
	v_mfma_f32_16x16x32_bf16 v[124:127], v[172:175], v[204:207], v[124:127]
	v_mfma_f32_16x16x32_bf16 v[120:123], v[180:183], v[204:207], v[120:123]
	v_mfma_f32_16x16x32_bf16 v[112:115], v[172:175], v[212:215], v[112:115]
	v_mfma_f32_16x16x32_bf16 v[104:107], v[180:183], v[212:215], v[104:107]
	v_mfma_f32_16x16x32_bf16 v[96:99], v[172:175], v[224:227], v[96:99]
	v_mfma_f32_16x16x32_bf16 v[88:91], v[180:183], v[224:227], v[88:91]
	v_mfma_f32_16x16x32_bf16 v[80:83], v[172:175], v[232:235], v[80:83]
	v_mfma_f32_16x16x32_bf16 v[72:75], v[180:183], v[232:235], v[72:75]
	s_setprio 0
	s_setprio 1
	v_mfma_f32_16x16x32_bf16 v[116:119], v[184:187], v[200:203], v[116:119]
	v_mfma_f32_16x16x32_bf16 v[108:111], v[192:195], v[200:203], v[108:111]
	v_mfma_f32_16x16x32_bf16 v[100:103], v[184:187], v[208:211], v[100:103]
	v_mfma_f32_16x16x32_bf16 v[92:95], v[192:195], v[208:211], v[92:95]
	v_mfma_f32_16x16x32_bf16 v[84:87], v[184:187], v[216:219], v[84:87]
	v_mfma_f32_16x16x32_bf16 v[76:79], v[192:195], v[216:219], v[76:79]
	v_mfma_f32_16x16x32_bf16 v[68:71], v[184:187], v[228:231], v[68:71]
	v_mfma_f32_16x16x32_bf16 v[64:67], v[192:195], v[228:231], v[64:67]
	v_mfma_f32_16x16x32_bf16 v[116:119], v[188:191], v[204:207], v[116:119]
	v_mfma_f32_16x16x32_bf16 v[108:111], v[196:199], v[204:207], v[108:111]
	v_mfma_f32_16x16x32_bf16 v[100:103], v[188:191], v[212:215], v[100:103]
	v_mfma_f32_16x16x32_bf16 v[92:95], v[196:199], v[212:215], v[92:95]
	v_mfma_f32_16x16x32_bf16 v[84:87], v[188:191], v[224:227], v[84:87]
	v_mfma_f32_16x16x32_bf16 v[76:79], v[196:199], v[224:227], v[76:79]
	v_mfma_f32_16x16x32_bf16 v[68:71], v[188:191], v[232:235], v[68:71]
	v_mfma_f32_16x16x32_bf16 v[64:67], v[196:199], v[232:235], v[64:67]
	s_setprio 0
	s_barrier
	s_mov_b32 m0, s71
	v_lshl_add_u64 v[146:147], v[146:147], 0, s[10:11]
	s_add_u32 s64, s64, 0x40080
	ds_read_b128 v[200:203], v148 offset:49152
	ds_read_b128 v[204:207], v148 offset:50176
	ds_read_b128 v[208:211], v148 offset:51200
	ds_read_b128 v[212:215], v148 offset:52224
	ds_read_b128 v[216:219], v148 offset:53248
	ds_read_b128 v[224:227], v148 offset:54272
	ds_read_b128 v[228:231], v148 offset:55296
	ds_read_b128 v[232:235], v148 offset:56320
	global_load_lds_dwordx4 v[146:147], off
	v_lshl_add_u64 v[146:147], v[220:221], 0, s[10:11]
	s_mov_b32 m0, s72
	s_addc_u32 s65, s65, 0
	global_load_lds_dwordx4 v[146:147], off
	s_mov_b32 m0, s75
	v_lshl_add_u64 v[146:147], s[64:65], 0, v[130:131]
	global_load_lds_dwordx4 v[146:147], off
	s_mov_b32 m0, s76
	v_lshl_add_u64 v[146:147], s[64:65], 0, v[134:135]
	global_load_lds_dwordx4 v[146:147], off
	s_mov_b32 m0, s73
	v_lshl_add_u64 v[146:147], v[236:237], 0, s[10:11]
	global_load_lds_dwordx4 v[146:147], off
	s_mov_b32 m0, s74
	v_lshl_add_u64 v[146:147], v[238:239], 0, s[10:11]
	global_load_lds_dwordx4 v[146:147], off
	s_waitcnt vmcnt(8)
	s_waitcnt lgkmcnt(0)
	s_barrier
	s_setprio 1
	s_waitcnt lgkmcnt(0)
	v_mfma_f32_16x16x32_bf16 v[60:63], v[168:171], v[200:203], v[60:63]
	v_mfma_f32_16x16x32_bf16 v[56:59], v[176:179], v[200:203], v[56:59]
	v_mfma_f32_16x16x32_bf16 v[48:51], v[168:171], v[208:211], v[48:51]
	v_mfma_f32_16x16x32_bf16 v[40:43], v[176:179], v[208:211], v[40:43]
	v_mfma_f32_16x16x32_bf16 v[32:35], v[168:171], v[216:219], v[32:35]
	v_mfma_f32_16x16x32_bf16 v[24:27], v[176:179], v[216:219], v[24:27]
	v_mfma_f32_16x16x32_bf16 v[16:19], v[168:171], v[228:231], v[16:19]
	v_mfma_f32_16x16x32_bf16 v[8:11], v[176:179], v[228:231], v[8:11]
	v_mfma_f32_16x16x32_bf16 v[60:63], v[172:175], v[204:207], v[60:63]
	v_mfma_f32_16x16x32_bf16 v[56:59], v[180:183], v[204:207], v[56:59]
	v_mfma_f32_16x16x32_bf16 v[48:51], v[172:175], v[212:215], v[48:51]
	v_mfma_f32_16x16x32_bf16 v[40:43], v[180:183], v[212:215], v[40:43]
	v_mfma_f32_16x16x32_bf16 v[32:35], v[172:175], v[224:227], v[32:35]
	v_mfma_f32_16x16x32_bf16 v[24:27], v[180:183], v[224:227], v[24:27]
	v_mfma_f32_16x16x32_bf16 v[16:19], v[172:175], v[232:235], v[16:19]
	v_mfma_f32_16x16x32_bf16 v[8:11], v[180:183], v[232:235], v[8:11]
	s_setprio 0
	s_setprio 1
	v_mfma_f32_16x16x32_bf16 v[52:55], v[184:187], v[200:203], v[52:55]
	v_mfma_f32_16x16x32_bf16 v[44:47], v[192:195], v[200:203], v[44:47]
	v_mfma_f32_16x16x32_bf16 v[36:39], v[184:187], v[208:211], v[36:39]
	v_mfma_f32_16x16x32_bf16 v[28:31], v[192:195], v[208:211], v[28:31]
	v_mfma_f32_16x16x32_bf16 v[20:23], v[184:187], v[216:219], v[20:23]
	v_mfma_f32_16x16x32_bf16 v[12:15], v[192:195], v[216:219], v[12:15]
	v_mfma_f32_16x16x32_bf16 v[4:7], v[184:187], v[228:231], v[4:7]
	v_mfma_f32_16x16x32_bf16 v[0:3], v[192:195], v[228:231], v[0:3]
	v_mfma_f32_16x16x32_bf16 v[52:55], v[188:191], v[204:207], v[52:55]
	v_mfma_f32_16x16x32_bf16 v[44:47], v[196:199], v[204:207], v[44:47]
	v_mfma_f32_16x16x32_bf16 v[36:39], v[188:191], v[212:215], v[36:39]
	v_mfma_f32_16x16x32_bf16 v[28:31], v[196:199], v[212:215], v[28:31]
	v_mfma_f32_16x16x32_bf16 v[20:23], v[188:191], v[224:227], v[20:23]
	v_mfma_f32_16x16x32_bf16 v[12:15], v[196:199], v[224:227], v[12:15]
	v_mfma_f32_16x16x32_bf16 v[4:7], v[188:191], v[232:235], v[4:7]
	v_mfma_f32_16x16x32_bf16 v[0:3], v[196:199], v[232:235], v[0:3]
	s_setprio 0
	s_barrier
	s_add_i32 s87, s87, 2
	s_add_u32 s58, s58, 0x100
	s_addc_u32 s59, s59, 0
	s_add_u32 s85, s85, 0x100
	s_addc_u32 s86, s86, 0
	s_cmp_gt_u32 s87, 13
	s_cbranch_scc0 .LBB0_189
	s_and_b64 vcc, exec, s[12:13]
	s_cbranch_vccz .LBB0_192
	s_barrier

;     __host__ __device__ bool next(int i, Unit& u) const { const int L = i * G + c; if (L >= 16 * nkc) return false; u.kc = L % nkc; const int t = L / nkc; u.pn = t & 3; u.pm = 33 * (t >> 2); return true; }
; #define PG8_LDA(dst, b, h) do { _Pragma("unroll") for (int m = 0; m < 4; ++m) _Pragma("unroll") for (int k = 0; k < 2; ++k) dst[m][k] = *(const PG8_LAS bf16x8*)(lds + PG8_SA(b, h) + aoff + m * 2048 + k * 1024); } while (0)
; template <class Epi, class Sched, bool ALIGN_EPI = false, bool SP2 = false>
; __device__ __forceinline__ void gemm_phase(PG8_LAS unsigned char* lds, const Gemm g, const Sched& S, const Epi& E) {
;     ...
;         const bool has_next = S.next(ui + 1, nxt);
;         const char* nA = has_next ? (const char*)g.A + (size_t)nxt.pm * tstep + (size_t)nxt.kc * cstep : cA; const char* nB = has_next ? (const char*)g.Bt + (size_t)nxt.pn * tstep + (size_t)nxt.kc * cstep : cB;
;         for (int t = 0; t < nt; t += 2) {
;             const bool last = (t == nt - 2);
;             const char* a1 = cA + (size_t)(t + 1) * kstep;
;             const char* a2 = last ? nA : cA + (size_t)(t + 2) * kstep; const char* b2 = last ? nB : cB + (size_t)(t + 2) * kstep;
;             const char* a3 = a2 + kstep; const char* b3 = b2 + kstep;
;             if (last && has_next) S.a_ready(nxt);
;             if constexpr (SP2) {
;             PG8_LDB(B0, 0, 0); PG8_LDB(B1, 0, 1); PG8_SCHED; PG8_LDA(At, 0, 0); PG8_STAGE(PG8_SA(1, 1), a1 + hstep, voffA);
;             PG8_WAIT_V(8); PG8_WAIT_L(0); PG8_BAR; PG8_MMA(0, 0, At, B0); PG8_MMA(0, 1, At, B1); PG8_BAR; PG8_SCHED;
;             PG8_LDA(At, 0, 1); PG8_STAGE(PG8_SB(0, 0), b2, voffB); PG8_STAGE(PG8_SB(0, 1), b2 + hstep, voffB); PG8_STAGE(PG8_SA(0, 0), a2, voffA);
;             PG8_WAIT_V(8); PG8_WAIT_L(0); PG8_BAR; PG8_MMA(1, 0, At, B0); PG8_MMA(1, 1, At, B1); PG8_BAR; PG8_SCHED;
;             PG8_LDB(B0, 1, 0); PG8_LDB(B1, 1, 1); PG8_SCHED; PG8_LDA(At, 1, 0); PG8_STAGE(PG8_SA(0, 1), a2 + hstep, voffA);
;             PG8_WAIT_V(8); PG8_WAIT_L(0); PG8_BAR; PG8_MMA(0, 0, At, B0); PG8_MMA(0, 1, At, B1); PG8_BAR; PG8_SCHED;
;             PG8_LDA(At, 1, 1); PG8_STAGE(PG8_SB(1, 0), b3, voffB); PG8_STAGE(PG8_SB(1, 1), b3 + hstep, voffB); PG8_STAGE(PG8_SA(1, 0), a3, voffA);
;             PG8_WAIT_V(8); PG8_WAIT_L(0); PG8_BAR; PG8_MMA(1, 0, At, B0); PG8_MMA(1, 1, At, B1); PG8_BAR; PG8_SCHED;
.LBB0_633:
	s_ashr_i32 s57, s56, 31
	s_lshl_b64 s[6:7], s[56:57], 19
	s_add_u32 s58, s46, s6
	s_addc_u32 s59, s47, s7
	s_and_b64 s[6:7], s[4:5], exec
	s_cselect_b32 s57, s59, s65
	s_cselect_b32 vcc_lo, s58, s64
	s_ashr_i32 s55, s54, 31
	s_lshl_b64 s[6:7], s[54:55], 19
	s_add_u32 s60, s0, s6
	s_addc_u32 s61, s1, s7
	s_and_b64 s[6:7], s[4:5], exec
	s_cselect_b32 s55, s61, s67
	s_cselect_b32 vcc_hi, s60, s66
	s_add_u32 s90, s66, 0x100
	s_addc_u32 s92, s67, 0
	s_mov_b32 s6, -2
	s_waitcnt vmcnt(0)
	ds_read_b128 v[142:145], v174
	ds_read_b128 v[146:149], v175
	ds_read_b128 v[150:153], v176
	ds_read_b128 v[154:157], v177
	ds_read_b128 v[158:161], v178
	ds_read_b128 v[162:165], v179
	ds_read_b128 v[166:169], v180
	ds_read_b128 v[190:193], v181
	s_add_u32 s66, s64, 0x100
	s_addc_u32 s67, s65, 0
	s_cmp_eq_u32 s6, 12
	s_cselect_b32 s73, s57, s67
	s_cselect_b32 s72, vcc_lo, s66
	s_cselect_b32 s71, s55, s92
	s_cselect_b32 s70, vcc_hi, s90
	s_mov_b32 m0, s86
	v_lshl_add_u64 v[170:171], s[64:65], 0, v[134:135]
	ds_read_b128 v[194:197], v172
	ds_read_b128 v[198:201], v172 offset:1024
	ds_read_b128 v[202:205], v172 offset:2048
	ds_read_b128 v[206:209], v172 offset:3072
	ds_read_b128 v[210:213], v172 offset:4096
	ds_read_b128 v[214:217], v172 offset:5120
	ds_read_b128 v[218:221], v172 offset:6144
	ds_read_b128 v[224:227], v172 offset:7168
	global_load_lds_dwordx4 v[170:171], off
	s_mov_b32 m0, s87
	v_lshl_add_u64 v[170:171], s[64:65], 0, v[136:137]
	global_load_lds_dwordx4 v[170:171], off
	s_waitcnt vmcnt(8)
	s_waitcnt lgkmcnt(0)
	s_barrier
	s_setprio 1
	s_waitcnt lgkmcnt(0)
	v_mfma_f32_16x16x32_bf16 v[124:127], v[142:145], v[194:197], 0
	v_mfma_f32_16x16x32_bf16 v[108:111], v[150:153], v[194:197], 0
	v_mfma_f32_16x16x32_bf16 v[120:123], v[142:145], v[202:205], 0
	v_mfma_f32_16x16x32_bf16 v[96:99], v[150:153], v[202:205], 0
	v_mfma_f32_16x16x32_bf16 v[116:119], v[142:145], v[210:213], 0
	v_mfma_f32_16x16x32_bf16 v[88:91], v[150:153], v[210:213], 0
	v_mfma_f32_16x16x32_bf16 v[112:115], v[142:145], v[218:221], 0
	v_mfma_f32_16x16x32_bf16 v[84:87], v[150:153], v[218:221], 0
	v_mfma_f32_16x16x32_bf16 v[124:127], v[146:149], v[198:201], v[124:127]
	v_mfma_f32_16x16x32_bf16 v[108:111], v[154:157], v[198:201], v[108:111]
	v_mfma_f32_16x16x32_bf16 v[120:123], v[146:149], v[206:209], v[120:123]
	v_mfma_f32_16x16x32_bf16 v[96:99], v[154:157], v[206:209], v[96:99]
	v_mfma_f32_16x16x32_bf16 v[116:119], v[146:149], v[214:217], v[116:119]
	v_mfma_f32_16x16x32_bf16 v[88:91], v[154:157], v[214:217], v[88:91]
	v_mfma_f32_16x16x32_bf16 v[112:115], v[146:149], v[224:227], v[112:115]
	v_mfma_f32_16x16x32_bf16 v[84:87], v[154:157], v[224:227], v[84:87]
	s_setprio 0
	s_setprio 1
	v_mfma_f32_16x16x32_bf16 v[68:71], v[158:161], v[194:197], 0
	v_mfma_f32_16x16x32_bf16 v[40:43], v[166:169], v[194:197], 0
	v_mfma_f32_16x16x32_bf16 v[60:63], v[158:161], v[202:205], 0
	v_mfma_f32_16x16x32_bf16 v[32:35], v[166:169], v[202:205], 0
	v_mfma_f32_16x16x32_bf16 v[52:55], v[158:161], v[210:213], 0
	v_mfma_f32_16x16x32_bf16 v[24:27], v[166:169], v[210:213], 0
	v_mfma_f32_16x16x32_bf16 v[48:51], v[158:161], v[218:221], 0
	v_mfma_f32_16x16x32_bf16 v[16:19], v[166:169], v[218:221], 0
	v_mfma_f32_16x16x32_bf16 v[68:71], v[162:165], v[198:201], v[68:71]
	v_mfma_f32_16x16x32_bf16 v[40:43], v[190:193], v[198:201], v[40:43]
	v_mfma_f32_16x16x32_bf16 v[60:63], v[162:165], v[206:209], v[60:63]
	v_mfma_f32_16x16x32_bf16 v[32:35], v[190:193], v[206:209], v[32:35]
	v_mfma_f32_16x16x32_bf16 v[52:55], v[162:165], v[214:217], v[52:55]
	v_mfma_f32_16x16x32_bf16 v[24:27], v[190:193], v[214:217], v[24:27]
	v_mfma_f32_16x16x32_bf16 v[48:51], v[162:165], v[224:227], v[48:51]
	v_mfma_f32_16x16x32_bf16 v[16:19], v[190:193], v[224:227], v[16:19]
	s_setprio 0
	s_barrier
	s_mov_b32 m0, s13
	v_lshl_add_u64 v[170:171], s[70:71], 0, v[128:129]
	s_add_u32 s64, s70, 0x40000
	ds_read_b128 v[194:197], v172 offset:16384
	ds_read_b128 v[198:201], v172 offset:17408
	ds_read_b128 v[202:205], v172 offset:18432
	ds_read_b128 v[206:209], v172 offset:19456
	ds_read_b128 v[210:213], v172 offset:20480
	ds_read_b128 v[214:217], v172 offset:21504
	ds_read_b128 v[218:221], v172 offset:22528
	ds_read_b128 v[224:227], v172 offset:23552
	global_load_lds_dwordx4 v[170:171], off
	v_lshl_add_u64 v[228:229], s[70:71], 0, v[130:131]
	s_mov_b32 m0, s14
	s_addc_u32 s65, s71, 0
	global_load_lds_dwordx4 v[228:229], off
	v_lshl_add_u64 v[230:231], s[64:65], 0, v[128:129]
	s_mov_b32 m0, s15
	v_lshl_add_u64 v[232:233], s[72:73], 0, v[130:131]
	global_load_lds_dwordx4 v[230:231], off
	s_mov_b32 m0, s33
	v_lshl_add_u64 v[230:231], s[64:65], 0, v[130:131]
	global_load_lds_dwordx4 v[230:231], off
	s_mov_b32 m0, s12
	v_lshl_add_u64 v[230:231], s[72:73], 0, v[128:129]
	global_load_lds_dwordx4 v[230:231], off
	s_mov_b32 m0, s39
	s_nop 0
	global_load_lds_dwordx4 v[232:233], off
	s_waitcnt vmcnt(8)
	s_waitcnt lgkmcnt(0)
	s_barrier
; #define PG8_STAGE(bufoff, gbase, voff) do { _Pragma("unroll") for (int _i = 0; _i < 2; ++_i) \
;         __builtin_amdgcn_global_load_lds((const unsigned*)((const char*)(gbase) + (voff)[_i]), (PG8_LAS unsigned*)(lds + (bufoff) + ldsw + _i * 8192), 16, 0, 0); } while (0)
; #define PG8_LDA(dst, b, h) do { _Pragma("unroll") for (int m = 0; m < 4; ++m) _Pragma("unroll") for (int k = 0; k < 2; ++k) dst[m][k] = *(const PG8_LAS bf16x8*)(lds + PG8_SA(b, h) + aoff + m * 2048 + k * 1024); } while (0)
; #define PG8_LDB(dst, b, h) do { _Pragma("unroll") for (int n = 0; n < 2; ++n) _Pragma("unroll") for (int k = 0; k < 2; ++k) dst[n][k] = *(const PG8_LAS bf16x8*)(lds + PG8_SB(b, h) + boff + n * 2048 + k * 1024); } while (0)
; #define PG8_MMA(ai, bj, At, Bt) do { __builtin_amdgcn_s_setprio(1); _Pragma("unroll") for (int m = 0; m < 4; ++m) _Pragma("unroll") for (int n = 0; n < 2; ++n) _Pragma("unroll") for (int k = 0; k < 2; ++k) \
;         acc[ai][bj][m][n] = __builtin_amdgcn_mfma_f32_16x16x32_bf16(Bt[n][k], At[m][k], acc[ai][bj][m][n], 0, 0, 0); __builtin_amdgcn_s_setprio(0); } while (0)
; #define PG8_WAIT_V(n) asm volatile("s_waitcnt vmcnt(" #n ")" ::: "memory")
; template <class Epi, class Sched, bool ALIGN_EPI = false, bool SP2 = false>
; __device__ __forceinline__ void gemm_phase(PG8_LAS unsigned char* lds, const Gemm g, const Sched& S, const Epi& E) {
;     ...
;             PG8_LDB(B0, 0, 0); PG8_LDB(B1, 0, 1); PG8_SCHED; PG8_LDA(At, 0, 0); PG8_STAGE(PG8_SA(1, 1), a1 + hstep, voffA);
;             PG8_WAIT_V(8); PG8_WAIT_L(0); PG8_BAR; PG8_MMA(0, 0, At, B0); PG8_MMA(0, 1, At, B1); PG8_BAR; PG8_SCHED;
;             PG8_LDA(At, 0, 1); PG8_STAGE(PG8_SB(0, 0), b2, voffB); PG8_STAGE(PG8_SB(0, 1), b2 + hstep, voffB); PG8_STAGE(PG8_SA(0, 0), a2, voffA);
;             PG8_WAIT_V(8); PG8_WAIT_L(0); PG8_BAR; PG8_MMA(1, 0, At, B0); PG8_MMA(1, 1, At, B1); PG8_BAR; PG8_SCHED;
;             PG8_LDB(B0, 1, 0); PG8_LDB(B1, 1, 1); PG8_SCHED; PG8_LDA(At, 1, 0); PG8_STAGE(PG8_SA(0, 1), a2 + hstep, voffA);
;             PG8_WAIT_V(8); PG8_WAIT_L(0); PG8_BAR; PG8_MMA(0, 0, At, B0); PG8_MMA(0, 1, At, B1); PG8_BAR; PG8_SCHED;
;             PG8_LDA(At, 1, 1); PG8_STAGE(PG8_SB(1, 0), b3, voffB); PG8_STAGE(PG8_SB(1, 1), b3 + hstep, voffB); PG8_STAGE(PG8_SA(1, 0), a3, voffA);
;             PG8_WAIT_V(8); PG8_WAIT_L(0); PG8_BAR; PG8_MMA(1, 0, At, B0); PG8_MMA(1, 1, At, B1); PG8_BAR; PG8_SCHED;
	s_setprio 1
	s_waitcnt lgkmcnt(0)
	v_mfma_f32_16x16x32_bf16 v[104:107], v[142:145], v[194:197], 0
	v_mfma_f32_16x16x32_bf16 v[76:79], v[150:153], v[194:197], 0
	v_mfma_f32_16x16x32_bf16 v[100:103], v[142:145], v[202:205], 0
	v_mfma_f32_16x16x32_bf16 v[72:75], v[150:153], v[202:205], 0
	v_mfma_f32_16x16x32_bf16 v[92:95], v[142:145], v[210:213], 0
	v_mfma_f32_16x16x32_bf16 v[64:67], v[150:153], v[210:213], 0
	v_mfma_f32_16x16x32_bf16 v[80:83], v[142:145], v[218:221], 0
	v_mfma_f32_16x16x32_bf16 v[56:59], v[150:153], v[218:221], 0
	v_mfma_f32_16x16x32_bf16 v[104:107], v[146:149], v[198:201], v[104:107]
	v_mfma_f32_16x16x32_bf16 v[76:79], v[154:157], v[198:201], v[76:79]
	v_mfma_f32_16x16x32_bf16 v[100:103], v[146:149], v[206:209], v[100:103]
	v_mfma_f32_16x16x32_bf16 v[72:75], v[154:157], v[206:209], v[72:75]
	v_mfma_f32_16x16x32_bf16 v[92:95], v[146:149], v[214:217], v[92:95]
	v_mfma_f32_16x16x32_bf16 v[64:67], v[154:157], v[214:217], v[64:67]
	v_mfma_f32_16x16x32_bf16 v[80:83], v[146:149], v[224:227], v[80:83]
	v_mfma_f32_16x16x32_bf16 v[56:59], v[154:157], v[224:227], v[56:59]
	s_setprio 0
	s_setprio 1
	v_mfma_f32_16x16x32_bf16 v[44:47], v[158:161], v[194:197], 0
	v_mfma_f32_16x16x32_bf16 v[12:15], v[166:169], v[194:197], 0
	v_mfma_f32_16x16x32_bf16 v[36:39], v[158:161], v[202:205], 0
	v_mfma_f32_16x16x32_bf16 v[8:11], v[166:169], v[202:205], 0
	v_mfma_f32_16x16x32_bf16 v[28:31], v[158:161], v[210:213], 0
	v_mfma_f32_16x16x32_bf16 v[4:7], v[166:169], v[210:213], 0
	v_mfma_f32_16x16x32_bf16 v[20:23], v[158:161], v[218:221], 0
	v_mfma_f32_16x16x32_bf16 v[0:3], v[166:169], v[218:221], 0
	v_mfma_f32_16x16x32_bf16 v[44:47], v[162:165], v[198:201], v[44:47]
	v_mfma_f32_16x16x32_bf16 v[12:15], v[190:193], v[198:201], v[12:15]
	v_mfma_f32_16x16x32_bf16 v[36:39], v[162:165], v[206:209], v[36:39]
	v_mfma_f32_16x16x32_bf16 v[8:11], v[190:193], v[206:209], v[8:11]
	v_mfma_f32_16x16x32_bf16 v[28:31], v[162:165], v[214:217], v[28:31]
	v_mfma_f32_16x16x32_bf16 v[4:7], v[190:193], v[214:217], v[4:7]
	v_mfma_f32_16x16x32_bf16 v[20:23], v[162:165], v[224:227], v[20:23]
	v_mfma_f32_16x16x32_bf16 v[0:3], v[190:193], v[224:227], v[0:3]
	s_setprio 0
	s_barrier
	ds_read_b128 v[142:145], v182
	ds_read_b128 v[146:149], v183
	ds_read_b128 v[150:153], v184
	ds_read_b128 v[154:157], v185
	ds_read_b128 v[158:161], v186
	ds_read_b128 v[162:165], v187
	ds_read_b128 v[166:169], v188
	ds_read_b128 v[190:193], v189
	s_add_u32 s64, s72, 0x40000
	s_addc_u32 s65, s73, 0
	s_mov_b32 m0, s43
	v_lshl_add_u64 v[234:235], s[64:65], 0, v[128:129]
	ds_read_b128 v[194:197], v172 offset:32768
	ds_read_b128 v[198:201], v172 offset:33792
	ds_read_b128 v[202:205], v172 offset:34816
	ds_read_b128 v[206:209], v172 offset:35840
	ds_read_b128 v[210:213], v172 offset:36864
	ds_read_b128 v[214:217], v172 offset:37888
	ds_read_b128 v[218:221], v172 offset:38912
	ds_read_b128 v[224:227], v172 offset:39936
	global_load_lds_dwordx4 v[234:235], off
	s_mov_b32 m0, s74
	v_lshl_add_u64 v[234:235], s[64:65], 0, v[130:131]
	global_load_lds_dwordx4 v[234:235], off
	s_waitcnt vmcnt(8)
	s_waitcnt lgkmcnt(0)
	s_barrier
	s_setprio 1
	s_waitcnt lgkmcnt(0)
	v_mfma_f32_16x16x32_bf16 v[124:127], v[142:145], v[194:197], v[124:127]
	v_mfma_f32_16x16x32_bf16 v[108:111], v[150:153], v[194:197], v[108:111]
	v_mfma_f32_16x16x32_bf16 v[120:123], v[142:145], v[202:205], v[120:123]
	v_mfma_f32_16x16x32_bf16 v[96:99], v[150:153], v[202:205], v[96:99]
	v_mfma_f32_16x16x32_bf16 v[116:119], v[142:145], v[210:213], v[116:119]
	v_mfma_f32_16x16x32_bf16 v[88:91], v[150:153], v[210:213], v[88:91]
	v_mfma_f32_16x16x32_bf16 v[112:115], v[142:145], v[218:221], v[112:115]
	v_mfma_f32_16x16x32_bf16 v[84:87], v[150:153], v[218:221], v[84:87]
	v_mfma_f32_16x16x32_bf16 v[124:127], v[146:149], v[198:201], v[124:127]
	v_mfma_f32_16x16x32_bf16 v[108:111], v[154:157], v[198:201], v[108:111]
	v_mfma_f32_16x16x32_bf16 v[120:123], v[146:149], v[206:209], v[120:123]
	v_mfma_f32_16x16x32_bf16 v[96:99], v[154:157], v[206:209], v[96:99]
	v_mfma_f32_16x16x32_bf16 v[116:119], v[146:149], v[214:217], v[116:119]
	v_mfma_f32_16x16x32_bf16 v[88:91], v[154:157], v[214:217], v[88:91]
	v_mfma_f32_16x16x32_bf16 v[112:115], v[146:149], v[224:227], v[112:115]
	v_mfma_f32_16x16x32_bf16 v[84:87], v[154:157], v[224:227], v[84:87]
	s_setprio 0
	s_setprio 1
	v_mfma_f32_16x16x32_bf16 v[68:71], v[158:161], v[194:197], v[68:71]
	v_mfma_f32_16x16x32_bf16 v[40:43], v[166:169], v[194:197], v[40:43]
	v_mfma_f32_16x16x32_bf16 v[60:63], v[158:161], v[202:205], v[60:63]
	v_mfma_f32_16x16x32_bf16 v[32:35], v[166:169], v[202:205], v[32:35]
	v_mfma_f32_16x16x32_bf16 v[52:55], v[158:161], v[210:213], v[52:55]
	v_mfma_f32_16x16x32_bf16 v[24:27], v[166:169], v[210:213], v[24:27]
	v_mfma_f32_16x16x32_bf16 v[48:51], v[158:161], v[218:221], v[48:51]
	v_mfma_f32_16x16x32_bf16 v[16:19], v[166:169], v[218:221], v[16:19]
	v_mfma_f32_16x16x32_bf16 v[68:71], v[162:165], v[198:201], v[68:71]
	v_mfma_f32_16x16x32_bf16 v[40:43], v[190:193], v[198:201], v[40:43]
	v_mfma_f32_16x16x32_bf16 v[60:63], v[162:165], v[206:209], v[60:63]
	v_mfma_f32_16x16x32_bf16 v[32:35], v[190:193], v[206:209], v[32:35]
	v_mfma_f32_16x16x32_bf16 v[52:55], v[162:165], v[214:217], v[52:55]
	v_mfma_f32_16x16x32_bf16 v[24:27], v[190:193], v[214:217], v[24:27]
	v_mfma_f32_16x16x32_bf16 v[48:51], v[162:165], v[224:227], v[48:51]
	v_mfma_f32_16x16x32_bf16 v[16:19], v[190:193], v[224:227], v[16:19]
	s_setprio 0
	s_barrier
; #define PG8_STAGE(bufoff, gbase, voff) do { _Pragma("unroll") for (int _i = 0; _i < 2; ++_i) \
;         __builtin_amdgcn_global_load_lds((const unsigned*)((const char*)(gbase) + (voff)[_i]), (PG8_LAS unsigned*)(lds + (bufoff) + ldsw + _i * 8192), 16, 0, 0); } while (0)
; #define PG8_LDA(dst, b, h) do { _Pragma("unroll") for (int m = 0; m < 4; ++m) _Pragma("unroll") for (int k = 0; k < 2; ++k) dst[m][k] = *(const PG8_LAS bf16x8*)(lds + PG8_SA(b, h) + aoff + m * 2048 + k * 1024); } while (0)
; #define PG8_LDB(dst, b, h) do { _Pragma("unroll") for (int n = 0; n < 2; ++n) _Pragma("unroll") for (int k = 0; k < 2; ++k) dst[n][k] = *(const PG8_LAS bf16x8*)(lds + PG8_SB(b, h) + boff + n * 2048 + k * 1024); } while (0)
; template <class Epi, class Sched, bool ALIGN_EPI = false, bool SP2 = false>
; __device__ __forceinline__ void gemm_phase(PG8_LAS unsigned char* lds, const Gemm g, const Sched& S, const Epi& E) {
;     ...
;         for (int t = 0; t < nt; t += 2) {
;             const bool last = (t == nt - 2);
;             const char* a1 = cA + (size_t)(t + 1) * kstep;
;             const char* a2 = last ? nA : cA + (size_t)(t + 2) * kstep; const char* b2 = last ? nB : cB + (size_t)(t + 2) * kstep;
;             const char* a3 = a2 + kstep; const char* b3 = b2 + kstep;
;             if (last && has_next) S.a_ready(nxt);
;             if constexpr (SP2) {
;             PG8_LDB(B0, 0, 0); PG8_LDB(B1, 0, 1); PG8_SCHED; PG8_LDA(At, 0, 0); PG8_STAGE(PG8_SA(1, 1), a1 + hstep, voffA);
;             PG8_WAIT_V(8); PG8_WAIT_L(0); PG8_BAR; PG8_MMA(0, 0, At, B0); PG8_MMA(0, 1, At, B1); PG8_BAR; PG8_SCHED;
;             PG8_LDA(At, 0, 1); PG8_STAGE(PG8_SB(0, 0), b2, voffB); PG8_STAGE(PG8_SB(0, 1), b2 + hstep, voffB); PG8_STAGE(PG8_SA(0, 0), a2, voffA);
;             PG8_WAIT_V(8); PG8_WAIT_L(0); PG8_BAR; PG8_MMA(1, 0, At, B0); PG8_MMA(1, 1, At, B1); PG8_BAR; PG8_SCHED;
;             PG8_LDB(B0, 1, 0); PG8_LDB(B1, 1, 1); PG8_SCHED; PG8_LDA(At, 1, 0); PG8_STAGE(PG8_SA(0, 1), a2 + hstep, voffA);
;             PG8_WAIT_V(8); PG8_WAIT_L(0); PG8_BAR; PG8_MMA(0, 0, At, B0); PG8_MMA(0, 1, At, B1); PG8_BAR; PG8_SCHED;
;             PG8_LDA(At, 1, 1); PG8_STAGE(PG8_SB(1, 0), b3, voffB); PG8_STAGE(PG8_SB(1, 1), b3 + hstep, voffB); PG8_STAGE(PG8_SA(1, 0), a3, voffA);
;             PG8_WAIT_V(8); PG8_WAIT_L(0); PG8_BAR; PG8_MMA(1, 0, At, B0); PG8_MMA(1, 1, At, B1); PG8_BAR; PG8_SCHED;
	s_mov_b32 m0, s78
	v_lshl_add_u64 v[170:171], v[170:171], 0, s[10:11]
	s_add_u32 s64, s70, 0x40080
	ds_read_b128 v[194:197], v172 offset:49152
	ds_read_b128 v[198:201], v172 offset:50176
	ds_read_b128 v[202:205], v172 offset:51200
	ds_read_b128 v[206:209], v172 offset:52224
	ds_read_b128 v[210:213], v172 offset:53248
	ds_read_b128 v[214:217], v172 offset:54272
	ds_read_b128 v[218:221], v172 offset:55296
	ds_read_b128 v[224:227], v172 offset:56320
	global_load_lds_dwordx4 v[170:171], off
	v_lshl_add_u64 v[170:171], v[228:229], 0, s[10:11]
	s_mov_b32 m0, s79
	s_addc_u32 s65, s71, 0
	global_load_lds_dwordx4 v[170:171], off
	s_mov_b32 m0, s82
	v_lshl_add_u64 v[170:171], s[64:65], 0, v[128:129]
	global_load_lds_dwordx4 v[170:171], off
	s_mov_b32 m0, s83
	v_lshl_add_u64 v[170:171], s[64:65], 0, v[130:131]
	global_load_lds_dwordx4 v[170:171], off
	s_mov_b32 m0, s80
	v_lshl_add_u64 v[170:171], v[230:231], 0, s[10:11]
	global_load_lds_dwordx4 v[170:171], off
	s_mov_b32 m0, s81
	v_lshl_add_u64 v[170:171], v[232:233], 0, s[10:11]
	global_load_lds_dwordx4 v[170:171], off
	s_waitcnt vmcnt(8)
	s_waitcnt lgkmcnt(0)
	s_barrier
	s_setprio 1
	s_waitcnt lgkmcnt(0)
	v_mfma_f32_16x16x32_bf16 v[104:107], v[142:145], v[194:197], v[104:107]
	v_mfma_f32_16x16x32_bf16 v[76:79], v[150:153], v[194:197], v[76:79]
	v_mfma_f32_16x16x32_bf16 v[100:103], v[142:145], v[202:205], v[100:103]
	v_mfma_f32_16x16x32_bf16 v[72:75], v[150:153], v[202:205], v[72:75]
	v_mfma_f32_16x16x32_bf16 v[92:95], v[142:145], v[210:213], v[92:95]
	v_mfma_f32_16x16x32_bf16 v[64:67], v[150:153], v[210:213], v[64:67]
	v_mfma_f32_16x16x32_bf16 v[80:83], v[142:145], v[218:221], v[80:83]
	v_mfma_f32_16x16x32_bf16 v[56:59], v[150:153], v[218:221], v[56:59]
	v_mfma_f32_16x16x32_bf16 v[104:107], v[146:149], v[198:201], v[104:107]
	v_mfma_f32_16x16x32_bf16 v[76:79], v[154:157], v[198:201], v[76:79]
	v_mfma_f32_16x16x32_bf16 v[100:103], v[146:149], v[206:209], v[100:103]
	v_mfma_f32_16x16x32_bf16 v[72:75], v[154:157], v[206:209], v[72:75]
	v_mfma_f32_16x16x32_bf16 v[92:95], v[146:149], v[214:217], v[92:95]
	v_mfma_f32_16x16x32_bf16 v[64:67], v[154:157], v[214:217], v[64:67]
	v_mfma_f32_16x16x32_bf16 v[80:83], v[146:149], v[224:227], v[80:83]
	v_mfma_f32_16x16x32_bf16 v[56:59], v[154:157], v[224:227], v[56:59]
	s_setprio 0
	s_setprio 1
	v_mfma_f32_16x16x32_bf16 v[44:47], v[158:161], v[194:197], v[44:47]
	v_mfma_f32_16x16x32_bf16 v[12:15], v[166:169], v[194:197], v[12:15]
	v_mfma_f32_16x16x32_bf16 v[36:39], v[158:161], v[202:205], v[36:39]
	v_mfma_f32_16x16x32_bf16 v[8:11], v[166:169], v[202:205], v[8:11]
	v_mfma_f32_16x16x32_bf16 v[28:31], v[158:161], v[210:213], v[28:31]
	v_mfma_f32_16x16x32_bf16 v[4:7], v[166:169], v[210:213], v[4:7]
	v_mfma_f32_16x16x32_bf16 v[20:23], v[158:161], v[218:221], v[20:23]
	v_mfma_f32_16x16x32_bf16 v[0:3], v[166:169], v[218:221], v[0:3]
	v_mfma_f32_16x16x32_bf16 v[44:47], v[162:165], v[198:201], v[44:47]
	v_mfma_f32_16x16x32_bf16 v[12:15], v[190:193], v[198:201], v[12:15]
	v_mfma_f32_16x16x32_bf16 v[36:39], v[162:165], v[206:209], v[36:39]
	v_mfma_f32_16x16x32_bf16 v[8:11], v[190:193], v[206:209], v[8:11]
	v_mfma_f32_16x16x32_bf16 v[28:31], v[162:165], v[214:217], v[28:31]
	v_mfma_f32_16x16x32_bf16 v[4:7], v[190:193], v[214:217], v[4:7]
	v_mfma_f32_16x16x32_bf16 v[20:23], v[162:165], v[224:227], v[20:23]
	v_mfma_f32_16x16x32_bf16 v[0:3], v[190:193], v[224:227], v[0:3]
	s_setprio 0
	s_barrier
	s_add_i32 s6, s6, 2
	s_add_u32 s90, s90, 0x100
	s_addc_u32 s92, s92, 0
	s_mov_b64 s[64:65], s[66:67]
.LBB0_634:
	ds_read_b128 v[142:145], v174
	ds_read_b128 v[146:149], v175
	ds_read_b128 v[150:153], v176
	ds_read_b128 v[154:157], v177
	ds_read_b128 v[158:161], v178
	ds_read_b128 v[162:165], v179
	ds_read_b128 v[166:169], v180
	ds_read_b128 v[190:193], v181
	s_add_u32 s66, s64, 0x100
	s_addc_u32 s67, s65, 0
	s_cmp_eq_u32 s6, 12
	s_cselect_b32 s73, s57, s67
	s_cselect_b32 s72, vcc_lo, s66
	s_cselect_b32 s71, s55, s92
	s_cselect_b32 s70, vcc_hi, s90
	s_mov_b32 m0, s86
	v_lshl_add_u64 v[170:171], s[64:65], 0, v[134:135]
	ds_read_b128 v[194:197], v172
	ds_read_b128 v[198:201], v172 offset:1024
	ds_read_b128 v[202:205], v172 offset:2048
	ds_read_b128 v[206:209], v172 offset:3072
	ds_read_b128 v[210:213], v172 offset:4096
	ds_read_b128 v[214:217], v172 offset:5120
	ds_read_b128 v[218:221], v172 offset:6144
	ds_read_b128 v[224:227], v172 offset:7168
	global_load_lds_dwordx4 v[170:171], off
	s_mov_b32 m0, s87
	v_lshl_add_u64 v[170:171], s[64:65], 0, v[136:137]
	global_load_lds_dwordx4 v[170:171], off
	s_waitcnt vmcnt(8)
	s_waitcnt lgkmcnt(0)
	s_barrier
; #define PG8_STAGE(bufoff, gbase, voff) do { _Pragma("unroll") for (int _i = 0; _i < 2; ++_i) \
;         __builtin_amdgcn_global_load_lds((const unsigned*)((const char*)(gbase) + (voff)[_i]), (PG8_LAS unsigned*)(lds + (bufoff) + ldsw + _i * 8192), 16, 0, 0); } while (0)
; #define PG8_LDA(dst, b, h) do { _Pragma("unroll") for (int m = 0; m < 4; ++m) _Pragma("unroll") for (int k = 0; k < 2; ++k) dst[m][k] = *(const PG8_LAS bf16x8*)(lds + PG8_SA(b, h) + aoff + m * 2048 + k * 1024); } while (0)
; #define PG8_LDB(dst, b, h) do { _Pragma("unroll") for (int n = 0; n < 2; ++n) _Pragma("unroll") for (int k = 0; k < 2; ++k) dst[n][k] = *(const PG8_LAS bf16x8*)(lds + PG8_SB(b, h) + boff + n * 2048 + k * 1024); } while (0)
; #define PG8_MMA(ai, bj, At, Bt) do { __builtin_amdgcn_s_setprio(1); _Pragma("unroll") for (int m = 0; m < 4; ++m) _Pragma("unroll") for (int n = 0; n < 2; ++n) _Pragma("unroll") for (int k = 0; k < 2; ++k) \
;         acc[ai][bj][m][n] = __builtin_amdgcn_mfma_f32_16x16x32_bf16(Bt[n][k], At[m][k], acc[ai][bj][m][n], 0, 0, 0); __builtin_amdgcn_s_setprio(0); } while (0)
; #define PG8_WAIT_V(n) asm volatile("s_waitcnt vmcnt(" #n ")" ::: "memory")
; template <class Epi, class Sched, bool ALIGN_EPI = false, bool SP2 = false>
; __device__ __forceinline__ void gemm_phase(PG8_LAS unsigned char* lds, const Gemm g, const Sched& S, const Epi& E) {
;     ...
;             PG8_LDB(B0, 0, 0); PG8_LDB(B1, 0, 1); PG8_SCHED; PG8_LDA(At, 0, 0); PG8_STAGE(PG8_SA(1, 1), a1 + hstep, voffA);
;             PG8_WAIT_V(8); PG8_WAIT_L(0); PG8_BAR; PG8_MMA(0, 0, At, B0); PG8_MMA(0, 1, At, B1); PG8_BAR; PG8_SCHED;
;             PG8_LDA(At, 0, 1); PG8_STAGE(PG8_SB(0, 0), b2, voffB); PG8_STAGE(PG8_SB(0, 1), b2 + hstep, voffB); PG8_STAGE(PG8_SA(0, 0), a2, voffA);
;             PG8_WAIT_V(8); PG8_WAIT_L(0); PG8_BAR; PG8_MMA(1, 0, At, B0); PG8_MMA(1, 1, At, B1); PG8_BAR; PG8_SCHED;
;             PG8_LDB(B0, 1, 0); PG8_LDB(B1, 1, 1); PG8_SCHED; PG8_LDA(At, 1, 0); PG8_STAGE(PG8_SA(0, 1), a2 + hstep, voffA);
;             PG8_WAIT_V(8); PG8_WAIT_L(0); PG8_BAR; PG8_MMA(0, 0, At, B0); PG8_MMA(0, 1, At, B1); PG8_BAR; PG8_SCHED;
;             PG8_LDA(At, 1, 1); PG8_STAGE(PG8_SB(1, 0), b3, voffB); PG8_STAGE(PG8_SB(1, 1), b3 + hstep, voffB); PG8_STAGE(PG8_SA(1, 0), a3, voffA);
;             PG8_WAIT_V(8); PG8_WAIT_L(0); PG8_BAR; PG8_MMA(1, 0, At, B0); PG8_MMA(1, 1, At, B1); PG8_BAR; PG8_SCHED;
	s_setprio 1
	s_waitcnt lgkmcnt(0)
	v_mfma_f32_16x16x32_bf16 v[124:127], v[142:145], v[194:197], v[124:127]
	v_mfma_f32_16x16x32_bf16 v[108:111], v[150:153], v[194:197], v[108:111]
	v_mfma_f32_16x16x32_bf16 v[120:123], v[142:145], v[202:205], v[120:123]
	v_mfma_f32_16x16x32_bf16 v[96:99], v[150:153], v[202:205], v[96:99]
	v_mfma_f32_16x16x32_bf16 v[116:119], v[142:145], v[210:213], v[116:119]
	v_mfma_f32_16x16x32_bf16 v[88:91], v[150:153], v[210:213], v[88:91]
	v_mfma_f32_16x16x32_bf16 v[112:115], v[142:145], v[218:221], v[112:115]
	v_mfma_f32_16x16x32_bf16 v[84:87], v[150:153], v[218:221], v[84:87]
	v_mfma_f32_16x16x32_bf16 v[124:127], v[146:149], v[198:201], v[124:127]
	v_mfma_f32_16x16x32_bf16 v[108:111], v[154:157], v[198:201], v[108:111]
	v_mfma_f32_16x16x32_bf16 v[120:123], v[146:149], v[206:209], v[120:123]
	v_mfma_f32_16x16x32_bf16 v[96:99], v[154:157], v[206:209], v[96:99]
	v_mfma_f32_16x16x32_bf16 v[116:119], v[146:149], v[214:217], v[116:119]
	v_mfma_f32_16x16x32_bf16 v[88:91], v[154:157], v[214:217], v[88:91]
	v_mfma_f32_16x16x32_bf16 v[112:115], v[146:149], v[224:227], v[112:115]
	v_mfma_f32_16x16x32_bf16 v[84:87], v[154:157], v[224:227], v[84:87]
	s_setprio 0
	s_setprio 1
	v_mfma_f32_16x16x32_bf16 v[68:71], v[158:161], v[194:197], v[68:71]
	v_mfma_f32_16x16x32_bf16 v[40:43], v[166:169], v[194:197], v[40:43]
	v_mfma_f32_16x16x32_bf16 v[60:63], v[158:161], v[202:205], v[60:63]
	v_mfma_f32_16x16x32_bf16 v[32:35], v[166:169], v[202:205], v[32:35]
	v_mfma_f32_16x16x32_bf16 v[52:55], v[158:161], v[210:213], v[52:55]
	v_mfma_f32_16x16x32_bf16 v[24:27], v[166:169], v[210:213], v[24:27]
	v_mfma_f32_16x16x32_bf16 v[48:51], v[158:161], v[218:221], v[48:51]
	v_mfma_f32_16x16x32_bf16 v[16:19], v[166:169], v[218:221], v[16:19]
	v_mfma_f32_16x16x32_bf16 v[68:71], v[162:165], v[198:201], v[68:71]
	v_mfma_f32_16x16x32_bf16 v[40:43], v[190:193], v[198:201], v[40:43]
	v_mfma_f32_16x16x32_bf16 v[60:63], v[162:165], v[206:209], v[60:63]
	v_mfma_f32_16x16x32_bf16 v[32:35], v[190:193], v[206:209], v[32:35]
	v_mfma_f32_16x16x32_bf16 v[52:55], v[162:165], v[214:217], v[52:55]
	v_mfma_f32_16x16x32_bf16 v[24:27], v[190:193], v[214:217], v[24:27]
	v_mfma_f32_16x16x32_bf16 v[48:51], v[162:165], v[224:227], v[48:51]
	v_mfma_f32_16x16x32_bf16 v[16:19], v[190:193], v[224:227], v[16:19]
	s_setprio 0
	s_barrier
	s_mov_b32 m0, s13
	v_lshl_add_u64 v[170:171], s[70:71], 0, v[128:129]
	s_add_u32 s64, s70, 0x40000
	ds_read_b128 v[194:197], v172 offset:16384
	ds_read_b128 v[198:201], v172 offset:17408
	ds_read_b128 v[202:205], v172 offset:18432
	ds_read_b128 v[206:209], v172 offset:19456
	ds_read_b128 v[210:213], v172 offset:20480
	ds_read_b128 v[214:217], v172 offset:21504
	ds_read_b128 v[218:221], v172 offset:22528
	ds_read_b128 v[224:227], v172 offset:23552
	global_load_lds_dwordx4 v[170:171], off
	v_lshl_add_u64 v[228:229], s[70:71], 0, v[130:131]
	s_mov_b32 m0, s14
	s_addc_u32 s65, s71, 0
	global_load_lds_dwordx4 v[228:229], off
	v_lshl_add_u64 v[230:231], s[64:65], 0, v[128:129]
	s_mov_b32 m0, s15
	v_lshl_add_u64 v[232:233], s[72:73], 0, v[130:131]
	global_load_lds_dwordx4 v[230:231], off
	s_mov_b32 m0, s33
	v_lshl_add_u64 v[230:231], s[64:65], 0, v[130:131]
	global_load_lds_dwordx4 v[230:231], off
	s_mov_b32 m0, s12
	v_lshl_add_u64 v[230:231], s[72:73], 0, v[128:129]
	global_load_lds_dwordx4 v[230:231], off
	s_mov_b32 m0, s39
	s_nop 0
	global_load_lds_dwordx4 v[232:233], off
	s_waitcnt vmcnt(8)
	s_waitcnt lgkmcnt(0)
	s_barrier
	s_setprio 1
	s_waitcnt lgkmcnt(0)
	v_mfma_f32_16x16x32_bf16 v[104:107], v[142:145], v[194:197], v[104:107]
	v_mfma_f32_16x16x32_bf16 v[76:79], v[150:153], v[194:197], v[76:79]
	v_mfma_f32_16x16x32_bf16 v[100:103], v[142:145], v[202:205], v[100:103]
	v_mfma_f32_16x16x32_bf16 v[72:75], v[150:153], v[202:205], v[72:75]
	v_mfma_f32_16x16x32_bf16 v[92:95], v[142:145], v[210:213], v[92:95]
	v_mfma_f32_16x16x32_bf16 v[64:67], v[150:153], v[210:213], v[64:67]
	v_mfma_f32_16x16x32_bf16 v[80:83], v[142:145], v[218:221], v[80:83]
	v_mfma_f32_16x16x32_bf16 v[56:59], v[150:153], v[218:221], v[56:59]
	v_mfma_f32_16x16x32_bf16 v[104:107], v[146:149], v[198:201], v[104:107]
	v_mfma_f32_16x16x32_bf16 v[76:79], v[154:157], v[198:201], v[76:79]
	v_mfma_f32_16x16x32_bf16 v[100:103], v[146:149], v[206:209], v[100:103]
	v_mfma_f32_16x16x32_bf16 v[72:75], v[154:157], v[206:209], v[72:75]
	v_mfma_f32_16x16x32_bf16 v[92:95], v[146:149], v[214:217], v[92:95]
	v_mfma_f32_16x16x32_bf16 v[64:67], v[154:157], v[214:217], v[64:67]
	v_mfma_f32_16x16x32_bf16 v[80:83], v[146:149], v[224:227], v[80:83]
	v_mfma_f32_16x16x32_bf16 v[56:59], v[154:157], v[224:227], v[56:59]
	s_setprio 0
	s_setprio 1
	v_mfma_f32_16x16x32_bf16 v[44:47], v[158:161], v[194:197], v[44:47]
	v_mfma_f32_16x16x32_bf16 v[12:15], v[166:169], v[194:197], v[12:15]
	v_mfma_f32_16x16x32_bf16 v[36:39], v[158:161], v[202:205], v[36:39]
	v_mfma_f32_16x16x32_bf16 v[8:11], v[166:169], v[202:205], v[8:11]
	v_mfma_f32_16x16x32_bf16 v[28:31], v[158:161], v[210:213], v[28:31]
	v_mfma_f32_16x16x32_bf16 v[4:7], v[166:169], v[210:213], v[4:7]
	v_mfma_f32_16x16x32_bf16 v[20:23], v[158:161], v[218:221], v[20:23]
	v_mfma_f32_16x16x32_bf16 v[0:3], v[166:169], v[218:221], v[0:3]
	v_mfma_f32_16x16x32_bf16 v[44:47], v[162:165], v[198:201], v[44:47]
	v_mfma_f32_16x16x32_bf16 v[12:15], v[190:193], v[198:201], v[12:15]
	v_mfma_f32_16x16x32_bf16 v[36:39], v[162:165], v[206:209], v[36:39]
	v_mfma_f32_16x16x32_bf16 v[8:11], v[190:193], v[206:209], v[8:11]
	v_mfma_f32_16x16x32_bf16 v[28:31], v[162:165], v[214:217], v[28:31]
	v_mfma_f32_16x16x32_bf16 v[4:7], v[190:193], v[214:217], v[4:7]
	v_mfma_f32_16x16x32_bf16 v[20:23], v[162:165], v[224:227], v[20:23]
	v_mfma_f32_16x16x32_bf16 v[0:3], v[190:193], v[224:227], v[0:3]
	s_setprio 0
	s_barrier
; #define PG8_STAGE(bufoff, gbase, voff) do { _Pragma("unroll") for (int _i = 0; _i < 2; ++_i) \
;         __builtin_amdgcn_global_load_lds((const unsigned*)((const char*)(gbase) + (voff)[_i]), (PG8_LAS unsigned*)(lds + (bufoff) + ldsw + _i * 8192), 16, 0, 0); } while (0)
; #define PG8_LDA(dst, b, h) do { _Pragma("unroll") for (int m = 0; m < 4; ++m) _Pragma("unroll") for (int k = 0; k < 2; ++k) dst[m][k] = *(const PG8_LAS bf16x8*)(lds + PG8_SA(b, h) + aoff + m * 2048 + k * 1024); } while (0)
; #define PG8_LDB(dst, b, h) do { _Pragma("unroll") for (int n = 0; n < 2; ++n) _Pragma("unroll") for (int k = 0; k < 2; ++k) dst[n][k] = *(const PG8_LAS bf16x8*)(lds + PG8_SB(b, h) + boff + n * 2048 + k * 1024); } while (0)
; #define PG8_MMA(ai, bj, At, Bt) do { __builtin_amdgcn_s_setprio(1); _Pragma("unroll") for (int m = 0; m < 4; ++m) _Pragma("unroll") for (int n = 0; n < 2; ++n) _Pragma("unroll") for (int k = 0; k < 2; ++k) \
;         acc[ai][bj][m][n] = __builtin_amdgcn_mfma_f32_16x16x32_bf16(Bt[n][k], At[m][k], acc[ai][bj][m][n], 0, 0, 0); __builtin_amdgcn_s_setprio(0); } while (0)
; template <class Epi, class Sched, bool ALIGN_EPI = false, bool SP2 = false>
; __device__ __forceinline__ void gemm_phase(PG8_LAS unsigned char* lds, const Gemm g, const Sched& S, const Epi& E) {
;     ...
;             PG8_LDB(B0, 0, 0); PG8_LDB(B1, 0, 1); PG8_SCHED; PG8_LDA(At, 0, 0); PG8_STAGE(PG8_SA(1, 1), a1 + hstep, voffA);
;             PG8_WAIT_V(8); PG8_WAIT_L(0); PG8_BAR; PG8_MMA(0, 0, At, B0); PG8_MMA(0, 1, At, B1); PG8_BAR; PG8_SCHED;
;             PG8_LDA(At, 0, 1); PG8_STAGE(PG8_SB(0, 0), b2, voffB); PG8_STAGE(PG8_SB(0, 1), b2 + hstep, voffB); PG8_STAGE(PG8_SA(0, 0), a2, voffA);
;             PG8_WAIT_V(8); PG8_WAIT_L(0); PG8_BAR; PG8_MMA(1, 0, At, B0); PG8_MMA(1, 1, At, B1); PG8_BAR; PG8_SCHED;
;             PG8_LDB(B0, 1, 0); PG8_LDB(B1, 1, 1); PG8_SCHED; PG8_LDA(At, 1, 0); PG8_STAGE(PG8_SA(0, 1), a2 + hstep, voffA);
;             PG8_WAIT_V(8); PG8_WAIT_L(0); PG8_BAR; PG8_MMA(0, 0, At, B0); PG8_MMA(0, 1, At, B1); PG8_BAR; PG8_SCHED;
;             PG8_LDA(At, 1, 1); PG8_STAGE(PG8_SB(1, 0), b3, voffB); PG8_STAGE(PG8_SB(1, 1), b3 + hstep, voffB); PG8_STAGE(PG8_SA(1, 0), a3, voffA);
;             PG8_WAIT_V(8); PG8_WAIT_L(0); PG8_BAR; PG8_MMA(1, 0, At, B0); PG8_MMA(1, 1, At, B1); PG8_BAR; PG8_SCHED;
;     ...
;         if constexpr (ALIGN_EPI) { if (wr == 0) PG8_BAR; }
	ds_read_b128 v[142:145], v182
	ds_read_b128 v[146:149], v183
	ds_read_b128 v[150:153], v184
	ds_read_b128 v[154:157], v185
	ds_read_b128 v[158:161], v186
	ds_read_b128 v[162:165], v187
	ds_read_b128 v[166:169], v188
	ds_read_b128 v[190:193], v189
	s_add_u32 s64, s72, 0x40000
	s_addc_u32 s65, s73, 0
	s_mov_b32 m0, s43
	v_lshl_add_u64 v[234:235], s[64:65], 0, v[128:129]
	ds_read_b128 v[194:197], v172 offset:32768
	ds_read_b128 v[198:201], v172 offset:33792
	ds_read_b128 v[202:205], v172 offset:34816
	ds_read_b128 v[206:209], v172 offset:35840
	ds_read_b128 v[210:213], v172 offset:36864
	ds_read_b128 v[214:217], v172 offset:37888
	ds_read_b128 v[218:221], v172 offset:38912
	ds_read_b128 v[224:227], v172 offset:39936
	global_load_lds_dwordx4 v[234:235], off
	s_mov_b32 m0, s74
	v_lshl_add_u64 v[234:235], s[64:65], 0, v[130:131]
	global_load_lds_dwordx4 v[234:235], off
	s_waitcnt vmcnt(8)
	s_waitcnt lgkmcnt(0)
	s_barrier
	s_setprio 1
	s_waitcnt lgkmcnt(0)
	v_mfma_f32_16x16x32_bf16 v[124:127], v[142:145], v[194:197], v[124:127]
	v_mfma_f32_16x16x32_bf16 v[108:111], v[150:153], v[194:197], v[108:111]
	v_mfma_f32_16x16x32_bf16 v[120:123], v[142:145], v[202:205], v[120:123]
	v_mfma_f32_16x16x32_bf16 v[96:99], v[150:153], v[202:205], v[96:99]
	v_mfma_f32_16x16x32_bf16 v[116:119], v[142:145], v[210:213], v[116:119]
	v_mfma_f32_16x16x32_bf16 v[88:91], v[150:153], v[210:213], v[88:91]
	v_mfma_f32_16x16x32_bf16 v[112:115], v[142:145], v[218:221], v[112:115]
	v_mfma_f32_16x16x32_bf16 v[84:87], v[150:153], v[218:221], v[84:87]
	v_mfma_f32_16x16x32_bf16 v[124:127], v[146:149], v[198:201], v[124:127]
	v_mfma_f32_16x16x32_bf16 v[108:111], v[154:157], v[198:201], v[108:111]
	v_mfma_f32_16x16x32_bf16 v[120:123], v[146:149], v[206:209], v[120:123]
	v_mfma_f32_16x16x32_bf16 v[96:99], v[154:157], v[206:209], v[96:99]
	v_mfma_f32_16x16x32_bf16 v[116:119], v[146:149], v[214:217], v[116:119]
	v_mfma_f32_16x16x32_bf16 v[88:91], v[154:157], v[214:217], v[88:91]
	v_mfma_f32_16x16x32_bf16 v[112:115], v[146:149], v[224:227], v[112:115]
	v_mfma_f32_16x16x32_bf16 v[84:87], v[154:157], v[224:227], v[84:87]
	s_setprio 0
	s_setprio 1
	v_mfma_f32_16x16x32_bf16 v[68:71], v[158:161], v[194:197], v[68:71]
	v_mfma_f32_16x16x32_bf16 v[40:43], v[166:169], v[194:197], v[40:43]
	v_mfma_f32_16x16x32_bf16 v[60:63], v[158:161], v[202:205], v[60:63]
	v_mfma_f32_16x16x32_bf16 v[32:35], v[166:169], v[202:205], v[32:35]
	v_mfma_f32_16x16x32_bf16 v[52:55], v[158:161], v[210:213], v[52:55]
	v_mfma_f32_16x16x32_bf16 v[24:27], v[166:169], v[210:213], v[24:27]
	v_mfma_f32_16x16x32_bf16 v[48:51], v[158:161], v[218:221], v[48:51]
	v_mfma_f32_16x16x32_bf16 v[16:19], v[166:169], v[218:221], v[16:19]
	v_mfma_f32_16x16x32_bf16 v[68:71], v[162:165], v[198:201], v[68:71]
	v_mfma_f32_16x16x32_bf16 v[40:43], v[190:193], v[198:201], v[40:43]
	v_mfma_f32_16x16x32_bf16 v[60:63], v[162:165], v[206:209], v[60:63]
	v_mfma_f32_16x16x32_bf16 v[32:35], v[190:193], v[206:209], v[32:35]
	v_mfma_f32_16x16x32_bf16 v[52:55], v[162:165], v[214:217], v[52:55]
	v_mfma_f32_16x16x32_bf16 v[24:27], v[190:193], v[214:217], v[24:27]
	v_mfma_f32_16x16x32_bf16 v[48:51], v[162:165], v[224:227], v[48:51]
	v_mfma_f32_16x16x32_bf16 v[16:19], v[190:193], v[224:227], v[16:19]
	s_setprio 0
	s_barrier
	s_mov_b32 m0, s78
	v_lshl_add_u64 v[170:171], v[170:171], 0, s[10:11]
	s_add_u32 s64, s70, 0x40080
	ds_read_b128 v[194:197], v172 offset:49152
	ds_read_b128 v[198:201], v172 offset:50176
	ds_read_b128 v[202:205], v172 offset:51200
	ds_read_b128 v[206:209], v172 offset:52224
	ds_read_b128 v[210:213], v172 offset:53248
	ds_read_b128 v[214:217], v172 offset:54272
	ds_read_b128 v[218:221], v172 offset:55296
	ds_read_b128 v[224:227], v172 offset:56320
	global_load_lds_dwordx4 v[170:171], off
	v_lshl_add_u64 v[170:171], v[228:229], 0, s[10:11]
	s_mov_b32 m0, s79
	s_addc_u32 s65, s71, 0
	global_load_lds_dwordx4 v[170:171], off
	s_mov_b32 m0, s82
	v_lshl_add_u64 v[170:171], s[64:65], 0, v[128:129]
	global_load_lds_dwordx4 v[170:171], off
	s_mov_b32 m0, s83
	v_lshl_add_u64 v[170:171], s[64:65], 0, v[130:131]
	global_load_lds_dwordx4 v[170:171], off
	s_mov_b32 m0, s80
	v_lshl_add_u64 v[170:171], v[230:231], 0, s[10:11]
	global_load_lds_dwordx4 v[170:171], off
	s_mov_b32 m0, s81
	v_lshl_add_u64 v[170:171], v[232:233], 0, s[10:11]
	global_load_lds_dwordx4 v[170:171], off
	s_waitcnt vmcnt(8)
	s_waitcnt lgkmcnt(0)
	s_barrier
	s_setprio 1
	s_waitcnt lgkmcnt(0)
	v_mfma_f32_16x16x32_bf16 v[104:107], v[142:145], v[194:197], v[104:107]
	v_mfma_f32_16x16x32_bf16 v[76:79], v[150:153], v[194:197], v[76:79]
	v_mfma_f32_16x16x32_bf16 v[100:103], v[142:145], v[202:205], v[100:103]
	v_mfma_f32_16x16x32_bf16 v[72:75], v[150:153], v[202:205], v[72:75]
	v_mfma_f32_16x16x32_bf16 v[92:95], v[142:145], v[210:213], v[92:95]
	v_mfma_f32_16x16x32_bf16 v[64:67], v[150:153], v[210:213], v[64:67]
	v_mfma_f32_16x16x32_bf16 v[80:83], v[142:145], v[218:221], v[80:83]
	v_mfma_f32_16x16x32_bf16 v[56:59], v[150:153], v[218:221], v[56:59]
	v_mfma_f32_16x16x32_bf16 v[104:107], v[146:149], v[198:201], v[104:107]
	v_mfma_f32_16x16x32_bf16 v[76:79], v[154:157], v[198:201], v[76:79]
	v_mfma_f32_16x16x32_bf16 v[100:103], v[146:149], v[206:209], v[100:103]
	v_mfma_f32_16x16x32_bf16 v[72:75], v[154:157], v[206:209], v[72:75]
	v_mfma_f32_16x16x32_bf16 v[92:95], v[146:149], v[214:217], v[92:95]
	v_mfma_f32_16x16x32_bf16 v[64:67], v[154:157], v[214:217], v[64:67]
	v_mfma_f32_16x16x32_bf16 v[80:83], v[146:149], v[224:227], v[80:83]
	v_mfma_f32_16x16x32_bf16 v[56:59], v[154:157], v[224:227], v[56:59]
	s_setprio 0
	s_setprio 1
	v_mfma_f32_16x16x32_bf16 v[44:47], v[158:161], v[194:197], v[44:47]
	v_mfma_f32_16x16x32_bf16 v[12:15], v[166:169], v[194:197], v[12:15]
	v_mfma_f32_16x16x32_bf16 v[36:39], v[158:161], v[202:205], v[36:39]
	v_mfma_f32_16x16x32_bf16 v[8:11], v[166:169], v[202:205], v[8:11]
	v_mfma_f32_16x16x32_bf16 v[28:31], v[158:161], v[210:213], v[28:31]
	v_mfma_f32_16x16x32_bf16 v[4:7], v[166:169], v[210:213], v[4:7]
	v_mfma_f32_16x16x32_bf16 v[20:23], v[158:161], v[218:221], v[20:23]
	v_mfma_f32_16x16x32_bf16 v[0:3], v[166:169], v[218:221], v[0:3]
	v_mfma_f32_16x16x32_bf16 v[44:47], v[162:165], v[198:201], v[44:47]
	v_mfma_f32_16x16x32_bf16 v[12:15], v[190:193], v[198:201], v[12:15]
	v_mfma_f32_16x16x32_bf16 v[36:39], v[162:165], v[206:209], v[36:39]
	v_mfma_f32_16x16x32_bf16 v[8:11], v[190:193], v[206:209], v[8:11]
	v_mfma_f32_16x16x32_bf16 v[28:31], v[162:165], v[214:217], v[28:31]
	v_mfma_f32_16x16x32_bf16 v[4:7], v[190:193], v[214:217], v[4:7]
	v_mfma_f32_16x16x32_bf16 v[20:23], v[162:165], v[224:227], v[20:23]
	v_mfma_f32_16x16x32_bf16 v[0:3], v[190:193], v[224:227], v[0:3]
	s_setprio 0
	s_barrier
	s_add_i32 s6, s6, 2
	s_add_u32 s90, s90, 0x100
	s_addc_u32 s92, s92, 0
	s_cmp_gt_u32 s6, 13
	s_mov_b64 s[64:65], s[66:67]
	s_cbranch_scc0 .LBB0_634
	s_and_b64 vcc, exec, s[52:53]
	s_cbranch_vccz .LBB0_637
	s_barrier

;     __host__ __device__ bool next(int i, Unit& u) const { const int L = i * G + c; if (L >= 16 * nkc) return false; u.kc = L % nkc; const int t = L / nkc; u.pn = t & 3; u.pm = 33 * (t >> 2); return true; }
; #define PG8_LDA(dst, b, h) do { _Pragma("unroll") for (int m = 0; m < 4; ++m) _Pragma("unroll") for (int k = 0; k < 2; ++k) dst[m][k] = *(const PG8_LAS bf16x8*)(lds + PG8_SA(b, h) + aoff + m * 2048 + k * 1024); } while (0)
; template <class Epi, class Sched, bool ALIGN_EPI = false, bool SP2 = false>
; __device__ __forceinline__ void gemm_phase(PG8_LAS unsigned char* lds, const Gemm g, const Sched& S, const Epi& E) {
;     ...
;         const bool has_next = S.next(ui + 1, nxt);
;         const char* nA = has_next ? (const char*)g.A + (size_t)nxt.pm * tstep + (size_t)nxt.kc * cstep : cA; const char* nB = has_next ? (const char*)g.Bt + (size_t)nxt.pn * tstep + (size_t)nxt.kc * cstep : cB;
;         for (int t = 0; t < nt; t += 2) {
;             const bool last = (t == nt - 2);
;             const char* a1 = cA + (size_t)(t + 1) * kstep;
;             const char* a2 = last ? nA : cA + (size_t)(t + 2) * kstep; const char* b2 = last ? nB : cB + (size_t)(t + 2) * kstep;
;             const char* a3 = a2 + kstep; const char* b3 = b2 + kstep;
;             if (last && has_next) S.a_ready(nxt);
;             if constexpr (SP2) {
;             PG8_LDB(B0, 0, 0); PG8_LDB(B1, 0, 1); PG8_SCHED; PG8_LDA(At, 0, 0); PG8_STAGE(PG8_SA(1, 1), a1 + hstep, voffA);
;             PG8_WAIT_V(8); PG8_WAIT_L(0); PG8_BAR; PG8_MMA(0, 0, At, B0); PG8_MMA(0, 1, At, B1); PG8_BAR; PG8_SCHED;
;             PG8_LDA(At, 0, 1); PG8_STAGE(PG8_SB(0, 0), b2, voffB); PG8_STAGE(PG8_SB(0, 1), b2 + hstep, voffB); PG8_STAGE(PG8_SA(0, 0), a2, voffA);
;             PG8_WAIT_V(8); PG8_WAIT_L(0); PG8_BAR; PG8_MMA(1, 0, At, B0); PG8_MMA(1, 1, At, B1); PG8_BAR; PG8_SCHED;
;             PG8_LDB(B0, 1, 0); PG8_LDB(B1, 1, 1); PG8_SCHED; PG8_LDA(At, 1, 0); PG8_STAGE(PG8_SA(0, 1), a2 + hstep, voffA);
;             PG8_WAIT_V(8); PG8_WAIT_L(0); PG8_BAR; PG8_MMA(0, 0, At, B0); PG8_MMA(0, 1, At, B1); PG8_BAR; PG8_SCHED;
;             PG8_LDA(At, 1, 1); PG8_STAGE(PG8_SB(1, 0), b3, voffB); PG8_STAGE(PG8_SB(1, 1), b3 + hstep, voffB); PG8_STAGE(PG8_SA(1, 0), a3, voffA);
;             PG8_WAIT_V(8); PG8_WAIT_L(0); PG8_BAR; PG8_MMA(1, 0, At, B0); PG8_MMA(1, 1, At, B1); PG8_BAR; PG8_SCHED;
.LBB0_653:
	s_ashr_i32 s59, s58, 31
	s_lshl_b64 s[6:7], s[58:59], 19
	s_add_u32 s57, s46, s6
	s_addc_u32 s59, s47, s7
	s_ashr_i32 s55, s54, 31
	s_lshl_b64 s[6:7], s[54:55], 9
	s_add_u32 s66, s57, s6
	s_addc_u32 s67, s59, s7
	s_ashr_i32 s57, s56, 31
	s_lshl_b64 s[70:71], s[56:57], 19
	s_add_u32 s55, s0, s70
	s_addc_u32 s57, s1, s71
	s_add_u32 s70, s55, s6
	s_addc_u32 s71, s57, s7
	s_and_b64 vcc, exec, s[4:5]
	s_cbranch_vccnz .LBB0_661
	s_and_b64 s[6:7], s[62:63], exec
	s_cselect_b32 s55, s67, s73
	s_cselect_b32 s57, s66, s72
	s_cselect_b32 s59, s71, s75
	s_cselect_b32 s61, s70, s74
	s_add_u32 s90, s74, 0x100
	s_addc_u32 s92, s75, 0
	s_mov_b32 s6, 0
	ds_read_b128 v[156:159], v140
	ds_read_b128 v[160:163], v141
	ds_read_b128 v[164:167], v142
	ds_read_b128 v[168:171], v143
	ds_read_b128 v[172:175], v144
	ds_read_b128 v[176:179], v145
	ds_read_b128 v[180:183], v146
	ds_read_b128 v[184:187], v147
	s_add_i32 s7, s6, 2
	s_add_u32 s74, s72, 0x100
	s_addc_u32 s75, s73, 0
	s_cmp_eq_u32 s87, s6
	s_cselect_b32 s79, s55, s75
	s_cselect_b32 s78, s57, s74
	s_cselect_b32 s77, s59, s92
	s_cselect_b32 s76, s61, s90
	s_mov_b32 m0, s88
	v_lshl_add_u64 v[220:221], s[72:73], 0, v[134:135]
	ds_read_b128 v[188:191], v138
	ds_read_b128 v[192:195], v138 offset:1024
	ds_read_b128 v[196:199], v138 offset:2048
	ds_read_b128 v[200:203], v138 offset:3072
	ds_read_b128 v[204:207], v138 offset:4096
	ds_read_b128 v[208:211], v138 offset:5120
	ds_read_b128 v[212:215], v138 offset:6144
	ds_read_b128 v[216:219], v138 offset:7168
	global_load_lds_dwordx4 v[220:221], off
	s_mov_b32 m0, s89
	v_lshl_add_u64 v[220:221], s[72:73], 0, v[136:137]
	global_load_lds_dwordx4 v[220:221], off
	s_waitcnt vmcnt(8)
	s_waitcnt lgkmcnt(0)
	s_barrier
	s_setprio 1
	s_waitcnt lgkmcnt(0)
	v_mfma_f32_16x16x32_bf16 v[124:127], v[156:159], v[188:191], 0
	v_mfma_f32_16x16x32_bf16 v[120:123], v[164:167], v[188:191], 0
	v_mfma_f32_16x16x32_bf16 v[108:111], v[156:159], v[196:199], 0
	v_mfma_f32_16x16x32_bf16 v[104:107], v[164:167], v[196:199], 0
	v_mfma_f32_16x16x32_bf16 v[92:95], v[156:159], v[204:207], 0
	v_mfma_f32_16x16x32_bf16 v[88:91], v[164:167], v[204:207], 0
	v_mfma_f32_16x16x32_bf16 v[76:79], v[156:159], v[212:215], 0
	v_mfma_f32_16x16x32_bf16 v[72:75], v[164:167], v[212:215], 0
	v_mfma_f32_16x16x32_bf16 v[124:127], v[160:163], v[192:195], v[124:127]
	v_mfma_f32_16x16x32_bf16 v[120:123], v[168:171], v[192:195], v[120:123]
	v_mfma_f32_16x16x32_bf16 v[108:111], v[160:163], v[200:203], v[108:111]
	v_mfma_f32_16x16x32_bf16 v[104:107], v[168:171], v[200:203], v[104:107]
	v_mfma_f32_16x16x32_bf16 v[92:95], v[160:163], v[208:211], v[92:95]
	v_mfma_f32_16x16x32_bf16 v[88:91], v[168:171], v[208:211], v[88:91]
	v_mfma_f32_16x16x32_bf16 v[76:79], v[160:163], v[216:219], v[76:79]
	v_mfma_f32_16x16x32_bf16 v[72:75], v[168:171], v[216:219], v[72:75]
	s_setprio 0
	s_setprio 1
	v_mfma_f32_16x16x32_bf16 v[116:119], v[172:175], v[188:191], 0
	v_mfma_f32_16x16x32_bf16 v[112:115], v[180:183], v[188:191], 0
	v_mfma_f32_16x16x32_bf16 v[100:103], v[172:175], v[196:199], 0
	v_mfma_f32_16x16x32_bf16 v[96:99], v[180:183], v[196:199], 0
	v_mfma_f32_16x16x32_bf16 v[84:87], v[172:175], v[204:207], 0
	v_mfma_f32_16x16x32_bf16 v[80:83], v[180:183], v[204:207], 0
	v_mfma_f32_16x16x32_bf16 v[68:71], v[172:175], v[212:215], 0
	v_mfma_f32_16x16x32_bf16 v[64:67], v[180:183], v[212:215], 0
	v_mfma_f32_16x16x32_bf16 v[116:119], v[176:179], v[192:195], v[116:119]
	v_mfma_f32_16x16x32_bf16 v[112:115], v[184:187], v[192:195], v[112:115]
	v_mfma_f32_16x16x32_bf16 v[100:103], v[176:179], v[200:203], v[100:103]
	v_mfma_f32_16x16x32_bf16 v[96:99], v[184:187], v[200:203], v[96:99]
	v_mfma_f32_16x16x32_bf16 v[84:87], v[176:179], v[208:211], v[84:87]
	v_mfma_f32_16x16x32_bf16 v[80:83], v[184:187], v[208:211], v[80:83]
	v_mfma_f32_16x16x32_bf16 v[68:71], v[176:179], v[216:219], v[68:71]
	v_mfma_f32_16x16x32_bf16 v[64:67], v[184:187], v[216:219], v[64:67]
	s_setprio 0
	s_barrier
	s_mov_b32 m0, s13
	v_lshl_add_u64 v[220:221], s[76:77], 0, v[130:131]
	s_add_u32 s72, s76, 0x40000
	ds_read_b128 v[188:191], v138 offset:16384
	ds_read_b128 v[192:195], v138 offset:17408
	ds_read_b128 v[196:199], v138 offset:18432
	ds_read_b128 v[200:203], v138 offset:19456
	ds_read_b128 v[204:207], v138 offset:20480
	ds_read_b128 v[208:211], v138 offset:21504
	ds_read_b128 v[212:215], v138 offset:22528
	ds_read_b128 v[216:219], v138 offset:23552
	global_load_lds_dwordx4 v[220:221], off
	v_lshl_add_u64 v[224:225], s[76:77], 0, v[128:129]
	s_mov_b32 m0, s14
	s_addc_u32 s73, s77, 0
	global_load_lds_dwordx4 v[224:225], off
	v_lshl_add_u64 v[226:227], s[72:73], 0, v[130:131]
	s_mov_b32 m0, s15
	v_lshl_add_u64 v[228:229], s[78:79], 0, v[128:129]
	global_load_lds_dwordx4 v[226:227], off
	s_mov_b32 m0, s33
	v_lshl_add_u64 v[226:227], s[72:73], 0, v[128:129]
	global_load_lds_dwordx4 v[226:227], off
	s_mov_b32 m0, s12
	v_lshl_add_u64 v[226:227], s[78:79], 0, v[130:131]
	global_load_lds_dwordx4 v[226:227], off
	s_mov_b32 m0, s39
	s_nop 0
	global_load_lds_dwordx4 v[228:229], off
	s_waitcnt vmcnt(8)
	s_waitcnt lgkmcnt(0)
	s_barrier
; #define PG8_STAGE(bufoff, gbase, voff) do { _Pragma("unroll") for (int _i = 0; _i < 2; ++_i) \
;         __builtin_amdgcn_global_load_lds((const unsigned*)((const char*)(gbase) + (voff)[_i]), (PG8_LAS unsigned*)(lds + (bufoff) + ldsw + _i * 8192), 16, 0, 0); } while (0)
; #define PG8_LDA(dst, b, h) do { _Pragma("unroll") for (int m = 0; m < 4; ++m) _Pragma("unroll") for (int k = 0; k < 2; ++k) dst[m][k] = *(const PG8_LAS bf16x8*)(lds + PG8_SA(b, h) + aoff + m * 2048 + k * 1024); } while (0)
; #define PG8_LDB(dst, b, h) do { _Pragma("unroll") for (int n = 0; n < 2; ++n) _Pragma("unroll") for (int k = 0; k < 2; ++k) dst[n][k] = *(const PG8_LAS bf16x8*)(lds + PG8_SB(b, h) + boff + n * 2048 + k * 1024); } while (0)
; #define PG8_MMA(ai, bj, At, Bt) do { __builtin_amdgcn_s_setprio(1); _Pragma("unroll") for (int m = 0; m < 4; ++m) _Pragma("unroll") for (int n = 0; n < 2; ++n) _Pragma("unroll") for (int k = 0; k < 2; ++k) \
;         acc[ai][bj][m][n] = __builtin_amdgcn_mfma_f32_16x16x32_bf16(Bt[n][k], At[m][k], acc[ai][bj][m][n], 0, 0, 0); __builtin_amdgcn_s_setprio(0); } while (0)
; #define PG8_WAIT_V(n) asm volatile("s_waitcnt vmcnt(" #n ")" ::: "memory")
; template <class Epi, class Sched, bool ALIGN_EPI = false, bool SP2 = false>
; __device__ __forceinline__ void gemm_phase(PG8_LAS unsigned char* lds, const Gemm g, const Sched& S, const Epi& E) {
;     ...
;             PG8_LDB(B0, 0, 0); PG8_LDB(B1, 0, 1); PG8_SCHED; PG8_LDA(At, 0, 0); PG8_STAGE(PG8_SA(1, 1), a1 + hstep, voffA);
;             PG8_WAIT_V(8); PG8_WAIT_L(0); PG8_BAR; PG8_MMA(0, 0, At, B0); PG8_MMA(0, 1, At, B1); PG8_BAR; PG8_SCHED;
;             PG8_LDA(At, 0, 1); PG8_STAGE(PG8_SB(0, 0), b2, voffB); PG8_STAGE(PG8_SB(0, 1), b2 + hstep, voffB); PG8_STAGE(PG8_SA(0, 0), a2, voffA);
;             PG8_WAIT_V(8); PG8_WAIT_L(0); PG8_BAR; PG8_MMA(1, 0, At, B0); PG8_MMA(1, 1, At, B1); PG8_BAR; PG8_SCHED;
;             PG8_LDB(B0, 1, 0); PG8_LDB(B1, 1, 1); PG8_SCHED; PG8_LDA(At, 1, 0); PG8_STAGE(PG8_SA(0, 1), a2 + hstep, voffA);
;             PG8_WAIT_V(8); PG8_WAIT_L(0); PG8_BAR; PG8_MMA(0, 0, At, B0); PG8_MMA(0, 1, At, B1); PG8_BAR; PG8_SCHED;
;             PG8_LDA(At, 1, 1); PG8_STAGE(PG8_SB(1, 0), b3, voffB); PG8_STAGE(PG8_SB(1, 1), b3 + hstep, voffB); PG8_STAGE(PG8_SA(1, 0), a3, voffA);
;             PG8_WAIT_V(8); PG8_WAIT_L(0); PG8_BAR; PG8_MMA(1, 0, At, B0); PG8_MMA(1, 1, At, B1); PG8_BAR; PG8_SCHED;
	s_setprio 1
	s_waitcnt lgkmcnt(0)
	v_mfma_f32_16x16x32_bf16 v[60:63], v[156:159], v[188:191], 0
	v_mfma_f32_16x16x32_bf16 v[56:59], v[164:167], v[188:191], 0
	v_mfma_f32_16x16x32_bf16 v[44:47], v[156:159], v[196:199], 0
	v_mfma_f32_16x16x32_bf16 v[40:43], v[164:167], v[196:199], 0
	v_mfma_f32_16x16x32_bf16 v[28:31], v[156:159], v[204:207], 0
	v_mfma_f32_16x16x32_bf16 v[24:27], v[164:167], v[204:207], 0
	v_mfma_f32_16x16x32_bf16 v[12:15], v[156:159], v[212:215], 0
	v_mfma_f32_16x16x32_bf16 v[8:11], v[164:167], v[212:215], 0
	v_mfma_f32_16x16x32_bf16 v[60:63], v[160:163], v[192:195], v[60:63]
	v_mfma_f32_16x16x32_bf16 v[56:59], v[168:171], v[192:195], v[56:59]
	v_mfma_f32_16x16x32_bf16 v[44:47], v[160:163], v[200:203], v[44:47]
	v_mfma_f32_16x16x32_bf16 v[40:43], v[168:171], v[200:203], v[40:43]
	v_mfma_f32_16x16x32_bf16 v[28:31], v[160:163], v[208:211], v[28:31]
	v_mfma_f32_16x16x32_bf16 v[24:27], v[168:171], v[208:211], v[24:27]
	v_mfma_f32_16x16x32_bf16 v[12:15], v[160:163], v[216:219], v[12:15]
	v_mfma_f32_16x16x32_bf16 v[8:11], v[168:171], v[216:219], v[8:11]
	s_setprio 0
	s_setprio 1
	v_mfma_f32_16x16x32_bf16 v[52:55], v[172:175], v[188:191], 0
	v_mfma_f32_16x16x32_bf16 v[48:51], v[180:183], v[188:191], 0
	v_mfma_f32_16x16x32_bf16 v[36:39], v[172:175], v[196:199], 0
	v_mfma_f32_16x16x32_bf16 v[32:35], v[180:183], v[196:199], 0
	v_mfma_f32_16x16x32_bf16 v[20:23], v[172:175], v[204:207], 0
	v_mfma_f32_16x16x32_bf16 v[16:19], v[180:183], v[204:207], 0
	v_mfma_f32_16x16x32_bf16 v[4:7], v[172:175], v[212:215], 0
	v_mfma_f32_16x16x32_bf16 v[0:3], v[180:183], v[212:215], 0
	v_mfma_f32_16x16x32_bf16 v[52:55], v[176:179], v[192:195], v[52:55]
	v_mfma_f32_16x16x32_bf16 v[48:51], v[184:187], v[192:195], v[48:51]
	v_mfma_f32_16x16x32_bf16 v[36:39], v[176:179], v[200:203], v[36:39]
	v_mfma_f32_16x16x32_bf16 v[32:35], v[184:187], v[200:203], v[32:35]
	v_mfma_f32_16x16x32_bf16 v[20:23], v[176:179], v[208:211], v[20:23]
	v_mfma_f32_16x16x32_bf16 v[16:19], v[184:187], v[208:211], v[16:19]
	v_mfma_f32_16x16x32_bf16 v[4:7], v[176:179], v[216:219], v[4:7]
	v_mfma_f32_16x16x32_bf16 v[0:3], v[184:187], v[216:219], v[0:3]
	s_setprio 0
	s_barrier
	ds_read_b128 v[156:159], v148
	ds_read_b128 v[160:163], v149
	ds_read_b128 v[164:167], v150
	ds_read_b128 v[168:171], v151
	ds_read_b128 v[172:175], v152
	ds_read_b128 v[176:179], v153
	ds_read_b128 v[180:183], v154
	ds_read_b128 v[184:187], v155
	s_add_u32 s72, s78, 0x40000
	s_addc_u32 s73, s79, 0
	s_mov_b32 m0, s43
	v_lshl_add_u64 v[230:231], s[72:73], 0, v[130:131]
	ds_read_b128 v[188:191], v138 offset:32768
	ds_read_b128 v[192:195], v138 offset:33792
	ds_read_b128 v[196:199], v138 offset:34816
	ds_read_b128 v[200:203], v138 offset:35840
	ds_read_b128 v[204:207], v138 offset:36864
	ds_read_b128 v[208:211], v138 offset:37888
	ds_read_b128 v[212:215], v138 offset:38912
	ds_read_b128 v[216:219], v138 offset:39936
	global_load_lds_dwordx4 v[230:231], off
	s_mov_b32 m0, s65
	v_lshl_add_u64 v[230:231], s[72:73], 0, v[128:129]
	global_load_lds_dwordx4 v[230:231], off
	s_waitcnt vmcnt(8)
	s_waitcnt lgkmcnt(0)
	s_barrier
	s_setprio 1
	s_waitcnt lgkmcnt(0)
	v_mfma_f32_16x16x32_bf16 v[124:127], v[156:159], v[188:191], v[124:127]
	v_mfma_f32_16x16x32_bf16 v[120:123], v[164:167], v[188:191], v[120:123]
	v_mfma_f32_16x16x32_bf16 v[108:111], v[156:159], v[196:199], v[108:111]
	v_mfma_f32_16x16x32_bf16 v[104:107], v[164:167], v[196:199], v[104:107]
	v_mfma_f32_16x16x32_bf16 v[92:95], v[156:159], v[204:207], v[92:95]
	v_mfma_f32_16x16x32_bf16 v[88:91], v[164:167], v[204:207], v[88:91]
	v_mfma_f32_16x16x32_bf16 v[76:79], v[156:159], v[212:215], v[76:79]
	v_mfma_f32_16x16x32_bf16 v[72:75], v[164:167], v[212:215], v[72:75]
	v_mfma_f32_16x16x32_bf16 v[124:127], v[160:163], v[192:195], v[124:127]
	v_mfma_f32_16x16x32_bf16 v[120:123], v[168:171], v[192:195], v[120:123]
	v_mfma_f32_16x16x32_bf16 v[108:111], v[160:163], v[200:203], v[108:111]
	v_mfma_f32_16x16x32_bf16 v[104:107], v[168:171], v[200:203], v[104:107]
	v_mfma_f32_16x16x32_bf16 v[92:95], v[160:163], v[208:211], v[92:95]
	v_mfma_f32_16x16x32_bf16 v[88:91], v[168:171], v[208:211], v[88:91]
	v_mfma_f32_16x16x32_bf16 v[76:79], v[160:163], v[216:219], v[76:79]
	v_mfma_f32_16x16x32_bf16 v[72:75], v[168:171], v[216:219], v[72:75]
	s_setprio 0
	s_setprio 1
	v_mfma_f32_16x16x32_bf16 v[116:119], v[172:175], v[188:191], v[116:119]
	v_mfma_f32_16x16x32_bf16 v[112:115], v[180:183], v[188:191], v[112:115]
	v_mfma_f32_16x16x32_bf16 v[100:103], v[172:175], v[196:199], v[100:103]
	v_mfma_f32_16x16x32_bf16 v[96:99], v[180:183], v[196:199], v[96:99]
	v_mfma_f32_16x16x32_bf16 v[84:87], v[172:175], v[204:207], v[84:87]
	v_mfma_f32_16x16x32_bf16 v[80:83], v[180:183], v[204:207], v[80:83]
	v_mfma_f32_16x16x32_bf16 v[68:71], v[172:175], v[212:215], v[68:71]
	v_mfma_f32_16x16x32_bf16 v[64:67], v[180:183], v[212:215], v[64:67]
	v_mfma_f32_16x16x32_bf16 v[116:119], v[176:179], v[192:195], v[116:119]
	v_mfma_f32_16x16x32_bf16 v[112:115], v[184:187], v[192:195], v[112:115]
	v_mfma_f32_16x16x32_bf16 v[100:103], v[176:179], v[200:203], v[100:103]
	v_mfma_f32_16x16x32_bf16 v[96:99], v[184:187], v[200:203], v[96:99]
	v_mfma_f32_16x16x32_bf16 v[84:87], v[176:179], v[208:211], v[84:87]
	v_mfma_f32_16x16x32_bf16 v[80:83], v[184:187], v[208:211], v[80:83]
	v_mfma_f32_16x16x32_bf16 v[68:71], v[176:179], v[216:219], v[68:71]
	v_mfma_f32_16x16x32_bf16 v[64:67], v[184:187], v[216:219], v[64:67]
	s_setprio 0
	s_barrier
; #define PG8_STAGE(bufoff, gbase, voff) do { _Pragma("unroll") for (int _i = 0; _i < 2; ++_i) \
;         __builtin_amdgcn_global_load_lds((const unsigned*)((const char*)(gbase) + (voff)[_i]), (PG8_LAS unsigned*)(lds + (bufoff) + ldsw + _i * 8192), 16, 0, 0); } while (0)
; #define PG8_LDA(dst, b, h) do { _Pragma("unroll") for (int m = 0; m < 4; ++m) _Pragma("unroll") for (int k = 0; k < 2; ++k) dst[m][k] = *(const PG8_LAS bf16x8*)(lds + PG8_SA(b, h) + aoff + m * 2048 + k * 1024); } while (0)
; #define PG8_LDB(dst, b, h) do { _Pragma("unroll") for (int n = 0; n < 2; ++n) _Pragma("unroll") for (int k = 0; k < 2; ++k) dst[n][k] = *(const PG8_LAS bf16x8*)(lds + PG8_SB(b, h) + boff + n * 2048 + k * 1024); } while (0)
; template <class Epi, class Sched, bool ALIGN_EPI = false, bool SP2 = false>
; __device__ __forceinline__ void gemm_phase(PG8_LAS unsigned char* lds, const Gemm g, const Sched& S, const Epi& E) {
;     ...
;         for (int t = 0; t < nt; t += 2) {
;             const bool last = (t == nt - 2);
;             const char* a1 = cA + (size_t)(t + 1) * kstep;
;             const char* a2 = last ? nA : cA + (size_t)(t + 2) * kstep; const char* b2 = last ? nB : cB + (size_t)(t + 2) * kstep;
;             const char* a3 = a2 + kstep; const char* b3 = b2 + kstep;
;             if (last && has_next) S.a_ready(nxt);
;             if constexpr (SP2) {
;             PG8_LDB(B0, 0, 0); PG8_LDB(B1, 0, 1); PG8_SCHED; PG8_LDA(At, 0, 0); PG8_STAGE(PG8_SA(1, 1), a1 + hstep, voffA);
;             PG8_WAIT_V(8); PG8_WAIT_L(0); PG8_BAR; PG8_MMA(0, 0, At, B0); PG8_MMA(0, 1, At, B1); PG8_BAR; PG8_SCHED;
;             PG8_LDA(At, 0, 1); PG8_STAGE(PG8_SB(0, 0), b2, voffB); PG8_STAGE(PG8_SB(0, 1), b2 + hstep, voffB); PG8_STAGE(PG8_SA(0, 0), a2, voffA);
;             PG8_WAIT_V(8); PG8_WAIT_L(0); PG8_BAR; PG8_MMA(1, 0, At, B0); PG8_MMA(1, 1, At, B1); PG8_BAR; PG8_SCHED;
;             PG8_LDB(B0, 1, 0); PG8_LDB(B1, 1, 1); PG8_SCHED; PG8_LDA(At, 1, 0); PG8_STAGE(PG8_SA(0, 1), a2 + hstep, voffA);
;             PG8_WAIT_V(8); PG8_WAIT_L(0); PG8_BAR; PG8_MMA(0, 0, At, B0); PG8_MMA(0, 1, At, B1); PG8_BAR; PG8_SCHED;
;             PG8_LDA(At, 1, 1); PG8_STAGE(PG8_SB(1, 0), b3, voffB); PG8_STAGE(PG8_SB(1, 1), b3 + hstep, voffB); PG8_STAGE(PG8_SA(1, 0), a3, voffA);
;             PG8_WAIT_V(8); PG8_WAIT_L(0); PG8_BAR; PG8_MMA(1, 0, At, B0); PG8_MMA(1, 1, At, B1); PG8_BAR; PG8_SCHED;
	s_mov_b32 m0, s81
	v_lshl_add_u64 v[220:221], v[220:221], 0, s[36:37]
	s_add_u32 s72, s76, 0x40080
	ds_read_b128 v[188:191], v138 offset:49152
	ds_read_b128 v[192:195], v138 offset:50176
	ds_read_b128 v[196:199], v138 offset:51200
	ds_read_b128 v[200:203], v138 offset:52224
	ds_read_b128 v[204:207], v138 offset:53248
	ds_read_b128 v[208:211], v138 offset:54272
	ds_read_b128 v[212:215], v138 offset:55296
	ds_read_b128 v[216:219], v138 offset:56320
	global_load_lds_dwordx4 v[220:221], off
	v_lshl_add_u64 v[220:221], v[224:225], 0, s[36:37]
	s_mov_b32 m0, s82
	s_addc_u32 s73, s77, 0
	global_load_lds_dwordx4 v[220:221], off
	s_mov_b32 m0, s85
	v_lshl_add_u64 v[220:221], s[72:73], 0, v[130:131]
	global_load_lds_dwordx4 v[220:221], off
	s_mov_b32 m0, s86
	v_lshl_add_u64 v[220:221], s[72:73], 0, v[128:129]
	global_load_lds_dwordx4 v[220:221], off
	s_mov_b32 m0, s83
	v_lshl_add_u64 v[220:221], v[226:227], 0, s[36:37]
	global_load_lds_dwordx4 v[220:221], off
	s_mov_b32 m0, s84
	v_lshl_add_u64 v[220:221], v[228:229], 0, s[36:37]
	global_load_lds_dwordx4 v[220:221], off
	s_waitcnt vmcnt(8)
	s_waitcnt lgkmcnt(0)
	s_barrier
	s_setprio 1
	s_waitcnt lgkmcnt(0)
	v_mfma_f32_16x16x32_bf16 v[60:63], v[156:159], v[188:191], v[60:63]
	v_mfma_f32_16x16x32_bf16 v[56:59], v[164:167], v[188:191], v[56:59]
	v_mfma_f32_16x16x32_bf16 v[44:47], v[156:159], v[196:199], v[44:47]
	v_mfma_f32_16x16x32_bf16 v[40:43], v[164:167], v[196:199], v[40:43]
	v_mfma_f32_16x16x32_bf16 v[28:31], v[156:159], v[204:207], v[28:31]
	v_mfma_f32_16x16x32_bf16 v[24:27], v[164:167], v[204:207], v[24:27]
	v_mfma_f32_16x16x32_bf16 v[12:15], v[156:159], v[212:215], v[12:15]
	v_mfma_f32_16x16x32_bf16 v[8:11], v[164:167], v[212:215], v[8:11]
	v_mfma_f32_16x16x32_bf16 v[60:63], v[160:163], v[192:195], v[60:63]
	v_mfma_f32_16x16x32_bf16 v[56:59], v[168:171], v[192:195], v[56:59]
	v_mfma_f32_16x16x32_bf16 v[44:47], v[160:163], v[200:203], v[44:47]
	v_mfma_f32_16x16x32_bf16 v[40:43], v[168:171], v[200:203], v[40:43]
	v_mfma_f32_16x16x32_bf16 v[28:31], v[160:163], v[208:211], v[28:31]
	v_mfma_f32_16x16x32_bf16 v[24:27], v[168:171], v[208:211], v[24:27]
	v_mfma_f32_16x16x32_bf16 v[12:15], v[160:163], v[216:219], v[12:15]
	v_mfma_f32_16x16x32_bf16 v[8:11], v[168:171], v[216:219], v[8:11]
	s_setprio 0
	s_setprio 1
	v_mfma_f32_16x16x32_bf16 v[52:55], v[172:175], v[188:191], v[52:55]
	v_mfma_f32_16x16x32_bf16 v[48:51], v[180:183], v[188:191], v[48:51]
	v_mfma_f32_16x16x32_bf16 v[36:39], v[172:175], v[196:199], v[36:39]
	v_mfma_f32_16x16x32_bf16 v[32:35], v[180:183], v[196:199], v[32:35]
	v_mfma_f32_16x16x32_bf16 v[20:23], v[172:175], v[204:207], v[20:23]
	v_mfma_f32_16x16x32_bf16 v[16:19], v[180:183], v[204:207], v[16:19]
	v_mfma_f32_16x16x32_bf16 v[4:7], v[172:175], v[212:215], v[4:7]
	v_mfma_f32_16x16x32_bf16 v[0:3], v[180:183], v[212:215], v[0:3]
	v_mfma_f32_16x16x32_bf16 v[52:55], v[176:179], v[192:195], v[52:55]
	v_mfma_f32_16x16x32_bf16 v[48:51], v[184:187], v[192:195], v[48:51]
	v_mfma_f32_16x16x32_bf16 v[36:39], v[176:179], v[200:203], v[36:39]
	v_mfma_f32_16x16x32_bf16 v[32:35], v[184:187], v[200:203], v[32:35]
	v_mfma_f32_16x16x32_bf16 v[20:23], v[176:179], v[208:211], v[20:23]
	v_mfma_f32_16x16x32_bf16 v[16:19], v[184:187], v[208:211], v[16:19]
	v_mfma_f32_16x16x32_bf16 v[4:7], v[176:179], v[216:219], v[4:7]
	v_mfma_f32_16x16x32_bf16 v[0:3], v[184:187], v[216:219], v[0:3]
	s_setprio 0
	s_barrier
	s_add_u32 s90, s90, 0x100
	s_addc_u32 s92, s92, 0
	s_mov_b64 s[72:73], s[74:75]
	s_mov_b32 s6, s7
.LBB0_655:
	ds_read_b128 v[156:159], v140
	ds_read_b128 v[160:163], v141
	ds_read_b128 v[164:167], v142
	ds_read_b128 v[168:171], v143
	ds_read_b128 v[172:175], v144
	ds_read_b128 v[176:179], v145
	ds_read_b128 v[180:183], v146
	ds_read_b128 v[184:187], v147
	s_add_i32 s7, s6, 2
	s_add_u32 s74, s72, 0x100
	s_addc_u32 s75, s73, 0
	s_cmp_eq_u32 s87, s6
	s_cselect_b32 s79, s55, s75
	s_cselect_b32 s78, s57, s74
	s_cselect_b32 s77, s59, s92
	s_cselect_b32 s76, s61, s90
	s_mov_b32 m0, s88
	v_lshl_add_u64 v[220:221], s[72:73], 0, v[134:135]
	ds_read_b128 v[188:191], v138
	ds_read_b128 v[192:195], v138 offset:1024
	ds_read_b128 v[196:199], v138 offset:2048
	ds_read_b128 v[200:203], v138 offset:3072
	ds_read_b128 v[204:207], v138 offset:4096
	ds_read_b128 v[208:211], v138 offset:5120
	ds_read_b128 v[212:215], v138 offset:6144
	ds_read_b128 v[216:219], v138 offset:7168
	global_load_lds_dwordx4 v[220:221], off
	s_mov_b32 m0, s89
	v_lshl_add_u64 v[220:221], s[72:73], 0, v[136:137]
	global_load_lds_dwordx4 v[220:221], off
	s_waitcnt vmcnt(8)
	s_waitcnt lgkmcnt(0)
	s_barrier
; #define PG8_STAGE(bufoff, gbase, voff) do { _Pragma("unroll") for (int _i = 0; _i < 2; ++_i) \
;         __builtin_amdgcn_global_load_lds((const unsigned*)((const char*)(gbase) + (voff)[_i]), (PG8_LAS unsigned*)(lds + (bufoff) + ldsw + _i * 8192), 16, 0, 0); } while (0)
; #define PG8_LDA(dst, b, h) do { _Pragma("unroll") for (int m = 0; m < 4; ++m) _Pragma("unroll") for (int k = 0; k < 2; ++k) dst[m][k] = *(const PG8_LAS bf16x8*)(lds + PG8_SA(b, h) + aoff + m * 2048 + k * 1024); } while (0)
; #define PG8_MMA(ai, bj, At, Bt) do { __builtin_amdgcn_s_setprio(1); _Pragma("unroll") for (int m = 0; m < 4; ++m) _Pragma("unroll") for (int n = 0; n < 2; ++n) _Pragma("unroll") for (int k = 0; k < 2; ++k) \
;         acc[ai][bj][m][n] = __builtin_amdgcn_mfma_f32_16x16x32_bf16(Bt[n][k], At[m][k], acc[ai][bj][m][n], 0, 0, 0); __builtin_amdgcn_s_setprio(0); } while (0)
; #define PG8_WAIT_V(n) asm volatile("s_waitcnt vmcnt(" #n ")" ::: "memory")
; #define PG8_WAIT_L(n) asm volatile("s_waitcnt lgkmcnt(" #n ")" ::: "memory")
; #define PG8_BAR __builtin_amdgcn_s_barrier()
; #define PG8_SCHED __builtin_amdgcn_sched_barrier(0)
; template <class Epi, class Sched, bool ALIGN_EPI = false, bool SP2 = false>
; __device__ __forceinline__ void gemm_phase(PG8_LAS unsigned char* lds, const Gemm g, const Sched& S, const Epi& E) {
;     ...
;             PG8_WAIT_V(8); PG8_WAIT_L(0); PG8_BAR; PG8_MMA(0, 0, At, B0); PG8_MMA(0, 1, At, B1); PG8_BAR; PG8_SCHED;
;             PG8_LDA(At, 0, 1); PG8_STAGE(PG8_SB(0, 0), b2, voffB); PG8_STAGE(PG8_SB(0, 1), b2 + hstep, voffB); PG8_STAGE(PG8_SA(0, 0), a2, voffA);
;             PG8_WAIT_V(8); PG8_WAIT_L(0); PG8_BAR; PG8_MMA(1, 0, At, B0); PG8_MMA(1, 1, At, B1); PG8_BAR; PG8_SCHED;
	s_setprio 1
	s_waitcnt lgkmcnt(0)
	v_mfma_f32_16x16x32_bf16 v[124:127], v[156:159], v[188:191], v[124:127]
	v_mfma_f32_16x16x32_bf16 v[120:123], v[164:167], v[188:191], v[120:123]
	v_mfma_f32_16x16x32_bf16 v[108:111], v[156:159], v[196:199], v[108:111]
	v_mfma_f32_16x16x32_bf16 v[104:107], v[164:167], v[196:199], v[104:107]
	v_mfma_f32_16x16x32_bf16 v[92:95], v[156:159], v[204:207], v[92:95]
	v_mfma_f32_16x16x32_bf16 v[88:91], v[164:167], v[204:207], v[88:91]
	v_mfma_f32_16x16x32_bf16 v[76:79], v[156:159], v[212:215], v[76:79]
	v_mfma_f32_16x16x32_bf16 v[72:75], v[164:167], v[212:215], v[72:75]
	v_mfma_f32_16x16x32_bf16 v[124:127], v[160:163], v[192:195], v[124:127]
	v_mfma_f32_16x16x32_bf16 v[120:123], v[168:171], v[192:195], v[120:123]
	v_mfma_f32_16x16x32_bf16 v[108:111], v[160:163], v[200:203], v[108:111]
	v_mfma_f32_16x16x32_bf16 v[104:107], v[168:171], v[200:203], v[104:107]
	v_mfma_f32_16x16x32_bf16 v[92:95], v[160:163], v[208:211], v[92:95]
	v_mfma_f32_16x16x32_bf16 v[88:91], v[168:171], v[208:211], v[88:91]
	v_mfma_f32_16x16x32_bf16 v[76:79], v[160:163], v[216:219], v[76:79]
	v_mfma_f32_16x16x32_bf16 v[72:75], v[168:171], v[216:219], v[72:75]
	s_setprio 0
	s_setprio 1
	v_mfma_f32_16x16x32_bf16 v[116:119], v[172:175], v[188:191], v[116:119]
	v_mfma_f32_16x16x32_bf16 v[112:115], v[180:183], v[188:191], v[112:115]
	v_mfma_f32_16x16x32_bf16 v[100:103], v[172:175], v[196:199], v[100:103]
	v_mfma_f32_16x16x32_bf16 v[96:99], v[180:183], v[196:199], v[96:99]
	v_mfma_f32_16x16x32_bf16 v[84:87], v[172:175], v[204:207], v[84:87]
	v_mfma_f32_16x16x32_bf16 v[80:83], v[180:183], v[204:207], v[80:83]
	v_mfma_f32_16x16x32_bf16 v[68:71], v[172:175], v[212:215], v[68:71]
	v_mfma_f32_16x16x32_bf16 v[64:67], v[180:183], v[212:215], v[64:67]
	v_mfma_f32_16x16x32_bf16 v[116:119], v[176:179], v[192:195], v[116:119]
	v_mfma_f32_16x16x32_bf16 v[112:115], v[184:187], v[192:195], v[112:115]
	v_mfma_f32_16x16x32_bf16 v[100:103], v[176:179], v[200:203], v[100:103]
	v_mfma_f32_16x16x32_bf16 v[96:99], v[184:187], v[200:203], v[96:99]
	v_mfma_f32_16x16x32_bf16 v[84:87], v[176:179], v[208:211], v[84:87]
	v_mfma_f32_16x16x32_bf16 v[80:83], v[184:187], v[208:211], v[80:83]
	v_mfma_f32_16x16x32_bf16 v[68:71], v[176:179], v[216:219], v[68:71]
	v_mfma_f32_16x16x32_bf16 v[64:67], v[184:187], v[216:219], v[64:67]
	s_setprio 0
	s_barrier
	s_mov_b32 m0, s13
	v_lshl_add_u64 v[220:221], s[76:77], 0, v[130:131]
	s_add_u32 s72, s76, 0x40000
	ds_read_b128 v[188:191], v138 offset:16384
	ds_read_b128 v[192:195], v138 offset:17408
	ds_read_b128 v[196:199], v138 offset:18432
	ds_read_b128 v[200:203], v138 offset:19456
	ds_read_b128 v[204:207], v138 offset:20480
	ds_read_b128 v[208:211], v138 offset:21504
	ds_read_b128 v[212:215], v138 offset:22528
	ds_read_b128 v[216:219], v138 offset:23552
	global_load_lds_dwordx4 v[220:221], off
	v_lshl_add_u64 v[224:225], s[76:77], 0, v[128:129]
	s_mov_b32 m0, s14
	s_addc_u32 s73, s77, 0
	global_load_lds_dwordx4 v[224:225], off
	v_lshl_add_u64 v[226:227], s[72:73], 0, v[130:131]
	s_mov_b32 m0, s15
	v_lshl_add_u64 v[228:229], s[78:79], 0, v[128:129]
	global_load_lds_dwordx4 v[226:227], off
	s_mov_b32 m0, s33
	v_lshl_add_u64 v[226:227], s[72:73], 0, v[128:129]
	global_load_lds_dwordx4 v[226:227], off
	s_mov_b32 m0, s12
	v_lshl_add_u64 v[226:227], s[78:79], 0, v[130:131]
	global_load_lds_dwordx4 v[226:227], off
	s_mov_b32 m0, s39
	s_nop 0
	global_load_lds_dwordx4 v[228:229], off
	s_waitcnt vmcnt(8)
	s_waitcnt lgkmcnt(0)
	s_barrier
	s_setprio 1
	s_waitcnt lgkmcnt(0)
	v_mfma_f32_16x16x32_bf16 v[60:63], v[156:159], v[188:191], v[60:63]
	v_mfma_f32_16x16x32_bf16 v[56:59], v[164:167], v[188:191], v[56:59]
	v_mfma_f32_16x16x32_bf16 v[44:47], v[156:159], v[196:199], v[44:47]
	v_mfma_f32_16x16x32_bf16 v[40:43], v[164:167], v[196:199], v[40:43]
	v_mfma_f32_16x16x32_bf16 v[28:31], v[156:159], v[204:207], v[28:31]
	v_mfma_f32_16x16x32_bf16 v[24:27], v[164:167], v[204:207], v[24:27]
	v_mfma_f32_16x16x32_bf16 v[12:15], v[156:159], v[212:215], v[12:15]
	v_mfma_f32_16x16x32_bf16 v[8:11], v[164:167], v[212:215], v[8:11]
	v_mfma_f32_16x16x32_bf16 v[60:63], v[160:163], v[192:195], v[60:63]
	v_mfma_f32_16x16x32_bf16 v[56:59], v[168:171], v[192:195], v[56:59]
	v_mfma_f32_16x16x32_bf16 v[44:47], v[160:163], v[200:203], v[44:47]
	v_mfma_f32_16x16x32_bf16 v[40:43], v[168:171], v[200:203], v[40:43]
	v_mfma_f32_16x16x32_bf16 v[28:31], v[160:163], v[208:211], v[28:31]
	v_mfma_f32_16x16x32_bf16 v[24:27], v[168:171], v[208:211], v[24:27]
	v_mfma_f32_16x16x32_bf16 v[12:15], v[160:163], v[216:219], v[12:15]
	v_mfma_f32_16x16x32_bf16 v[8:11], v[168:171], v[216:219], v[8:11]
	s_setprio 0
	s_setprio 1
	v_mfma_f32_16x16x32_bf16 v[52:55], v[172:175], v[188:191], v[52:55]
	v_mfma_f32_16x16x32_bf16 v[48:51], v[180:183], v[188:191], v[48:51]
	v_mfma_f32_16x16x32_bf16 v[36:39], v[172:175], v[196:199], v[36:39]
	v_mfma_f32_16x16x32_bf16 v[32:35], v[180:183], v[196:199], v[32:35]
	v_mfma_f32_16x16x32_bf16 v[20:23], v[172:175], v[204:207], v[20:23]
	v_mfma_f32_16x16x32_bf16 v[16:19], v[180:183], v[204:207], v[16:19]
	v_mfma_f32_16x16x32_bf16 v[4:7], v[172:175], v[212:215], v[4:7]
	v_mfma_f32_16x16x32_bf16 v[0:3], v[180:183], v[212:215], v[0:3]
	v_mfma_f32_16x16x32_bf16 v[52:55], v[176:179], v[192:195], v[52:55]
	v_mfma_f32_16x16x32_bf16 v[48:51], v[184:187], v[192:195], v[48:51]
	v_mfma_f32_16x16x32_bf16 v[36:39], v[176:179], v[200:203], v[36:39]
	v_mfma_f32_16x16x32_bf16 v[32:35], v[184:187], v[200:203], v[32:35]
	v_mfma_f32_16x16x32_bf16 v[20:23], v[176:179], v[208:211], v[20:23]
	v_mfma_f32_16x16x32_bf16 v[16:19], v[184:187], v[208:211], v[16:19]
	v_mfma_f32_16x16x32_bf16 v[4:7], v[176:179], v[216:219], v[4:7]
	v_mfma_f32_16x16x32_bf16 v[0:3], v[184:187], v[216:219], v[0:3]
	s_setprio 0
	s_barrier
; #define PG8_STAGE(bufoff, gbase, voff) do { _Pragma("unroll") for (int _i = 0; _i < 2; ++_i) \
;         __builtin_amdgcn_global_load_lds((const unsigned*)((const char*)(gbase) + (voff)[_i]), (PG8_LAS unsigned*)(lds + (bufoff) + ldsw + _i * 8192), 16, 0, 0); } while (0)
; #define PG8_LDA(dst, b, h) do { _Pragma("unroll") for (int m = 0; m < 4; ++m) _Pragma("unroll") for (int k = 0; k < 2; ++k) dst[m][k] = *(const PG8_LAS bf16x8*)(lds + PG8_SA(b, h) + aoff + m * 2048 + k * 1024); } while (0)
; #define PG8_LDB(dst, b, h) do { _Pragma("unroll") for (int n = 0; n < 2; ++n) _Pragma("unroll") for (int k = 0; k < 2; ++k) dst[n][k] = *(const PG8_LAS bf16x8*)(lds + PG8_SB(b, h) + boff + n * 2048 + k * 1024); } while (0)
; #define PG8_MMA(ai, bj, At, Bt) do { __builtin_amdgcn_s_setprio(1); _Pragma("unroll") for (int m = 0; m < 4; ++m) _Pragma("unroll") for (int n = 0; n < 2; ++n) _Pragma("unroll") for (int k = 0; k < 2; ++k) \
;         acc[ai][bj][m][n] = __builtin_amdgcn_mfma_f32_16x16x32_bf16(Bt[n][k], At[m][k], acc[ai][bj][m][n], 0, 0, 0); __builtin_amdgcn_s_setprio(0); } while (0)
; #define PG8_WAIT_V(n) asm volatile("s_waitcnt vmcnt(" #n ")" ::: "memory")
; #define PG8_WAIT_L(n) asm volatile("s_waitcnt lgkmcnt(" #n ")" ::: "memory")
; #define PG8_BAR __builtin_amdgcn_s_barrier()
; #define PG8_SCHED __builtin_amdgcn_sched_barrier(0)
; template <class Epi, class Sched, bool ALIGN_EPI = false, bool SP2 = false>
; __device__ __forceinline__ void gemm_phase(PG8_LAS unsigned char* lds, const Gemm g, const Sched& S, const Epi& E) {
;     ...
;             PG8_LDB(B0, 1, 0); PG8_LDB(B1, 1, 1); PG8_SCHED; PG8_LDA(At, 1, 0); PG8_STAGE(PG8_SA(0, 1), a2 + hstep, voffA);
;             PG8_WAIT_V(8); PG8_WAIT_L(0); PG8_BAR; PG8_MMA(0, 0, At, B0); PG8_MMA(0, 1, At, B1); PG8_BAR; PG8_SCHED;
;             PG8_LDA(At, 1, 1); PG8_STAGE(PG8_SB(1, 0), b3, voffB); PG8_STAGE(PG8_SB(1, 1), b3 + hstep, voffB); PG8_STAGE(PG8_SA(1, 0), a3, voffA);
;             PG8_WAIT_V(8); PG8_WAIT_L(0); PG8_BAR; PG8_MMA(1, 0, At, B0); PG8_MMA(1, 1, At, B1); PG8_BAR; PG8_SCHED;
	ds_read_b128 v[156:159], v148
	ds_read_b128 v[160:163], v149
	ds_read_b128 v[164:167], v150
	ds_read_b128 v[168:171], v151
	ds_read_b128 v[172:175], v152
	ds_read_b128 v[176:179], v153
	ds_read_b128 v[180:183], v154
	ds_read_b128 v[184:187], v155
	s_add_u32 s72, s78, 0x40000
	s_addc_u32 s73, s79, 0
	s_mov_b32 m0, s43
	v_lshl_add_u64 v[230:231], s[72:73], 0, v[130:131]
	ds_read_b128 v[188:191], v138 offset:32768
	ds_read_b128 v[192:195], v138 offset:33792
	ds_read_b128 v[196:199], v138 offset:34816
	ds_read_b128 v[200:203], v138 offset:35840
	ds_read_b128 v[204:207], v138 offset:36864
	ds_read_b128 v[208:211], v138 offset:37888
	ds_read_b128 v[212:215], v138 offset:38912
	ds_read_b128 v[216:219], v138 offset:39936
	global_load_lds_dwordx4 v[230:231], off
	s_mov_b32 m0, s65
	v_lshl_add_u64 v[230:231], s[72:73], 0, v[128:129]
	global_load_lds_dwordx4 v[230:231], off
	s_waitcnt vmcnt(8)
	s_waitcnt lgkmcnt(0)
	s_barrier
	s_setprio 1
	s_waitcnt lgkmcnt(0)
	v_mfma_f32_16x16x32_bf16 v[124:127], v[156:159], v[188:191], v[124:127]
	v_mfma_f32_16x16x32_bf16 v[120:123], v[164:167], v[188:191], v[120:123]
	v_mfma_f32_16x16x32_bf16 v[108:111], v[156:159], v[196:199], v[108:111]
	v_mfma_f32_16x16x32_bf16 v[104:107], v[164:167], v[196:199], v[104:107]
	v_mfma_f32_16x16x32_bf16 v[92:95], v[156:159], v[204:207], v[92:95]
	v_mfma_f32_16x16x32_bf16 v[88:91], v[164:167], v[204:207], v[88:91]
	v_mfma_f32_16x16x32_bf16 v[76:79], v[156:159], v[212:215], v[76:79]
	v_mfma_f32_16x16x32_bf16 v[72:75], v[164:167], v[212:215], v[72:75]
	v_mfma_f32_16x16x32_bf16 v[124:127], v[160:163], v[192:195], v[124:127]
	v_mfma_f32_16x16x32_bf16 v[120:123], v[168:171], v[192:195], v[120:123]
	v_mfma_f32_16x16x32_bf16 v[108:111], v[160:163], v[200:203], v[108:111]
	v_mfma_f32_16x16x32_bf16 v[104:107], v[168:171], v[200:203], v[104:107]
	v_mfma_f32_16x16x32_bf16 v[92:95], v[160:163], v[208:211], v[92:95]
	v_mfma_f32_16x16x32_bf16 v[88:91], v[168:171], v[208:211], v[88:91]
	v_mfma_f32_16x16x32_bf16 v[76:79], v[160:163], v[216:219], v[76:79]
	v_mfma_f32_16x16x32_bf16 v[72:75], v[168:171], v[216:219], v[72:75]
	s_setprio 0
	s_setprio 1
	v_mfma_f32_16x16x32_bf16 v[116:119], v[172:175], v[188:191], v[116:119]
	v_mfma_f32_16x16x32_bf16 v[112:115], v[180:183], v[188:191], v[112:115]
	v_mfma_f32_16x16x32_bf16 v[100:103], v[172:175], v[196:199], v[100:103]
	v_mfma_f32_16x16x32_bf16 v[96:99], v[180:183], v[196:199], v[96:99]
	v_mfma_f32_16x16x32_bf16 v[84:87], v[172:175], v[204:207], v[84:87]
	v_mfma_f32_16x16x32_bf16 v[80:83], v[180:183], v[204:207], v[80:83]
	v_mfma_f32_16x16x32_bf16 v[68:71], v[172:175], v[212:215], v[68:71]
	v_mfma_f32_16x16x32_bf16 v[64:67], v[180:183], v[212:215], v[64:67]
	v_mfma_f32_16x16x32_bf16 v[116:119], v[176:179], v[192:195], v[116:119]
	v_mfma_f32_16x16x32_bf16 v[112:115], v[184:187], v[192:195], v[112:115]
	v_mfma_f32_16x16x32_bf16 v[100:103], v[176:179], v[200:203], v[100:103]
	v_mfma_f32_16x16x32_bf16 v[96:99], v[184:187], v[200:203], v[96:99]
	v_mfma_f32_16x16x32_bf16 v[84:87], v[176:179], v[208:211], v[84:87]
	v_mfma_f32_16x16x32_bf16 v[80:83], v[184:187], v[208:211], v[80:83]
	v_mfma_f32_16x16x32_bf16 v[68:71], v[176:179], v[216:219], v[68:71]
	v_mfma_f32_16x16x32_bf16 v[64:67], v[184:187], v[216:219], v[64:67]
	s_setprio 0
	s_barrier
	s_mov_b32 m0, s81
	v_lshl_add_u64 v[220:221], v[220:221], 0, s[36:37]
	s_add_u32 s72, s76, 0x40080
	ds_read_b128 v[188:191], v138 offset:49152
	ds_read_b128 v[192:195], v138 offset:50176
	ds_read_b128 v[196:199], v138 offset:51200
	ds_read_b128 v[200:203], v138 offset:52224
	ds_read_b128 v[204:207], v138 offset:53248
	ds_read_b128 v[208:211], v138 offset:54272
	ds_read_b128 v[212:215], v138 offset:55296
	ds_read_b128 v[216:219], v138 offset:56320
	global_load_lds_dwordx4 v[220:221], off
	v_lshl_add_u64 v[220:221], v[224:225], 0, s[36:37]
	s_mov_b32 m0, s82
	s_addc_u32 s73, s77, 0
	global_load_lds_dwordx4 v[220:221], off
	s_mov_b32 m0, s85
	v_lshl_add_u64 v[220:221], s[72:73], 0, v[130:131]
	global_load_lds_dwordx4 v[220:221], off
	s_mov_b32 m0, s86
	v_lshl_add_u64 v[220:221], s[72:73], 0, v[128:129]
	global_load_lds_dwordx4 v[220:221], off
	s_mov_b32 m0, s83
	v_lshl_add_u64 v[220:221], v[226:227], 0, s[36:37]
	global_load_lds_dwordx4 v[220:221], off
	s_mov_b32 m0, s84
	v_lshl_add_u64 v[220:221], v[228:229], 0, s[36:37]
	global_load_lds_dwordx4 v[220:221], off
	s_waitcnt vmcnt(8)
	s_waitcnt lgkmcnt(0)
	s_barrier
	s_setprio 1
	s_waitcnt lgkmcnt(0)
	v_mfma_f32_16x16x32_bf16 v[60:63], v[156:159], v[188:191], v[60:63]
	v_mfma_f32_16x16x32_bf16 v[56:59], v[164:167], v[188:191], v[56:59]
	v_mfma_f32_16x16x32_bf16 v[44:47], v[156:159], v[196:199], v[44:47]
	v_mfma_f32_16x16x32_bf16 v[40:43], v[164:167], v[196:199], v[40:43]
	v_mfma_f32_16x16x32_bf16 v[28:31], v[156:159], v[204:207], v[28:31]
	v_mfma_f32_16x16x32_bf16 v[24:27], v[164:167], v[204:207], v[24:27]
	v_mfma_f32_16x16x32_bf16 v[12:15], v[156:159], v[212:215], v[12:15]
	v_mfma_f32_16x16x32_bf16 v[8:11], v[164:167], v[212:215], v[8:11]
	v_mfma_f32_16x16x32_bf16 v[60:63], v[160:163], v[192:195], v[60:63]
	v_mfma_f32_16x16x32_bf16 v[56:59], v[168:171], v[192:195], v[56:59]
	v_mfma_f32_16x16x32_bf16 v[44:47], v[160:163], v[200:203], v[44:47]
	v_mfma_f32_16x16x32_bf16 v[40:43], v[168:171], v[200:203], v[40:43]
	v_mfma_f32_16x16x32_bf16 v[28:31], v[160:163], v[208:211], v[28:31]
	v_mfma_f32_16x16x32_bf16 v[24:27], v[168:171], v[208:211], v[24:27]
	v_mfma_f32_16x16x32_bf16 v[12:15], v[160:163], v[216:219], v[12:15]
	v_mfma_f32_16x16x32_bf16 v[8:11], v[168:171], v[216:219], v[8:11]
	s_setprio 0
	s_setprio 1
	v_mfma_f32_16x16x32_bf16 v[52:55], v[172:175], v[188:191], v[52:55]
	v_mfma_f32_16x16x32_bf16 v[48:51], v[180:183], v[188:191], v[48:51]
	v_mfma_f32_16x16x32_bf16 v[36:39], v[172:175], v[196:199], v[36:39]
	v_mfma_f32_16x16x32_bf16 v[32:35], v[180:183], v[196:199], v[32:35]
	v_mfma_f32_16x16x32_bf16 v[20:23], v[172:175], v[204:207], v[20:23]
	v_mfma_f32_16x16x32_bf16 v[16:19], v[180:183], v[204:207], v[16:19]
	v_mfma_f32_16x16x32_bf16 v[4:7], v[172:175], v[212:215], v[4:7]
	v_mfma_f32_16x16x32_bf16 v[0:3], v[180:183], v[212:215], v[0:3]
	v_mfma_f32_16x16x32_bf16 v[52:55], v[176:179], v[192:195], v[52:55]
	v_mfma_f32_16x16x32_bf16 v[48:51], v[184:187], v[192:195], v[48:51]
	v_mfma_f32_16x16x32_bf16 v[36:39], v[176:179], v[200:203], v[36:39]
	v_mfma_f32_16x16x32_bf16 v[32:35], v[184:187], v[200:203], v[32:35]
	v_mfma_f32_16x16x32_bf16 v[20:23], v[176:179], v[208:211], v[20:23]
	v_mfma_f32_16x16x32_bf16 v[16:19], v[184:187], v[208:211], v[16:19]
	v_mfma_f32_16x16x32_bf16 v[4:7], v[176:179], v[216:219], v[4:7]
	v_mfma_f32_16x16x32_bf16 v[0:3], v[184:187], v[216:219], v[0:3]
	s_setprio 0
	s_barrier
	s_add_u32 s90, s90, 0x100
	s_addc_u32 s92, s92, 0
	s_cmp_ge_i32 s7, s3
	s_mov_b64 s[72:73], s[74:75]
	s_mov_b32 s6, s7
	s_cbranch_scc0 .LBB0_655
	s_and_b64 vcc, exec, s[52:53]
	s_cbranch_vccz .LBB0_658

;     __host__ __device__ bool next(int i, Unit& u) const { const int L = i * G + c; if (L >= 16 * nkc) return false; u.kc = L % nkc; const int t = L / nkc; u.pn = t & 3; u.pm = 33 * (t >> 2); return true; }
; #define PG8_STAGE(bufoff, gbase, voff) do { _Pragma("unroll") for (int _i = 0; _i < 2; ++_i) \
;         __builtin_amdgcn_global_load_lds((const unsigned*)((const char*)(gbase) + (voff)[_i]), (PG8_LAS unsigned*)(lds + (bufoff) + ldsw + _i * 8192), 16, 0, 0); } while (0)
; #define PG8_LDA(dst, b, h) do { _Pragma("unroll") for (int m = 0; m < 4; ++m) _Pragma("unroll") for (int k = 0; k < 2; ++k) dst[m][k] = *(const PG8_LAS bf16x8*)(lds + PG8_SA(b, h) + aoff + m * 2048 + k * 1024); } while (0)
; #define PG8_LDB(dst, b, h) do { _Pragma("unroll") for (int n = 0; n < 2; ++n) _Pragma("unroll") for (int k = 0; k < 2; ++k) dst[n][k] = *(const PG8_LAS bf16x8*)(lds + PG8_SB(b, h) + boff + n * 2048 + k * 1024); } while (0)
; #define PG8_WAIT_V(n) asm volatile("s_waitcnt vmcnt(" #n ")" ::: "memory")
; #define PG8_WAIT_L(n) asm volatile("s_waitcnt lgkmcnt(" #n ")" ::: "memory")
; template <class Epi, class Sched, bool ALIGN_EPI = false, bool SP2 = false>
; __device__ __forceinline__ void gemm_phase(PG8_LAS unsigned char* lds, const Gemm g, const Sched& S, const Epi& E) {
;     ...
;         const bool has_next = S.next(ui + 1, nxt);
;         const char* nA = has_next ? (const char*)g.A + (size_t)nxt.pm * tstep + (size_t)nxt.kc * cstep : cA; const char* nB = has_next ? (const char*)g.Bt + (size_t)nxt.pn * tstep + (size_t)nxt.kc * cstep : cB;
;         for (int t = 0; t < nt; t += 2) {
;             const bool last = (t == nt - 2);
;             const char* a1 = cA + (size_t)(t + 1) * kstep;
;             const char* a2 = last ? nA : cA + (size_t)(t + 2) * kstep; const char* b2 = last ? nB : cB + (size_t)(t + 2) * kstep;
;             const char* a3 = a2 + kstep; const char* b3 = b2 + kstep;
;             if (last && has_next) S.a_ready(nxt);
;             if constexpr (SP2) {
;             PG8_LDB(B0, 0, 0); PG8_LDB(B1, 0, 1); PG8_SCHED; PG8_LDA(At, 0, 0); PG8_STAGE(PG8_SA(1, 1), a1 + hstep, voffA);
;             PG8_WAIT_V(8); PG8_WAIT_L(0); PG8_BAR; PG8_MMA(0, 0, At, B0); PG8_MMA(0, 1, At, B1); PG8_BAR; PG8_SCHED;
;             PG8_LDA(At, 0, 1); PG8_STAGE(PG8_SB(0, 0), b2, voffB); PG8_STAGE(PG8_SB(0, 1), b2 + hstep, voffB); PG8_STAGE(PG8_SA(0, 0), a2, voffA);
.LBB0_792:
	s_ashr_i32 s55, s54, 31
	s_lshl_b64 s[6:7], s[54:55], 19
	s_add_u32 s56, s46, s6
	s_addc_u32 s57, s47, s7
	s_and_b64 s[6:7], s[4:5], exec
	s_cselect_b32 s55, s57, s63
	s_cselect_b32 s82, s56, s62
	s_ashr_i32 s53, s52, 31
	s_lshl_b64 s[6:7], s[52:53], 19
	s_add_u32 s58, s1, s6
	s_addc_u32 s59, s3, s7
	s_and_b64 s[6:7], s[4:5], exec
	s_cselect_b32 s53, s59, s65
	s_cselect_b32 s83, s58, s64
	s_add_u32 s62, s62, 0x40080
	s_addc_u32 s63, s63, 0
	s_add_u32 s84, s64, 0x100
	s_addc_u32 s85, s65, 0
	s_mov_b32 s86, -2
	ds_read_b128 v[166:169], v149
	ds_read_b128 v[170:173], v150
	ds_read_b128 v[174:177], v151
	ds_read_b128 v[178:181], v152
	ds_read_b128 v[182:185], v153
	ds_read_b128 v[186:189], v154
	ds_read_b128 v[190:193], v155
	ds_read_b128 v[194:197], v156
	s_add_u32 s6, s62, 0xfffc0080
	s_addc_u32 s7, s63, -1
	s_cmp_eq_u32 s86, 12
	s_cselect_b32 s67, s55, s7
	s_cselect_b32 s66, s82, s6
	s_cselect_b32 s65, s53, s85
	s_cselect_b32 s64, s83, s84
	s_mov_b32 m0, s79
	v_lshl_add_u64 v[144:145], s[62:63], 0, v[136:137]
	ds_read_b128 v[198:201], v147
	ds_read_b128 v[202:205], v147 offset:1024
	ds_read_b128 v[206:209], v147 offset:2048
	ds_read_b128 v[210:213], v147 offset:3072
	ds_read_b128 v[214:217], v147 offset:4096
	ds_read_b128 v[218:221], v147 offset:5120
	ds_read_b128 v[224:227], v147 offset:6144
	ds_read_b128 v[228:231], v147 offset:7168
	global_load_lds_dwordx4 v[144:145], off
	s_mov_b32 m0, s80
	v_lshl_add_u64 v[144:145], s[62:63], 0, v[138:139]
	global_load_lds_dwordx4 v[144:145], off
	s_waitcnt vmcnt(8)
	s_waitcnt lgkmcnt(0)
	s_barrier
	s_setprio 1
	s_waitcnt lgkmcnt(0)
	v_mfma_f32_16x16x32_bf16 v[124:127], v[166:169], v[198:201], 0
	v_mfma_f32_16x16x32_bf16 v[120:123], v[174:177], v[198:201], 0
	v_mfma_f32_16x16x32_bf16 v[108:111], v[166:169], v[206:209], 0
	v_mfma_f32_16x16x32_bf16 v[104:107], v[174:177], v[206:209], 0
	v_mfma_f32_16x16x32_bf16 v[92:95], v[166:169], v[214:217], 0
	v_mfma_f32_16x16x32_bf16 v[88:91], v[174:177], v[214:217], 0
	v_mfma_f32_16x16x32_bf16 v[76:79], v[166:169], v[224:227], 0
	v_mfma_f32_16x16x32_bf16 v[72:75], v[174:177], v[224:227], 0
	v_mfma_f32_16x16x32_bf16 v[124:127], v[170:173], v[202:205], v[124:127]
	v_mfma_f32_16x16x32_bf16 v[120:123], v[178:181], v[202:205], v[120:123]
	v_mfma_f32_16x16x32_bf16 v[108:111], v[170:173], v[210:213], v[108:111]
	v_mfma_f32_16x16x32_bf16 v[104:107], v[178:181], v[210:213], v[104:107]
	v_mfma_f32_16x16x32_bf16 v[92:95], v[170:173], v[218:221], v[92:95]
	v_mfma_f32_16x16x32_bf16 v[88:91], v[178:181], v[218:221], v[88:91]
	v_mfma_f32_16x16x32_bf16 v[76:79], v[170:173], v[228:231], v[76:79]
	v_mfma_f32_16x16x32_bf16 v[72:75], v[178:181], v[228:231], v[72:75]
	s_setprio 0
	s_setprio 1
	v_mfma_f32_16x16x32_bf16 v[116:119], v[182:185], v[198:201], 0
	v_mfma_f32_16x16x32_bf16 v[112:115], v[190:193], v[198:201], 0
	v_mfma_f32_16x16x32_bf16 v[100:103], v[182:185], v[206:209], 0
	v_mfma_f32_16x16x32_bf16 v[96:99], v[190:193], v[206:209], 0
	v_mfma_f32_16x16x32_bf16 v[84:87], v[182:185], v[214:217], 0
	v_mfma_f32_16x16x32_bf16 v[80:83], v[190:193], v[214:217], 0
	v_mfma_f32_16x16x32_bf16 v[68:71], v[182:185], v[224:227], 0
	v_mfma_f32_16x16x32_bf16 v[64:67], v[190:193], v[224:227], 0
	v_mfma_f32_16x16x32_bf16 v[116:119], v[186:189], v[202:205], v[116:119]
	v_mfma_f32_16x16x32_bf16 v[112:115], v[194:197], v[202:205], v[112:115]
	v_mfma_f32_16x16x32_bf16 v[100:103], v[186:189], v[210:213], v[100:103]
	v_mfma_f32_16x16x32_bf16 v[96:99], v[194:197], v[210:213], v[96:99]
	v_mfma_f32_16x16x32_bf16 v[84:87], v[186:189], v[218:221], v[84:87]
	v_mfma_f32_16x16x32_bf16 v[80:83], v[194:197], v[218:221], v[80:83]
	v_mfma_f32_16x16x32_bf16 v[68:71], v[186:189], v[228:231], v[68:71]
	v_mfma_f32_16x16x32_bf16 v[64:67], v[194:197], v[228:231], v[64:67]
	s_setprio 0
	s_barrier
	s_mov_b32 m0, s15
	v_lshl_add_u64 v[144:145], s[64:65], 0, v[132:133]
	s_add_u32 s6, s64, 0x40000
	ds_read_b128 v[198:201], v147 offset:16384
	ds_read_b128 v[202:205], v147 offset:17408
	ds_read_b128 v[206:209], v147 offset:18432
	ds_read_b128 v[210:213], v147 offset:19456
	ds_read_b128 v[214:217], v147 offset:20480
	ds_read_b128 v[218:221], v147 offset:21504
	ds_read_b128 v[224:227], v147 offset:22528
	ds_read_b128 v[228:231], v147 offset:23552
	global_load_lds_dwordx4 v[144:145], off
	v_lshl_add_u64 v[232:233], s[64:65], 0, v[128:129]
	s_mov_b32 m0, s39
	s_addc_u32 s7, s65, 0
	global_load_lds_dwordx4 v[232:233], off
	v_lshl_add_u64 v[234:235], s[6:7], 0, v[132:133]
	s_mov_b32 m0, s43
	v_lshl_add_u64 v[236:237], s[66:67], 0, v[130:131]
	global_load_lds_dwordx4 v[234:235], off
	s_mov_b32 m0, s61
	v_lshl_add_u64 v[234:235], s[6:7], 0, v[128:129]
	global_load_lds_dwordx4 v[234:235], off
	s_mov_b32 m0, s12
	v_lshl_add_u64 v[234:235], s[66:67], 0, v[134:135]
	global_load_lds_dwordx4 v[234:235], off
	s_mov_b32 m0, s68
	s_nop 0
	global_load_lds_dwordx4 v[236:237], off
	s_waitcnt vmcnt(8)
	s_waitcnt lgkmcnt(0)
	s_barrier
; #define PG8_STAGE(bufoff, gbase, voff) do { _Pragma("unroll") for (int _i = 0; _i < 2; ++_i) \
;         __builtin_amdgcn_global_load_lds((const unsigned*)((const char*)(gbase) + (voff)[_i]), (PG8_LAS unsigned*)(lds + (bufoff) + ldsw + _i * 8192), 16, 0, 0); } while (0)
; #define PG8_LDA(dst, b, h) do { _Pragma("unroll") for (int m = 0; m < 4; ++m) _Pragma("unroll") for (int k = 0; k < 2; ++k) dst[m][k] = *(const PG8_LAS bf16x8*)(lds + PG8_SA(b, h) + aoff + m * 2048 + k * 1024); } while (0)
; #define PG8_LDB(dst, b, h) do { _Pragma("unroll") for (int n = 0; n < 2; ++n) _Pragma("unroll") for (int k = 0; k < 2; ++k) dst[n][k] = *(const PG8_LAS bf16x8*)(lds + PG8_SB(b, h) + boff + n * 2048 + k * 1024); } while (0)
; #define PG8_MMA(ai, bj, At, Bt) do { __builtin_amdgcn_s_setprio(1); _Pragma("unroll") for (int m = 0; m < 4; ++m) _Pragma("unroll") for (int n = 0; n < 2; ++n) _Pragma("unroll") for (int k = 0; k < 2; ++k) \
;         acc[ai][bj][m][n] = __builtin_amdgcn_mfma_f32_16x16x32_bf16(Bt[n][k], At[m][k], acc[ai][bj][m][n], 0, 0, 0); __builtin_amdgcn_s_setprio(0); } while (0)
; #define PG8_WAIT_V(n) asm volatile("s_waitcnt vmcnt(" #n ")" ::: "memory")
; #define PG8_WAIT_L(n) asm volatile("s_waitcnt lgkmcnt(" #n ")" ::: "memory")
; #define PG8_BAR __builtin_amdgcn_s_barrier()
; #define PG8_SCHED __builtin_amdgcn_sched_barrier(0)
; template <class Epi, class Sched, bool ALIGN_EPI = false, bool SP2 = false>
; __device__ __forceinline__ void gemm_phase(PG8_LAS unsigned char* lds, const Gemm g, const Sched& S, const Epi& E) {
;     ...
;             PG8_WAIT_V(8); PG8_WAIT_L(0); PG8_BAR; PG8_MMA(1, 0, At, B0); PG8_MMA(1, 1, At, B1); PG8_BAR; PG8_SCHED;
;             PG8_LDB(B0, 1, 0); PG8_LDB(B1, 1, 1); PG8_SCHED; PG8_LDA(At, 1, 0); PG8_STAGE(PG8_SA(0, 1), a2 + hstep, voffA);
;             PG8_WAIT_V(8); PG8_WAIT_L(0); PG8_BAR; PG8_MMA(0, 0, At, B0); PG8_MMA(0, 1, At, B1); PG8_BAR; PG8_SCHED;
	s_setprio 1
	s_waitcnt lgkmcnt(0)
	v_mfma_f32_16x16x32_bf16 v[60:63], v[166:169], v[198:201], 0
	v_mfma_f32_16x16x32_bf16 v[56:59], v[174:177], v[198:201], 0
	v_mfma_f32_16x16x32_bf16 v[44:47], v[166:169], v[206:209], 0
	v_mfma_f32_16x16x32_bf16 v[40:43], v[174:177], v[206:209], 0
	v_mfma_f32_16x16x32_bf16 v[28:31], v[166:169], v[214:217], 0
	v_mfma_f32_16x16x32_bf16 v[24:27], v[174:177], v[214:217], 0
	v_mfma_f32_16x16x32_bf16 v[12:15], v[166:169], v[224:227], 0
	v_mfma_f32_16x16x32_bf16 v[8:11], v[174:177], v[224:227], 0
	v_mfma_f32_16x16x32_bf16 v[60:63], v[170:173], v[202:205], v[60:63]
	v_mfma_f32_16x16x32_bf16 v[56:59], v[178:181], v[202:205], v[56:59]
	v_mfma_f32_16x16x32_bf16 v[44:47], v[170:173], v[210:213], v[44:47]
	v_mfma_f32_16x16x32_bf16 v[40:43], v[178:181], v[210:213], v[40:43]
	v_mfma_f32_16x16x32_bf16 v[28:31], v[170:173], v[218:221], v[28:31]
	v_mfma_f32_16x16x32_bf16 v[24:27], v[178:181], v[218:221], v[24:27]
	v_mfma_f32_16x16x32_bf16 v[12:15], v[170:173], v[228:231], v[12:15]
	v_mfma_f32_16x16x32_bf16 v[8:11], v[178:181], v[228:231], v[8:11]
	s_setprio 0
	s_setprio 1
	v_mfma_f32_16x16x32_bf16 v[52:55], v[182:185], v[198:201], 0
	v_mfma_f32_16x16x32_bf16 v[48:51], v[190:193], v[198:201], 0
	v_mfma_f32_16x16x32_bf16 v[36:39], v[182:185], v[206:209], 0
	v_mfma_f32_16x16x32_bf16 v[32:35], v[190:193], v[206:209], 0
	v_mfma_f32_16x16x32_bf16 v[20:23], v[182:185], v[214:217], 0
	v_mfma_f32_16x16x32_bf16 v[16:19], v[190:193], v[214:217], 0
	v_mfma_f32_16x16x32_bf16 v[4:7], v[182:185], v[224:227], 0
	v_mfma_f32_16x16x32_bf16 v[0:3], v[190:193], v[224:227], 0
	v_mfma_f32_16x16x32_bf16 v[52:55], v[186:189], v[202:205], v[52:55]
	v_mfma_f32_16x16x32_bf16 v[48:51], v[194:197], v[202:205], v[48:51]
	v_mfma_f32_16x16x32_bf16 v[36:39], v[186:189], v[210:213], v[36:39]
	v_mfma_f32_16x16x32_bf16 v[32:35], v[194:197], v[210:213], v[32:35]
	v_mfma_f32_16x16x32_bf16 v[20:23], v[186:189], v[218:221], v[20:23]
	v_mfma_f32_16x16x32_bf16 v[16:19], v[194:197], v[218:221], v[16:19]
	v_mfma_f32_16x16x32_bf16 v[4:7], v[186:189], v[228:231], v[4:7]
	v_mfma_f32_16x16x32_bf16 v[0:3], v[194:197], v[228:231], v[0:3]
	s_setprio 0
	s_barrier
	ds_read_b128 v[166:169], v157
	ds_read_b128 v[170:173], v158
	ds_read_b128 v[174:177], v159
	ds_read_b128 v[178:181], v160
	ds_read_b128 v[182:185], v161
	ds_read_b128 v[186:189], v162
	ds_read_b128 v[190:193], v163
	ds_read_b128 v[194:197], v164
	s_add_u32 s6, s66, 0x40000
	s_addc_u32 s7, s67, 0
	s_mov_b32 m0, s69
	v_lshl_add_u64 v[238:239], s[6:7], 0, v[134:135]
	ds_read_b128 v[198:201], v147 offset:32768
	ds_read_b128 v[202:205], v147 offset:33792
	ds_read_b128 v[206:209], v147 offset:34816
	ds_read_b128 v[210:213], v147 offset:35840
	ds_read_b128 v[214:217], v147 offset:36864
	ds_read_b128 v[218:221], v147 offset:37888
	ds_read_b128 v[224:227], v147 offset:38912
	ds_read_b128 v[228:231], v147 offset:39936
	global_load_lds_dwordx4 v[238:239], off
	s_mov_b32 m0, s70
	v_lshl_add_u64 v[238:239], s[6:7], 0, v[130:131]
	global_load_lds_dwordx4 v[238:239], off
	s_waitcnt vmcnt(8)
	s_waitcnt lgkmcnt(0)
	s_barrier
	s_setprio 1
	s_waitcnt lgkmcnt(0)
	v_mfma_f32_16x16x32_bf16 v[124:127], v[166:169], v[198:201], v[124:127]
	v_mfma_f32_16x16x32_bf16 v[120:123], v[174:177], v[198:201], v[120:123]
	v_mfma_f32_16x16x32_bf16 v[108:111], v[166:169], v[206:209], v[108:111]
	v_mfma_f32_16x16x32_bf16 v[104:107], v[174:177], v[206:209], v[104:107]
	v_mfma_f32_16x16x32_bf16 v[92:95], v[166:169], v[214:217], v[92:95]
	v_mfma_f32_16x16x32_bf16 v[88:91], v[174:177], v[214:217], v[88:91]
	v_mfma_f32_16x16x32_bf16 v[76:79], v[166:169], v[224:227], v[76:79]
	v_mfma_f32_16x16x32_bf16 v[72:75], v[174:177], v[224:227], v[72:75]
	v_mfma_f32_16x16x32_bf16 v[124:127], v[170:173], v[202:205], v[124:127]
	v_mfma_f32_16x16x32_bf16 v[120:123], v[178:181], v[202:205], v[120:123]
	v_mfma_f32_16x16x32_bf16 v[108:111], v[170:173], v[210:213], v[108:111]
	v_mfma_f32_16x16x32_bf16 v[104:107], v[178:181], v[210:213], v[104:107]
	v_mfma_f32_16x16x32_bf16 v[92:95], v[170:173], v[218:221], v[92:95]
	v_mfma_f32_16x16x32_bf16 v[88:91], v[178:181], v[218:221], v[88:91]
	v_mfma_f32_16x16x32_bf16 v[76:79], v[170:173], v[228:231], v[76:79]
	v_mfma_f32_16x16x32_bf16 v[72:75], v[178:181], v[228:231], v[72:75]
	s_setprio 0
	s_setprio 1
	v_mfma_f32_16x16x32_bf16 v[116:119], v[182:185], v[198:201], v[116:119]
	v_mfma_f32_16x16x32_bf16 v[112:115], v[190:193], v[198:201], v[112:115]
	v_mfma_f32_16x16x32_bf16 v[100:103], v[182:185], v[206:209], v[100:103]
	v_mfma_f32_16x16x32_bf16 v[96:99], v[190:193], v[206:209], v[96:99]
	v_mfma_f32_16x16x32_bf16 v[84:87], v[182:185], v[214:217], v[84:87]
	v_mfma_f32_16x16x32_bf16 v[80:83], v[190:193], v[214:217], v[80:83]
	v_mfma_f32_16x16x32_bf16 v[68:71], v[182:185], v[224:227], v[68:71]
	v_mfma_f32_16x16x32_bf16 v[64:67], v[190:193], v[224:227], v[64:67]
	v_mfma_f32_16x16x32_bf16 v[116:119], v[186:189], v[202:205], v[116:119]
	v_mfma_f32_16x16x32_bf16 v[112:115], v[194:197], v[202:205], v[112:115]
	v_mfma_f32_16x16x32_bf16 v[100:103], v[186:189], v[210:213], v[100:103]
	v_mfma_f32_16x16x32_bf16 v[96:99], v[194:197], v[210:213], v[96:99]
	v_mfma_f32_16x16x32_bf16 v[84:87], v[186:189], v[218:221], v[84:87]
	v_mfma_f32_16x16x32_bf16 v[80:83], v[194:197], v[218:221], v[80:83]
	v_mfma_f32_16x16x32_bf16 v[68:71], v[186:189], v[228:231], v[68:71]
	v_mfma_f32_16x16x32_bf16 v[64:67], v[194:197], v[228:231], v[64:67]
	s_setprio 0
	s_barrier
; #define PG8_STAGE(bufoff, gbase, voff) do { _Pragma("unroll") for (int _i = 0; _i < 2; ++_i) \
;         __builtin_amdgcn_global_load_lds((const unsigned*)((const char*)(gbase) + (voff)[_i]), (PG8_LAS unsigned*)(lds + (bufoff) + ldsw + _i * 8192), 16, 0, 0); } while (0)
; #define PG8_LDA(dst, b, h) do { _Pragma("unroll") for (int m = 0; m < 4; ++m) _Pragma("unroll") for (int k = 0; k < 2; ++k) dst[m][k] = *(const PG8_LAS bf16x8*)(lds + PG8_SA(b, h) + aoff + m * 2048 + k * 1024); } while (0)
; #define PG8_LDB(dst, b, h) do { _Pragma("unroll") for (int n = 0; n < 2; ++n) _Pragma("unroll") for (int k = 0; k < 2; ++k) dst[n][k] = *(const PG8_LAS bf16x8*)(lds + PG8_SB(b, h) + boff + n * 2048 + k * 1024); } while (0)
; #define PG8_MMA(ai, bj, At, Bt) do { __builtin_amdgcn_s_setprio(1); _Pragma("unroll") for (int m = 0; m < 4; ++m) _Pragma("unroll") for (int n = 0; n < 2; ++n) _Pragma("unroll") for (int k = 0; k < 2; ++k) \
;         acc[ai][bj][m][n] = __builtin_amdgcn_mfma_f32_16x16x32_bf16(Bt[n][k], At[m][k], acc[ai][bj][m][n], 0, 0, 0); __builtin_amdgcn_s_setprio(0); } while (0)
; #define PG8_WAIT_V(n) asm volatile("s_waitcnt vmcnt(" #n ")" ::: "memory")
; #define PG8_WAIT_L(n) asm volatile("s_waitcnt lgkmcnt(" #n ")" ::: "memory")
; #define PG8_BAR __builtin_amdgcn_s_barrier()
; #define PG8_SCHED __builtin_amdgcn_sched_barrier(0)
; template <class Epi, class Sched, bool ALIGN_EPI = false, bool SP2 = false>
; __device__ __forceinline__ void gemm_phase(PG8_LAS unsigned char* lds, const Gemm g, const Sched& S, const Epi& E) {
;     ...
;             PG8_LDB(B0, 0, 0); PG8_LDB(B1, 0, 1); PG8_SCHED; PG8_LDA(At, 0, 0); PG8_STAGE(PG8_SA(1, 1), a1 + hstep, voffA);
;             PG8_WAIT_V(8); PG8_WAIT_L(0); PG8_BAR; PG8_MMA(0, 0, At, B0); PG8_MMA(0, 1, At, B1); PG8_BAR; PG8_SCHED;
;     ...
;             PG8_LDA(At, 1, 1); PG8_STAGE(PG8_SB(1, 0), b3, voffB); PG8_STAGE(PG8_SB(1, 1), b3 + hstep, voffB); PG8_STAGE(PG8_SA(1, 0), a3, voffA);
;             PG8_WAIT_V(8); PG8_WAIT_L(0); PG8_BAR; PG8_MMA(1, 0, At, B0); PG8_MMA(1, 1, At, B1); PG8_BAR; PG8_SCHED;
	s_mov_b32 m0, s72
	v_lshl_add_u64 v[144:145], v[144:145], 0, s[36:37]
	s_add_u32 s6, s64, 0x40080
	ds_read_b128 v[198:201], v147 offset:49152
	ds_read_b128 v[202:205], v147 offset:50176
	ds_read_b128 v[206:209], v147 offset:51200
	ds_read_b128 v[210:213], v147 offset:52224
	ds_read_b128 v[214:217], v147 offset:53248
	ds_read_b128 v[218:221], v147 offset:54272
	ds_read_b128 v[224:227], v147 offset:55296
	ds_read_b128 v[228:231], v147 offset:56320
	global_load_lds_dwordx4 v[144:145], off
	v_lshl_add_u64 v[144:145], v[232:233], 0, s[36:37]
	s_mov_b32 m0, s73
	s_addc_u32 s7, s65, 0
	global_load_lds_dwordx4 v[144:145], off
	s_mov_b32 m0, s76
	v_lshl_add_u64 v[144:145], s[6:7], 0, v[132:133]
	global_load_lds_dwordx4 v[144:145], off
	s_mov_b32 m0, s77
	v_lshl_add_u64 v[144:145], s[6:7], 0, v[128:129]
	global_load_lds_dwordx4 v[144:145], off
	s_mov_b32 m0, s74
	v_lshl_add_u64 v[144:145], v[234:235], 0, s[36:37]
	global_load_lds_dwordx4 v[144:145], off
	s_mov_b32 m0, s75
	v_lshl_add_u64 v[144:145], v[236:237], 0, s[36:37]
	global_load_lds_dwordx4 v[144:145], off
	s_waitcnt vmcnt(8)
	s_waitcnt lgkmcnt(0)
	s_barrier
	s_setprio 1
	s_waitcnt lgkmcnt(0)
	v_mfma_f32_16x16x32_bf16 v[60:63], v[166:169], v[198:201], v[60:63]
	v_mfma_f32_16x16x32_bf16 v[56:59], v[174:177], v[198:201], v[56:59]
	v_mfma_f32_16x16x32_bf16 v[44:47], v[166:169], v[206:209], v[44:47]
	v_mfma_f32_16x16x32_bf16 v[40:43], v[174:177], v[206:209], v[40:43]
	v_mfma_f32_16x16x32_bf16 v[28:31], v[166:169], v[214:217], v[28:31]
	v_mfma_f32_16x16x32_bf16 v[24:27], v[174:177], v[214:217], v[24:27]
	v_mfma_f32_16x16x32_bf16 v[12:15], v[166:169], v[224:227], v[12:15]
	v_mfma_f32_16x16x32_bf16 v[8:11], v[174:177], v[224:227], v[8:11]
	v_mfma_f32_16x16x32_bf16 v[60:63], v[170:173], v[202:205], v[60:63]
	v_mfma_f32_16x16x32_bf16 v[56:59], v[178:181], v[202:205], v[56:59]
	v_mfma_f32_16x16x32_bf16 v[44:47], v[170:173], v[210:213], v[44:47]
	v_mfma_f32_16x16x32_bf16 v[40:43], v[178:181], v[210:213], v[40:43]
	v_mfma_f32_16x16x32_bf16 v[28:31], v[170:173], v[218:221], v[28:31]
	v_mfma_f32_16x16x32_bf16 v[24:27], v[178:181], v[218:221], v[24:27]
	v_mfma_f32_16x16x32_bf16 v[12:15], v[170:173], v[228:231], v[12:15]
	v_mfma_f32_16x16x32_bf16 v[8:11], v[178:181], v[228:231], v[8:11]
	s_setprio 0
	s_setprio 1
	v_mfma_f32_16x16x32_bf16 v[52:55], v[182:185], v[198:201], v[52:55]
	v_mfma_f32_16x16x32_bf16 v[48:51], v[190:193], v[198:201], v[48:51]
	v_mfma_f32_16x16x32_bf16 v[36:39], v[182:185], v[206:209], v[36:39]
	v_mfma_f32_16x16x32_bf16 v[32:35], v[190:193], v[206:209], v[32:35]
	v_mfma_f32_16x16x32_bf16 v[20:23], v[182:185], v[214:217], v[20:23]
	v_mfma_f32_16x16x32_bf16 v[16:19], v[190:193], v[214:217], v[16:19]
	v_mfma_f32_16x16x32_bf16 v[4:7], v[182:185], v[224:227], v[4:7]
	v_mfma_f32_16x16x32_bf16 v[0:3], v[190:193], v[224:227], v[0:3]
	v_mfma_f32_16x16x32_bf16 v[52:55], v[186:189], v[202:205], v[52:55]
	v_mfma_f32_16x16x32_bf16 v[48:51], v[194:197], v[202:205], v[48:51]
	v_mfma_f32_16x16x32_bf16 v[36:39], v[186:189], v[210:213], v[36:39]
	v_mfma_f32_16x16x32_bf16 v[32:35], v[194:197], v[210:213], v[32:35]
	v_mfma_f32_16x16x32_bf16 v[20:23], v[186:189], v[218:221], v[20:23]
	v_mfma_f32_16x16x32_bf16 v[16:19], v[194:197], v[218:221], v[16:19]
	v_mfma_f32_16x16x32_bf16 v[4:7], v[186:189], v[228:231], v[4:7]
	v_mfma_f32_16x16x32_bf16 v[0:3], v[194:197], v[228:231], v[0:3]
	s_setprio 0
	s_barrier
	s_add_i32 s86, s86, 2
	s_add_u32 s62, s62, 0x100
	s_addc_u32 s63, s63, 0
	s_add_u32 s84, s84, 0x100
	s_addc_u32 s85, s85, 0
.LBB0_793:
	ds_read_b128 v[166:169], v149
	ds_read_b128 v[170:173], v150
	ds_read_b128 v[174:177], v151
	ds_read_b128 v[178:181], v152
	ds_read_b128 v[182:185], v153
	ds_read_b128 v[186:189], v154
	ds_read_b128 v[190:193], v155
	ds_read_b128 v[194:197], v156
	s_add_u32 s6, s62, 0xfffc0080
	s_addc_u32 s7, s63, -1
	s_cmp_eq_u32 s86, 12
	s_cselect_b32 s67, s55, s7
	s_cselect_b32 s66, s82, s6
	s_cselect_b32 s65, s53, s85
	s_cselect_b32 s64, s83, s84
	s_mov_b32 m0, s79
	v_lshl_add_u64 v[144:145], s[62:63], 0, v[136:137]
	ds_read_b128 v[198:201], v147
	ds_read_b128 v[202:205], v147 offset:1024
	ds_read_b128 v[206:209], v147 offset:2048
	ds_read_b128 v[210:213], v147 offset:3072
	ds_read_b128 v[214:217], v147 offset:4096
	ds_read_b128 v[218:221], v147 offset:5120
	ds_read_b128 v[224:227], v147 offset:6144
	ds_read_b128 v[228:231], v147 offset:7168
	global_load_lds_dwordx4 v[144:145], off
	s_mov_b32 m0, s80
	v_lshl_add_u64 v[144:145], s[62:63], 0, v[138:139]
	global_load_lds_dwordx4 v[144:145], off
	s_waitcnt vmcnt(8)
	s_waitcnt lgkmcnt(0)
	s_barrier
; #define PG8_STAGE(bufoff, gbase, voff) do { _Pragma("unroll") for (int _i = 0; _i < 2; ++_i) \
;         __builtin_amdgcn_global_load_lds((const unsigned*)((const char*)(gbase) + (voff)[_i]), (PG8_LAS unsigned*)(lds + (bufoff) + ldsw + _i * 8192), 16, 0, 0); } while (0)
; #define PG8_LDA(dst, b, h) do { _Pragma("unroll") for (int m = 0; m < 4; ++m) _Pragma("unroll") for (int k = 0; k < 2; ++k) dst[m][k] = *(const PG8_LAS bf16x8*)(lds + PG8_SA(b, h) + aoff + m * 2048 + k * 1024); } while (0)
; #define PG8_MMA(ai, bj, At, Bt) do { __builtin_amdgcn_s_setprio(1); _Pragma("unroll") for (int m = 0; m < 4; ++m) _Pragma("unroll") for (int n = 0; n < 2; ++n) _Pragma("unroll") for (int k = 0; k < 2; ++k) \
;         acc[ai][bj][m][n] = __builtin_amdgcn_mfma_f32_16x16x32_bf16(Bt[n][k], At[m][k], acc[ai][bj][m][n], 0, 0, 0); __builtin_amdgcn_s_setprio(0); } while (0)
; #define PG8_WAIT_V(n) asm volatile("s_waitcnt vmcnt(" #n ")" ::: "memory")
; #define PG8_WAIT_L(n) asm volatile("s_waitcnt lgkmcnt(" #n ")" ::: "memory")
; #define PG8_BAR __builtin_amdgcn_s_barrier()
; #define PG8_SCHED __builtin_amdgcn_sched_barrier(0)
; template <class Epi, class Sched, bool ALIGN_EPI = false, bool SP2 = false>
; __device__ __forceinline__ void gemm_phase(PG8_LAS unsigned char* lds, const Gemm g, const Sched& S, const Epi& E) {
;     ...
;             PG8_WAIT_V(8); PG8_WAIT_L(0); PG8_BAR; PG8_MMA(0, 0, At, B0); PG8_MMA(0, 1, At, B1); PG8_BAR; PG8_SCHED;
;             PG8_LDA(At, 0, 1); PG8_STAGE(PG8_SB(0, 0), b2, voffB); PG8_STAGE(PG8_SB(0, 1), b2 + hstep, voffB); PG8_STAGE(PG8_SA(0, 0), a2, voffA);
;             PG8_WAIT_V(8); PG8_WAIT_L(0); PG8_BAR; PG8_MMA(1, 0, At, B0); PG8_MMA(1, 1, At, B1); PG8_BAR; PG8_SCHED;
	s_setprio 1
	s_waitcnt lgkmcnt(0)
	v_mfma_f32_16x16x32_bf16 v[124:127], v[166:169], v[198:201], v[124:127]
	v_mfma_f32_16x16x32_bf16 v[120:123], v[174:177], v[198:201], v[120:123]
	v_mfma_f32_16x16x32_bf16 v[108:111], v[166:169], v[206:209], v[108:111]
	v_mfma_f32_16x16x32_bf16 v[104:107], v[174:177], v[206:209], v[104:107]
	v_mfma_f32_16x16x32_bf16 v[92:95], v[166:169], v[214:217], v[92:95]
	v_mfma_f32_16x16x32_bf16 v[88:91], v[174:177], v[214:217], v[88:91]
	v_mfma_f32_16x16x32_bf16 v[76:79], v[166:169], v[224:227], v[76:79]
	v_mfma_f32_16x16x32_bf16 v[72:75], v[174:177], v[224:227], v[72:75]
	v_mfma_f32_16x16x32_bf16 v[124:127], v[170:173], v[202:205], v[124:127]
	v_mfma_f32_16x16x32_bf16 v[120:123], v[178:181], v[202:205], v[120:123]
	v_mfma_f32_16x16x32_bf16 v[108:111], v[170:173], v[210:213], v[108:111]
	v_mfma_f32_16x16x32_bf16 v[104:107], v[178:181], v[210:213], v[104:107]
	v_mfma_f32_16x16x32_bf16 v[92:95], v[170:173], v[218:221], v[92:95]
	v_mfma_f32_16x16x32_bf16 v[88:91], v[178:181], v[218:221], v[88:91]
	v_mfma_f32_16x16x32_bf16 v[76:79], v[170:173], v[228:231], v[76:79]
	v_mfma_f32_16x16x32_bf16 v[72:75], v[178:181], v[228:231], v[72:75]
	s_setprio 0
	s_setprio 1
	v_mfma_f32_16x16x32_bf16 v[116:119], v[182:185], v[198:201], v[116:119]
	v_mfma_f32_16x16x32_bf16 v[112:115], v[190:193], v[198:201], v[112:115]
	v_mfma_f32_16x16x32_bf16 v[100:103], v[182:185], v[206:209], v[100:103]
	v_mfma_f32_16x16x32_bf16 v[96:99], v[190:193], v[206:209], v[96:99]
	v_mfma_f32_16x16x32_bf16 v[84:87], v[182:185], v[214:217], v[84:87]
	v_mfma_f32_16x16x32_bf16 v[80:83], v[190:193], v[214:217], v[80:83]
	v_mfma_f32_16x16x32_bf16 v[68:71], v[182:185], v[224:227], v[68:71]
	v_mfma_f32_16x16x32_bf16 v[64:67], v[190:193], v[224:227], v[64:67]
	v_mfma_f32_16x16x32_bf16 v[116:119], v[186:189], v[202:205], v[116:119]
	v_mfma_f32_16x16x32_bf16 v[112:115], v[194:197], v[202:205], v[112:115]
	v_mfma_f32_16x16x32_bf16 v[100:103], v[186:189], v[210:213], v[100:103]
	v_mfma_f32_16x16x32_bf16 v[96:99], v[194:197], v[210:213], v[96:99]
	v_mfma_f32_16x16x32_bf16 v[84:87], v[186:189], v[218:221], v[84:87]
	v_mfma_f32_16x16x32_bf16 v[80:83], v[194:197], v[218:221], v[80:83]
	v_mfma_f32_16x16x32_bf16 v[68:71], v[186:189], v[228:231], v[68:71]
	v_mfma_f32_16x16x32_bf16 v[64:67], v[194:197], v[228:231], v[64:67]
	s_setprio 0
	s_barrier
	s_mov_b32 m0, s15
	v_lshl_add_u64 v[144:145], s[64:65], 0, v[132:133]
	s_add_u32 s6, s64, 0x40000
	ds_read_b128 v[198:201], v147 offset:16384
	ds_read_b128 v[202:205], v147 offset:17408
	ds_read_b128 v[206:209], v147 offset:18432
	ds_read_b128 v[210:213], v147 offset:19456
	ds_read_b128 v[214:217], v147 offset:20480
	ds_read_b128 v[218:221], v147 offset:21504
	ds_read_b128 v[224:227], v147 offset:22528
	ds_read_b128 v[228:231], v147 offset:23552
	global_load_lds_dwordx4 v[144:145], off
	v_lshl_add_u64 v[232:233], s[64:65], 0, v[128:129]
	s_mov_b32 m0, s39
	s_addc_u32 s7, s65, 0
	global_load_lds_dwordx4 v[232:233], off
	v_lshl_add_u64 v[234:235], s[6:7], 0, v[132:133]
	s_mov_b32 m0, s43
	v_lshl_add_u64 v[236:237], s[66:67], 0, v[130:131]
	global_load_lds_dwordx4 v[234:235], off
	s_mov_b32 m0, s61
	v_lshl_add_u64 v[234:235], s[6:7], 0, v[128:129]
	global_load_lds_dwordx4 v[234:235], off
	s_mov_b32 m0, s12
	v_lshl_add_u64 v[234:235], s[66:67], 0, v[134:135]
	global_load_lds_dwordx4 v[234:235], off
	s_mov_b32 m0, s68
	s_nop 0
	global_load_lds_dwordx4 v[236:237], off
	s_waitcnt vmcnt(8)
	s_waitcnt lgkmcnt(0)
	s_barrier
	s_setprio 1
	s_waitcnt lgkmcnt(0)
	v_mfma_f32_16x16x32_bf16 v[60:63], v[166:169], v[198:201], v[60:63]
	v_mfma_f32_16x16x32_bf16 v[56:59], v[174:177], v[198:201], v[56:59]
	v_mfma_f32_16x16x32_bf16 v[44:47], v[166:169], v[206:209], v[44:47]
	v_mfma_f32_16x16x32_bf16 v[40:43], v[174:177], v[206:209], v[40:43]
	v_mfma_f32_16x16x32_bf16 v[28:31], v[166:169], v[214:217], v[28:31]
	v_mfma_f32_16x16x32_bf16 v[24:27], v[174:177], v[214:217], v[24:27]
	v_mfma_f32_16x16x32_bf16 v[12:15], v[166:169], v[224:227], v[12:15]
	v_mfma_f32_16x16x32_bf16 v[8:11], v[174:177], v[224:227], v[8:11]
	v_mfma_f32_16x16x32_bf16 v[60:63], v[170:173], v[202:205], v[60:63]
	v_mfma_f32_16x16x32_bf16 v[56:59], v[178:181], v[202:205], v[56:59]
	v_mfma_f32_16x16x32_bf16 v[44:47], v[170:173], v[210:213], v[44:47]
	v_mfma_f32_16x16x32_bf16 v[40:43], v[178:181], v[210:213], v[40:43]
	v_mfma_f32_16x16x32_bf16 v[28:31], v[170:173], v[218:221], v[28:31]
	v_mfma_f32_16x16x32_bf16 v[24:27], v[178:181], v[218:221], v[24:27]
	v_mfma_f32_16x16x32_bf16 v[12:15], v[170:173], v[228:231], v[12:15]
	v_mfma_f32_16x16x32_bf16 v[8:11], v[178:181], v[228:231], v[8:11]
	s_setprio 0
	s_setprio 1
	v_mfma_f32_16x16x32_bf16 v[52:55], v[182:185], v[198:201], v[52:55]
	v_mfma_f32_16x16x32_bf16 v[48:51], v[190:193], v[198:201], v[48:51]
	v_mfma_f32_16x16x32_bf16 v[36:39], v[182:185], v[206:209], v[36:39]
	v_mfma_f32_16x16x32_bf16 v[32:35], v[190:193], v[206:209], v[32:35]
	v_mfma_f32_16x16x32_bf16 v[20:23], v[182:185], v[214:217], v[20:23]
	v_mfma_f32_16x16x32_bf16 v[16:19], v[190:193], v[214:217], v[16:19]
	v_mfma_f32_16x16x32_bf16 v[4:7], v[182:185], v[224:227], v[4:7]
	v_mfma_f32_16x16x32_bf16 v[0:3], v[190:193], v[224:227], v[0:3]
	v_mfma_f32_16x16x32_bf16 v[52:55], v[186:189], v[202:205], v[52:55]
	v_mfma_f32_16x16x32_bf16 v[48:51], v[194:197], v[202:205], v[48:51]
	v_mfma_f32_16x16x32_bf16 v[36:39], v[186:189], v[210:213], v[36:39]
	v_mfma_f32_16x16x32_bf16 v[32:35], v[194:197], v[210:213], v[32:35]
	v_mfma_f32_16x16x32_bf16 v[20:23], v[186:189], v[218:221], v[20:23]
	v_mfma_f32_16x16x32_bf16 v[16:19], v[194:197], v[218:221], v[16:19]
	v_mfma_f32_16x16x32_bf16 v[4:7], v[186:189], v[228:231], v[4:7]
	v_mfma_f32_16x16x32_bf16 v[0:3], v[194:197], v[228:231], v[0:3]
	s_setprio 0
	s_barrier
; #define PG8_STAGE(bufoff, gbase, voff) do { _Pragma("unroll") for (int _i = 0; _i < 2; ++_i) \
;         __builtin_amdgcn_global_load_lds((const unsigned*)((const char*)(gbase) + (voff)[_i]), (PG8_LAS unsigned*)(lds + (bufoff) + ldsw + _i * 8192), 16, 0, 0); } while (0)
; #define PG8_LDA(dst, b, h) do { _Pragma("unroll") for (int m = 0; m < 4; ++m) _Pragma("unroll") for (int k = 0; k < 2; ++k) dst[m][k] = *(const PG8_LAS bf16x8*)(lds + PG8_SA(b, h) + aoff + m * 2048 + k * 1024); } while (0)
; #define PG8_LDB(dst, b, h) do { _Pragma("unroll") for (int n = 0; n < 2; ++n) _Pragma("unroll") for (int k = 0; k < 2; ++k) dst[n][k] = *(const PG8_LAS bf16x8*)(lds + PG8_SB(b, h) + boff + n * 2048 + k * 1024); } while (0)
; #define PG8_MMA(ai, bj, At, Bt) do { __builtin_amdgcn_s_setprio(1); _Pragma("unroll") for (int m = 0; m < 4; ++m) _Pragma("unroll") for (int n = 0; n < 2; ++n) _Pragma("unroll") for (int k = 0; k < 2; ++k) \
;         acc[ai][bj][m][n] = __builtin_amdgcn_mfma_f32_16x16x32_bf16(Bt[n][k], At[m][k], acc[ai][bj][m][n], 0, 0, 0); __builtin_amdgcn_s_setprio(0); } while (0)
; #define PG8_WAIT_V(n) asm volatile("s_waitcnt vmcnt(" #n ")" ::: "memory")
; #define PG8_WAIT_L(n) asm volatile("s_waitcnt lgkmcnt(" #n ")" ::: "memory")
; #define PG8_BAR __builtin_amdgcn_s_barrier()
; #define PG8_SCHED __builtin_amdgcn_sched_barrier(0)
; template <class Epi, class Sched, bool ALIGN_EPI = false, bool SP2 = false>
; __device__ __forceinline__ void gemm_phase(PG8_LAS unsigned char* lds, const Gemm g, const Sched& S, const Epi& E) {
;     ...
;             PG8_LDB(B0, 1, 0); PG8_LDB(B1, 1, 1); PG8_SCHED; PG8_LDA(At, 1, 0); PG8_STAGE(PG8_SA(0, 1), a2 + hstep, voffA);
;             PG8_WAIT_V(8); PG8_WAIT_L(0); PG8_BAR; PG8_MMA(0, 0, At, B0); PG8_MMA(0, 1, At, B1); PG8_BAR; PG8_SCHED;
;             PG8_LDA(At, 1, 1); PG8_STAGE(PG8_SB(1, 0), b3, voffB); PG8_STAGE(PG8_SB(1, 1), b3 + hstep, voffB); PG8_STAGE(PG8_SA(1, 0), a3, voffA);
;             PG8_WAIT_V(8); PG8_WAIT_L(0); PG8_BAR; PG8_MMA(1, 0, At, B0); PG8_MMA(1, 1, At, B1); PG8_BAR; PG8_SCHED;
;     ...
;         if constexpr (ALIGN_EPI) { if (wr == 0) PG8_BAR; }
	ds_read_b128 v[166:169], v157
	ds_read_b128 v[170:173], v158
	ds_read_b128 v[174:177], v159
	ds_read_b128 v[178:181], v160
	ds_read_b128 v[182:185], v161
	ds_read_b128 v[186:189], v162
	ds_read_b128 v[190:193], v163
	ds_read_b128 v[194:197], v164
	s_add_u32 s6, s66, 0x40000
	s_addc_u32 s7, s67, 0
	s_mov_b32 m0, s69
	v_lshl_add_u64 v[238:239], s[6:7], 0, v[134:135]
	ds_read_b128 v[198:201], v147 offset:32768
	ds_read_b128 v[202:205], v147 offset:33792
	ds_read_b128 v[206:209], v147 offset:34816
	ds_read_b128 v[210:213], v147 offset:35840
	ds_read_b128 v[214:217], v147 offset:36864
	ds_read_b128 v[218:221], v147 offset:37888
	ds_read_b128 v[224:227], v147 offset:38912
	ds_read_b128 v[228:231], v147 offset:39936
	global_load_lds_dwordx4 v[238:239], off
	s_mov_b32 m0, s70
	v_lshl_add_u64 v[238:239], s[6:7], 0, v[130:131]
	global_load_lds_dwordx4 v[238:239], off
	s_waitcnt vmcnt(8)
	s_waitcnt lgkmcnt(0)
	s_barrier
	s_setprio 1
	s_waitcnt lgkmcnt(0)
	v_mfma_f32_16x16x32_bf16 v[124:127], v[166:169], v[198:201], v[124:127]
	v_mfma_f32_16x16x32_bf16 v[120:123], v[174:177], v[198:201], v[120:123]
	v_mfma_f32_16x16x32_bf16 v[108:111], v[166:169], v[206:209], v[108:111]
	v_mfma_f32_16x16x32_bf16 v[104:107], v[174:177], v[206:209], v[104:107]
	v_mfma_f32_16x16x32_bf16 v[92:95], v[166:169], v[214:217], v[92:95]
	v_mfma_f32_16x16x32_bf16 v[88:91], v[174:177], v[214:217], v[88:91]
	v_mfma_f32_16x16x32_bf16 v[76:79], v[166:169], v[224:227], v[76:79]
	v_mfma_f32_16x16x32_bf16 v[72:75], v[174:177], v[224:227], v[72:75]
	v_mfma_f32_16x16x32_bf16 v[124:127], v[170:173], v[202:205], v[124:127]
	v_mfma_f32_16x16x32_bf16 v[120:123], v[178:181], v[202:205], v[120:123]
	v_mfma_f32_16x16x32_bf16 v[108:111], v[170:173], v[210:213], v[108:111]
	v_mfma_f32_16x16x32_bf16 v[104:107], v[178:181], v[210:213], v[104:107]
	v_mfma_f32_16x16x32_bf16 v[92:95], v[170:173], v[218:221], v[92:95]
	v_mfma_f32_16x16x32_bf16 v[88:91], v[178:181], v[218:221], v[88:91]
	v_mfma_f32_16x16x32_bf16 v[76:79], v[170:173], v[228:231], v[76:79]
	v_mfma_f32_16x16x32_bf16 v[72:75], v[178:181], v[228:231], v[72:75]
	s_setprio 0
	s_setprio 1
	v_mfma_f32_16x16x32_bf16 v[116:119], v[182:185], v[198:201], v[116:119]
	v_mfma_f32_16x16x32_bf16 v[112:115], v[190:193], v[198:201], v[112:115]
	v_mfma_f32_16x16x32_bf16 v[100:103], v[182:185], v[206:209], v[100:103]
	v_mfma_f32_16x16x32_bf16 v[96:99], v[190:193], v[206:209], v[96:99]
	v_mfma_f32_16x16x32_bf16 v[84:87], v[182:185], v[214:217], v[84:87]
	v_mfma_f32_16x16x32_bf16 v[80:83], v[190:193], v[214:217], v[80:83]
	v_mfma_f32_16x16x32_bf16 v[68:71], v[182:185], v[224:227], v[68:71]
	v_mfma_f32_16x16x32_bf16 v[64:67], v[190:193], v[224:227], v[64:67]
	v_mfma_f32_16x16x32_bf16 v[116:119], v[186:189], v[202:205], v[116:119]
	v_mfma_f32_16x16x32_bf16 v[112:115], v[194:197], v[202:205], v[112:115]
	v_mfma_f32_16x16x32_bf16 v[100:103], v[186:189], v[210:213], v[100:103]
	v_mfma_f32_16x16x32_bf16 v[96:99], v[194:197], v[210:213], v[96:99]
	v_mfma_f32_16x16x32_bf16 v[84:87], v[186:189], v[218:221], v[84:87]
	v_mfma_f32_16x16x32_bf16 v[80:83], v[194:197], v[218:221], v[80:83]
	v_mfma_f32_16x16x32_bf16 v[68:71], v[186:189], v[228:231], v[68:71]
	v_mfma_f32_16x16x32_bf16 v[64:67], v[194:197], v[228:231], v[64:67]
	s_setprio 0
	s_barrier
	s_mov_b32 m0, s72
	v_lshl_add_u64 v[144:145], v[144:145], 0, s[36:37]
	s_add_u32 s6, s64, 0x40080
	ds_read_b128 v[198:201], v147 offset:49152
	ds_read_b128 v[202:205], v147 offset:50176
	ds_read_b128 v[206:209], v147 offset:51200
	ds_read_b128 v[210:213], v147 offset:52224
	ds_read_b128 v[214:217], v147 offset:53248
	ds_read_b128 v[218:221], v147 offset:54272
	ds_read_b128 v[224:227], v147 offset:55296
	ds_read_b128 v[228:231], v147 offset:56320
	global_load_lds_dwordx4 v[144:145], off
	v_lshl_add_u64 v[144:145], v[232:233], 0, s[36:37]
	s_mov_b32 m0, s73
	s_addc_u32 s7, s65, 0
	global_load_lds_dwordx4 v[144:145], off
	s_mov_b32 m0, s76
	v_lshl_add_u64 v[144:145], s[6:7], 0, v[132:133]
	global_load_lds_dwordx4 v[144:145], off
	s_mov_b32 m0, s77
	v_lshl_add_u64 v[144:145], s[6:7], 0, v[128:129]
	global_load_lds_dwordx4 v[144:145], off
	s_mov_b32 m0, s74
	v_lshl_add_u64 v[144:145], v[234:235], 0, s[36:37]
	global_load_lds_dwordx4 v[144:145], off
	s_mov_b32 m0, s75
	v_lshl_add_u64 v[144:145], v[236:237], 0, s[36:37]
	global_load_lds_dwordx4 v[144:145], off
	s_waitcnt vmcnt(8)
	s_waitcnt lgkmcnt(0)
	s_barrier
	s_setprio 1
	s_waitcnt lgkmcnt(0)
	v_mfma_f32_16x16x32_bf16 v[60:63], v[166:169], v[198:201], v[60:63]
	v_mfma_f32_16x16x32_bf16 v[56:59], v[174:177], v[198:201], v[56:59]
	v_mfma_f32_16x16x32_bf16 v[44:47], v[166:169], v[206:209], v[44:47]
	v_mfma_f32_16x16x32_bf16 v[40:43], v[174:177], v[206:209], v[40:43]
	v_mfma_f32_16x16x32_bf16 v[28:31], v[166:169], v[214:217], v[28:31]
	v_mfma_f32_16x16x32_bf16 v[24:27], v[174:177], v[214:217], v[24:27]
	v_mfma_f32_16x16x32_bf16 v[12:15], v[166:169], v[224:227], v[12:15]
	v_mfma_f32_16x16x32_bf16 v[8:11], v[174:177], v[224:227], v[8:11]
	v_mfma_f32_16x16x32_bf16 v[60:63], v[170:173], v[202:205], v[60:63]
	v_mfma_f32_16x16x32_bf16 v[56:59], v[178:181], v[202:205], v[56:59]
	v_mfma_f32_16x16x32_bf16 v[44:47], v[170:173], v[210:213], v[44:47]
	v_mfma_f32_16x16x32_bf16 v[40:43], v[178:181], v[210:213], v[40:43]
	v_mfma_f32_16x16x32_bf16 v[28:31], v[170:173], v[218:221], v[28:31]
	v_mfma_f32_16x16x32_bf16 v[24:27], v[178:181], v[218:221], v[24:27]
	v_mfma_f32_16x16x32_bf16 v[12:15], v[170:173], v[228:231], v[12:15]
	v_mfma_f32_16x16x32_bf16 v[8:11], v[178:181], v[228:231], v[8:11]
	s_setprio 0
	s_setprio 1
	v_mfma_f32_16x16x32_bf16 v[52:55], v[182:185], v[198:201], v[52:55]
	v_mfma_f32_16x16x32_bf16 v[48:51], v[190:193], v[198:201], v[48:51]
	v_mfma_f32_16x16x32_bf16 v[36:39], v[182:185], v[206:209], v[36:39]
	v_mfma_f32_16x16x32_bf16 v[32:35], v[190:193], v[206:209], v[32:35]
	v_mfma_f32_16x16x32_bf16 v[20:23], v[182:185], v[214:217], v[20:23]
	v_mfma_f32_16x16x32_bf16 v[16:19], v[190:193], v[214:217], v[16:19]
	v_mfma_f32_16x16x32_bf16 v[4:7], v[182:185], v[224:227], v[4:7]
	v_mfma_f32_16x16x32_bf16 v[0:3], v[190:193], v[224:227], v[0:3]
	v_mfma_f32_16x16x32_bf16 v[52:55], v[186:189], v[202:205], v[52:55]
	v_mfma_f32_16x16x32_bf16 v[48:51], v[194:197], v[202:205], v[48:51]
	v_mfma_f32_16x16x32_bf16 v[36:39], v[186:189], v[210:213], v[36:39]
	v_mfma_f32_16x16x32_bf16 v[32:35], v[194:197], v[210:213], v[32:35]
	v_mfma_f32_16x16x32_bf16 v[20:23], v[186:189], v[218:221], v[20:23]
	v_mfma_f32_16x16x32_bf16 v[16:19], v[194:197], v[218:221], v[16:19]
	v_mfma_f32_16x16x32_bf16 v[4:7], v[186:189], v[228:231], v[4:7]
	v_mfma_f32_16x16x32_bf16 v[0:3], v[194:197], v[228:231], v[0:3]
	s_setprio 0
	s_barrier
	s_add_i32 s86, s86, 2
	s_add_u32 s62, s62, 0x100
	s_addc_u32 s63, s63, 0
	s_add_u32 s84, s84, 0x100
	s_addc_u32 s85, s85, 0
	s_cmp_gt_u32 s86, 13
	s_cbranch_scc0 .LBB0_793
	s_and_b64 vcc, exec, s[40:41]
	s_cbranch_vccz .LBB0_796
	s_barrier

; #define PG8_STAGE(bufoff, gbase, voff) do { _Pragma("unroll") for (int _i = 0; _i < 2; ++_i) \
;         __builtin_amdgcn_global_load_lds((const unsigned*)((const char*)(gbase) + (voff)[_i]), (PG8_LAS unsigned*)(lds + (bufoff) + ldsw + _i * 8192), 16, 0, 0); } while (0)
; #define PG8_LDA(dst, b, h) do { _Pragma("unroll") for (int m = 0; m < 4; ++m) _Pragma("unroll") for (int k = 0; k < 2; ++k) dst[m][k] = *(const PG8_LAS bf16x8*)(lds + PG8_SA(b, h) + aoff + m * 2048 + k * 1024); } while (0)
; #define PG8_LDB(dst, b, h) do { _Pragma("unroll") for (int n = 0; n < 2; ++n) _Pragma("unroll") for (int k = 0; k < 2; ++k) dst[n][k] = *(const PG8_LAS bf16x8*)(lds + PG8_SB(b, h) + boff + n * 2048 + k * 1024); } while (0)
; #define PG8_MMA(ai, bj, At, Bt) do { __builtin_amdgcn_s_setprio(1); _Pragma("unroll") for (int m = 0; m < 4; ++m) _Pragma("unroll") for (int n = 0; n < 2; ++n) _Pragma("unroll") for (int k = 0; k < 2; ++k) \
;         acc[ai][bj][m][n] = __builtin_amdgcn_mfma_f32_16x16x32_bf16(Bt[n][k], At[m][k], acc[ai][bj][m][n], 0, 0, 0); __builtin_amdgcn_s_setprio(0); } while (0)
; #define PG8_WAIT_V(n) asm volatile("s_waitcnt vmcnt(" #n ")" ::: "memory")
; #define PG8_WAIT_L(n) asm volatile("s_waitcnt lgkmcnt(" #n ")" ::: "memory")
; #define PG8_BAR __builtin_amdgcn_s_barrier()
; #define PG8_SCHED __builtin_amdgcn_sched_barrier(0)
; template <class Epi, class Sched, bool ALIGN_EPI = false, bool SP2 = false>
; __device__ __forceinline__ void gemm_phase(PG8_LAS unsigned char* lds, const Gemm g, const Sched& S, const Epi& E) {
;     ...
;             PG8_LDB(B0, 0, 0); PG8_LDB(B1, 0, 1); PG8_SCHED; PG8_LDA(At, 0, 0); PG8_STAGE(PG8_SA(1, 1), a1 + hstep, voffA);
;             PG8_WAIT_V(8); PG8_WAIT_L(0); PG8_BAR; PG8_MMA(0, 0, At, B0); PG8_MMA(0, 1, At, B1); PG8_BAR; PG8_SCHED;
;             PG8_LDA(At, 0, 1); PG8_STAGE(PG8_SB(0, 0), b2, voffB); PG8_STAGE(PG8_SB(0, 1), b2 + hstep, voffB); PG8_STAGE(PG8_SA(0, 0), a2, voffA);
;             PG8_WAIT_V(8); PG8_WAIT_L(0); PG8_BAR; PG8_MMA(1, 0, At, B0); PG8_MMA(1, 1, At, B1); PG8_BAR; PG8_SCHED;
.LBB0_872:
	s_add_u32 s57, s60, 0x100
	s_addc_u32 s88, s61, 0
	s_mov_b32 s89, -2
	ds_read_b128 v[142:145], v174
	ds_read_b128 v[146:149], v175
	ds_read_b128 v[150:153], v176
	ds_read_b128 v[154:157], v177
	ds_read_b128 v[158:161], v178
	ds_read_b128 v[162:165], v179
	ds_read_b128 v[166:169], v180
	ds_read_b128 v[190:193], v181
	s_add_u32 s60, s58, 0x100
	s_addc_u32 s61, s59, 0
	s_cmp_eq_u32 s89, 40
	s_cselect_b32 s65, s9, s61
	s_cselect_b32 s64, s8, s60
	s_cselect_b32 s63, s55, s88
	s_cselect_b32 s62, s54, s57
	s_mov_b32 m0, s78
	v_lshl_add_u64 v[170:171], s[58:59], 0, v[134:135]
	ds_read_b128 v[194:197], v172
	ds_read_b128 v[198:201], v172 offset:1024
	ds_read_b128 v[202:205], v172 offset:2048
	ds_read_b128 v[206:209], v172 offset:3072
	ds_read_b128 v[210:213], v172 offset:4096
	ds_read_b128 v[214:217], v172 offset:5120
	ds_read_b128 v[218:221], v172 offset:6144
	ds_read_b128 v[224:227], v172 offset:7168
	global_load_lds_dwordx4 v[170:171], off
	s_mov_b32 m0, s79
	v_lshl_add_u64 v[170:171], s[58:59], 0, v[136:137]
	global_load_lds_dwordx4 v[170:171], off
	s_waitcnt vmcnt(8)
	s_waitcnt lgkmcnt(0)
	s_barrier
	s_setprio 1
	s_waitcnt lgkmcnt(0)
	v_mfma_f32_16x16x32_bf16 v[124:127], v[142:145], v[194:197], 0
	v_mfma_f32_16x16x32_bf16 v[108:111], v[150:153], v[194:197], 0
	v_mfma_f32_16x16x32_bf16 v[120:123], v[142:145], v[202:205], 0
	v_mfma_f32_16x16x32_bf16 v[96:99], v[150:153], v[202:205], 0
	v_mfma_f32_16x16x32_bf16 v[116:119], v[142:145], v[210:213], 0
	v_mfma_f32_16x16x32_bf16 v[88:91], v[150:153], v[210:213], 0
	v_mfma_f32_16x16x32_bf16 v[112:115], v[142:145], v[218:221], 0
	v_mfma_f32_16x16x32_bf16 v[84:87], v[150:153], v[218:221], 0
	v_mfma_f32_16x16x32_bf16 v[124:127], v[146:149], v[198:201], v[124:127]
	v_mfma_f32_16x16x32_bf16 v[108:111], v[154:157], v[198:201], v[108:111]
	v_mfma_f32_16x16x32_bf16 v[120:123], v[146:149], v[206:209], v[120:123]
	v_mfma_f32_16x16x32_bf16 v[96:99], v[154:157], v[206:209], v[96:99]
	v_mfma_f32_16x16x32_bf16 v[116:119], v[146:149], v[214:217], v[116:119]
	v_mfma_f32_16x16x32_bf16 v[88:91], v[154:157], v[214:217], v[88:91]
	v_mfma_f32_16x16x32_bf16 v[112:115], v[146:149], v[224:227], v[112:115]
	v_mfma_f32_16x16x32_bf16 v[84:87], v[154:157], v[224:227], v[84:87]
	s_setprio 0
	s_setprio 1
	v_mfma_f32_16x16x32_bf16 v[68:71], v[158:161], v[194:197], 0
	v_mfma_f32_16x16x32_bf16 v[40:43], v[166:169], v[194:197], 0
	v_mfma_f32_16x16x32_bf16 v[60:63], v[158:161], v[202:205], 0
	v_mfma_f32_16x16x32_bf16 v[32:35], v[166:169], v[202:205], 0
	v_mfma_f32_16x16x32_bf16 v[52:55], v[158:161], v[210:213], 0
	v_mfma_f32_16x16x32_bf16 v[24:27], v[166:169], v[210:213], 0
	v_mfma_f32_16x16x32_bf16 v[48:51], v[158:161], v[218:221], 0
	v_mfma_f32_16x16x32_bf16 v[16:19], v[166:169], v[218:221], 0
	v_mfma_f32_16x16x32_bf16 v[68:71], v[162:165], v[198:201], v[68:71]
	v_mfma_f32_16x16x32_bf16 v[40:43], v[190:193], v[198:201], v[40:43]
	v_mfma_f32_16x16x32_bf16 v[60:63], v[162:165], v[206:209], v[60:63]
	v_mfma_f32_16x16x32_bf16 v[32:35], v[190:193], v[206:209], v[32:35]
	v_mfma_f32_16x16x32_bf16 v[52:55], v[162:165], v[214:217], v[52:55]
	v_mfma_f32_16x16x32_bf16 v[24:27], v[190:193], v[214:217], v[24:27]
	v_mfma_f32_16x16x32_bf16 v[48:51], v[162:165], v[224:227], v[48:51]
	v_mfma_f32_16x16x32_bf16 v[16:19], v[190:193], v[224:227], v[16:19]
	s_setprio 0
	s_barrier
	s_mov_b32 m0, s12
	v_lshl_add_u64 v[170:171], s[62:63], 0, v[128:129]
	s_add_u32 s58, s62, 0xb0000
	ds_read_b128 v[194:197], v172 offset:16384
	ds_read_b128 v[198:201], v172 offset:17408
	ds_read_b128 v[202:205], v172 offset:18432
	ds_read_b128 v[206:209], v172 offset:19456
	ds_read_b128 v[210:213], v172 offset:20480
	ds_read_b128 v[214:217], v172 offset:21504
	ds_read_b128 v[218:221], v172 offset:22528
	ds_read_b128 v[224:227], v172 offset:23552
	global_load_lds_dwordx4 v[170:171], off
	v_lshl_add_u64 v[228:229], s[62:63], 0, v[130:131]
	s_mov_b32 m0, s13
	s_addc_u32 s59, s63, 0
	global_load_lds_dwordx4 v[228:229], off
	v_lshl_add_u64 v[230:231], s[58:59], 0, v[128:129]
	s_mov_b32 m0, s14
	v_lshl_add_u64 v[232:233], s[64:65], 0, v[130:131]
	global_load_lds_dwordx4 v[230:231], off
	s_mov_b32 m0, s15
	v_lshl_add_u64 v[230:231], s[58:59], 0, v[130:131]
	global_load_lds_dwordx4 v[230:231], off
	s_mov_b32 m0, s5
	v_lshl_add_u64 v[230:231], s[64:65], 0, v[128:129]
	global_load_lds_dwordx4 v[230:231], off
	s_mov_b32 m0, s39
	s_nop 0
	global_load_lds_dwordx4 v[232:233], off
	s_waitcnt vmcnt(8)
	s_waitcnt lgkmcnt(0)
	s_barrier
	s_setprio 1
	s_waitcnt lgkmcnt(0)
	v_mfma_f32_16x16x32_bf16 v[104:107], v[142:145], v[194:197], 0
	v_mfma_f32_16x16x32_bf16 v[76:79], v[150:153], v[194:197], 0
	v_mfma_f32_16x16x32_bf16 v[100:103], v[142:145], v[202:205], 0
	v_mfma_f32_16x16x32_bf16 v[72:75], v[150:153], v[202:205], 0
	v_mfma_f32_16x16x32_bf16 v[92:95], v[142:145], v[210:213], 0
	v_mfma_f32_16x16x32_bf16 v[64:67], v[150:153], v[210:213], 0
	v_mfma_f32_16x16x32_bf16 v[80:83], v[142:145], v[218:221], 0
	v_mfma_f32_16x16x32_bf16 v[56:59], v[150:153], v[218:221], 0
	v_mfma_f32_16x16x32_bf16 v[104:107], v[146:149], v[198:201], v[104:107]
	v_mfma_f32_16x16x32_bf16 v[76:79], v[154:157], v[198:201], v[76:79]
	v_mfma_f32_16x16x32_bf16 v[100:103], v[146:149], v[206:209], v[100:103]
	v_mfma_f32_16x16x32_bf16 v[72:75], v[154:157], v[206:209], v[72:75]
	v_mfma_f32_16x16x32_bf16 v[92:95], v[146:149], v[214:217], v[92:95]
	v_mfma_f32_16x16x32_bf16 v[64:67], v[154:157], v[214:217], v[64:67]
	v_mfma_f32_16x16x32_bf16 v[80:83], v[146:149], v[224:227], v[80:83]
	v_mfma_f32_16x16x32_bf16 v[56:59], v[154:157], v[224:227], v[56:59]
	s_setprio 0
	s_setprio 1
	v_mfma_f32_16x16x32_bf16 v[44:47], v[158:161], v[194:197], 0
	v_mfma_f32_16x16x32_bf16 v[12:15], v[166:169], v[194:197], 0
	v_mfma_f32_16x16x32_bf16 v[36:39], v[158:161], v[202:205], 0
	v_mfma_f32_16x16x32_bf16 v[8:11], v[166:169], v[202:205], 0
	v_mfma_f32_16x16x32_bf16 v[28:31], v[158:161], v[210:213], 0
	v_mfma_f32_16x16x32_bf16 v[4:7], v[166:169], v[210:213], 0
	v_mfma_f32_16x16x32_bf16 v[20:23], v[158:161], v[218:221], 0
	v_mfma_f32_16x16x32_bf16 v[0:3], v[166:169], v[218:221], 0
	v_mfma_f32_16x16x32_bf16 v[44:47], v[162:165], v[198:201], v[44:47]
	v_mfma_f32_16x16x32_bf16 v[12:15], v[190:193], v[198:201], v[12:15]
	v_mfma_f32_16x16x32_bf16 v[36:39], v[162:165], v[206:209], v[36:39]
	v_mfma_f32_16x16x32_bf16 v[8:11], v[190:193], v[206:209], v[8:11]
	v_mfma_f32_16x16x32_bf16 v[28:31], v[162:165], v[214:217], v[28:31]
	v_mfma_f32_16x16x32_bf16 v[4:7], v[190:193], v[214:217], v[4:7]
	v_mfma_f32_16x16x32_bf16 v[20:23], v[162:165], v[224:227], v[20:23]
	v_mfma_f32_16x16x32_bf16 v[0:3], v[190:193], v[224:227], v[0:3]
	s_setprio 0
	s_barrier
; #define PG8_STAGE(bufoff, gbase, voff) do { _Pragma("unroll") for (int _i = 0; _i < 2; ++_i) \
;         __builtin_amdgcn_global_load_lds((const unsigned*)((const char*)(gbase) + (voff)[_i]), (PG8_LAS unsigned*)(lds + (bufoff) + ldsw + _i * 8192), 16, 0, 0); } while (0)
; #define PG8_LDA(dst, b, h) do { _Pragma("unroll") for (int m = 0; m < 4; ++m) _Pragma("unroll") for (int k = 0; k < 2; ++k) dst[m][k] = *(const PG8_LAS bf16x8*)(lds + PG8_SA(b, h) + aoff + m * 2048 + k * 1024); } while (0)
; #define PG8_LDB(dst, b, h) do { _Pragma("unroll") for (int n = 0; n < 2; ++n) _Pragma("unroll") for (int k = 0; k < 2; ++k) dst[n][k] = *(const PG8_LAS bf16x8*)(lds + PG8_SB(b, h) + boff + n * 2048 + k * 1024); } while (0)
; #define PG8_MMA(ai, bj, At, Bt) do { __builtin_amdgcn_s_setprio(1); _Pragma("unroll") for (int m = 0; m < 4; ++m) _Pragma("unroll") for (int n = 0; n < 2; ++n) _Pragma("unroll") for (int k = 0; k < 2; ++k) \
;         acc[ai][bj][m][n] = __builtin_amdgcn_mfma_f32_16x16x32_bf16(Bt[n][k], At[m][k], acc[ai][bj][m][n], 0, 0, 0); __builtin_amdgcn_s_setprio(0); } while (0)
; #define PG8_WAIT_V(n) asm volatile("s_waitcnt vmcnt(" #n ")" ::: "memory")
; #define PG8_WAIT_L(n) asm volatile("s_waitcnt lgkmcnt(" #n ")" ::: "memory")
; #define PG8_BAR __builtin_amdgcn_s_barrier()
; #define PG8_SCHED __builtin_amdgcn_sched_barrier(0)
; template <class Epi, class Sched, bool ALIGN_EPI = false, bool SP2 = false>
; __device__ __forceinline__ void gemm_phase(PG8_LAS unsigned char* lds, const Gemm g, const Sched& S, const Epi& E) {
;     ...
;             PG8_LDB(B0, 1, 0); PG8_LDB(B1, 1, 1); PG8_SCHED; PG8_LDA(At, 1, 0); PG8_STAGE(PG8_SA(0, 1), a2 + hstep, voffA);
;             PG8_WAIT_V(8); PG8_WAIT_L(0); PG8_BAR; PG8_MMA(0, 0, At, B0); PG8_MMA(0, 1, At, B1); PG8_BAR; PG8_SCHED;
;             PG8_LDA(At, 1, 1); PG8_STAGE(PG8_SB(1, 0), b3, voffB); PG8_STAGE(PG8_SB(1, 1), b3 + hstep, voffB); PG8_STAGE(PG8_SA(1, 0), a3, voffA);
;             PG8_WAIT_V(8); PG8_WAIT_L(0); PG8_BAR; PG8_MMA(1, 0, At, B0); PG8_MMA(1, 1, At, B1); PG8_BAR; PG8_SCHED;
	ds_read_b128 v[142:145], v182
	ds_read_b128 v[146:149], v183
	ds_read_b128 v[150:153], v184
	ds_read_b128 v[154:157], v185
	ds_read_b128 v[158:161], v186
	ds_read_b128 v[162:165], v187
	ds_read_b128 v[166:169], v188
	ds_read_b128 v[190:193], v189
	s_add_u32 s58, s64, 0xb0000
	s_addc_u32 s59, s65, 0
	s_mov_b32 m0, s43
	v_lshl_add_u64 v[234:235], s[58:59], 0, v[128:129]
	ds_read_b128 v[194:197], v172 offset:32768
	ds_read_b128 v[198:201], v172 offset:33792
	ds_read_b128 v[202:205], v172 offset:34816
	ds_read_b128 v[206:209], v172 offset:35840
	ds_read_b128 v[210:213], v172 offset:36864
	ds_read_b128 v[214:217], v172 offset:37888
	ds_read_b128 v[218:221], v172 offset:38912
	ds_read_b128 v[224:227], v172 offset:39936
	global_load_lds_dwordx4 v[234:235], off
	s_mov_b32 m0, s66
	v_lshl_add_u64 v[234:235], s[58:59], 0, v[130:131]
	global_load_lds_dwordx4 v[234:235], off
	s_waitcnt vmcnt(8)
	s_waitcnt lgkmcnt(0)
	s_barrier
	s_setprio 1
	s_waitcnt lgkmcnt(0)
	v_mfma_f32_16x16x32_bf16 v[124:127], v[142:145], v[194:197], v[124:127]
	v_mfma_f32_16x16x32_bf16 v[108:111], v[150:153], v[194:197], v[108:111]
	v_mfma_f32_16x16x32_bf16 v[120:123], v[142:145], v[202:205], v[120:123]
	v_mfma_f32_16x16x32_bf16 v[96:99], v[150:153], v[202:205], v[96:99]
	v_mfma_f32_16x16x32_bf16 v[116:119], v[142:145], v[210:213], v[116:119]
	v_mfma_f32_16x16x32_bf16 v[88:91], v[150:153], v[210:213], v[88:91]
	v_mfma_f32_16x16x32_bf16 v[112:115], v[142:145], v[218:221], v[112:115]
	v_mfma_f32_16x16x32_bf16 v[84:87], v[150:153], v[218:221], v[84:87]
	v_mfma_f32_16x16x32_bf16 v[124:127], v[146:149], v[198:201], v[124:127]
	v_mfma_f32_16x16x32_bf16 v[108:111], v[154:157], v[198:201], v[108:111]
	v_mfma_f32_16x16x32_bf16 v[120:123], v[146:149], v[206:209], v[120:123]
	v_mfma_f32_16x16x32_bf16 v[96:99], v[154:157], v[206:209], v[96:99]
	v_mfma_f32_16x16x32_bf16 v[116:119], v[146:149], v[214:217], v[116:119]
	v_mfma_f32_16x16x32_bf16 v[88:91], v[154:157], v[214:217], v[88:91]
	v_mfma_f32_16x16x32_bf16 v[112:115], v[146:149], v[224:227], v[112:115]
	v_mfma_f32_16x16x32_bf16 v[84:87], v[154:157], v[224:227], v[84:87]
	s_setprio 0
	s_setprio 1
	v_mfma_f32_16x16x32_bf16 v[68:71], v[158:161], v[194:197], v[68:71]
	v_mfma_f32_16x16x32_bf16 v[40:43], v[166:169], v[194:197], v[40:43]
	v_mfma_f32_16x16x32_bf16 v[60:63], v[158:161], v[202:205], v[60:63]
	v_mfma_f32_16x16x32_bf16 v[32:35], v[166:169], v[202:205], v[32:35]
	v_mfma_f32_16x16x32_bf16 v[52:55], v[158:161], v[210:213], v[52:55]
	v_mfma_f32_16x16x32_bf16 v[24:27], v[166:169], v[210:213], v[24:27]
	v_mfma_f32_16x16x32_bf16 v[48:51], v[158:161], v[218:221], v[48:51]
	v_mfma_f32_16x16x32_bf16 v[16:19], v[166:169], v[218:221], v[16:19]
	v_mfma_f32_16x16x32_bf16 v[68:71], v[162:165], v[198:201], v[68:71]
	v_mfma_f32_16x16x32_bf16 v[40:43], v[190:193], v[198:201], v[40:43]
	v_mfma_f32_16x16x32_bf16 v[60:63], v[162:165], v[206:209], v[60:63]
	v_mfma_f32_16x16x32_bf16 v[32:35], v[190:193], v[206:209], v[32:35]
	v_mfma_f32_16x16x32_bf16 v[52:55], v[162:165], v[214:217], v[52:55]
	v_mfma_f32_16x16x32_bf16 v[24:27], v[190:193], v[214:217], v[24:27]
	v_mfma_f32_16x16x32_bf16 v[48:51], v[162:165], v[224:227], v[48:51]
	v_mfma_f32_16x16x32_bf16 v[16:19], v[190:193], v[224:227], v[16:19]
	s_setprio 0
	s_barrier
	s_mov_b32 m0, s70
	v_lshl_add_u64 v[170:171], v[170:171], 0, s[40:41]
	s_add_u32 s58, s62, 0xb0080
	ds_read_b128 v[194:197], v172 offset:49152
	ds_read_b128 v[198:201], v172 offset:50176
	ds_read_b128 v[202:205], v172 offset:51200
	ds_read_b128 v[206:209], v172 offset:52224
	ds_read_b128 v[210:213], v172 offset:53248
	ds_read_b128 v[214:217], v172 offset:54272
	ds_read_b128 v[218:221], v172 offset:55296
	ds_read_b128 v[224:227], v172 offset:56320
	global_load_lds_dwordx4 v[170:171], off
	v_lshl_add_u64 v[170:171], v[228:229], 0, s[40:41]
	s_mov_b32 m0, s71
	s_addc_u32 s59, s63, 0
	global_load_lds_dwordx4 v[170:171], off
	s_mov_b32 m0, s74
	v_lshl_add_u64 v[170:171], s[58:59], 0, v[128:129]
	global_load_lds_dwordx4 v[170:171], off
	s_mov_b32 m0, s75
	v_lshl_add_u64 v[170:171], s[58:59], 0, v[130:131]
	global_load_lds_dwordx4 v[170:171], off
	s_mov_b32 m0, s72
	v_lshl_add_u64 v[170:171], v[230:231], 0, s[40:41]
	global_load_lds_dwordx4 v[170:171], off
	s_mov_b32 m0, s73
	v_lshl_add_u64 v[170:171], v[232:233], 0, s[40:41]
	global_load_lds_dwordx4 v[170:171], off
	s_waitcnt vmcnt(8)
	s_waitcnt lgkmcnt(0)
	s_barrier
	s_setprio 1
	s_waitcnt lgkmcnt(0)
	v_mfma_f32_16x16x32_bf16 v[104:107], v[142:145], v[194:197], v[104:107]
	v_mfma_f32_16x16x32_bf16 v[76:79], v[150:153], v[194:197], v[76:79]
	v_mfma_f32_16x16x32_bf16 v[100:103], v[142:145], v[202:205], v[100:103]
	v_mfma_f32_16x16x32_bf16 v[72:75], v[150:153], v[202:205], v[72:75]
	v_mfma_f32_16x16x32_bf16 v[92:95], v[142:145], v[210:213], v[92:95]
	v_mfma_f32_16x16x32_bf16 v[64:67], v[150:153], v[210:213], v[64:67]
	v_mfma_f32_16x16x32_bf16 v[80:83], v[142:145], v[218:221], v[80:83]
	v_mfma_f32_16x16x32_bf16 v[56:59], v[150:153], v[218:221], v[56:59]
	v_mfma_f32_16x16x32_bf16 v[104:107], v[146:149], v[198:201], v[104:107]
	v_mfma_f32_16x16x32_bf16 v[76:79], v[154:157], v[198:201], v[76:79]
	v_mfma_f32_16x16x32_bf16 v[100:103], v[146:149], v[206:209], v[100:103]
	v_mfma_f32_16x16x32_bf16 v[72:75], v[154:157], v[206:209], v[72:75]
	v_mfma_f32_16x16x32_bf16 v[92:95], v[146:149], v[214:217], v[92:95]
	v_mfma_f32_16x16x32_bf16 v[64:67], v[154:157], v[214:217], v[64:67]
	v_mfma_f32_16x16x32_bf16 v[80:83], v[146:149], v[224:227], v[80:83]
	v_mfma_f32_16x16x32_bf16 v[56:59], v[154:157], v[224:227], v[56:59]
	s_setprio 0
	s_setprio 1
	v_mfma_f32_16x16x32_bf16 v[44:47], v[158:161], v[194:197], v[44:47]
	v_mfma_f32_16x16x32_bf16 v[12:15], v[166:169], v[194:197], v[12:15]
	v_mfma_f32_16x16x32_bf16 v[36:39], v[158:161], v[202:205], v[36:39]
	v_mfma_f32_16x16x32_bf16 v[8:11], v[166:169], v[202:205], v[8:11]
	v_mfma_f32_16x16x32_bf16 v[28:31], v[158:161], v[210:213], v[28:31]
	v_mfma_f32_16x16x32_bf16 v[4:7], v[166:169], v[210:213], v[4:7]
	v_mfma_f32_16x16x32_bf16 v[20:23], v[158:161], v[218:221], v[20:23]
	v_mfma_f32_16x16x32_bf16 v[0:3], v[166:169], v[218:221], v[0:3]
	v_mfma_f32_16x16x32_bf16 v[44:47], v[162:165], v[198:201], v[44:47]
	v_mfma_f32_16x16x32_bf16 v[12:15], v[190:193], v[198:201], v[12:15]
	v_mfma_f32_16x16x32_bf16 v[36:39], v[162:165], v[206:209], v[36:39]
	v_mfma_f32_16x16x32_bf16 v[8:11], v[190:193], v[206:209], v[8:11]
	v_mfma_f32_16x16x32_bf16 v[28:31], v[162:165], v[214:217], v[28:31]
	v_mfma_f32_16x16x32_bf16 v[4:7], v[190:193], v[214:217], v[4:7]
	v_mfma_f32_16x16x32_bf16 v[20:23], v[162:165], v[224:227], v[20:23]
	v_mfma_f32_16x16x32_bf16 v[0:3], v[190:193], v[224:227], v[0:3]
	s_setprio 0
	s_barrier
	s_add_i32 s89, s89, 2
	s_add_u32 s57, s57, 0x100
	s_addc_u32 s88, s88, 0
	s_mov_b64 s[58:59], s[60:61]
; #define PG8_STAGE(bufoff, gbase, voff) do { _Pragma("unroll") for (int _i = 0; _i < 2; ++_i) \
;         __builtin_amdgcn_global_load_lds((const unsigned*)((const char*)(gbase) + (voff)[_i]), (PG8_LAS unsigned*)(lds + (bufoff) + ldsw + _i * 8192), 16, 0, 0); } while (0)
; #define PG8_LDA(dst, b, h) do { _Pragma("unroll") for (int m = 0; m < 4; ++m) _Pragma("unroll") for (int k = 0; k < 2; ++k) dst[m][k] = *(const PG8_LAS bf16x8*)(lds + PG8_SA(b, h) + aoff + m * 2048 + k * 1024); } while (0)
; #define PG8_LDB(dst, b, h) do { _Pragma("unroll") for (int n = 0; n < 2; ++n) _Pragma("unroll") for (int k = 0; k < 2; ++k) dst[n][k] = *(const PG8_LAS bf16x8*)(lds + PG8_SB(b, h) + boff + n * 2048 + k * 1024); } while (0)
; #define PG8_MMA(ai, bj, At, Bt) do { __builtin_amdgcn_s_setprio(1); _Pragma("unroll") for (int m = 0; m < 4; ++m) _Pragma("unroll") for (int n = 0; n < 2; ++n) _Pragma("unroll") for (int k = 0; k < 2; ++k) \
;         acc[ai][bj][m][n] = __builtin_amdgcn_mfma_f32_16x16x32_bf16(Bt[n][k], At[m][k], acc[ai][bj][m][n], 0, 0, 0); __builtin_amdgcn_s_setprio(0); } while (0)
; #define PG8_WAIT_V(n) asm volatile("s_waitcnt vmcnt(" #n ")" ::: "memory")
; #define PG8_WAIT_L(n) asm volatile("s_waitcnt lgkmcnt(" #n ")" ::: "memory")
; #define PG8_BAR __builtin_amdgcn_s_barrier()
; #define PG8_SCHED __builtin_amdgcn_sched_barrier(0)
; template <class Epi, class Sched, bool ALIGN_EPI = false, bool SP2 = false>
; __device__ __forceinline__ void gemm_phase(PG8_LAS unsigned char* lds, const Gemm g, const Sched& S, const Epi& E) {
;     ...
;             PG8_LDB(B0, 0, 0); PG8_LDB(B1, 0, 1); PG8_SCHED; PG8_LDA(At, 0, 0); PG8_STAGE(PG8_SA(1, 1), a1 + hstep, voffA);
;             PG8_WAIT_V(8); PG8_WAIT_L(0); PG8_BAR; PG8_MMA(0, 0, At, B0); PG8_MMA(0, 1, At, B1); PG8_BAR; PG8_SCHED;
;             PG8_LDA(At, 0, 1); PG8_STAGE(PG8_SB(0, 0), b2, voffB); PG8_STAGE(PG8_SB(0, 1), b2 + hstep, voffB); PG8_STAGE(PG8_SA(0, 0), a2, voffA);
.LBB0_873:
	ds_read_b128 v[142:145], v174
	ds_read_b128 v[146:149], v175
	ds_read_b128 v[150:153], v176
	ds_read_b128 v[154:157], v177
	ds_read_b128 v[158:161], v178
	ds_read_b128 v[162:165], v179
	ds_read_b128 v[166:169], v180
	ds_read_b128 v[190:193], v181
	s_add_u32 s60, s58, 0x100
	s_addc_u32 s61, s59, 0
	s_cmp_eq_u32 s89, 40
	s_cselect_b32 s65, s9, s61
	s_cselect_b32 s64, s8, s60
	s_cselect_b32 s63, s55, s88
	s_cselect_b32 s62, s54, s57
	s_mov_b32 m0, s78
	v_lshl_add_u64 v[170:171], s[58:59], 0, v[134:135]
	ds_read_b128 v[194:197], v172
	ds_read_b128 v[198:201], v172 offset:1024
	ds_read_b128 v[202:205], v172 offset:2048
	ds_read_b128 v[206:209], v172 offset:3072
	ds_read_b128 v[210:213], v172 offset:4096
	ds_read_b128 v[214:217], v172 offset:5120
	ds_read_b128 v[218:221], v172 offset:6144
	ds_read_b128 v[224:227], v172 offset:7168
	global_load_lds_dwordx4 v[170:171], off
	s_mov_b32 m0, s79
	v_lshl_add_u64 v[170:171], s[58:59], 0, v[136:137]
	global_load_lds_dwordx4 v[170:171], off
	s_waitcnt vmcnt(8)
	s_waitcnt lgkmcnt(0)
	s_barrier
	s_setprio 1
	s_waitcnt lgkmcnt(0)
	v_mfma_f32_16x16x32_bf16 v[124:127], v[142:145], v[194:197], v[124:127]
	v_mfma_f32_16x16x32_bf16 v[108:111], v[150:153], v[194:197], v[108:111]
	v_mfma_f32_16x16x32_bf16 v[120:123], v[142:145], v[202:205], v[120:123]
	v_mfma_f32_16x16x32_bf16 v[96:99], v[150:153], v[202:205], v[96:99]
	v_mfma_f32_16x16x32_bf16 v[116:119], v[142:145], v[210:213], v[116:119]
	v_mfma_f32_16x16x32_bf16 v[88:91], v[150:153], v[210:213], v[88:91]
	v_mfma_f32_16x16x32_bf16 v[112:115], v[142:145], v[218:221], v[112:115]
	v_mfma_f32_16x16x32_bf16 v[84:87], v[150:153], v[218:221], v[84:87]
	v_mfma_f32_16x16x32_bf16 v[124:127], v[146:149], v[198:201], v[124:127]
	v_mfma_f32_16x16x32_bf16 v[108:111], v[154:157], v[198:201], v[108:111]
	v_mfma_f32_16x16x32_bf16 v[120:123], v[146:149], v[206:209], v[120:123]
	v_mfma_f32_16x16x32_bf16 v[96:99], v[154:157], v[206:209], v[96:99]
	v_mfma_f32_16x16x32_bf16 v[116:119], v[146:149], v[214:217], v[116:119]
	v_mfma_f32_16x16x32_bf16 v[88:91], v[154:157], v[214:217], v[88:91]
	v_mfma_f32_16x16x32_bf16 v[112:115], v[146:149], v[224:227], v[112:115]
	v_mfma_f32_16x16x32_bf16 v[84:87], v[154:157], v[224:227], v[84:87]
	s_setprio 0
	s_setprio 1
	v_mfma_f32_16x16x32_bf16 v[68:71], v[158:161], v[194:197], v[68:71]
	v_mfma_f32_16x16x32_bf16 v[40:43], v[166:169], v[194:197], v[40:43]
	v_mfma_f32_16x16x32_bf16 v[60:63], v[158:161], v[202:205], v[60:63]
	v_mfma_f32_16x16x32_bf16 v[32:35], v[166:169], v[202:205], v[32:35]
	v_mfma_f32_16x16x32_bf16 v[52:55], v[158:161], v[210:213], v[52:55]
	v_mfma_f32_16x16x32_bf16 v[24:27], v[166:169], v[210:213], v[24:27]
	v_mfma_f32_16x16x32_bf16 v[48:51], v[158:161], v[218:221], v[48:51]
	v_mfma_f32_16x16x32_bf16 v[16:19], v[166:169], v[218:221], v[16:19]
	v_mfma_f32_16x16x32_bf16 v[68:71], v[162:165], v[198:201], v[68:71]
	v_mfma_f32_16x16x32_bf16 v[40:43], v[190:193], v[198:201], v[40:43]
	v_mfma_f32_16x16x32_bf16 v[60:63], v[162:165], v[206:209], v[60:63]
	v_mfma_f32_16x16x32_bf16 v[32:35], v[190:193], v[206:209], v[32:35]
	v_mfma_f32_16x16x32_bf16 v[52:55], v[162:165], v[214:217], v[52:55]
	v_mfma_f32_16x16x32_bf16 v[24:27], v[190:193], v[214:217], v[24:27]
	v_mfma_f32_16x16x32_bf16 v[48:51], v[162:165], v[224:227], v[48:51]
	v_mfma_f32_16x16x32_bf16 v[16:19], v[190:193], v[224:227], v[16:19]
	s_setprio 0
	s_barrier
	s_mov_b32 m0, s12
	v_lshl_add_u64 v[170:171], s[62:63], 0, v[128:129]
	s_add_u32 s58, s62, 0xb0000
	ds_read_b128 v[194:197], v172 offset:16384
	ds_read_b128 v[198:201], v172 offset:17408
	ds_read_b128 v[202:205], v172 offset:18432
	ds_read_b128 v[206:209], v172 offset:19456
	ds_read_b128 v[210:213], v172 offset:20480
	ds_read_b128 v[214:217], v172 offset:21504
	ds_read_b128 v[218:221], v172 offset:22528
	ds_read_b128 v[224:227], v172 offset:23552
	global_load_lds_dwordx4 v[170:171], off
	v_lshl_add_u64 v[228:229], s[62:63], 0, v[130:131]
	s_mov_b32 m0, s13
	s_addc_u32 s59, s63, 0
	global_load_lds_dwordx4 v[228:229], off
	v_lshl_add_u64 v[230:231], s[58:59], 0, v[128:129]
	s_mov_b32 m0, s14
	v_lshl_add_u64 v[232:233], s[64:65], 0, v[130:131]
	global_load_lds_dwordx4 v[230:231], off
	s_mov_b32 m0, s15
	v_lshl_add_u64 v[230:231], s[58:59], 0, v[130:131]
	global_load_lds_dwordx4 v[230:231], off
	s_mov_b32 m0, s5
	v_lshl_add_u64 v[230:231], s[64:65], 0, v[128:129]
	global_load_lds_dwordx4 v[230:231], off
	s_mov_b32 m0, s39
	s_nop 0
	global_load_lds_dwordx4 v[232:233], off
	s_waitcnt vmcnt(8)
	s_waitcnt lgkmcnt(0)
	s_barrier
; #define PG8_STAGE(bufoff, gbase, voff) do { _Pragma("unroll") for (int _i = 0; _i < 2; ++_i) \
;         __builtin_amdgcn_global_load_lds((const unsigned*)((const char*)(gbase) + (voff)[_i]), (PG8_LAS unsigned*)(lds + (bufoff) + ldsw + _i * 8192), 16, 0, 0); } while (0)
; #define PG8_LDA(dst, b, h) do { _Pragma("unroll") for (int m = 0; m < 4; ++m) _Pragma("unroll") for (int k = 0; k < 2; ++k) dst[m][k] = *(const PG8_LAS bf16x8*)(lds + PG8_SA(b, h) + aoff + m * 2048 + k * 1024); } while (0)
; #define PG8_LDB(dst, b, h) do { _Pragma("unroll") for (int n = 0; n < 2; ++n) _Pragma("unroll") for (int k = 0; k < 2; ++k) dst[n][k] = *(const PG8_LAS bf16x8*)(lds + PG8_SB(b, h) + boff + n * 2048 + k * 1024); } while (0)
; #define PG8_MMA(ai, bj, At, Bt) do { __builtin_amdgcn_s_setprio(1); _Pragma("unroll") for (int m = 0; m < 4; ++m) _Pragma("unroll") for (int n = 0; n < 2; ++n) _Pragma("unroll") for (int k = 0; k < 2; ++k) \
;         acc[ai][bj][m][n] = __builtin_amdgcn_mfma_f32_16x16x32_bf16(Bt[n][k], At[m][k], acc[ai][bj][m][n], 0, 0, 0); __builtin_amdgcn_s_setprio(0); } while (0)
; #define PG8_WAIT_V(n) asm volatile("s_waitcnt vmcnt(" #n ")" ::: "memory")
; #define PG8_WAIT_L(n) asm volatile("s_waitcnt lgkmcnt(" #n ")" ::: "memory")
; #define PG8_BAR __builtin_amdgcn_s_barrier()
; #define PG8_SCHED __builtin_amdgcn_sched_barrier(0)
; template <class Epi, class Sched, bool ALIGN_EPI = false, bool SP2 = false>
; __device__ __forceinline__ void gemm_phase(PG8_LAS unsigned char* lds, const Gemm g, const Sched& S, const Epi& E) {
;     ...
;             PG8_WAIT_V(8); PG8_WAIT_L(0); PG8_BAR; PG8_MMA(1, 0, At, B0); PG8_MMA(1, 1, At, B1); PG8_BAR; PG8_SCHED;
;             PG8_LDB(B0, 1, 0); PG8_LDB(B1, 1, 1); PG8_SCHED; PG8_LDA(At, 1, 0); PG8_STAGE(PG8_SA(0, 1), a2 + hstep, voffA);
;             PG8_WAIT_V(8); PG8_WAIT_L(0); PG8_BAR; PG8_MMA(0, 0, At, B0); PG8_MMA(0, 1, At, B1); PG8_BAR; PG8_SCHED;
	s_setprio 1
	s_waitcnt lgkmcnt(0)
	v_mfma_f32_16x16x32_bf16 v[104:107], v[142:145], v[194:197], v[104:107]
	v_mfma_f32_16x16x32_bf16 v[76:79], v[150:153], v[194:197], v[76:79]
	v_mfma_f32_16x16x32_bf16 v[100:103], v[142:145], v[202:205], v[100:103]
	v_mfma_f32_16x16x32_bf16 v[72:75], v[150:153], v[202:205], v[72:75]
	v_mfma_f32_16x16x32_bf16 v[92:95], v[142:145], v[210:213], v[92:95]
	v_mfma_f32_16x16x32_bf16 v[64:67], v[150:153], v[210:213], v[64:67]
	v_mfma_f32_16x16x32_bf16 v[80:83], v[142:145], v[218:221], v[80:83]
	v_mfma_f32_16x16x32_bf16 v[56:59], v[150:153], v[218:221], v[56:59]
	v_mfma_f32_16x16x32_bf16 v[104:107], v[146:149], v[198:201], v[104:107]
	v_mfma_f32_16x16x32_bf16 v[76:79], v[154:157], v[198:201], v[76:79]
	v_mfma_f32_16x16x32_bf16 v[100:103], v[146:149], v[206:209], v[100:103]
	v_mfma_f32_16x16x32_bf16 v[72:75], v[154:157], v[206:209], v[72:75]
	v_mfma_f32_16x16x32_bf16 v[92:95], v[146:149], v[214:217], v[92:95]
	v_mfma_f32_16x16x32_bf16 v[64:67], v[154:157], v[214:217], v[64:67]
	v_mfma_f32_16x16x32_bf16 v[80:83], v[146:149], v[224:227], v[80:83]
	v_mfma_f32_16x16x32_bf16 v[56:59], v[154:157], v[224:227], v[56:59]
	s_setprio 0
	s_setprio 1
	v_mfma_f32_16x16x32_bf16 v[44:47], v[158:161], v[194:197], v[44:47]
	v_mfma_f32_16x16x32_bf16 v[12:15], v[166:169], v[194:197], v[12:15]
	v_mfma_f32_16x16x32_bf16 v[36:39], v[158:161], v[202:205], v[36:39]
	v_mfma_f32_16x16x32_bf16 v[8:11], v[166:169], v[202:205], v[8:11]
	v_mfma_f32_16x16x32_bf16 v[28:31], v[158:161], v[210:213], v[28:31]
	v_mfma_f32_16x16x32_bf16 v[4:7], v[166:169], v[210:213], v[4:7]
	v_mfma_f32_16x16x32_bf16 v[20:23], v[158:161], v[218:221], v[20:23]
	v_mfma_f32_16x16x32_bf16 v[0:3], v[166:169], v[218:221], v[0:3]
	v_mfma_f32_16x16x32_bf16 v[44:47], v[162:165], v[198:201], v[44:47]
	v_mfma_f32_16x16x32_bf16 v[12:15], v[190:193], v[198:201], v[12:15]
	v_mfma_f32_16x16x32_bf16 v[36:39], v[162:165], v[206:209], v[36:39]
	v_mfma_f32_16x16x32_bf16 v[8:11], v[190:193], v[206:209], v[8:11]
	v_mfma_f32_16x16x32_bf16 v[28:31], v[162:165], v[214:217], v[28:31]
	v_mfma_f32_16x16x32_bf16 v[4:7], v[190:193], v[214:217], v[4:7]
	v_mfma_f32_16x16x32_bf16 v[20:23], v[162:165], v[224:227], v[20:23]
	v_mfma_f32_16x16x32_bf16 v[0:3], v[190:193], v[224:227], v[0:3]
	s_setprio 0
	s_barrier
	ds_read_b128 v[142:145], v182
	ds_read_b128 v[146:149], v183
	ds_read_b128 v[150:153], v184
	ds_read_b128 v[154:157], v185
	ds_read_b128 v[158:161], v186
	ds_read_b128 v[162:165], v187
	ds_read_b128 v[166:169], v188
	ds_read_b128 v[190:193], v189
	s_add_u32 s58, s64, 0xb0000
	s_addc_u32 s59, s65, 0
	s_mov_b32 m0, s43
	v_lshl_add_u64 v[234:235], s[58:59], 0, v[128:129]
	ds_read_b128 v[194:197], v172 offset:32768
	ds_read_b128 v[198:201], v172 offset:33792
	ds_read_b128 v[202:205], v172 offset:34816
	ds_read_b128 v[206:209], v172 offset:35840
	ds_read_b128 v[210:213], v172 offset:36864
	ds_read_b128 v[214:217], v172 offset:37888
	ds_read_b128 v[218:221], v172 offset:38912
	ds_read_b128 v[224:227], v172 offset:39936
	global_load_lds_dwordx4 v[234:235], off
	s_mov_b32 m0, s66
	v_lshl_add_u64 v[234:235], s[58:59], 0, v[130:131]
	global_load_lds_dwordx4 v[234:235], off
	s_waitcnt vmcnt(8)
	s_waitcnt lgkmcnt(0)
	s_barrier
	s_setprio 1
	s_waitcnt lgkmcnt(0)
	v_mfma_f32_16x16x32_bf16 v[124:127], v[142:145], v[194:197], v[124:127]
	v_mfma_f32_16x16x32_bf16 v[108:111], v[150:153], v[194:197], v[108:111]
	v_mfma_f32_16x16x32_bf16 v[120:123], v[142:145], v[202:205], v[120:123]
	v_mfma_f32_16x16x32_bf16 v[96:99], v[150:153], v[202:205], v[96:99]
	v_mfma_f32_16x16x32_bf16 v[116:119], v[142:145], v[210:213], v[116:119]
	v_mfma_f32_16x16x32_bf16 v[88:91], v[150:153], v[210:213], v[88:91]
	v_mfma_f32_16x16x32_bf16 v[112:115], v[142:145], v[218:221], v[112:115]
	v_mfma_f32_16x16x32_bf16 v[84:87], v[150:153], v[218:221], v[84:87]
	v_mfma_f32_16x16x32_bf16 v[124:127], v[146:149], v[198:201], v[124:127]
	v_mfma_f32_16x16x32_bf16 v[108:111], v[154:157], v[198:201], v[108:111]
	v_mfma_f32_16x16x32_bf16 v[120:123], v[146:149], v[206:209], v[120:123]
	v_mfma_f32_16x16x32_bf16 v[96:99], v[154:157], v[206:209], v[96:99]
	v_mfma_f32_16x16x32_bf16 v[116:119], v[146:149], v[214:217], v[116:119]
	v_mfma_f32_16x16x32_bf16 v[88:91], v[154:157], v[214:217], v[88:91]
	v_mfma_f32_16x16x32_bf16 v[112:115], v[146:149], v[224:227], v[112:115]
	v_mfma_f32_16x16x32_bf16 v[84:87], v[154:157], v[224:227], v[84:87]
	s_setprio 0
	s_setprio 1
	v_mfma_f32_16x16x32_bf16 v[68:71], v[158:161], v[194:197], v[68:71]
	v_mfma_f32_16x16x32_bf16 v[40:43], v[166:169], v[194:197], v[40:43]
	v_mfma_f32_16x16x32_bf16 v[60:63], v[158:161], v[202:205], v[60:63]
	v_mfma_f32_16x16x32_bf16 v[32:35], v[166:169], v[202:205], v[32:35]
	v_mfma_f32_16x16x32_bf16 v[52:55], v[158:161], v[210:213], v[52:55]
	v_mfma_f32_16x16x32_bf16 v[24:27], v[166:169], v[210:213], v[24:27]
	v_mfma_f32_16x16x32_bf16 v[48:51], v[158:161], v[218:221], v[48:51]
	v_mfma_f32_16x16x32_bf16 v[16:19], v[166:169], v[218:221], v[16:19]
	v_mfma_f32_16x16x32_bf16 v[68:71], v[162:165], v[198:201], v[68:71]
	v_mfma_f32_16x16x32_bf16 v[40:43], v[190:193], v[198:201], v[40:43]
	v_mfma_f32_16x16x32_bf16 v[60:63], v[162:165], v[206:209], v[60:63]
	v_mfma_f32_16x16x32_bf16 v[32:35], v[190:193], v[206:209], v[32:35]
	v_mfma_f32_16x16x32_bf16 v[52:55], v[162:165], v[214:217], v[52:55]
	v_mfma_f32_16x16x32_bf16 v[24:27], v[190:193], v[214:217], v[24:27]
	v_mfma_f32_16x16x32_bf16 v[48:51], v[162:165], v[224:227], v[48:51]
	v_mfma_f32_16x16x32_bf16 v[16:19], v[190:193], v[224:227], v[16:19]
	s_setprio 0
	s_barrier
; #define PG8_STAGE(bufoff, gbase, voff) do { _Pragma("unroll") for (int _i = 0; _i < 2; ++_i) \
;         __builtin_amdgcn_global_load_lds((const unsigned*)((const char*)(gbase) + (voff)[_i]), (PG8_LAS unsigned*)(lds + (bufoff) + ldsw + _i * 8192), 16, 0, 0); } while (0)
; #define PG8_LDA(dst, b, h) do { _Pragma("unroll") for (int m = 0; m < 4; ++m) _Pragma("unroll") for (int k = 0; k < 2; ++k) dst[m][k] = *(const PG8_LAS bf16x8*)(lds + PG8_SA(b, h) + aoff + m * 2048 + k * 1024); } while (0)
; #define PG8_MMA(ai, bj, At, Bt) do { __builtin_amdgcn_s_setprio(1); _Pragma("unroll") for (int m = 0; m < 4; ++m) _Pragma("unroll") for (int n = 0; n < 2; ++n) _Pragma("unroll") for (int k = 0; k < 2; ++k) \
;         acc[ai][bj][m][n] = __builtin_amdgcn_mfma_f32_16x16x32_bf16(Bt[n][k], At[m][k], acc[ai][bj][m][n], 0, 0, 0); __builtin_amdgcn_s_setprio(0); } while (0)
; #define PG8_WAIT_V(n) asm volatile("s_waitcnt vmcnt(" #n ")" ::: "memory")
; #define PG8_WAIT_L(n) asm volatile("s_waitcnt lgkmcnt(" #n ")" ::: "memory")
; #define PG8_BAR __builtin_amdgcn_s_barrier()
; #define PG8_SCHED __builtin_amdgcn_sched_barrier(0)
; template <class Epi, class Sched, bool ALIGN_EPI = false, bool SP2 = false>
; __device__ __forceinline__ void gemm_phase(PG8_LAS unsigned char* lds, const Gemm g, const Sched& S, const Epi& E) {
;     ...
;             PG8_LDA(At, 1, 1); PG8_STAGE(PG8_SB(1, 0), b3, voffB); PG8_STAGE(PG8_SB(1, 1), b3 + hstep, voffB); PG8_STAGE(PG8_SA(1, 0), a3, voffA);
;             PG8_WAIT_V(8); PG8_WAIT_L(0); PG8_BAR; PG8_MMA(1, 0, At, B0); PG8_MMA(1, 1, At, B1); PG8_BAR; PG8_SCHED;
;     ...
;         if constexpr (ALIGN_EPI) { if (wr == 0) PG8_BAR; }
	s_mov_b32 m0, s70
	v_lshl_add_u64 v[170:171], v[170:171], 0, s[40:41]
	s_add_u32 s58, s62, 0xb0080
	ds_read_b128 v[194:197], v172 offset:49152
	ds_read_b128 v[198:201], v172 offset:50176
	ds_read_b128 v[202:205], v172 offset:51200
	ds_read_b128 v[206:209], v172 offset:52224
	ds_read_b128 v[210:213], v172 offset:53248
	ds_read_b128 v[214:217], v172 offset:54272
	ds_read_b128 v[218:221], v172 offset:55296
	ds_read_b128 v[224:227], v172 offset:56320
	global_load_lds_dwordx4 v[170:171], off
	v_lshl_add_u64 v[170:171], v[228:229], 0, s[40:41]
	s_mov_b32 m0, s71
	s_addc_u32 s59, s63, 0
	global_load_lds_dwordx4 v[170:171], off
	s_mov_b32 m0, s74
	v_lshl_add_u64 v[170:171], s[58:59], 0, v[128:129]
	global_load_lds_dwordx4 v[170:171], off
	s_mov_b32 m0, s75
	v_lshl_add_u64 v[170:171], s[58:59], 0, v[130:131]
	global_load_lds_dwordx4 v[170:171], off
	s_mov_b32 m0, s72
	v_lshl_add_u64 v[170:171], v[230:231], 0, s[40:41]
	global_load_lds_dwordx4 v[170:171], off
	s_mov_b32 m0, s73
	v_lshl_add_u64 v[170:171], v[232:233], 0, s[40:41]
	global_load_lds_dwordx4 v[170:171], off
	s_waitcnt vmcnt(8)
	s_waitcnt lgkmcnt(0)
	s_barrier
	s_setprio 1
	s_waitcnt lgkmcnt(0)
	v_mfma_f32_16x16x32_bf16 v[104:107], v[142:145], v[194:197], v[104:107]
	v_mfma_f32_16x16x32_bf16 v[76:79], v[150:153], v[194:197], v[76:79]
	v_mfma_f32_16x16x32_bf16 v[100:103], v[142:145], v[202:205], v[100:103]
	v_mfma_f32_16x16x32_bf16 v[72:75], v[150:153], v[202:205], v[72:75]
	v_mfma_f32_16x16x32_bf16 v[92:95], v[142:145], v[210:213], v[92:95]
	v_mfma_f32_16x16x32_bf16 v[64:67], v[150:153], v[210:213], v[64:67]
	v_mfma_f32_16x16x32_bf16 v[80:83], v[142:145], v[218:221], v[80:83]
	v_mfma_f32_16x16x32_bf16 v[56:59], v[150:153], v[218:221], v[56:59]
	v_mfma_f32_16x16x32_bf16 v[104:107], v[146:149], v[198:201], v[104:107]
	v_mfma_f32_16x16x32_bf16 v[76:79], v[154:157], v[198:201], v[76:79]
	v_mfma_f32_16x16x32_bf16 v[100:103], v[146:149], v[206:209], v[100:103]
	v_mfma_f32_16x16x32_bf16 v[72:75], v[154:157], v[206:209], v[72:75]
	v_mfma_f32_16x16x32_bf16 v[92:95], v[146:149], v[214:217], v[92:95]
	v_mfma_f32_16x16x32_bf16 v[64:67], v[154:157], v[214:217], v[64:67]
	v_mfma_f32_16x16x32_bf16 v[80:83], v[146:149], v[224:227], v[80:83]
	v_mfma_f32_16x16x32_bf16 v[56:59], v[154:157], v[224:227], v[56:59]
	s_setprio 0
	s_setprio 1
	v_mfma_f32_16x16x32_bf16 v[44:47], v[158:161], v[194:197], v[44:47]
	v_mfma_f32_16x16x32_bf16 v[12:15], v[166:169], v[194:197], v[12:15]
	v_mfma_f32_16x16x32_bf16 v[36:39], v[158:161], v[202:205], v[36:39]
	v_mfma_f32_16x16x32_bf16 v[8:11], v[166:169], v[202:205], v[8:11]
	v_mfma_f32_16x16x32_bf16 v[28:31], v[158:161], v[210:213], v[28:31]
	v_mfma_f32_16x16x32_bf16 v[4:7], v[166:169], v[210:213], v[4:7]
	v_mfma_f32_16x16x32_bf16 v[20:23], v[158:161], v[218:221], v[20:23]
	v_mfma_f32_16x16x32_bf16 v[0:3], v[166:169], v[218:221], v[0:3]
	v_mfma_f32_16x16x32_bf16 v[44:47], v[162:165], v[198:201], v[44:47]
	v_mfma_f32_16x16x32_bf16 v[12:15], v[190:193], v[198:201], v[12:15]
	v_mfma_f32_16x16x32_bf16 v[36:39], v[162:165], v[206:209], v[36:39]
	v_mfma_f32_16x16x32_bf16 v[8:11], v[190:193], v[206:209], v[8:11]
	v_mfma_f32_16x16x32_bf16 v[28:31], v[162:165], v[214:217], v[28:31]
	v_mfma_f32_16x16x32_bf16 v[4:7], v[190:193], v[214:217], v[4:7]
	v_mfma_f32_16x16x32_bf16 v[20:23], v[162:165], v[224:227], v[20:23]
	v_mfma_f32_16x16x32_bf16 v[0:3], v[190:193], v[224:227], v[0:3]
	s_setprio 0
	s_barrier
	s_add_i32 s89, s89, 2
	s_add_u32 s57, s57, 0x100
	s_addc_u32 s88, s88, 0
	s_cmp_gt_u32 s89, 41
	s_mov_b64 s[58:59], s[60:61]
	s_cbranch_scc0 .LBB0_873
	s_and_b64 vcc, exec, s[52:53]
	s_cbranch_vccz .LBB0_876
	s_barrier

; #define PG8_STAGE(bufoff, gbase, voff) do { _Pragma("unroll") for (int _i = 0; _i < 2; ++_i) \
;         __builtin_amdgcn_global_load_lds((const unsigned*)((const char*)(gbase) + (voff)[_i]), (PG8_LAS unsigned*)(lds + (bufoff) + ldsw + _i * 8192), 16, 0, 0); } while (0)
; #define PG8_LDA(dst, b, h) do { _Pragma("unroll") for (int m = 0; m < 4; ++m) _Pragma("unroll") for (int k = 0; k < 2; ++k) dst[m][k] = *(const PG8_LAS bf16x8*)(lds + PG8_SA(b, h) + aoff + m * 2048 + k * 1024); } while (0)
; #define PG8_LDB(dst, b, h) do { _Pragma("unroll") for (int n = 0; n < 2; ++n) _Pragma("unroll") for (int k = 0; k < 2; ++k) dst[n][k] = *(const PG8_LAS bf16x8*)(lds + PG8_SB(b, h) + boff + n * 2048 + k * 1024); } while (0)
; #define PG8_MMA(ai, bj, At, Bt) do { __builtin_amdgcn_s_setprio(1); _Pragma("unroll") for (int m = 0; m < 4; ++m) _Pragma("unroll") for (int n = 0; n < 2; ++n) _Pragma("unroll") for (int k = 0; k < 2; ++k) \
;         acc[ai][bj][m][n] = __builtin_amdgcn_mfma_f32_16x16x32_bf16(Bt[n][k], At[m][k], acc[ai][bj][m][n], 0, 0, 0); __builtin_amdgcn_s_setprio(0); } while (0)
; #define PG8_WAIT_V(n) asm volatile("s_waitcnt vmcnt(" #n ")" ::: "memory")
; #define PG8_WAIT_L(n) asm volatile("s_waitcnt lgkmcnt(" #n ")" ::: "memory")
; #define PG8_BAR __builtin_amdgcn_s_barrier()
; #define PG8_SCHED __builtin_amdgcn_sched_barrier(0)
; template <class Epi, class Sched, bool ALIGN_EPI = false, bool SP2 = false>
; __device__ __forceinline__ void gemm_phase(PG8_LAS unsigned char* lds, const Gemm g, const Sched& S, const Epi& E) {
;     ...
;             PG8_LDB(B0, 0, 0); PG8_LDB(B1, 0, 1); PG8_SCHED; PG8_LDA(At, 0, 0); PG8_STAGE(PG8_SA(1, 1), a1 + hstep, voffA);
;             PG8_WAIT_V(8); PG8_WAIT_L(0); PG8_BAR; PG8_MMA(0, 0, At, B0); PG8_MMA(0, 1, At, B1); PG8_BAR; PG8_SCHED;
;             PG8_LDA(At, 0, 1); PG8_STAGE(PG8_SB(0, 0), b2, voffB); PG8_STAGE(PG8_SB(0, 1), b2 + hstep, voffB); PG8_STAGE(PG8_SA(0, 0), a2, voffA);
;             PG8_WAIT_V(8); PG8_WAIT_L(0); PG8_BAR; PG8_MMA(1, 0, At, B0); PG8_MMA(1, 1, At, B1); PG8_BAR; PG8_SCHED;
.LBB0_895:
	s_add_u32 s33, s64, 0x100
	s_addc_u32 s55, s65, 0
	s_mov_b32 s57, 0
	ds_read_b128 v[156:159], v140
	ds_read_b128 v[160:163], v141
	ds_read_b128 v[164:167], v142
	ds_read_b128 v[168:171], v143
	ds_read_b128 v[172:175], v144
	ds_read_b128 v[176:179], v145
	ds_read_b128 v[180:183], v146
	ds_read_b128 v[184:187], v147
	s_add_i32 s86, s57, 2
	s_add_u32 s64, s62, 0x100
	s_addc_u32 s65, s63, 0
	s_cmp_eq_u32 s78, s57
	s_cselect_b32 s69, s59, s65
	s_cselect_b32 s68, s58, s64
	s_cselect_b32 s67, s61, s55
	s_cselect_b32 s66, s60, s33
	s_mov_b32 m0, s79
	v_lshl_add_u64 v[220:221], s[62:63], 0, v[134:135]
	ds_read_b128 v[188:191], v138
	ds_read_b128 v[192:195], v138 offset:1024
	ds_read_b128 v[196:199], v138 offset:2048
	ds_read_b128 v[200:203], v138 offset:3072
	ds_read_b128 v[204:207], v138 offset:4096
	ds_read_b128 v[208:211], v138 offset:5120
	ds_read_b128 v[212:215], v138 offset:6144
	ds_read_b128 v[216:219], v138 offset:7168
	global_load_lds_dwordx4 v[220:221], off
	s_mov_b32 m0, s80
	v_lshl_add_u64 v[220:221], s[62:63], 0, v[136:137]
	global_load_lds_dwordx4 v[220:221], off
	s_waitcnt vmcnt(8)
	s_waitcnt lgkmcnt(0)
	s_barrier
	s_setprio 1
	s_waitcnt lgkmcnt(0)
	v_mfma_f32_16x16x32_bf16 v[124:127], v[156:159], v[188:191], 0
	v_mfma_f32_16x16x32_bf16 v[120:123], v[164:167], v[188:191], 0
	v_mfma_f32_16x16x32_bf16 v[108:111], v[156:159], v[196:199], 0
	v_mfma_f32_16x16x32_bf16 v[104:107], v[164:167], v[196:199], 0
	v_mfma_f32_16x16x32_bf16 v[92:95], v[156:159], v[204:207], 0
	v_mfma_f32_16x16x32_bf16 v[88:91], v[164:167], v[204:207], 0
	v_mfma_f32_16x16x32_bf16 v[76:79], v[156:159], v[212:215], 0
	v_mfma_f32_16x16x32_bf16 v[72:75], v[164:167], v[212:215], 0
	v_mfma_f32_16x16x32_bf16 v[124:127], v[160:163], v[192:195], v[124:127]
	v_mfma_f32_16x16x32_bf16 v[120:123], v[168:171], v[192:195], v[120:123]
	v_mfma_f32_16x16x32_bf16 v[108:111], v[160:163], v[200:203], v[108:111]
	v_mfma_f32_16x16x32_bf16 v[104:107], v[168:171], v[200:203], v[104:107]
	v_mfma_f32_16x16x32_bf16 v[92:95], v[160:163], v[208:211], v[92:95]
	v_mfma_f32_16x16x32_bf16 v[88:91], v[168:171], v[208:211], v[88:91]
	v_mfma_f32_16x16x32_bf16 v[76:79], v[160:163], v[216:219], v[76:79]
	v_mfma_f32_16x16x32_bf16 v[72:75], v[168:171], v[216:219], v[72:75]
	s_setprio 0
	s_setprio 1
	v_mfma_f32_16x16x32_bf16 v[116:119], v[172:175], v[188:191], 0
	v_mfma_f32_16x16x32_bf16 v[112:115], v[180:183], v[188:191], 0
	v_mfma_f32_16x16x32_bf16 v[100:103], v[172:175], v[196:199], 0
	v_mfma_f32_16x16x32_bf16 v[96:99], v[180:183], v[196:199], 0
	v_mfma_f32_16x16x32_bf16 v[84:87], v[172:175], v[204:207], 0
	v_mfma_f32_16x16x32_bf16 v[80:83], v[180:183], v[204:207], 0
	v_mfma_f32_16x16x32_bf16 v[68:71], v[172:175], v[212:215], 0
	v_mfma_f32_16x16x32_bf16 v[64:67], v[180:183], v[212:215], 0
	v_mfma_f32_16x16x32_bf16 v[116:119], v[176:179], v[192:195], v[116:119]
	v_mfma_f32_16x16x32_bf16 v[112:115], v[184:187], v[192:195], v[112:115]
	v_mfma_f32_16x16x32_bf16 v[100:103], v[176:179], v[200:203], v[100:103]
	v_mfma_f32_16x16x32_bf16 v[96:99], v[184:187], v[200:203], v[96:99]
	v_mfma_f32_16x16x32_bf16 v[84:87], v[176:179], v[208:211], v[84:87]
	v_mfma_f32_16x16x32_bf16 v[80:83], v[184:187], v[208:211], v[80:83]
	v_mfma_f32_16x16x32_bf16 v[68:71], v[176:179], v[216:219], v[68:71]
	v_mfma_f32_16x16x32_bf16 v[64:67], v[184:187], v[216:219], v[64:67]
	s_setprio 0
	s_barrier
	s_mov_b32 m0, s12
	v_lshl_add_u64 v[220:221], s[66:67], 0, v[130:131]
	s_add_u32 s62, s66, 0xb0000
	ds_read_b128 v[188:191], v138 offset:16384
	ds_read_b128 v[192:195], v138 offset:17408
	ds_read_b128 v[196:199], v138 offset:18432
	ds_read_b128 v[200:203], v138 offset:19456
	ds_read_b128 v[204:207], v138 offset:20480
	ds_read_b128 v[208:211], v138 offset:21504
	ds_read_b128 v[212:215], v138 offset:22528
	ds_read_b128 v[216:219], v138 offset:23552
	global_load_lds_dwordx4 v[220:221], off
	v_lshl_add_u64 v[224:225], s[66:67], 0, v[128:129]
	s_mov_b32 m0, s13
	s_addc_u32 s63, s67, 0
	global_load_lds_dwordx4 v[224:225], off
	v_lshl_add_u64 v[226:227], s[62:63], 0, v[130:131]
	s_mov_b32 m0, s14
	v_lshl_add_u64 v[228:229], s[68:69], 0, v[128:129]
	global_load_lds_dwordx4 v[226:227], off
	s_mov_b32 m0, s15
	v_lshl_add_u64 v[226:227], s[62:63], 0, v[128:129]
	global_load_lds_dwordx4 v[226:227], off
	s_mov_b32 m0, s5
	v_lshl_add_u64 v[226:227], s[68:69], 0, v[130:131]
	global_load_lds_dwordx4 v[226:227], off
	s_mov_b32 m0, s39
	s_nop 0
	global_load_lds_dwordx4 v[228:229], off
	s_waitcnt vmcnt(8)
	s_waitcnt lgkmcnt(0)
	s_barrier
	s_setprio 1
	s_waitcnt lgkmcnt(0)
	v_mfma_f32_16x16x32_bf16 v[60:63], v[156:159], v[188:191], 0
	v_mfma_f32_16x16x32_bf16 v[56:59], v[164:167], v[188:191], 0
	v_mfma_f32_16x16x32_bf16 v[44:47], v[156:159], v[196:199], 0
	v_mfma_f32_16x16x32_bf16 v[40:43], v[164:167], v[196:199], 0
	v_mfma_f32_16x16x32_bf16 v[28:31], v[156:159], v[204:207], 0
	v_mfma_f32_16x16x32_bf16 v[24:27], v[164:167], v[204:207], 0
	v_mfma_f32_16x16x32_bf16 v[12:15], v[156:159], v[212:215], 0
	v_mfma_f32_16x16x32_bf16 v[8:11], v[164:167], v[212:215], 0
	v_mfma_f32_16x16x32_bf16 v[60:63], v[160:163], v[192:195], v[60:63]
	v_mfma_f32_16x16x32_bf16 v[56:59], v[168:171], v[192:195], v[56:59]
	v_mfma_f32_16x16x32_bf16 v[44:47], v[160:163], v[200:203], v[44:47]
	v_mfma_f32_16x16x32_bf16 v[40:43], v[168:171], v[200:203], v[40:43]
	v_mfma_f32_16x16x32_bf16 v[28:31], v[160:163], v[208:211], v[28:31]
	v_mfma_f32_16x16x32_bf16 v[24:27], v[168:171], v[208:211], v[24:27]
	v_mfma_f32_16x16x32_bf16 v[12:15], v[160:163], v[216:219], v[12:15]
	v_mfma_f32_16x16x32_bf16 v[8:11], v[168:171], v[216:219], v[8:11]
	s_setprio 0
	s_setprio 1
	v_mfma_f32_16x16x32_bf16 v[52:55], v[172:175], v[188:191], 0
	v_mfma_f32_16x16x32_bf16 v[48:51], v[180:183], v[188:191], 0
	v_mfma_f32_16x16x32_bf16 v[36:39], v[172:175], v[196:199], 0
	v_mfma_f32_16x16x32_bf16 v[32:35], v[180:183], v[196:199], 0
	v_mfma_f32_16x16x32_bf16 v[20:23], v[172:175], v[204:207], 0
	v_mfma_f32_16x16x32_bf16 v[16:19], v[180:183], v[204:207], 0
	v_mfma_f32_16x16x32_bf16 v[4:7], v[172:175], v[212:215], 0
	v_mfma_f32_16x16x32_bf16 v[0:3], v[180:183], v[212:215], 0
	v_mfma_f32_16x16x32_bf16 v[52:55], v[176:179], v[192:195], v[52:55]
	v_mfma_f32_16x16x32_bf16 v[48:51], v[184:187], v[192:195], v[48:51]
	v_mfma_f32_16x16x32_bf16 v[36:39], v[176:179], v[200:203], v[36:39]
	v_mfma_f32_16x16x32_bf16 v[32:35], v[184:187], v[200:203], v[32:35]
	v_mfma_f32_16x16x32_bf16 v[20:23], v[176:179], v[208:211], v[20:23]
	v_mfma_f32_16x16x32_bf16 v[16:19], v[184:187], v[208:211], v[16:19]
	v_mfma_f32_16x16x32_bf16 v[4:7], v[176:179], v[216:219], v[4:7]
	v_mfma_f32_16x16x32_bf16 v[0:3], v[184:187], v[216:219], v[0:3]
	s_setprio 0
	s_barrier
; #define PG8_STAGE(bufoff, gbase, voff) do { _Pragma("unroll") for (int _i = 0; _i < 2; ++_i) \
;         __builtin_amdgcn_global_load_lds((const unsigned*)((const char*)(gbase) + (voff)[_i]), (PG8_LAS unsigned*)(lds + (bufoff) + ldsw + _i * 8192), 16, 0, 0); } while (0)
; #define PG8_LDA(dst, b, h) do { _Pragma("unroll") for (int m = 0; m < 4; ++m) _Pragma("unroll") for (int k = 0; k < 2; ++k) dst[m][k] = *(const PG8_LAS bf16x8*)(lds + PG8_SA(b, h) + aoff + m * 2048 + k * 1024); } while (0)
; #define PG8_LDB(dst, b, h) do { _Pragma("unroll") for (int n = 0; n < 2; ++n) _Pragma("unroll") for (int k = 0; k < 2; ++k) dst[n][k] = *(const PG8_LAS bf16x8*)(lds + PG8_SB(b, h) + boff + n * 2048 + k * 1024); } while (0)
; #define PG8_MMA(ai, bj, At, Bt) do { __builtin_amdgcn_s_setprio(1); _Pragma("unroll") for (int m = 0; m < 4; ++m) _Pragma("unroll") for (int n = 0; n < 2; ++n) _Pragma("unroll") for (int k = 0; k < 2; ++k) \
;         acc[ai][bj][m][n] = __builtin_amdgcn_mfma_f32_16x16x32_bf16(Bt[n][k], At[m][k], acc[ai][bj][m][n], 0, 0, 0); __builtin_amdgcn_s_setprio(0); } while (0)
; #define PG8_WAIT_V(n) asm volatile("s_waitcnt vmcnt(" #n ")" ::: "memory")
; #define PG8_WAIT_L(n) asm volatile("s_waitcnt lgkmcnt(" #n ")" ::: "memory")
; #define PG8_BAR __builtin_amdgcn_s_barrier()
; #define PG8_SCHED __builtin_amdgcn_sched_barrier(0)
; template <class Epi, class Sched, bool ALIGN_EPI = false, bool SP2 = false>
; __device__ __forceinline__ void gemm_phase(PG8_LAS unsigned char* lds, const Gemm g, const Sched& S, const Epi& E) {
;     ...
;             PG8_LDB(B0, 1, 0); PG8_LDB(B1, 1, 1); PG8_SCHED; PG8_LDA(At, 1, 0); PG8_STAGE(PG8_SA(0, 1), a2 + hstep, voffA);
;             PG8_WAIT_V(8); PG8_WAIT_L(0); PG8_BAR; PG8_MMA(0, 0, At, B0); PG8_MMA(0, 1, At, B1); PG8_BAR; PG8_SCHED;
;             PG8_LDA(At, 1, 1); PG8_STAGE(PG8_SB(1, 0), b3, voffB); PG8_STAGE(PG8_SB(1, 1), b3 + hstep, voffB); PG8_STAGE(PG8_SA(1, 0), a3, voffA);
;             PG8_WAIT_V(8); PG8_WAIT_L(0); PG8_BAR; PG8_MMA(1, 0, At, B0); PG8_MMA(1, 1, At, B1); PG8_BAR; PG8_SCHED;
	ds_read_b128 v[156:159], v148
	ds_read_b128 v[160:163], v149
	ds_read_b128 v[164:167], v150
	ds_read_b128 v[168:171], v151
	ds_read_b128 v[172:175], v152
	ds_read_b128 v[176:179], v153
	ds_read_b128 v[180:183], v154
	ds_read_b128 v[184:187], v155
	s_add_u32 s62, s68, 0xb0000
	s_addc_u32 s63, s69, 0
	s_mov_b32 m0, s43
	v_lshl_add_u64 v[230:231], s[62:63], 0, v[130:131]
	ds_read_b128 v[188:191], v138 offset:32768
	ds_read_b128 v[192:195], v138 offset:33792
	ds_read_b128 v[196:199], v138 offset:34816
	ds_read_b128 v[200:203], v138 offset:35840
	ds_read_b128 v[204:207], v138 offset:36864
	ds_read_b128 v[208:211], v138 offset:37888
	ds_read_b128 v[212:215], v138 offset:38912
	ds_read_b128 v[216:219], v138 offset:39936
	global_load_lds_dwordx4 v[230:231], off
	s_mov_b32 m0, s70
	v_lshl_add_u64 v[230:231], s[62:63], 0, v[128:129]
	global_load_lds_dwordx4 v[230:231], off
	s_waitcnt vmcnt(8)
	s_waitcnt lgkmcnt(0)
	s_barrier
	s_setprio 1
	s_waitcnt lgkmcnt(0)
	v_mfma_f32_16x16x32_bf16 v[124:127], v[156:159], v[188:191], v[124:127]
	v_mfma_f32_16x16x32_bf16 v[120:123], v[164:167], v[188:191], v[120:123]
	v_mfma_f32_16x16x32_bf16 v[108:111], v[156:159], v[196:199], v[108:111]
	v_mfma_f32_16x16x32_bf16 v[104:107], v[164:167], v[196:199], v[104:107]
	v_mfma_f32_16x16x32_bf16 v[92:95], v[156:159], v[204:207], v[92:95]
	v_mfma_f32_16x16x32_bf16 v[88:91], v[164:167], v[204:207], v[88:91]
	v_mfma_f32_16x16x32_bf16 v[76:79], v[156:159], v[212:215], v[76:79]
	v_mfma_f32_16x16x32_bf16 v[72:75], v[164:167], v[212:215], v[72:75]
	v_mfma_f32_16x16x32_bf16 v[124:127], v[160:163], v[192:195], v[124:127]
	v_mfma_f32_16x16x32_bf16 v[120:123], v[168:171], v[192:195], v[120:123]
	v_mfma_f32_16x16x32_bf16 v[108:111], v[160:163], v[200:203], v[108:111]
	v_mfma_f32_16x16x32_bf16 v[104:107], v[168:171], v[200:203], v[104:107]
	v_mfma_f32_16x16x32_bf16 v[92:95], v[160:163], v[208:211], v[92:95]
	v_mfma_f32_16x16x32_bf16 v[88:91], v[168:171], v[208:211], v[88:91]
	v_mfma_f32_16x16x32_bf16 v[76:79], v[160:163], v[216:219], v[76:79]
	v_mfma_f32_16x16x32_bf16 v[72:75], v[168:171], v[216:219], v[72:75]
	s_setprio 0
	s_setprio 1
	v_mfma_f32_16x16x32_bf16 v[116:119], v[172:175], v[188:191], v[116:119]
	v_mfma_f32_16x16x32_bf16 v[112:115], v[180:183], v[188:191], v[112:115]
	v_mfma_f32_16x16x32_bf16 v[100:103], v[172:175], v[196:199], v[100:103]
	v_mfma_f32_16x16x32_bf16 v[96:99], v[180:183], v[196:199], v[96:99]
	v_mfma_f32_16x16x32_bf16 v[84:87], v[172:175], v[204:207], v[84:87]
	v_mfma_f32_16x16x32_bf16 v[80:83], v[180:183], v[204:207], v[80:83]
	v_mfma_f32_16x16x32_bf16 v[68:71], v[172:175], v[212:215], v[68:71]
	v_mfma_f32_16x16x32_bf16 v[64:67], v[180:183], v[212:215], v[64:67]
	v_mfma_f32_16x16x32_bf16 v[116:119], v[176:179], v[192:195], v[116:119]
	v_mfma_f32_16x16x32_bf16 v[112:115], v[184:187], v[192:195], v[112:115]
	v_mfma_f32_16x16x32_bf16 v[100:103], v[176:179], v[200:203], v[100:103]
	v_mfma_f32_16x16x32_bf16 v[96:99], v[184:187], v[200:203], v[96:99]
	v_mfma_f32_16x16x32_bf16 v[84:87], v[176:179], v[208:211], v[84:87]
	v_mfma_f32_16x16x32_bf16 v[80:83], v[184:187], v[208:211], v[80:83]
	v_mfma_f32_16x16x32_bf16 v[68:71], v[176:179], v[216:219], v[68:71]
	v_mfma_f32_16x16x32_bf16 v[64:67], v[184:187], v[216:219], v[64:67]
	s_setprio 0
	s_barrier
	s_mov_b32 m0, s72
	v_lshl_add_u64 v[220:221], v[220:221], 0, s[40:41]
	s_add_u32 s62, s66, 0xb0080
	ds_read_b128 v[188:191], v138 offset:49152
	ds_read_b128 v[192:195], v138 offset:50176
	ds_read_b128 v[196:199], v138 offset:51200
	ds_read_b128 v[200:203], v138 offset:52224
	ds_read_b128 v[204:207], v138 offset:53248
	ds_read_b128 v[208:211], v138 offset:54272
	ds_read_b128 v[212:215], v138 offset:55296
	ds_read_b128 v[216:219], v138 offset:56320
	global_load_lds_dwordx4 v[220:221], off
	v_lshl_add_u64 v[220:221], v[224:225], 0, s[40:41]
	s_mov_b32 m0, s73
	s_addc_u32 s63, s67, 0
	global_load_lds_dwordx4 v[220:221], off
	s_mov_b32 m0, s76
	v_lshl_add_u64 v[220:221], s[62:63], 0, v[130:131]
	global_load_lds_dwordx4 v[220:221], off
	s_mov_b32 m0, s77
	v_lshl_add_u64 v[220:221], s[62:63], 0, v[128:129]
	global_load_lds_dwordx4 v[220:221], off
	s_mov_b32 m0, s74
	v_lshl_add_u64 v[220:221], v[226:227], 0, s[40:41]
	global_load_lds_dwordx4 v[220:221], off
	s_mov_b32 m0, s75
	v_lshl_add_u64 v[220:221], v[228:229], 0, s[40:41]
	global_load_lds_dwordx4 v[220:221], off
	s_waitcnt vmcnt(8)
	s_waitcnt lgkmcnt(0)
	s_barrier
	s_setprio 1
	s_waitcnt lgkmcnt(0)
	v_mfma_f32_16x16x32_bf16 v[60:63], v[156:159], v[188:191], v[60:63]
	v_mfma_f32_16x16x32_bf16 v[56:59], v[164:167], v[188:191], v[56:59]
	v_mfma_f32_16x16x32_bf16 v[44:47], v[156:159], v[196:199], v[44:47]
	v_mfma_f32_16x16x32_bf16 v[40:43], v[164:167], v[196:199], v[40:43]
	v_mfma_f32_16x16x32_bf16 v[28:31], v[156:159], v[204:207], v[28:31]
	v_mfma_f32_16x16x32_bf16 v[24:27], v[164:167], v[204:207], v[24:27]
	v_mfma_f32_16x16x32_bf16 v[12:15], v[156:159], v[212:215], v[12:15]
	v_mfma_f32_16x16x32_bf16 v[8:11], v[164:167], v[212:215], v[8:11]
	v_mfma_f32_16x16x32_bf16 v[60:63], v[160:163], v[192:195], v[60:63]
	v_mfma_f32_16x16x32_bf16 v[56:59], v[168:171], v[192:195], v[56:59]
	v_mfma_f32_16x16x32_bf16 v[44:47], v[160:163], v[200:203], v[44:47]
	v_mfma_f32_16x16x32_bf16 v[40:43], v[168:171], v[200:203], v[40:43]
	v_mfma_f32_16x16x32_bf16 v[28:31], v[160:163], v[208:211], v[28:31]
	v_mfma_f32_16x16x32_bf16 v[24:27], v[168:171], v[208:211], v[24:27]
	v_mfma_f32_16x16x32_bf16 v[12:15], v[160:163], v[216:219], v[12:15]
	v_mfma_f32_16x16x32_bf16 v[8:11], v[168:171], v[216:219], v[8:11]
	s_setprio 0
	s_setprio 1
	v_mfma_f32_16x16x32_bf16 v[52:55], v[172:175], v[188:191], v[52:55]
	v_mfma_f32_16x16x32_bf16 v[48:51], v[180:183], v[188:191], v[48:51]
	v_mfma_f32_16x16x32_bf16 v[36:39], v[172:175], v[196:199], v[36:39]
	v_mfma_f32_16x16x32_bf16 v[32:35], v[180:183], v[196:199], v[32:35]
	v_mfma_f32_16x16x32_bf16 v[20:23], v[172:175], v[204:207], v[20:23]
	v_mfma_f32_16x16x32_bf16 v[16:19], v[180:183], v[204:207], v[16:19]
	v_mfma_f32_16x16x32_bf16 v[4:7], v[172:175], v[212:215], v[4:7]
	v_mfma_f32_16x16x32_bf16 v[0:3], v[180:183], v[212:215], v[0:3]
	v_mfma_f32_16x16x32_bf16 v[52:55], v[176:179], v[192:195], v[52:55]
	v_mfma_f32_16x16x32_bf16 v[48:51], v[184:187], v[192:195], v[48:51]
	v_mfma_f32_16x16x32_bf16 v[36:39], v[176:179], v[200:203], v[36:39]
	v_mfma_f32_16x16x32_bf16 v[32:35], v[184:187], v[200:203], v[32:35]
	v_mfma_f32_16x16x32_bf16 v[20:23], v[176:179], v[208:211], v[20:23]
	v_mfma_f32_16x16x32_bf16 v[16:19], v[184:187], v[208:211], v[16:19]
	v_mfma_f32_16x16x32_bf16 v[4:7], v[176:179], v[216:219], v[4:7]
	v_mfma_f32_16x16x32_bf16 v[0:3], v[184:187], v[216:219], v[0:3]
	s_setprio 0
	s_barrier
	s_add_u32 s33, s33, 0x100
	s_addc_u32 s55, s55, 0
	s_mov_b64 s[62:63], s[64:65]
	s_mov_b32 s57, s86
; #define PG8_STAGE(bufoff, gbase, voff) do { _Pragma("unroll") for (int _i = 0; _i < 2; ++_i) \
;         __builtin_amdgcn_global_load_lds((const unsigned*)((const char*)(gbase) + (voff)[_i]), (PG8_LAS unsigned*)(lds + (bufoff) + ldsw + _i * 8192), 16, 0, 0); } while (0)
; #define PG8_LDA(dst, b, h) do { _Pragma("unroll") for (int m = 0; m < 4; ++m) _Pragma("unroll") for (int k = 0; k < 2; ++k) dst[m][k] = *(const PG8_LAS bf16x8*)(lds + PG8_SA(b, h) + aoff + m * 2048 + k * 1024); } while (0)
; #define PG8_LDB(dst, b, h) do { _Pragma("unroll") for (int n = 0; n < 2; ++n) _Pragma("unroll") for (int k = 0; k < 2; ++k) dst[n][k] = *(const PG8_LAS bf16x8*)(lds + PG8_SB(b, h) + boff + n * 2048 + k * 1024); } while (0)
; #define PG8_MMA(ai, bj, At, Bt) do { __builtin_amdgcn_s_setprio(1); _Pragma("unroll") for (int m = 0; m < 4; ++m) _Pragma("unroll") for (int n = 0; n < 2; ++n) _Pragma("unroll") for (int k = 0; k < 2; ++k) \
;         acc[ai][bj][m][n] = __builtin_amdgcn_mfma_f32_16x16x32_bf16(Bt[n][k], At[m][k], acc[ai][bj][m][n], 0, 0, 0); __builtin_amdgcn_s_setprio(0); } while (0)
; #define PG8_WAIT_V(n) asm volatile("s_waitcnt vmcnt(" #n ")" ::: "memory")
; #define PG8_WAIT_L(n) asm volatile("s_waitcnt lgkmcnt(" #n ")" ::: "memory")
; #define PG8_BAR __builtin_amdgcn_s_barrier()
; #define PG8_SCHED __builtin_amdgcn_sched_barrier(0)
; template <class Epi, class Sched, bool ALIGN_EPI = false, bool SP2 = false>
; __device__ __forceinline__ void gemm_phase(PG8_LAS unsigned char* lds, const Gemm g, const Sched& S, const Epi& E) {
;     ...
;             PG8_LDB(B0, 0, 0); PG8_LDB(B1, 0, 1); PG8_SCHED; PG8_LDA(At, 0, 0); PG8_STAGE(PG8_SA(1, 1), a1 + hstep, voffA);
;             PG8_WAIT_V(8); PG8_WAIT_L(0); PG8_BAR; PG8_MMA(0, 0, At, B0); PG8_MMA(0, 1, At, B1); PG8_BAR; PG8_SCHED;
;             PG8_LDA(At, 0, 1); PG8_STAGE(PG8_SB(0, 0), b2, voffB); PG8_STAGE(PG8_SB(0, 1), b2 + hstep, voffB); PG8_STAGE(PG8_SA(0, 0), a2, voffA);
.LBB0_896:
	ds_read_b128 v[156:159], v140
	ds_read_b128 v[160:163], v141
	ds_read_b128 v[164:167], v142
	ds_read_b128 v[168:171], v143
	ds_read_b128 v[172:175], v144
	ds_read_b128 v[176:179], v145
	ds_read_b128 v[180:183], v146
	ds_read_b128 v[184:187], v147
	s_add_i32 s86, s57, 2
	s_add_u32 s64, s62, 0x100
	s_addc_u32 s65, s63, 0
	s_cmp_eq_u32 s78, s57
	s_cselect_b32 s69, s59, s65
	s_cselect_b32 s68, s58, s64
	s_cselect_b32 s67, s61, s55
	s_cselect_b32 s66, s60, s33
	s_mov_b32 m0, s79
	v_lshl_add_u64 v[220:221], s[62:63], 0, v[134:135]
	ds_read_b128 v[188:191], v138
	ds_read_b128 v[192:195], v138 offset:1024
	ds_read_b128 v[196:199], v138 offset:2048
	ds_read_b128 v[200:203], v138 offset:3072
	ds_read_b128 v[204:207], v138 offset:4096
	ds_read_b128 v[208:211], v138 offset:5120
	ds_read_b128 v[212:215], v138 offset:6144
	ds_read_b128 v[216:219], v138 offset:7168
	global_load_lds_dwordx4 v[220:221], off
	s_mov_b32 m0, s80
	v_lshl_add_u64 v[220:221], s[62:63], 0, v[136:137]
	global_load_lds_dwordx4 v[220:221], off
	s_waitcnt vmcnt(8)
	s_waitcnt lgkmcnt(0)
	s_barrier
	s_setprio 1
	s_waitcnt lgkmcnt(0)
	v_mfma_f32_16x16x32_bf16 v[124:127], v[156:159], v[188:191], v[124:127]
	v_mfma_f32_16x16x32_bf16 v[120:123], v[164:167], v[188:191], v[120:123]
	v_mfma_f32_16x16x32_bf16 v[108:111], v[156:159], v[196:199], v[108:111]
	v_mfma_f32_16x16x32_bf16 v[104:107], v[164:167], v[196:199], v[104:107]
	v_mfma_f32_16x16x32_bf16 v[92:95], v[156:159], v[204:207], v[92:95]
	v_mfma_f32_16x16x32_bf16 v[88:91], v[164:167], v[204:207], v[88:91]
	v_mfma_f32_16x16x32_bf16 v[76:79], v[156:159], v[212:215], v[76:79]
	v_mfma_f32_16x16x32_bf16 v[72:75], v[164:167], v[212:215], v[72:75]
	v_mfma_f32_16x16x32_bf16 v[124:127], v[160:163], v[192:195], v[124:127]
	v_mfma_f32_16x16x32_bf16 v[120:123], v[168:171], v[192:195], v[120:123]
	v_mfma_f32_16x16x32_bf16 v[108:111], v[160:163], v[200:203], v[108:111]
	v_mfma_f32_16x16x32_bf16 v[104:107], v[168:171], v[200:203], v[104:107]
	v_mfma_f32_16x16x32_bf16 v[92:95], v[160:163], v[208:211], v[92:95]
	v_mfma_f32_16x16x32_bf16 v[88:91], v[168:171], v[208:211], v[88:91]
	v_mfma_f32_16x16x32_bf16 v[76:79], v[160:163], v[216:219], v[76:79]
	v_mfma_f32_16x16x32_bf16 v[72:75], v[168:171], v[216:219], v[72:75]
	s_setprio 0
	s_setprio 1
	v_mfma_f32_16x16x32_bf16 v[116:119], v[172:175], v[188:191], v[116:119]
	v_mfma_f32_16x16x32_bf16 v[112:115], v[180:183], v[188:191], v[112:115]
	v_mfma_f32_16x16x32_bf16 v[100:103], v[172:175], v[196:199], v[100:103]
	v_mfma_f32_16x16x32_bf16 v[96:99], v[180:183], v[196:199], v[96:99]
	v_mfma_f32_16x16x32_bf16 v[84:87], v[172:175], v[204:207], v[84:87]
	v_mfma_f32_16x16x32_bf16 v[80:83], v[180:183], v[204:207], v[80:83]
	v_mfma_f32_16x16x32_bf16 v[68:71], v[172:175], v[212:215], v[68:71]
	v_mfma_f32_16x16x32_bf16 v[64:67], v[180:183], v[212:215], v[64:67]
	v_mfma_f32_16x16x32_bf16 v[116:119], v[176:179], v[192:195], v[116:119]
	v_mfma_f32_16x16x32_bf16 v[112:115], v[184:187], v[192:195], v[112:115]
	v_mfma_f32_16x16x32_bf16 v[100:103], v[176:179], v[200:203], v[100:103]
	v_mfma_f32_16x16x32_bf16 v[96:99], v[184:187], v[200:203], v[96:99]
	v_mfma_f32_16x16x32_bf16 v[84:87], v[176:179], v[208:211], v[84:87]
	v_mfma_f32_16x16x32_bf16 v[80:83], v[184:187], v[208:211], v[80:83]
	v_mfma_f32_16x16x32_bf16 v[68:71], v[176:179], v[216:219], v[68:71]
	v_mfma_f32_16x16x32_bf16 v[64:67], v[184:187], v[216:219], v[64:67]
	s_setprio 0
	s_barrier
	s_mov_b32 m0, s12
	v_lshl_add_u64 v[220:221], s[66:67], 0, v[130:131]
	s_add_u32 s62, s66, 0xb0000
	ds_read_b128 v[188:191], v138 offset:16384
	ds_read_b128 v[192:195], v138 offset:17408
	ds_read_b128 v[196:199], v138 offset:18432
	ds_read_b128 v[200:203], v138 offset:19456
	ds_read_b128 v[204:207], v138 offset:20480
	ds_read_b128 v[208:211], v138 offset:21504
	ds_read_b128 v[212:215], v138 offset:22528
	ds_read_b128 v[216:219], v138 offset:23552
	global_load_lds_dwordx4 v[220:221], off
	v_lshl_add_u64 v[224:225], s[66:67], 0, v[128:129]
	s_mov_b32 m0, s13
	s_addc_u32 s63, s67, 0
	global_load_lds_dwordx4 v[224:225], off
	v_lshl_add_u64 v[226:227], s[62:63], 0, v[130:131]
	s_mov_b32 m0, s14
	v_lshl_add_u64 v[228:229], s[68:69], 0, v[128:129]
	global_load_lds_dwordx4 v[226:227], off
	s_mov_b32 m0, s15
	v_lshl_add_u64 v[226:227], s[62:63], 0, v[128:129]
	global_load_lds_dwordx4 v[226:227], off
	s_mov_b32 m0, s5
	v_lshl_add_u64 v[226:227], s[68:69], 0, v[130:131]
	global_load_lds_dwordx4 v[226:227], off
	s_mov_b32 m0, s39
	s_nop 0
	global_load_lds_dwordx4 v[228:229], off
	s_waitcnt vmcnt(8)
	s_waitcnt lgkmcnt(0)
	s_barrier
; #define PG8_STAGE(bufoff, gbase, voff) do { _Pragma("unroll") for (int _i = 0; _i < 2; ++_i) \
;         __builtin_amdgcn_global_load_lds((const unsigned*)((const char*)(gbase) + (voff)[_i]), (PG8_LAS unsigned*)(lds + (bufoff) + ldsw + _i * 8192), 16, 0, 0); } while (0)
; #define PG8_LDA(dst, b, h) do { _Pragma("unroll") for (int m = 0; m < 4; ++m) _Pragma("unroll") for (int k = 0; k < 2; ++k) dst[m][k] = *(const PG8_LAS bf16x8*)(lds + PG8_SA(b, h) + aoff + m * 2048 + k * 1024); } while (0)
; #define PG8_LDB(dst, b, h) do { _Pragma("unroll") for (int n = 0; n < 2; ++n) _Pragma("unroll") for (int k = 0; k < 2; ++k) dst[n][k] = *(const PG8_LAS bf16x8*)(lds + PG8_SB(b, h) + boff + n * 2048 + k * 1024); } while (0)
; #define PG8_MMA(ai, bj, At, Bt) do { __builtin_amdgcn_s_setprio(1); _Pragma("unroll") for (int m = 0; m < 4; ++m) _Pragma("unroll") for (int n = 0; n < 2; ++n) _Pragma("unroll") for (int k = 0; k < 2; ++k) \
;         acc[ai][bj][m][n] = __builtin_amdgcn_mfma_f32_16x16x32_bf16(Bt[n][k], At[m][k], acc[ai][bj][m][n], 0, 0, 0); __builtin_amdgcn_s_setprio(0); } while (0)
; #define PG8_WAIT_V(n) asm volatile("s_waitcnt vmcnt(" #n ")" ::: "memory")
; #define PG8_WAIT_L(n) asm volatile("s_waitcnt lgkmcnt(" #n ")" ::: "memory")
; #define PG8_BAR __builtin_amdgcn_s_barrier()
; #define PG8_SCHED __builtin_amdgcn_sched_barrier(0)
; template <class Epi, class Sched, bool ALIGN_EPI = false, bool SP2 = false>
; __device__ __forceinline__ void gemm_phase(PG8_LAS unsigned char* lds, const Gemm g, const Sched& S, const Epi& E) {
;     ...
;             PG8_WAIT_V(8); PG8_WAIT_L(0); PG8_BAR; PG8_MMA(1, 0, At, B0); PG8_MMA(1, 1, At, B1); PG8_BAR; PG8_SCHED;
;             PG8_LDB(B0, 1, 0); PG8_LDB(B1, 1, 1); PG8_SCHED; PG8_LDA(At, 1, 0); PG8_STAGE(PG8_SA(0, 1), a2 + hstep, voffA);
;             PG8_WAIT_V(8); PG8_WAIT_L(0); PG8_BAR; PG8_MMA(0, 0, At, B0); PG8_MMA(0, 1, At, B1); PG8_BAR; PG8_SCHED;
	s_setprio 1
	s_waitcnt lgkmcnt(0)
	v_mfma_f32_16x16x32_bf16 v[60:63], v[156:159], v[188:191], v[60:63]
	v_mfma_f32_16x16x32_bf16 v[56:59], v[164:167], v[188:191], v[56:59]
	v_mfma_f32_16x16x32_bf16 v[44:47], v[156:159], v[196:199], v[44:47]
	v_mfma_f32_16x16x32_bf16 v[40:43], v[164:167], v[196:199], v[40:43]
	v_mfma_f32_16x16x32_bf16 v[28:31], v[156:159], v[204:207], v[28:31]
	v_mfma_f32_16x16x32_bf16 v[24:27], v[164:167], v[204:207], v[24:27]
	v_mfma_f32_16x16x32_bf16 v[12:15], v[156:159], v[212:215], v[12:15]
	v_mfma_f32_16x16x32_bf16 v[8:11], v[164:167], v[212:215], v[8:11]
	v_mfma_f32_16x16x32_bf16 v[60:63], v[160:163], v[192:195], v[60:63]
	v_mfma_f32_16x16x32_bf16 v[56:59], v[168:171], v[192:195], v[56:59]
	v_mfma_f32_16x16x32_bf16 v[44:47], v[160:163], v[200:203], v[44:47]
	v_mfma_f32_16x16x32_bf16 v[40:43], v[168:171], v[200:203], v[40:43]
	v_mfma_f32_16x16x32_bf16 v[28:31], v[160:163], v[208:211], v[28:31]
	v_mfma_f32_16x16x32_bf16 v[24:27], v[168:171], v[208:211], v[24:27]
	v_mfma_f32_16x16x32_bf16 v[12:15], v[160:163], v[216:219], v[12:15]
	v_mfma_f32_16x16x32_bf16 v[8:11], v[168:171], v[216:219], v[8:11]
	s_setprio 0
	s_setprio 1
	v_mfma_f32_16x16x32_bf16 v[52:55], v[172:175], v[188:191], v[52:55]
	v_mfma_f32_16x16x32_bf16 v[48:51], v[180:183], v[188:191], v[48:51]
	v_mfma_f32_16x16x32_bf16 v[36:39], v[172:175], v[196:199], v[36:39]
	v_mfma_f32_16x16x32_bf16 v[32:35], v[180:183], v[196:199], v[32:35]
	v_mfma_f32_16x16x32_bf16 v[20:23], v[172:175], v[204:207], v[20:23]
	v_mfma_f32_16x16x32_bf16 v[16:19], v[180:183], v[204:207], v[16:19]
	v_mfma_f32_16x16x32_bf16 v[4:7], v[172:175], v[212:215], v[4:7]
	v_mfma_f32_16x16x32_bf16 v[0:3], v[180:183], v[212:215], v[0:3]
	v_mfma_f32_16x16x32_bf16 v[52:55], v[176:179], v[192:195], v[52:55]
	v_mfma_f32_16x16x32_bf16 v[48:51], v[184:187], v[192:195], v[48:51]
	v_mfma_f32_16x16x32_bf16 v[36:39], v[176:179], v[200:203], v[36:39]
	v_mfma_f32_16x16x32_bf16 v[32:35], v[184:187], v[200:203], v[32:35]
	v_mfma_f32_16x16x32_bf16 v[20:23], v[176:179], v[208:211], v[20:23]
	v_mfma_f32_16x16x32_bf16 v[16:19], v[184:187], v[208:211], v[16:19]
	v_mfma_f32_16x16x32_bf16 v[4:7], v[176:179], v[216:219], v[4:7]
	v_mfma_f32_16x16x32_bf16 v[0:3], v[184:187], v[216:219], v[0:3]
	s_setprio 0
	s_barrier
	ds_read_b128 v[156:159], v148
	ds_read_b128 v[160:163], v149
	ds_read_b128 v[164:167], v150
	ds_read_b128 v[168:171], v151
	ds_read_b128 v[172:175], v152
	ds_read_b128 v[176:179], v153
	ds_read_b128 v[180:183], v154
	ds_read_b128 v[184:187], v155
	s_add_u32 s62, s68, 0xb0000
	s_addc_u32 s63, s69, 0
	s_mov_b32 m0, s43
	v_lshl_add_u64 v[230:231], s[62:63], 0, v[130:131]
	ds_read_b128 v[188:191], v138 offset:32768
	ds_read_b128 v[192:195], v138 offset:33792
	ds_read_b128 v[196:199], v138 offset:34816
	ds_read_b128 v[200:203], v138 offset:35840
	ds_read_b128 v[204:207], v138 offset:36864
	ds_read_b128 v[208:211], v138 offset:37888
	ds_read_b128 v[212:215], v138 offset:38912
	ds_read_b128 v[216:219], v138 offset:39936
	global_load_lds_dwordx4 v[230:231], off
	s_mov_b32 m0, s70
	v_lshl_add_u64 v[230:231], s[62:63], 0, v[128:129]
	global_load_lds_dwordx4 v[230:231], off
	s_waitcnt vmcnt(8)
	s_waitcnt lgkmcnt(0)
	s_barrier
	s_setprio 1
	s_waitcnt lgkmcnt(0)
	v_mfma_f32_16x16x32_bf16 v[124:127], v[156:159], v[188:191], v[124:127]
	v_mfma_f32_16x16x32_bf16 v[120:123], v[164:167], v[188:191], v[120:123]
	v_mfma_f32_16x16x32_bf16 v[108:111], v[156:159], v[196:199], v[108:111]
	v_mfma_f32_16x16x32_bf16 v[104:107], v[164:167], v[196:199], v[104:107]
	v_mfma_f32_16x16x32_bf16 v[92:95], v[156:159], v[204:207], v[92:95]
	v_mfma_f32_16x16x32_bf16 v[88:91], v[164:167], v[204:207], v[88:91]
	v_mfma_f32_16x16x32_bf16 v[76:79], v[156:159], v[212:215], v[76:79]
	v_mfma_f32_16x16x32_bf16 v[72:75], v[164:167], v[212:215], v[72:75]
	v_mfma_f32_16x16x32_bf16 v[124:127], v[160:163], v[192:195], v[124:127]
	v_mfma_f32_16x16x32_bf16 v[120:123], v[168:171], v[192:195], v[120:123]
	v_mfma_f32_16x16x32_bf16 v[108:111], v[160:163], v[200:203], v[108:111]
	v_mfma_f32_16x16x32_bf16 v[104:107], v[168:171], v[200:203], v[104:107]
	v_mfma_f32_16x16x32_bf16 v[92:95], v[160:163], v[208:211], v[92:95]
	v_mfma_f32_16x16x32_bf16 v[88:91], v[168:171], v[208:211], v[88:91]
	v_mfma_f32_16x16x32_bf16 v[76:79], v[160:163], v[216:219], v[76:79]
	v_mfma_f32_16x16x32_bf16 v[72:75], v[168:171], v[216:219], v[72:75]
	s_setprio 0
	s_setprio 1
	v_mfma_f32_16x16x32_bf16 v[116:119], v[172:175], v[188:191], v[116:119]
	v_mfma_f32_16x16x32_bf16 v[112:115], v[180:183], v[188:191], v[112:115]
	v_mfma_f32_16x16x32_bf16 v[100:103], v[172:175], v[196:199], v[100:103]
	v_mfma_f32_16x16x32_bf16 v[96:99], v[180:183], v[196:199], v[96:99]
	v_mfma_f32_16x16x32_bf16 v[84:87], v[172:175], v[204:207], v[84:87]
	v_mfma_f32_16x16x32_bf16 v[80:83], v[180:183], v[204:207], v[80:83]
	v_mfma_f32_16x16x32_bf16 v[68:71], v[172:175], v[212:215], v[68:71]
	v_mfma_f32_16x16x32_bf16 v[64:67], v[180:183], v[212:215], v[64:67]
	v_mfma_f32_16x16x32_bf16 v[116:119], v[176:179], v[192:195], v[116:119]
	v_mfma_f32_16x16x32_bf16 v[112:115], v[184:187], v[192:195], v[112:115]
	v_mfma_f32_16x16x32_bf16 v[100:103], v[176:179], v[200:203], v[100:103]
	v_mfma_f32_16x16x32_bf16 v[96:99], v[184:187], v[200:203], v[96:99]
	v_mfma_f32_16x16x32_bf16 v[84:87], v[176:179], v[208:211], v[84:87]
	v_mfma_f32_16x16x32_bf16 v[80:83], v[184:187], v[208:211], v[80:83]
	v_mfma_f32_16x16x32_bf16 v[68:71], v[176:179], v[216:219], v[68:71]
	v_mfma_f32_16x16x32_bf16 v[64:67], v[184:187], v[216:219], v[64:67]
	s_setprio 0
	s_barrier
; #define PG8_STAGE(bufoff, gbase, voff) do { _Pragma("unroll") for (int _i = 0; _i < 2; ++_i) \
;         __builtin_amdgcn_global_load_lds((const unsigned*)((const char*)(gbase) + (voff)[_i]), (PG8_LAS unsigned*)(lds + (bufoff) + ldsw + _i * 8192), 16, 0, 0); } while (0)
; #define PG8_LDA(dst, b, h) do { _Pragma("unroll") for (int m = 0; m < 4; ++m) _Pragma("unroll") for (int k = 0; k < 2; ++k) dst[m][k] = *(const PG8_LAS bf16x8*)(lds + PG8_SA(b, h) + aoff + m * 2048 + k * 1024); } while (0)
; #define PG8_MMA(ai, bj, At, Bt) do { __builtin_amdgcn_s_setprio(1); _Pragma("unroll") for (int m = 0; m < 4; ++m) _Pragma("unroll") for (int n = 0; n < 2; ++n) _Pragma("unroll") for (int k = 0; k < 2; ++k) \
;         acc[ai][bj][m][n] = __builtin_amdgcn_mfma_f32_16x16x32_bf16(Bt[n][k], At[m][k], acc[ai][bj][m][n], 0, 0, 0); __builtin_amdgcn_s_setprio(0); } while (0)
; #define PG8_WAIT_V(n) asm volatile("s_waitcnt vmcnt(" #n ")" ::: "memory")
; #define PG8_WAIT_L(n) asm volatile("s_waitcnt lgkmcnt(" #n ")" ::: "memory")
; #define PG8_BAR __builtin_amdgcn_s_barrier()
; #define PG8_SCHED __builtin_amdgcn_sched_barrier(0)
; template <class Epi, class Sched, bool ALIGN_EPI = false, bool SP2 = false>
; __device__ __forceinline__ void gemm_phase(PG8_LAS unsigned char* lds, const Gemm g, const Sched& S, const Epi& E) {
;     ...
;             PG8_LDA(At, 1, 1); PG8_STAGE(PG8_SB(1, 0), b3, voffB); PG8_STAGE(PG8_SB(1, 1), b3 + hstep, voffB); PG8_STAGE(PG8_SA(1, 0), a3, voffA);
;             PG8_WAIT_V(8); PG8_WAIT_L(0); PG8_BAR; PG8_MMA(1, 0, At, B0); PG8_MMA(1, 1, At, B1); PG8_BAR; PG8_SCHED;
	s_mov_b32 m0, s72
	v_lshl_add_u64 v[220:221], v[220:221], 0, s[40:41]
	s_add_u32 s62, s66, 0xb0080
	ds_read_b128 v[188:191], v138 offset:49152
	ds_read_b128 v[192:195], v138 offset:50176
	ds_read_b128 v[196:199], v138 offset:51200
	ds_read_b128 v[200:203], v138 offset:52224
	ds_read_b128 v[204:207], v138 offset:53248
	ds_read_b128 v[208:211], v138 offset:54272
	ds_read_b128 v[212:215], v138 offset:55296
	ds_read_b128 v[216:219], v138 offset:56320
	global_load_lds_dwordx4 v[220:221], off
	v_lshl_add_u64 v[220:221], v[224:225], 0, s[40:41]
	s_mov_b32 m0, s73
	s_addc_u32 s63, s67, 0
	global_load_lds_dwordx4 v[220:221], off
	s_mov_b32 m0, s76
	v_lshl_add_u64 v[220:221], s[62:63], 0, v[130:131]
	global_load_lds_dwordx4 v[220:221], off
	s_mov_b32 m0, s77
	v_lshl_add_u64 v[220:221], s[62:63], 0, v[128:129]
	global_load_lds_dwordx4 v[220:221], off
	s_mov_b32 m0, s74
	v_lshl_add_u64 v[220:221], v[226:227], 0, s[40:41]
	global_load_lds_dwordx4 v[220:221], off
	s_mov_b32 m0, s75
	v_lshl_add_u64 v[220:221], v[228:229], 0, s[40:41]
	global_load_lds_dwordx4 v[220:221], off
	s_waitcnt vmcnt(8)
	s_waitcnt lgkmcnt(0)
	s_barrier
	s_setprio 1
	s_waitcnt lgkmcnt(0)
	v_mfma_f32_16x16x32_bf16 v[60:63], v[156:159], v[188:191], v[60:63]
	v_mfma_f32_16x16x32_bf16 v[56:59], v[164:167], v[188:191], v[56:59]
	v_mfma_f32_16x16x32_bf16 v[44:47], v[156:159], v[196:199], v[44:47]
	v_mfma_f32_16x16x32_bf16 v[40:43], v[164:167], v[196:199], v[40:43]
	v_mfma_f32_16x16x32_bf16 v[28:31], v[156:159], v[204:207], v[28:31]
	v_mfma_f32_16x16x32_bf16 v[24:27], v[164:167], v[204:207], v[24:27]
	v_mfma_f32_16x16x32_bf16 v[12:15], v[156:159], v[212:215], v[12:15]
	v_mfma_f32_16x16x32_bf16 v[8:11], v[164:167], v[212:215], v[8:11]
	v_mfma_f32_16x16x32_bf16 v[60:63], v[160:163], v[192:195], v[60:63]
	v_mfma_f32_16x16x32_bf16 v[56:59], v[168:171], v[192:195], v[56:59]
	v_mfma_f32_16x16x32_bf16 v[44:47], v[160:163], v[200:203], v[44:47]
	v_mfma_f32_16x16x32_bf16 v[40:43], v[168:171], v[200:203], v[40:43]
	v_mfma_f32_16x16x32_bf16 v[28:31], v[160:163], v[208:211], v[28:31]
	v_mfma_f32_16x16x32_bf16 v[24:27], v[168:171], v[208:211], v[24:27]
	v_mfma_f32_16x16x32_bf16 v[12:15], v[160:163], v[216:219], v[12:15]
	v_mfma_f32_16x16x32_bf16 v[8:11], v[168:171], v[216:219], v[8:11]
	s_setprio 0
	s_setprio 1
	v_mfma_f32_16x16x32_bf16 v[52:55], v[172:175], v[188:191], v[52:55]
	v_mfma_f32_16x16x32_bf16 v[48:51], v[180:183], v[188:191], v[48:51]
	v_mfma_f32_16x16x32_bf16 v[36:39], v[172:175], v[196:199], v[36:39]
	v_mfma_f32_16x16x32_bf16 v[32:35], v[180:183], v[196:199], v[32:35]
	v_mfma_f32_16x16x32_bf16 v[20:23], v[172:175], v[204:207], v[20:23]
	v_mfma_f32_16x16x32_bf16 v[16:19], v[180:183], v[204:207], v[16:19]
	v_mfma_f32_16x16x32_bf16 v[4:7], v[172:175], v[212:215], v[4:7]
	v_mfma_f32_16x16x32_bf16 v[0:3], v[180:183], v[212:215], v[0:3]
	v_mfma_f32_16x16x32_bf16 v[52:55], v[176:179], v[192:195], v[52:55]
	v_mfma_f32_16x16x32_bf16 v[48:51], v[184:187], v[192:195], v[48:51]
	v_mfma_f32_16x16x32_bf16 v[36:39], v[176:179], v[200:203], v[36:39]
	v_mfma_f32_16x16x32_bf16 v[32:35], v[184:187], v[200:203], v[32:35]
	v_mfma_f32_16x16x32_bf16 v[20:23], v[176:179], v[208:211], v[20:23]
	v_mfma_f32_16x16x32_bf16 v[16:19], v[184:187], v[208:211], v[16:19]
	v_mfma_f32_16x16x32_bf16 v[4:7], v[176:179], v[216:219], v[4:7]
	v_mfma_f32_16x16x32_bf16 v[0:3], v[184:187], v[216:219], v[0:3]
	s_setprio 0
	s_barrier
	s_add_u32 s33, s33, 0x100
	s_addc_u32 s55, s55, 0
	s_cmp_ge_i32 s86, s4
	s_mov_b64 s[62:63], s[64:65]
	s_mov_b32 s57, s86
	s_cbranch_scc0 .LBB0_896
	s_and_b64 vcc, exec, s[52:53]
	s_cbranch_vccz .LBB0_899

;     __host__ __device__ bool next(int i, Unit& u) const { const int L = i * G + c; if (L >= 16 * nkc) return false; u.kc = L % nkc; const int t = L / nkc; u.pn = t & 3; u.pm = 33 * (t >> 2); return true; }
; #define PG8_STAGE(bufoff, gbase, voff) do { _Pragma("unroll") for (int _i = 0; _i < 2; ++_i) \
;         __builtin_amdgcn_global_load_lds((const unsigned*)((const char*)(gbase) + (voff)[_i]), (PG8_LAS unsigned*)(lds + (bufoff) + ldsw + _i * 8192), 16, 0, 0); } while (0)
; #define PG8_LDA(dst, b, h) do { _Pragma("unroll") for (int m = 0; m < 4; ++m) _Pragma("unroll") for (int k = 0; k < 2; ++k) dst[m][k] = *(const PG8_LAS bf16x8*)(lds + PG8_SA(b, h) + aoff + m * 2048 + k * 1024); } while (0)
; #define PG8_LDB(dst, b, h) do { _Pragma("unroll") for (int n = 0; n < 2; ++n) _Pragma("unroll") for (int k = 0; k < 2; ++k) dst[n][k] = *(const PG8_LAS bf16x8*)(lds + PG8_SB(b, h) + boff + n * 2048 + k * 1024); } while (0)
; #define PG8_WAIT_V(n) asm volatile("s_waitcnt vmcnt(" #n ")" ::: "memory")
; #define PG8_WAIT_L(n) asm volatile("s_waitcnt lgkmcnt(" #n ")" ::: "memory")
; template <class Epi, class Sched, bool ALIGN_EPI = false, bool SP2 = false>
; __device__ __forceinline__ void gemm_phase(PG8_LAS unsigned char* lds, const Gemm g, const Sched& S, const Epi& E) {
;     ...
;         const bool has_next = S.next(ui + 1, nxt);
;         const char* nA = has_next ? (const char*)g.A + (size_t)nxt.pm * tstep + (size_t)nxt.kc * cstep : cA; const char* nB = has_next ? (const char*)g.Bt + (size_t)nxt.pn * tstep + (size_t)nxt.kc * cstep : cB;
;         for (int t = 0; t < nt; t += 2) {
;             const bool last = (t == nt - 2);
;             const char* a1 = cA + (size_t)(t + 1) * kstep;
;             const char* a2 = last ? nA : cA + (size_t)(t + 2) * kstep; const char* b2 = last ? nB : cB + (size_t)(t + 2) * kstep;
;             const char* a3 = a2 + kstep; const char* b3 = b2 + kstep;
;             if (last && has_next) S.a_ready(nxt);
;             if constexpr (SP2) {
;             PG8_LDB(B0, 0, 0); PG8_LDB(B1, 0, 1); PG8_SCHED; PG8_LDA(At, 0, 0); PG8_STAGE(PG8_SA(1, 1), a1 + hstep, voffA);
;             PG8_WAIT_V(8); PG8_WAIT_L(0); PG8_BAR; PG8_MMA(0, 0, At, B0); PG8_MMA(0, 1, At, B1); PG8_BAR; PG8_SCHED;
;             PG8_LDA(At, 0, 1); PG8_STAGE(PG8_SB(0, 0), b2, voffB); PG8_STAGE(PG8_SB(0, 1), b2 + hstep, voffB); PG8_STAGE(PG8_SA(0, 0), a2, voffA);
.LBB0_1029:
	s_ashr_i32 s57, s56, 31
	s_lshl_b64 s[58:59], s[56:57], 19
	s_add_u32 s58, s46, s58
	s_addc_u32 s59, s47, s59
	s_and_b64 s[60:61], s[8:9], exec
	s_cselect_b32 s33, s59, s11
	s_cselect_b32 s57, s58, s10
	s_ashr_i32 s55, s54, 31
	s_lshl_b64 s[60:61], s[54:55], 19
	s_add_u32 s60, s1, s60
	s_addc_u32 s61, s3, s61
	s_and_b64 s[68:69], s[8:9], exec
	s_cselect_b32 s55, s61, s67
	s_cselect_b32 s80, s60, s66
	s_add_u32 s10, s10, 0x40080
	s_addc_u32 s11, s11, 0
	s_add_u32 s81, s66, 0x100
	s_addc_u32 s82, s67, 0
	s_mov_b32 s83, -2
	ds_read_b128 v[128:131], v171
	ds_read_b128 v[132:135], v172
	ds_read_b128 v[188:191], v173
	ds_read_b128 v[192:195], v174
	ds_read_b128 v[196:199], v175
	ds_read_b128 v[200:203], v176
	ds_read_b128 v[204:207], v177
	ds_read_b128 v[208:211], v178
	s_add_u32 s66, s10, 0xfffc0080
	s_addc_u32 s67, s11, -1
	s_cmp_eq_u32 s83, 12
	s_cselect_b32 s69, s33, s67
	s_cselect_b32 s68, s57, s66
	s_cselect_b32 s67, s55, s82
	s_cselect_b32 s66, s80, s81
	s_mov_b32 m0, s77
	v_lshl_add_u64 v[136:137], s[10:11], 0, v[146:147]
	ds_read_b128 v[212:215], v159
	ds_read_b128 v[216:219], v159 offset:1024
	ds_read_b128 v[224:227], v159 offset:2048
	ds_read_b128 v[228:231], v159 offset:3072
	ds_read_b128 v[232:235], v159 offset:4096
	ds_read_b128 v[236:239], v159 offset:5120
	ds_read_b128 v[240:243], v159 offset:6144
	ds_read_b128 v[244:247], v159 offset:7168
	global_load_lds_dwordx4 v[136:137], off
	s_mov_b32 m0, s78
	v_lshl_add_u64 v[136:137], s[10:11], 0, v[148:149]
	global_load_lds_dwordx4 v[136:137], off
	s_waitcnt vmcnt(8)
	s_waitcnt lgkmcnt(0)
	s_barrier
	s_setprio 1
	s_waitcnt lgkmcnt(0)
	v_mfma_f32_16x16x32_bf16 v[124:127], v[128:131], v[212:215], 0
	v_mfma_f32_16x16x32_bf16 v[120:123], v[188:191], v[212:215], 0
	v_mfma_f32_16x16x32_bf16 v[108:111], v[128:131], v[224:227], 0
	v_mfma_f32_16x16x32_bf16 v[104:107], v[188:191], v[224:227], 0
	v_mfma_f32_16x16x32_bf16 v[92:95], v[128:131], v[232:235], 0
	v_mfma_f32_16x16x32_bf16 v[88:91], v[188:191], v[232:235], 0
	v_mfma_f32_16x16x32_bf16 v[76:79], v[128:131], v[240:243], 0
	v_mfma_f32_16x16x32_bf16 v[72:75], v[188:191], v[240:243], 0
	v_mfma_f32_16x16x32_bf16 v[124:127], v[132:135], v[216:219], v[124:127]
	v_mfma_f32_16x16x32_bf16 v[120:123], v[192:195], v[216:219], v[120:123]
	v_mfma_f32_16x16x32_bf16 v[108:111], v[132:135], v[228:231], v[108:111]
	v_mfma_f32_16x16x32_bf16 v[104:107], v[192:195], v[228:231], v[104:107]
	v_mfma_f32_16x16x32_bf16 v[92:95], v[132:135], v[236:239], v[92:95]
	v_mfma_f32_16x16x32_bf16 v[88:91], v[192:195], v[236:239], v[88:91]
	v_mfma_f32_16x16x32_bf16 v[76:79], v[132:135], v[244:247], v[76:79]
	v_mfma_f32_16x16x32_bf16 v[72:75], v[192:195], v[244:247], v[72:75]
	s_setprio 0
	s_setprio 1
	v_mfma_f32_16x16x32_bf16 v[116:119], v[196:199], v[212:215], 0
	v_mfma_f32_16x16x32_bf16 v[112:115], v[204:207], v[212:215], 0
	v_mfma_f32_16x16x32_bf16 v[100:103], v[196:199], v[224:227], 0
	v_mfma_f32_16x16x32_bf16 v[96:99], v[204:207], v[224:227], 0
	v_mfma_f32_16x16x32_bf16 v[84:87], v[196:199], v[232:235], 0
	v_mfma_f32_16x16x32_bf16 v[80:83], v[204:207], v[232:235], 0
	v_mfma_f32_16x16x32_bf16 v[68:71], v[196:199], v[240:243], 0
	v_mfma_f32_16x16x32_bf16 v[64:67], v[204:207], v[240:243], 0
	v_mfma_f32_16x16x32_bf16 v[116:119], v[200:203], v[216:219], v[116:119]
	v_mfma_f32_16x16x32_bf16 v[112:115], v[208:211], v[216:219], v[112:115]
	v_mfma_f32_16x16x32_bf16 v[100:103], v[200:203], v[228:231], v[100:103]
	v_mfma_f32_16x16x32_bf16 v[96:99], v[208:211], v[228:231], v[96:99]
	v_mfma_f32_16x16x32_bf16 v[84:87], v[200:203], v[236:239], v[84:87]
	v_mfma_f32_16x16x32_bf16 v[80:83], v[208:211], v[236:239], v[80:83]
	v_mfma_f32_16x16x32_bf16 v[68:71], v[200:203], v[244:247], v[68:71]
	v_mfma_f32_16x16x32_bf16 v[64:67], v[208:211], v[244:247], v[64:67]
	s_setprio 0
	s_barrier
	s_mov_b32 m0, s5
	v_lshl_add_u64 v[136:137], s[66:67], 0, v[140:141]
	s_add_u32 s84, s66, 0x40000
	ds_read_b128 v[212:215], v159 offset:16384
	ds_read_b128 v[216:219], v159 offset:17408
	ds_read_b128 v[224:227], v159 offset:18432
	ds_read_b128 v[228:231], v159 offset:19456
	ds_read_b128 v[232:235], v159 offset:20480
	ds_read_b128 v[236:239], v159 offset:21504
	ds_read_b128 v[240:243], v159 offset:22528
	ds_read_b128 v[244:247], v159 offset:23552
	global_load_lds_dwordx4 v[136:137], off
	v_lshl_add_u64 v[154:155], s[66:67], 0, v[144:145]
	s_mov_b32 m0, s12
	s_addc_u32 s85, s67, 0
	global_load_lds_dwordx4 v[154:155], off
	v_lshl_add_u64 v[220:221], s[84:85], 0, v[140:141]
	s_mov_b32 m0, s13
	v_lshl_add_u64 v[248:249], s[68:69], 0, v[142:143]
	global_load_lds_dwordx4 v[220:221], off
	s_mov_b32 m0, s14
	v_lshl_add_u64 v[220:221], s[84:85], 0, v[144:145]
	global_load_lds_dwordx4 v[220:221], off
	s_mov_b32 m0, s4
	v_lshl_add_u64 v[220:221], s[68:69], 0, v[138:139]
	global_load_lds_dwordx4 v[220:221], off
	s_mov_b32 m0, s15
	s_nop 0
	global_load_lds_dwordx4 v[248:249], off
	s_waitcnt vmcnt(8)
	s_waitcnt lgkmcnt(0)
	s_barrier
; #define PG8_STAGE(bufoff, gbase, voff) do { _Pragma("unroll") for (int _i = 0; _i < 2; ++_i) \
;         __builtin_amdgcn_global_load_lds((const unsigned*)((const char*)(gbase) + (voff)[_i]), (PG8_LAS unsigned*)(lds + (bufoff) + ldsw + _i * 8192), 16, 0, 0); } while (0)
; #define PG8_LDA(dst, b, h) do { _Pragma("unroll") for (int m = 0; m < 4; ++m) _Pragma("unroll") for (int k = 0; k < 2; ++k) dst[m][k] = *(const PG8_LAS bf16x8*)(lds + PG8_SA(b, h) + aoff + m * 2048 + k * 1024); } while (0)
; #define PG8_LDB(dst, b, h) do { _Pragma("unroll") for (int n = 0; n < 2; ++n) _Pragma("unroll") for (int k = 0; k < 2; ++k) dst[n][k] = *(const PG8_LAS bf16x8*)(lds + PG8_SB(b, h) + boff + n * 2048 + k * 1024); } while (0)
; #define PG8_MMA(ai, bj, At, Bt) do { __builtin_amdgcn_s_setprio(1); _Pragma("unroll") for (int m = 0; m < 4; ++m) _Pragma("unroll") for (int n = 0; n < 2; ++n) _Pragma("unroll") for (int k = 0; k < 2; ++k) \
;         acc[ai][bj][m][n] = __builtin_amdgcn_mfma_f32_16x16x32_bf16(Bt[n][k], At[m][k], acc[ai][bj][m][n], 0, 0, 0); __builtin_amdgcn_s_setprio(0); } while (0)
; #define PG8_WAIT_V(n) asm volatile("s_waitcnt vmcnt(" #n ")" ::: "memory")
; #define PG8_WAIT_L(n) asm volatile("s_waitcnt lgkmcnt(" #n ")" ::: "memory")
; #define PG8_BAR __builtin_amdgcn_s_barrier()
; #define PG8_SCHED __builtin_amdgcn_sched_barrier(0)
; template <class Epi, class Sched, bool ALIGN_EPI = false, bool SP2 = false>
; __device__ __forceinline__ void gemm_phase(PG8_LAS unsigned char* lds, const Gemm g, const Sched& S, const Epi& E) {
;     ...
;             PG8_WAIT_V(8); PG8_WAIT_L(0); PG8_BAR; PG8_MMA(1, 0, At, B0); PG8_MMA(1, 1, At, B1); PG8_BAR; PG8_SCHED;
;             PG8_LDB(B0, 1, 0); PG8_LDB(B1, 1, 1); PG8_SCHED; PG8_LDA(At, 1, 0); PG8_STAGE(PG8_SA(0, 1), a2 + hstep, voffA);
;             PG8_WAIT_V(8); PG8_WAIT_L(0); PG8_BAR; PG8_MMA(0, 0, At, B0); PG8_MMA(0, 1, At, B1); PG8_BAR; PG8_SCHED;
	s_setprio 1
	s_waitcnt lgkmcnt(0)
	v_mfma_f32_16x16x32_bf16 v[60:63], v[128:131], v[212:215], 0
	v_mfma_f32_16x16x32_bf16 v[56:59], v[188:191], v[212:215], 0
	v_mfma_f32_16x16x32_bf16 v[44:47], v[128:131], v[224:227], 0
	v_mfma_f32_16x16x32_bf16 v[40:43], v[188:191], v[224:227], 0
	v_mfma_f32_16x16x32_bf16 v[28:31], v[128:131], v[232:235], 0
	v_mfma_f32_16x16x32_bf16 v[24:27], v[188:191], v[232:235], 0
	v_mfma_f32_16x16x32_bf16 v[12:15], v[128:131], v[240:243], 0
	v_mfma_f32_16x16x32_bf16 v[8:11], v[188:191], v[240:243], 0
	v_mfma_f32_16x16x32_bf16 v[60:63], v[132:135], v[216:219], v[60:63]
	v_mfma_f32_16x16x32_bf16 v[56:59], v[192:195], v[216:219], v[56:59]
	v_mfma_f32_16x16x32_bf16 v[44:47], v[132:135], v[228:231], v[44:47]
	v_mfma_f32_16x16x32_bf16 v[40:43], v[192:195], v[228:231], v[40:43]
	v_mfma_f32_16x16x32_bf16 v[28:31], v[132:135], v[236:239], v[28:31]
	v_mfma_f32_16x16x32_bf16 v[24:27], v[192:195], v[236:239], v[24:27]
	v_mfma_f32_16x16x32_bf16 v[12:15], v[132:135], v[244:247], v[12:15]
	v_mfma_f32_16x16x32_bf16 v[8:11], v[192:195], v[244:247], v[8:11]
	s_setprio 0
	s_setprio 1
	v_mfma_f32_16x16x32_bf16 v[52:55], v[196:199], v[212:215], 0
	v_mfma_f32_16x16x32_bf16 v[48:51], v[204:207], v[212:215], 0
	v_mfma_f32_16x16x32_bf16 v[36:39], v[196:199], v[224:227], 0
	v_mfma_f32_16x16x32_bf16 v[32:35], v[204:207], v[224:227], 0
	v_mfma_f32_16x16x32_bf16 v[20:23], v[196:199], v[232:235], 0
	v_mfma_f32_16x16x32_bf16 v[16:19], v[204:207], v[232:235], 0
	v_mfma_f32_16x16x32_bf16 v[4:7], v[196:199], v[240:243], 0
	v_mfma_f32_16x16x32_bf16 v[0:3], v[204:207], v[240:243], 0
	v_mfma_f32_16x16x32_bf16 v[52:55], v[200:203], v[216:219], v[52:55]
	v_mfma_f32_16x16x32_bf16 v[48:51], v[208:211], v[216:219], v[48:51]
	v_mfma_f32_16x16x32_bf16 v[36:39], v[200:203], v[228:231], v[36:39]
	v_mfma_f32_16x16x32_bf16 v[32:35], v[208:211], v[228:231], v[32:35]
	v_mfma_f32_16x16x32_bf16 v[20:23], v[200:203], v[236:239], v[20:23]
	v_mfma_f32_16x16x32_bf16 v[16:19], v[208:211], v[236:239], v[16:19]
	v_mfma_f32_16x16x32_bf16 v[4:7], v[200:203], v[244:247], v[4:7]
	v_mfma_f32_16x16x32_bf16 v[0:3], v[208:211], v[244:247], v[0:3]
	s_setprio 0
	s_barrier
	ds_read_b128 v[128:131], v179
	ds_read_b128 v[132:135], v180
	ds_read_b128 v[188:191], v181
	ds_read_b128 v[192:195], v182
	ds_read_b128 v[196:199], v183
	ds_read_b128 v[200:203], v184
	ds_read_b128 v[204:207], v185
	ds_read_b128 v[208:211], v186
	s_add_u32 s68, s68, 0x40000
	s_addc_u32 s69, s69, 0
	s_mov_b32 m0, s39
	v_lshl_add_u64 v[250:251], s[68:69], 0, v[138:139]
	ds_read_b128 v[212:215], v159 offset:32768
	ds_read_b128 v[216:219], v159 offset:33792
	ds_read_b128 v[224:227], v159 offset:34816
	ds_read_b128 v[228:231], v159 offset:35840
	ds_read_b128 v[232:235], v159 offset:36864
	ds_read_b128 v[236:239], v159 offset:37888
	ds_read_b128 v[240:243], v159 offset:38912
	ds_read_b128 v[244:247], v159 offset:39936
	global_load_lds_dwordx4 v[250:251], off
	s_mov_b32 m0, s43
	v_lshl_add_u64 v[250:251], s[68:69], 0, v[142:143]
	global_load_lds_dwordx4 v[250:251], off
	s_waitcnt vmcnt(8)
	s_waitcnt lgkmcnt(0)
	s_barrier
	s_setprio 1
	s_waitcnt lgkmcnt(0)
	v_mfma_f32_16x16x32_bf16 v[124:127], v[128:131], v[212:215], v[124:127]
	v_mfma_f32_16x16x32_bf16 v[120:123], v[188:191], v[212:215], v[120:123]
	v_mfma_f32_16x16x32_bf16 v[108:111], v[128:131], v[224:227], v[108:111]
	v_mfma_f32_16x16x32_bf16 v[104:107], v[188:191], v[224:227], v[104:107]
	v_mfma_f32_16x16x32_bf16 v[92:95], v[128:131], v[232:235], v[92:95]
	v_mfma_f32_16x16x32_bf16 v[88:91], v[188:191], v[232:235], v[88:91]
	v_mfma_f32_16x16x32_bf16 v[76:79], v[128:131], v[240:243], v[76:79]
	v_mfma_f32_16x16x32_bf16 v[72:75], v[188:191], v[240:243], v[72:75]
	v_mfma_f32_16x16x32_bf16 v[124:127], v[132:135], v[216:219], v[124:127]
	v_mfma_f32_16x16x32_bf16 v[120:123], v[192:195], v[216:219], v[120:123]
	v_mfma_f32_16x16x32_bf16 v[108:111], v[132:135], v[228:231], v[108:111]
	v_mfma_f32_16x16x32_bf16 v[104:107], v[192:195], v[228:231], v[104:107]
	v_mfma_f32_16x16x32_bf16 v[92:95], v[132:135], v[236:239], v[92:95]
	v_mfma_f32_16x16x32_bf16 v[88:91], v[192:195], v[236:239], v[88:91]
	v_mfma_f32_16x16x32_bf16 v[76:79], v[132:135], v[244:247], v[76:79]
	v_mfma_f32_16x16x32_bf16 v[72:75], v[192:195], v[244:247], v[72:75]
	s_setprio 0
	s_setprio 1
	v_mfma_f32_16x16x32_bf16 v[116:119], v[196:199], v[212:215], v[116:119]
	v_mfma_f32_16x16x32_bf16 v[112:115], v[204:207], v[212:215], v[112:115]
	v_mfma_f32_16x16x32_bf16 v[100:103], v[196:199], v[224:227], v[100:103]
	v_mfma_f32_16x16x32_bf16 v[96:99], v[204:207], v[224:227], v[96:99]
	v_mfma_f32_16x16x32_bf16 v[84:87], v[196:199], v[232:235], v[84:87]
	v_mfma_f32_16x16x32_bf16 v[80:83], v[204:207], v[232:235], v[80:83]
	v_mfma_f32_16x16x32_bf16 v[68:71], v[196:199], v[240:243], v[68:71]
	v_mfma_f32_16x16x32_bf16 v[64:67], v[204:207], v[240:243], v[64:67]
	v_mfma_f32_16x16x32_bf16 v[116:119], v[200:203], v[216:219], v[116:119]
	v_mfma_f32_16x16x32_bf16 v[112:115], v[208:211], v[216:219], v[112:115]
	v_mfma_f32_16x16x32_bf16 v[100:103], v[200:203], v[228:231], v[100:103]
	v_mfma_f32_16x16x32_bf16 v[96:99], v[208:211], v[228:231], v[96:99]
	v_mfma_f32_16x16x32_bf16 v[84:87], v[200:203], v[236:239], v[84:87]
	v_mfma_f32_16x16x32_bf16 v[80:83], v[208:211], v[236:239], v[80:83]
	v_mfma_f32_16x16x32_bf16 v[68:71], v[200:203], v[244:247], v[68:71]
	v_mfma_f32_16x16x32_bf16 v[64:67], v[208:211], v[244:247], v[64:67]
	s_setprio 0
	s_barrier
; #define PG8_STAGE(bufoff, gbase, voff) do { _Pragma("unroll") for (int _i = 0; _i < 2; ++_i) \
;         __builtin_amdgcn_global_load_lds((const unsigned*)((const char*)(gbase) + (voff)[_i]), (PG8_LAS unsigned*)(lds + (bufoff) + ldsw + _i * 8192), 16, 0, 0); } while (0)
; #define PG8_LDA(dst, b, h) do { _Pragma("unroll") for (int m = 0; m < 4; ++m) _Pragma("unroll") for (int k = 0; k < 2; ++k) dst[m][k] = *(const PG8_LAS bf16x8*)(lds + PG8_SA(b, h) + aoff + m * 2048 + k * 1024); } while (0)
; #define PG8_LDB(dst, b, h) do { _Pragma("unroll") for (int n = 0; n < 2; ++n) _Pragma("unroll") for (int k = 0; k < 2; ++k) dst[n][k] = *(const PG8_LAS bf16x8*)(lds + PG8_SB(b, h) + boff + n * 2048 + k * 1024); } while (0)
; #define PG8_MMA(ai, bj, At, Bt) do { __builtin_amdgcn_s_setprio(1); _Pragma("unroll") for (int m = 0; m < 4; ++m) _Pragma("unroll") for (int n = 0; n < 2; ++n) _Pragma("unroll") for (int k = 0; k < 2; ++k) \
;         acc[ai][bj][m][n] = __builtin_amdgcn_mfma_f32_16x16x32_bf16(Bt[n][k], At[m][k], acc[ai][bj][m][n], 0, 0, 0); __builtin_amdgcn_s_setprio(0); } while (0)
; #define PG8_WAIT_V(n) asm volatile("s_waitcnt vmcnt(" #n ")" ::: "memory")
; #define PG8_WAIT_L(n) asm volatile("s_waitcnt lgkmcnt(" #n ")" ::: "memory")
; #define PG8_BAR __builtin_amdgcn_s_barrier()
; #define PG8_SCHED __builtin_amdgcn_sched_barrier(0)
; template <class Epi, class Sched, bool ALIGN_EPI = false, bool SP2 = false>
; __device__ __forceinline__ void gemm_phase(PG8_LAS unsigned char* lds, const Gemm g, const Sched& S, const Epi& E) {
;     ...
;             PG8_LDB(B0, 0, 0); PG8_LDB(B1, 0, 1); PG8_SCHED; PG8_LDA(At, 0, 0); PG8_STAGE(PG8_SA(1, 1), a1 + hstep, voffA);
;             PG8_WAIT_V(8); PG8_WAIT_L(0); PG8_BAR; PG8_MMA(0, 0, At, B0); PG8_MMA(0, 1, At, B1); PG8_BAR; PG8_SCHED;
;     ...
;             PG8_LDA(At, 1, 1); PG8_STAGE(PG8_SB(1, 0), b3, voffB); PG8_STAGE(PG8_SB(1, 1), b3 + hstep, voffB); PG8_STAGE(PG8_SA(1, 0), a3, voffA);
;             PG8_WAIT_V(8); PG8_WAIT_L(0); PG8_BAR; PG8_MMA(1, 0, At, B0); PG8_MMA(1, 1, At, B1); PG8_BAR; PG8_SCHED;
	s_mov_b32 m0, s63
	v_lshl_add_u64 v[136:137], v[136:137], 0, s[40:41]
	s_add_u32 s66, s66, 0x40080
	ds_read_b128 v[212:215], v159 offset:49152
	ds_read_b128 v[216:219], v159 offset:50176
	ds_read_b128 v[224:227], v159 offset:51200
	ds_read_b128 v[228:231], v159 offset:52224
	ds_read_b128 v[232:235], v159 offset:53248
	ds_read_b128 v[236:239], v159 offset:54272
	ds_read_b128 v[240:243], v159 offset:55296
	ds_read_b128 v[244:247], v159 offset:56320
	global_load_lds_dwordx4 v[136:137], off
	v_lshl_add_u64 v[136:137], v[154:155], 0, s[40:41]
	s_mov_b32 m0, s65
	s_addc_u32 s67, s67, 0
	global_load_lds_dwordx4 v[136:137], off
	s_mov_b32 m0, s72
	v_lshl_add_u64 v[136:137], s[66:67], 0, v[140:141]
	global_load_lds_dwordx4 v[136:137], off
	s_mov_b32 m0, s73
	v_lshl_add_u64 v[136:137], s[66:67], 0, v[144:145]
	global_load_lds_dwordx4 v[136:137], off
	s_mov_b32 m0, s70
	v_lshl_add_u64 v[136:137], v[220:221], 0, s[40:41]
	global_load_lds_dwordx4 v[136:137], off
	s_mov_b32 m0, s71
	v_lshl_add_u64 v[136:137], v[248:249], 0, s[40:41]
	global_load_lds_dwordx4 v[136:137], off
	s_waitcnt vmcnt(8)
	s_waitcnt lgkmcnt(0)
	s_barrier
	s_setprio 1
	s_waitcnt lgkmcnt(0)
	v_mfma_f32_16x16x32_bf16 v[60:63], v[128:131], v[212:215], v[60:63]
	v_mfma_f32_16x16x32_bf16 v[56:59], v[188:191], v[212:215], v[56:59]
	v_mfma_f32_16x16x32_bf16 v[44:47], v[128:131], v[224:227], v[44:47]
	v_mfma_f32_16x16x32_bf16 v[40:43], v[188:191], v[224:227], v[40:43]
	v_mfma_f32_16x16x32_bf16 v[28:31], v[128:131], v[232:235], v[28:31]
	v_mfma_f32_16x16x32_bf16 v[24:27], v[188:191], v[232:235], v[24:27]
	v_mfma_f32_16x16x32_bf16 v[12:15], v[128:131], v[240:243], v[12:15]
	v_mfma_f32_16x16x32_bf16 v[8:11], v[188:191], v[240:243], v[8:11]
	v_mfma_f32_16x16x32_bf16 v[60:63], v[132:135], v[216:219], v[60:63]
	v_mfma_f32_16x16x32_bf16 v[56:59], v[192:195], v[216:219], v[56:59]
	v_mfma_f32_16x16x32_bf16 v[44:47], v[132:135], v[228:231], v[44:47]
	v_mfma_f32_16x16x32_bf16 v[40:43], v[192:195], v[228:231], v[40:43]
	v_mfma_f32_16x16x32_bf16 v[28:31], v[132:135], v[236:239], v[28:31]
	v_mfma_f32_16x16x32_bf16 v[24:27], v[192:195], v[236:239], v[24:27]
	v_mfma_f32_16x16x32_bf16 v[12:15], v[132:135], v[244:247], v[12:15]
	v_mfma_f32_16x16x32_bf16 v[8:11], v[192:195], v[244:247], v[8:11]
	s_setprio 0
	s_setprio 1
	v_mfma_f32_16x16x32_bf16 v[52:55], v[196:199], v[212:215], v[52:55]
	v_mfma_f32_16x16x32_bf16 v[48:51], v[204:207], v[212:215], v[48:51]
	v_mfma_f32_16x16x32_bf16 v[36:39], v[196:199], v[224:227], v[36:39]
	v_mfma_f32_16x16x32_bf16 v[32:35], v[204:207], v[224:227], v[32:35]
	v_mfma_f32_16x16x32_bf16 v[20:23], v[196:199], v[232:235], v[20:23]
	v_mfma_f32_16x16x32_bf16 v[16:19], v[204:207], v[232:235], v[16:19]
	v_mfma_f32_16x16x32_bf16 v[4:7], v[196:199], v[240:243], v[4:7]
	v_mfma_f32_16x16x32_bf16 v[0:3], v[204:207], v[240:243], v[0:3]
	v_mfma_f32_16x16x32_bf16 v[52:55], v[200:203], v[216:219], v[52:55]
	v_mfma_f32_16x16x32_bf16 v[48:51], v[208:211], v[216:219], v[48:51]
	v_mfma_f32_16x16x32_bf16 v[36:39], v[200:203], v[228:231], v[36:39]
	v_mfma_f32_16x16x32_bf16 v[32:35], v[208:211], v[228:231], v[32:35]
	v_mfma_f32_16x16x32_bf16 v[20:23], v[200:203], v[236:239], v[20:23]
	v_mfma_f32_16x16x32_bf16 v[16:19], v[208:211], v[236:239], v[16:19]
	v_mfma_f32_16x16x32_bf16 v[4:7], v[200:203], v[244:247], v[4:7]
	v_mfma_f32_16x16x32_bf16 v[0:3], v[208:211], v[244:247], v[0:3]
	s_setprio 0
	s_barrier
	s_add_i32 s83, s83, 2
	s_add_u32 s10, s10, 0x100
	s_addc_u32 s11, s11, 0
	s_add_u32 s81, s81, 0x100
	s_addc_u32 s82, s82, 0
.LBB0_1030:
	ds_read_b128 v[128:131], v171
	ds_read_b128 v[132:135], v172
	ds_read_b128 v[188:191], v173
	ds_read_b128 v[192:195], v174
	ds_read_b128 v[196:199], v175
	ds_read_b128 v[200:203], v176
	ds_read_b128 v[204:207], v177
	ds_read_b128 v[208:211], v178
	s_add_u32 s66, s10, 0xfffc0080
	s_addc_u32 s67, s11, -1
	s_cmp_eq_u32 s83, 12
	s_cselect_b32 s69, s33, s67
	s_cselect_b32 s68, s57, s66
	s_cselect_b32 s67, s55, s82
	s_cselect_b32 s66, s80, s81
	s_mov_b32 m0, s77
	v_lshl_add_u64 v[136:137], s[10:11], 0, v[146:147]
	ds_read_b128 v[212:215], v159
	ds_read_b128 v[216:219], v159 offset:1024
	ds_read_b128 v[224:227], v159 offset:2048
	ds_read_b128 v[228:231], v159 offset:3072
	ds_read_b128 v[232:235], v159 offset:4096
	ds_read_b128 v[236:239], v159 offset:5120
	ds_read_b128 v[240:243], v159 offset:6144
	ds_read_b128 v[244:247], v159 offset:7168
	global_load_lds_dwordx4 v[136:137], off
	s_mov_b32 m0, s78
	v_lshl_add_u64 v[136:137], s[10:11], 0, v[148:149]
	global_load_lds_dwordx4 v[136:137], off
	s_waitcnt vmcnt(8)
	s_waitcnt lgkmcnt(0)
	s_barrier
; #define PG8_STAGE(bufoff, gbase, voff) do { _Pragma("unroll") for (int _i = 0; _i < 2; ++_i) \
;         __builtin_amdgcn_global_load_lds((const unsigned*)((const char*)(gbase) + (voff)[_i]), (PG8_LAS unsigned*)(lds + (bufoff) + ldsw + _i * 8192), 16, 0, 0); } while (0)
; #define PG8_LDA(dst, b, h) do { _Pragma("unroll") for (int m = 0; m < 4; ++m) _Pragma("unroll") for (int k = 0; k < 2; ++k) dst[m][k] = *(const PG8_LAS bf16x8*)(lds + PG8_SA(b, h) + aoff + m * 2048 + k * 1024); } while (0)
; #define PG8_MMA(ai, bj, At, Bt) do { __builtin_amdgcn_s_setprio(1); _Pragma("unroll") for (int m = 0; m < 4; ++m) _Pragma("unroll") for (int n = 0; n < 2; ++n) _Pragma("unroll") for (int k = 0; k < 2; ++k) \
;         acc[ai][bj][m][n] = __builtin_amdgcn_mfma_f32_16x16x32_bf16(Bt[n][k], At[m][k], acc[ai][bj][m][n], 0, 0, 0); __builtin_amdgcn_s_setprio(0); } while (0)
; #define PG8_WAIT_V(n) asm volatile("s_waitcnt vmcnt(" #n ")" ::: "memory")
; #define PG8_WAIT_L(n) asm volatile("s_waitcnt lgkmcnt(" #n ")" ::: "memory")
; #define PG8_BAR __builtin_amdgcn_s_barrier()
; #define PG8_SCHED __builtin_amdgcn_sched_barrier(0)
; template <class Epi, class Sched, bool ALIGN_EPI = false, bool SP2 = false>
; __device__ __forceinline__ void gemm_phase(PG8_LAS unsigned char* lds, const Gemm g, const Sched& S, const Epi& E) {
;     ...
;             PG8_WAIT_V(8); PG8_WAIT_L(0); PG8_BAR; PG8_MMA(0, 0, At, B0); PG8_MMA(0, 1, At, B1); PG8_BAR; PG8_SCHED;
;             PG8_LDA(At, 0, 1); PG8_STAGE(PG8_SB(0, 0), b2, voffB); PG8_STAGE(PG8_SB(0, 1), b2 + hstep, voffB); PG8_STAGE(PG8_SA(0, 0), a2, voffA);
;             PG8_WAIT_V(8); PG8_WAIT_L(0); PG8_BAR; PG8_MMA(1, 0, At, B0); PG8_MMA(1, 1, At, B1); PG8_BAR; PG8_SCHED;
	s_setprio 1
	s_waitcnt lgkmcnt(0)
	v_mfma_f32_16x16x32_bf16 v[124:127], v[128:131], v[212:215], v[124:127]
	v_mfma_f32_16x16x32_bf16 v[120:123], v[188:191], v[212:215], v[120:123]
	v_mfma_f32_16x16x32_bf16 v[108:111], v[128:131], v[224:227], v[108:111]
	v_mfma_f32_16x16x32_bf16 v[104:107], v[188:191], v[224:227], v[104:107]
	v_mfma_f32_16x16x32_bf16 v[92:95], v[128:131], v[232:235], v[92:95]
	v_mfma_f32_16x16x32_bf16 v[88:91], v[188:191], v[232:235], v[88:91]
	v_mfma_f32_16x16x32_bf16 v[76:79], v[128:131], v[240:243], v[76:79]
	v_mfma_f32_16x16x32_bf16 v[72:75], v[188:191], v[240:243], v[72:75]
	v_mfma_f32_16x16x32_bf16 v[124:127], v[132:135], v[216:219], v[124:127]
	v_mfma_f32_16x16x32_bf16 v[120:123], v[192:195], v[216:219], v[120:123]
	v_mfma_f32_16x16x32_bf16 v[108:111], v[132:135], v[228:231], v[108:111]
	v_mfma_f32_16x16x32_bf16 v[104:107], v[192:195], v[228:231], v[104:107]
	v_mfma_f32_16x16x32_bf16 v[92:95], v[132:135], v[236:239], v[92:95]
	v_mfma_f32_16x16x32_bf16 v[88:91], v[192:195], v[236:239], v[88:91]
	v_mfma_f32_16x16x32_bf16 v[76:79], v[132:135], v[244:247], v[76:79]
	v_mfma_f32_16x16x32_bf16 v[72:75], v[192:195], v[244:247], v[72:75]
	s_setprio 0
	s_setprio 1
	v_mfma_f32_16x16x32_bf16 v[116:119], v[196:199], v[212:215], v[116:119]
	v_mfma_f32_16x16x32_bf16 v[112:115], v[204:207], v[212:215], v[112:115]
	v_mfma_f32_16x16x32_bf16 v[100:103], v[196:199], v[224:227], v[100:103]
	v_mfma_f32_16x16x32_bf16 v[96:99], v[204:207], v[224:227], v[96:99]
	v_mfma_f32_16x16x32_bf16 v[84:87], v[196:199], v[232:235], v[84:87]
	v_mfma_f32_16x16x32_bf16 v[80:83], v[204:207], v[232:235], v[80:83]
	v_mfma_f32_16x16x32_bf16 v[68:71], v[196:199], v[240:243], v[68:71]
	v_mfma_f32_16x16x32_bf16 v[64:67], v[204:207], v[240:243], v[64:67]
	v_mfma_f32_16x16x32_bf16 v[116:119], v[200:203], v[216:219], v[116:119]
	v_mfma_f32_16x16x32_bf16 v[112:115], v[208:211], v[216:219], v[112:115]
	v_mfma_f32_16x16x32_bf16 v[100:103], v[200:203], v[228:231], v[100:103]
	v_mfma_f32_16x16x32_bf16 v[96:99], v[208:211], v[228:231], v[96:99]
	v_mfma_f32_16x16x32_bf16 v[84:87], v[200:203], v[236:239], v[84:87]
	v_mfma_f32_16x16x32_bf16 v[80:83], v[208:211], v[236:239], v[80:83]
	v_mfma_f32_16x16x32_bf16 v[68:71], v[200:203], v[244:247], v[68:71]
	v_mfma_f32_16x16x32_bf16 v[64:67], v[208:211], v[244:247], v[64:67]
	s_setprio 0
	s_barrier
	s_mov_b32 m0, s5
	v_lshl_add_u64 v[136:137], s[66:67], 0, v[140:141]
	s_add_u32 s84, s66, 0x40000
	ds_read_b128 v[212:215], v159 offset:16384
	ds_read_b128 v[216:219], v159 offset:17408
	ds_read_b128 v[224:227], v159 offset:18432
	ds_read_b128 v[228:231], v159 offset:19456
	ds_read_b128 v[232:235], v159 offset:20480
	ds_read_b128 v[236:239], v159 offset:21504
	ds_read_b128 v[240:243], v159 offset:22528
	ds_read_b128 v[244:247], v159 offset:23552
	global_load_lds_dwordx4 v[136:137], off
	v_lshl_add_u64 v[154:155], s[66:67], 0, v[144:145]
	s_mov_b32 m0, s12
	s_addc_u32 s85, s67, 0
	global_load_lds_dwordx4 v[154:155], off
	v_lshl_add_u64 v[220:221], s[84:85], 0, v[140:141]
	s_mov_b32 m0, s13
	v_lshl_add_u64 v[248:249], s[68:69], 0, v[142:143]
	global_load_lds_dwordx4 v[220:221], off
	s_mov_b32 m0, s14
	v_lshl_add_u64 v[220:221], s[84:85], 0, v[144:145]
	global_load_lds_dwordx4 v[220:221], off
	s_mov_b32 m0, s4
	v_lshl_add_u64 v[220:221], s[68:69], 0, v[138:139]
	global_load_lds_dwordx4 v[220:221], off
	s_mov_b32 m0, s15
	s_nop 0
	global_load_lds_dwordx4 v[248:249], off
	s_waitcnt vmcnt(8)
	s_waitcnt lgkmcnt(0)
	s_barrier
	s_setprio 1
	s_waitcnt lgkmcnt(0)
	v_mfma_f32_16x16x32_bf16 v[60:63], v[128:131], v[212:215], v[60:63]
	v_mfma_f32_16x16x32_bf16 v[56:59], v[188:191], v[212:215], v[56:59]
	v_mfma_f32_16x16x32_bf16 v[44:47], v[128:131], v[224:227], v[44:47]
	v_mfma_f32_16x16x32_bf16 v[40:43], v[188:191], v[224:227], v[40:43]
	v_mfma_f32_16x16x32_bf16 v[28:31], v[128:131], v[232:235], v[28:31]
	v_mfma_f32_16x16x32_bf16 v[24:27], v[188:191], v[232:235], v[24:27]
	v_mfma_f32_16x16x32_bf16 v[12:15], v[128:131], v[240:243], v[12:15]
	v_mfma_f32_16x16x32_bf16 v[8:11], v[188:191], v[240:243], v[8:11]
	v_mfma_f32_16x16x32_bf16 v[60:63], v[132:135], v[216:219], v[60:63]
	v_mfma_f32_16x16x32_bf16 v[56:59], v[192:195], v[216:219], v[56:59]
	v_mfma_f32_16x16x32_bf16 v[44:47], v[132:135], v[228:231], v[44:47]
	v_mfma_f32_16x16x32_bf16 v[40:43], v[192:195], v[228:231], v[40:43]
	v_mfma_f32_16x16x32_bf16 v[28:31], v[132:135], v[236:239], v[28:31]
	v_mfma_f32_16x16x32_bf16 v[24:27], v[192:195], v[236:239], v[24:27]
	v_mfma_f32_16x16x32_bf16 v[12:15], v[132:135], v[244:247], v[12:15]
	v_mfma_f32_16x16x32_bf16 v[8:11], v[192:195], v[244:247], v[8:11]
	s_setprio 0
	s_setprio 1
	v_mfma_f32_16x16x32_bf16 v[52:55], v[196:199], v[212:215], v[52:55]
	v_mfma_f32_16x16x32_bf16 v[48:51], v[204:207], v[212:215], v[48:51]
	v_mfma_f32_16x16x32_bf16 v[36:39], v[196:199], v[224:227], v[36:39]
	v_mfma_f32_16x16x32_bf16 v[32:35], v[204:207], v[224:227], v[32:35]
	v_mfma_f32_16x16x32_bf16 v[20:23], v[196:199], v[232:235], v[20:23]
	v_mfma_f32_16x16x32_bf16 v[16:19], v[204:207], v[232:235], v[16:19]
	v_mfma_f32_16x16x32_bf16 v[4:7], v[196:199], v[240:243], v[4:7]
	v_mfma_f32_16x16x32_bf16 v[0:3], v[204:207], v[240:243], v[0:3]
	v_mfma_f32_16x16x32_bf16 v[52:55], v[200:203], v[216:219], v[52:55]
	v_mfma_f32_16x16x32_bf16 v[48:51], v[208:211], v[216:219], v[48:51]
	v_mfma_f32_16x16x32_bf16 v[36:39], v[200:203], v[228:231], v[36:39]
	v_mfma_f32_16x16x32_bf16 v[32:35], v[208:211], v[228:231], v[32:35]
	v_mfma_f32_16x16x32_bf16 v[20:23], v[200:203], v[236:239], v[20:23]
	v_mfma_f32_16x16x32_bf16 v[16:19], v[208:211], v[236:239], v[16:19]
	v_mfma_f32_16x16x32_bf16 v[4:7], v[200:203], v[244:247], v[4:7]
	v_mfma_f32_16x16x32_bf16 v[0:3], v[208:211], v[244:247], v[0:3]
	s_setprio 0
	s_barrier
; #define PG8_STAGE(bufoff, gbase, voff) do { _Pragma("unroll") for (int _i = 0; _i < 2; ++_i) \
;         __builtin_amdgcn_global_load_lds((const unsigned*)((const char*)(gbase) + (voff)[_i]), (PG8_LAS unsigned*)(lds + (bufoff) + ldsw + _i * 8192), 16, 0, 0); } while (0)
; #define PG8_LDA(dst, b, h) do { _Pragma("unroll") for (int m = 0; m < 4; ++m) _Pragma("unroll") for (int k = 0; k < 2; ++k) dst[m][k] = *(const PG8_LAS bf16x8*)(lds + PG8_SA(b, h) + aoff + m * 2048 + k * 1024); } while (0)
; #define PG8_WAIT_V(n) asm volatile("s_waitcnt vmcnt(" #n ")" ::: "memory")
; #define PG8_WAIT_L(n) asm volatile("s_waitcnt lgkmcnt(" #n ")" ::: "memory")
; template <class Epi, class Sched, bool ALIGN_EPI = false, bool SP2 = false>
; __device__ __forceinline__ void gemm_phase(PG8_LAS unsigned char* lds, const Gemm g, const Sched& S, const Epi& E) {
;     ...
;         for (int t = 0; t < nt; t += 2) {
;             const bool last = (t == nt - 2);
;             const char* a1 = cA + (size_t)(t + 1) * kstep;
;             const char* a2 = last ? nA : cA + (size_t)(t + 2) * kstep; const char* b2 = last ? nB : cB + (size_t)(t + 2) * kstep;
;             const char* a3 = a2 + kstep; const char* b3 = b2 + kstep;
;             if (last && has_next) S.a_ready(nxt);
;             if constexpr (SP2) {
;             PG8_LDB(B0, 0, 0); PG8_LDB(B1, 0, 1); PG8_SCHED; PG8_LDA(At, 0, 0); PG8_STAGE(PG8_SA(1, 1), a1 + hstep, voffA);
;             PG8_WAIT_V(8); PG8_WAIT_L(0); PG8_BAR; PG8_MMA(0, 0, At, B0); PG8_MMA(0, 1, At, B1); PG8_BAR; PG8_SCHED;
;             PG8_LDA(At, 0, 1); PG8_STAGE(PG8_SB(0, 0), b2, voffB); PG8_STAGE(PG8_SB(0, 1), b2 + hstep, voffB); PG8_STAGE(PG8_SA(0, 0), a2, voffA);
;             PG8_WAIT_V(8); PG8_WAIT_L(0); PG8_BAR; PG8_MMA(1, 0, At, B0); PG8_MMA(1, 1, At, B1); PG8_BAR; PG8_SCHED;
;             PG8_LDB(B0, 1, 0); PG8_LDB(B1, 1, 1); PG8_SCHED; PG8_LDA(At, 1, 0); PG8_STAGE(PG8_SA(0, 1), a2 + hstep, voffA);
;             PG8_WAIT_V(8); PG8_WAIT_L(0); PG8_BAR; PG8_MMA(0, 0, At, B0); PG8_MMA(0, 1, At, B1); PG8_BAR; PG8_SCHED;
;             PG8_LDA(At, 1, 1); PG8_STAGE(PG8_SB(1, 0), b3, voffB); PG8_STAGE(PG8_SB(1, 1), b3 + hstep, voffB); PG8_STAGE(PG8_SA(1, 0), a3, voffA);
;             PG8_WAIT_V(8); PG8_WAIT_L(0); PG8_BAR; PG8_MMA(1, 0, At, B0); PG8_MMA(1, 1, At, B1); PG8_BAR; PG8_SCHED;
;     ...
;         if constexpr (ALIGN_EPI) { if (wr == 0) PG8_BAR; }
	ds_read_b128 v[128:131], v179
	ds_read_b128 v[132:135], v180
	ds_read_b128 v[188:191], v181
	ds_read_b128 v[192:195], v182
	ds_read_b128 v[196:199], v183
	ds_read_b128 v[200:203], v184
	ds_read_b128 v[204:207], v185
	ds_read_b128 v[208:211], v186
	s_add_u32 s68, s68, 0x40000
	s_addc_u32 s69, s69, 0
	s_mov_b32 m0, s39
	v_lshl_add_u64 v[250:251], s[68:69], 0, v[138:139]
	ds_read_b128 v[212:215], v159 offset:32768
	ds_read_b128 v[216:219], v159 offset:33792
	ds_read_b128 v[224:227], v159 offset:34816
	ds_read_b128 v[228:231], v159 offset:35840
	ds_read_b128 v[232:235], v159 offset:36864
	ds_read_b128 v[236:239], v159 offset:37888
	ds_read_b128 v[240:243], v159 offset:38912
	ds_read_b128 v[244:247], v159 offset:39936
	global_load_lds_dwordx4 v[250:251], off
	s_mov_b32 m0, s43
	v_lshl_add_u64 v[250:251], s[68:69], 0, v[142:143]
	global_load_lds_dwordx4 v[250:251], off
	s_waitcnt vmcnt(8)
	s_waitcnt lgkmcnt(0)
	s_barrier
	s_setprio 1
	s_waitcnt lgkmcnt(0)
	v_mfma_f32_16x16x32_bf16 v[124:127], v[128:131], v[212:215], v[124:127]
	v_mfma_f32_16x16x32_bf16 v[120:123], v[188:191], v[212:215], v[120:123]
	v_mfma_f32_16x16x32_bf16 v[108:111], v[128:131], v[224:227], v[108:111]
	v_mfma_f32_16x16x32_bf16 v[104:107], v[188:191], v[224:227], v[104:107]
	v_mfma_f32_16x16x32_bf16 v[92:95], v[128:131], v[232:235], v[92:95]
	v_mfma_f32_16x16x32_bf16 v[88:91], v[188:191], v[232:235], v[88:91]
	v_mfma_f32_16x16x32_bf16 v[76:79], v[128:131], v[240:243], v[76:79]
	v_mfma_f32_16x16x32_bf16 v[72:75], v[188:191], v[240:243], v[72:75]
	v_mfma_f32_16x16x32_bf16 v[124:127], v[132:135], v[216:219], v[124:127]
	v_mfma_f32_16x16x32_bf16 v[120:123], v[192:195], v[216:219], v[120:123]
	v_mfma_f32_16x16x32_bf16 v[108:111], v[132:135], v[228:231], v[108:111]
	v_mfma_f32_16x16x32_bf16 v[104:107], v[192:195], v[228:231], v[104:107]
	v_mfma_f32_16x16x32_bf16 v[92:95], v[132:135], v[236:239], v[92:95]
	v_mfma_f32_16x16x32_bf16 v[88:91], v[192:195], v[236:239], v[88:91]
	v_mfma_f32_16x16x32_bf16 v[76:79], v[132:135], v[244:247], v[76:79]
	v_mfma_f32_16x16x32_bf16 v[72:75], v[192:195], v[244:247], v[72:75]
	s_setprio 0
	s_setprio 1
	v_mfma_f32_16x16x32_bf16 v[116:119], v[196:199], v[212:215], v[116:119]
	v_mfma_f32_16x16x32_bf16 v[112:115], v[204:207], v[212:215], v[112:115]
	v_mfma_f32_16x16x32_bf16 v[100:103], v[196:199], v[224:227], v[100:103]
	v_mfma_f32_16x16x32_bf16 v[96:99], v[204:207], v[224:227], v[96:99]
	v_mfma_f32_16x16x32_bf16 v[84:87], v[196:199], v[232:235], v[84:87]
	v_mfma_f32_16x16x32_bf16 v[80:83], v[204:207], v[232:235], v[80:83]
	v_mfma_f32_16x16x32_bf16 v[68:71], v[196:199], v[240:243], v[68:71]
	v_mfma_f32_16x16x32_bf16 v[64:67], v[204:207], v[240:243], v[64:67]
	v_mfma_f32_16x16x32_bf16 v[116:119], v[200:203], v[216:219], v[116:119]
	v_mfma_f32_16x16x32_bf16 v[112:115], v[208:211], v[216:219], v[112:115]
	v_mfma_f32_16x16x32_bf16 v[100:103], v[200:203], v[228:231], v[100:103]
	v_mfma_f32_16x16x32_bf16 v[96:99], v[208:211], v[228:231], v[96:99]
	v_mfma_f32_16x16x32_bf16 v[84:87], v[200:203], v[236:239], v[84:87]
	v_mfma_f32_16x16x32_bf16 v[80:83], v[208:211], v[236:239], v[80:83]
	v_mfma_f32_16x16x32_bf16 v[68:71], v[200:203], v[244:247], v[68:71]
	v_mfma_f32_16x16x32_bf16 v[64:67], v[208:211], v[244:247], v[64:67]
	s_setprio 0
	s_barrier
	s_mov_b32 m0, s63
	v_lshl_add_u64 v[136:137], v[136:137], 0, s[40:41]
	s_add_u32 s66, s66, 0x40080
	ds_read_b128 v[212:215], v159 offset:49152
	ds_read_b128 v[216:219], v159 offset:50176
	ds_read_b128 v[224:227], v159 offset:51200
	ds_read_b128 v[228:231], v159 offset:52224
	ds_read_b128 v[232:235], v159 offset:53248
	ds_read_b128 v[236:239], v159 offset:54272
	ds_read_b128 v[240:243], v159 offset:55296
	ds_read_b128 v[244:247], v159 offset:56320
	global_load_lds_dwordx4 v[136:137], off
	v_lshl_add_u64 v[136:137], v[154:155], 0, s[40:41]
	s_mov_b32 m0, s65
	s_addc_u32 s67, s67, 0
	global_load_lds_dwordx4 v[136:137], off
	s_mov_b32 m0, s72
	v_lshl_add_u64 v[136:137], s[66:67], 0, v[140:141]
	global_load_lds_dwordx4 v[136:137], off
	s_mov_b32 m0, s73
	v_lshl_add_u64 v[136:137], s[66:67], 0, v[144:145]
	global_load_lds_dwordx4 v[136:137], off
	s_mov_b32 m0, s70
	v_lshl_add_u64 v[136:137], v[220:221], 0, s[40:41]
	global_load_lds_dwordx4 v[136:137], off
	s_mov_b32 m0, s71
	v_lshl_add_u64 v[136:137], v[248:249], 0, s[40:41]
	global_load_lds_dwordx4 v[136:137], off
	s_waitcnt vmcnt(8)
	s_waitcnt lgkmcnt(0)
	s_barrier
	s_setprio 1
	s_waitcnt lgkmcnt(0)
	v_mfma_f32_16x16x32_bf16 v[60:63], v[128:131], v[212:215], v[60:63]
	v_mfma_f32_16x16x32_bf16 v[56:59], v[188:191], v[212:215], v[56:59]
	v_mfma_f32_16x16x32_bf16 v[44:47], v[128:131], v[224:227], v[44:47]
	v_mfma_f32_16x16x32_bf16 v[40:43], v[188:191], v[224:227], v[40:43]
	v_mfma_f32_16x16x32_bf16 v[28:31], v[128:131], v[232:235], v[28:31]
	v_mfma_f32_16x16x32_bf16 v[24:27], v[188:191], v[232:235], v[24:27]
	v_mfma_f32_16x16x32_bf16 v[12:15], v[128:131], v[240:243], v[12:15]
	v_mfma_f32_16x16x32_bf16 v[8:11], v[188:191], v[240:243], v[8:11]
	v_mfma_f32_16x16x32_bf16 v[60:63], v[132:135], v[216:219], v[60:63]
	v_mfma_f32_16x16x32_bf16 v[56:59], v[192:195], v[216:219], v[56:59]
	v_mfma_f32_16x16x32_bf16 v[44:47], v[132:135], v[228:231], v[44:47]
	v_mfma_f32_16x16x32_bf16 v[40:43], v[192:195], v[228:231], v[40:43]
	v_mfma_f32_16x16x32_bf16 v[28:31], v[132:135], v[236:239], v[28:31]
	v_mfma_f32_16x16x32_bf16 v[24:27], v[192:195], v[236:239], v[24:27]
	v_mfma_f32_16x16x32_bf16 v[12:15], v[132:135], v[244:247], v[12:15]
	v_mfma_f32_16x16x32_bf16 v[8:11], v[192:195], v[244:247], v[8:11]
	s_setprio 0
	s_setprio 1
	v_mfma_f32_16x16x32_bf16 v[52:55], v[196:199], v[212:215], v[52:55]
	v_mfma_f32_16x16x32_bf16 v[48:51], v[204:207], v[212:215], v[48:51]
	v_mfma_f32_16x16x32_bf16 v[36:39], v[196:199], v[224:227], v[36:39]
	v_mfma_f32_16x16x32_bf16 v[32:35], v[204:207], v[224:227], v[32:35]
	v_mfma_f32_16x16x32_bf16 v[20:23], v[196:199], v[232:235], v[20:23]
	v_mfma_f32_16x16x32_bf16 v[16:19], v[204:207], v[232:235], v[16:19]
	v_mfma_f32_16x16x32_bf16 v[4:7], v[196:199], v[240:243], v[4:7]
	v_mfma_f32_16x16x32_bf16 v[0:3], v[204:207], v[240:243], v[0:3]
	v_mfma_f32_16x16x32_bf16 v[52:55], v[200:203], v[216:219], v[52:55]
	v_mfma_f32_16x16x32_bf16 v[48:51], v[208:211], v[216:219], v[48:51]
	v_mfma_f32_16x16x32_bf16 v[36:39], v[200:203], v[228:231], v[36:39]
	v_mfma_f32_16x16x32_bf16 v[32:35], v[208:211], v[228:231], v[32:35]
	v_mfma_f32_16x16x32_bf16 v[20:23], v[200:203], v[236:239], v[20:23]
	v_mfma_f32_16x16x32_bf16 v[16:19], v[208:211], v[236:239], v[16:19]
	v_mfma_f32_16x16x32_bf16 v[4:7], v[200:203], v[244:247], v[4:7]
	v_mfma_f32_16x16x32_bf16 v[0:3], v[208:211], v[244:247], v[0:3]
	s_setprio 0
	s_barrier
	s_add_i32 s83, s83, 2
	s_add_u32 s10, s10, 0x100
	s_addc_u32 s11, s11, 0
	s_add_u32 s81, s81, 0x100
	s_addc_u32 s82, s82, 0
	s_cmp_gt_u32 s83, 13
	s_cbranch_scc0 .LBB0_1030
	s_and_b64 vcc, exec, s[52:53]
	s_cbranch_vccz .LBB0_1033
	s_barrier

;     __host__ __device__ bool next(int i, Unit& u) const { const int L = i * G + c; if (L >= 16 * nkc) return false; u.kc = L % nkc; const int t = L / nkc; u.pn = t & 3; u.pm = 33 * (t >> 2); return true; }
; #define PG8_STAGE(bufoff, gbase, voff) do { _Pragma("unroll") for (int _i = 0; _i < 2; ++_i) \
;         __builtin_amdgcn_global_load_lds((const unsigned*)((const char*)(gbase) + (voff)[_i]), (PG8_LAS unsigned*)(lds + (bufoff) + ldsw + _i * 8192), 16, 0, 0); } while (0)
; #define PG8_LDA(dst, b, h) do { _Pragma("unroll") for (int m = 0; m < 4; ++m) _Pragma("unroll") for (int k = 0; k < 2; ++k) dst[m][k] = *(const PG8_LAS bf16x8*)(lds + PG8_SA(b, h) + aoff + m * 2048 + k * 1024); } while (0)
; #define PG8_LDB(dst, b, h) do { _Pragma("unroll") for (int n = 0; n < 2; ++n) _Pragma("unroll") for (int k = 0; k < 2; ++k) dst[n][k] = *(const PG8_LAS bf16x8*)(lds + PG8_SB(b, h) + boff + n * 2048 + k * 1024); } while (0)
; #define PG8_BAR __builtin_amdgcn_s_barrier()
; template <class Epi, class Sched, bool ALIGN_EPI = false, bool SP2 = false>
; __device__ __forceinline__ void gemm_phase(PG8_LAS unsigned char* lds, const Gemm g, const Sched& S, const Epi& E) {
;     ...
;         const bool has_next = S.next(ui + 1, nxt);
;         const char* nA = has_next ? (const char*)g.A + (size_t)nxt.pm * tstep + (size_t)nxt.kc * cstep : cA; const char* nB = has_next ? (const char*)g.Bt + (size_t)nxt.pn * tstep + (size_t)nxt.kc * cstep : cB;
;         for (int t = 0; t < nt; t += 2) {
;             const bool last = (t == nt - 2);
;             const char* a1 = cA + (size_t)(t + 1) * kstep;
;             const char* a2 = last ? nA : cA + (size_t)(t + 2) * kstep; const char* b2 = last ? nB : cB + (size_t)(t + 2) * kstep;
;             const char* a3 = a2 + kstep; const char* b3 = b2 + kstep;
;             if (last && has_next) S.a_ready(nxt);
;             if constexpr (SP2) {
;             PG8_LDB(B0, 0, 0); PG8_LDB(B1, 0, 1); PG8_SCHED; PG8_LDA(At, 0, 0); PG8_STAGE(PG8_SA(1, 1), a1 + hstep, voffA);
;             PG8_WAIT_V(8); PG8_WAIT_L(0); PG8_BAR; PG8_MMA(0, 0, At, B0); PG8_MMA(0, 1, At, B1); PG8_BAR; PG8_SCHED;
;             PG8_LDA(At, 0, 1); PG8_STAGE(PG8_SB(0, 0), b2, voffB); PG8_STAGE(PG8_SB(0, 1), b2 + hstep, voffB); PG8_STAGE(PG8_SA(0, 0), a2, voffA);
;             PG8_WAIT_V(8); PG8_WAIT_L(0); PG8_BAR; PG8_MMA(1, 0, At, B0); PG8_MMA(1, 1, At, B1); PG8_BAR; PG8_SCHED;
.LBB0_1306:
	s_ashr_i32 s21, s20, 31
	s_lshl_b64 s[22:23], s[20:21], 19
	s_add_u32 s22, s46, s22
	s_addc_u32 s23, s47, s23
	s_and_b64 s[24:25], s[6:7], exec
	s_cselect_b32 s21, s23, s41
	s_cselect_b32 s37, s22, s40
	s_ashr_i32 s19, s18, 31
	s_lshl_b64 s[24:25], s[18:19], 19
	s_add_u32 s24, s3, s24
	s_addc_u32 s25, s4, s25
	s_and_b64 s[52:53], s[6:7], exec
	s_cselect_b32 s19, s25, s51
	s_cselect_b32 s76, s24, s50
	s_add_u32 s77, s50, 0x100
	s_addc_u32 s78, s51, 0
	s_mov_b32 s79, -2
	ds_read_b128 v[142:145], v174
	ds_read_b128 v[146:149], v175
	ds_read_b128 v[150:153], v176
	ds_read_b128 v[154:157], v177
	ds_read_b128 v[158:161], v178
	ds_read_b128 v[162:165], v179
	ds_read_b128 v[166:169], v180
	ds_read_b128 v[190:193], v181
	s_add_u32 s50, s40, 0x100
	s_addc_u32 s51, s41, 0
	s_cmp_eq_u32 s79, 12
	s_cselect_b32 s55, s21, s51
	s_cselect_b32 s54, s37, s50
	s_cselect_b32 s53, s19, s78
	s_cselect_b32 s52, s76, s77
	s_mov_b32 m0, s68
	v_lshl_add_u64 v[170:171], s[40:41], 0, v[134:135]
	ds_read_b128 v[194:197], v172
	ds_read_b128 v[198:201], v172 offset:1024
	ds_read_b128 v[202:205], v172 offset:2048
	ds_read_b128 v[206:209], v172 offset:3072
	ds_read_b128 v[210:213], v172 offset:4096
	ds_read_b128 v[214:217], v172 offset:5120
	ds_read_b128 v[218:221], v172 offset:6144
	ds_read_b128 v[224:227], v172 offset:7168
	global_load_lds_dwordx4 v[170:171], off
	s_mov_b32 m0, s69
	v_lshl_add_u64 v[170:171], s[40:41], 0, v[136:137]
	global_load_lds_dwordx4 v[170:171], off
	s_waitcnt vmcnt(8)
	s_waitcnt lgkmcnt(0)
	s_barrier
	s_setprio 1
	s_waitcnt lgkmcnt(0)
	v_mfma_f32_16x16x32_bf16 v[124:127], v[142:145], v[194:197], 0
	v_mfma_f32_16x16x32_bf16 v[108:111], v[150:153], v[194:197], 0
	v_mfma_f32_16x16x32_bf16 v[120:123], v[142:145], v[202:205], 0
	v_mfma_f32_16x16x32_bf16 v[96:99], v[150:153], v[202:205], 0
	v_mfma_f32_16x16x32_bf16 v[116:119], v[142:145], v[210:213], 0
	v_mfma_f32_16x16x32_bf16 v[88:91], v[150:153], v[210:213], 0
	v_mfma_f32_16x16x32_bf16 v[112:115], v[142:145], v[218:221], 0
	v_mfma_f32_16x16x32_bf16 v[84:87], v[150:153], v[218:221], 0
	v_mfma_f32_16x16x32_bf16 v[124:127], v[146:149], v[198:201], v[124:127]
	v_mfma_f32_16x16x32_bf16 v[108:111], v[154:157], v[198:201], v[108:111]
	v_mfma_f32_16x16x32_bf16 v[120:123], v[146:149], v[206:209], v[120:123]
	v_mfma_f32_16x16x32_bf16 v[96:99], v[154:157], v[206:209], v[96:99]
	v_mfma_f32_16x16x32_bf16 v[116:119], v[146:149], v[214:217], v[116:119]
	v_mfma_f32_16x16x32_bf16 v[88:91], v[154:157], v[214:217], v[88:91]
	v_mfma_f32_16x16x32_bf16 v[112:115], v[146:149], v[224:227], v[112:115]
	v_mfma_f32_16x16x32_bf16 v[84:87], v[154:157], v[224:227], v[84:87]
	s_setprio 0
	s_setprio 1
	v_mfma_f32_16x16x32_bf16 v[68:71], v[158:161], v[194:197], 0
	v_mfma_f32_16x16x32_bf16 v[40:43], v[166:169], v[194:197], 0
	v_mfma_f32_16x16x32_bf16 v[60:63], v[158:161], v[202:205], 0
	v_mfma_f32_16x16x32_bf16 v[32:35], v[166:169], v[202:205], 0
	v_mfma_f32_16x16x32_bf16 v[52:55], v[158:161], v[210:213], 0
	v_mfma_f32_16x16x32_bf16 v[24:27], v[166:169], v[210:213], 0
	v_mfma_f32_16x16x32_bf16 v[48:51], v[158:161], v[218:221], 0
	v_mfma_f32_16x16x32_bf16 v[16:19], v[166:169], v[218:221], 0
	v_mfma_f32_16x16x32_bf16 v[68:71], v[162:165], v[198:201], v[68:71]
	v_mfma_f32_16x16x32_bf16 v[40:43], v[190:193], v[198:201], v[40:43]
	v_mfma_f32_16x16x32_bf16 v[60:63], v[162:165], v[206:209], v[60:63]
	v_mfma_f32_16x16x32_bf16 v[32:35], v[190:193], v[206:209], v[32:35]
	v_mfma_f32_16x16x32_bf16 v[52:55], v[162:165], v[214:217], v[52:55]
	v_mfma_f32_16x16x32_bf16 v[24:27], v[190:193], v[214:217], v[24:27]
	v_mfma_f32_16x16x32_bf16 v[48:51], v[162:165], v[224:227], v[48:51]
	v_mfma_f32_16x16x32_bf16 v[16:19], v[190:193], v[224:227], v[16:19]
	s_setprio 0
	s_barrier
	s_mov_b32 m0, s12
	v_lshl_add_u64 v[170:171], s[52:53], 0, v[128:129]
	s_add_u32 s40, s52, 0x40000
	ds_read_b128 v[194:197], v172 offset:16384
	ds_read_b128 v[198:201], v172 offset:17408
	ds_read_b128 v[202:205], v172 offset:18432
	ds_read_b128 v[206:209], v172 offset:19456
	ds_read_b128 v[210:213], v172 offset:20480
	ds_read_b128 v[214:217], v172 offset:21504
	ds_read_b128 v[218:221], v172 offset:22528
	ds_read_b128 v[224:227], v172 offset:23552
	global_load_lds_dwordx4 v[170:171], off
	v_lshl_add_u64 v[228:229], s[52:53], 0, v[130:131]
	s_mov_b32 m0, s13
	s_addc_u32 s41, s53, 0
	global_load_lds_dwordx4 v[228:229], off
	v_lshl_add_u64 v[236:237], s[40:41], 0, v[128:129]
	s_mov_b32 m0, s14
	v_lshl_add_u64 v[238:239], s[54:55], 0, v[130:131]
	global_load_lds_dwordx4 v[236:237], off
	s_mov_b32 m0, s15
	v_lshl_add_u64 v[236:237], s[40:41], 0, v[130:131]
	global_load_lds_dwordx4 v[236:237], off
	s_mov_b32 m0, s5
	v_lshl_add_u64 v[236:237], s[54:55], 0, v[128:129]
	global_load_lds_dwordx4 v[236:237], off
	s_mov_b32 m0, s39
	s_nop 0
	global_load_lds_dwordx4 v[238:239], off
	s_waitcnt vmcnt(8)
	s_waitcnt lgkmcnt(0)
	s_barrier
; #define PG8_STAGE(bufoff, gbase, voff) do { _Pragma("unroll") for (int _i = 0; _i < 2; ++_i) \
;         __builtin_amdgcn_global_load_lds((const unsigned*)((const char*)(gbase) + (voff)[_i]), (PG8_LAS unsigned*)(lds + (bufoff) + ldsw + _i * 8192), 16, 0, 0); } while (0)
; #define PG8_LDA(dst, b, h) do { _Pragma("unroll") for (int m = 0; m < 4; ++m) _Pragma("unroll") for (int k = 0; k < 2; ++k) dst[m][k] = *(const PG8_LAS bf16x8*)(lds + PG8_SA(b, h) + aoff + m * 2048 + k * 1024); } while (0)
; #define PG8_LDB(dst, b, h) do { _Pragma("unroll") for (int n = 0; n < 2; ++n) _Pragma("unroll") for (int k = 0; k < 2; ++k) dst[n][k] = *(const PG8_LAS bf16x8*)(lds + PG8_SB(b, h) + boff + n * 2048 + k * 1024); } while (0)
; #define PG8_MMA(ai, bj, At, Bt) do { __builtin_amdgcn_s_setprio(1); _Pragma("unroll") for (int m = 0; m < 4; ++m) _Pragma("unroll") for (int n = 0; n < 2; ++n) _Pragma("unroll") for (int k = 0; k < 2; ++k) \
;         acc[ai][bj][m][n] = __builtin_amdgcn_mfma_f32_16x16x32_bf16(Bt[n][k], At[m][k], acc[ai][bj][m][n], 0, 0, 0); __builtin_amdgcn_s_setprio(0); } while (0)
; #define PG8_WAIT_V(n) asm volatile("s_waitcnt vmcnt(" #n ")" ::: "memory")
; #define PG8_WAIT_L(n) asm volatile("s_waitcnt lgkmcnt(" #n ")" ::: "memory")
; #define PG8_BAR __builtin_amdgcn_s_barrier()
; #define PG8_SCHED __builtin_amdgcn_sched_barrier(0)
; template <class Epi, class Sched, bool ALIGN_EPI = false, bool SP2 = false>
; __device__ __forceinline__ void gemm_phase(PG8_LAS unsigned char* lds, const Gemm g, const Sched& S, const Epi& E) {
;     ...
;             PG8_WAIT_V(8); PG8_WAIT_L(0); PG8_BAR; PG8_MMA(1, 0, At, B0); PG8_MMA(1, 1, At, B1); PG8_BAR; PG8_SCHED;
;             PG8_LDB(B0, 1, 0); PG8_LDB(B1, 1, 1); PG8_SCHED; PG8_LDA(At, 1, 0); PG8_STAGE(PG8_SA(0, 1), a2 + hstep, voffA);
;             PG8_WAIT_V(8); PG8_WAIT_L(0); PG8_BAR; PG8_MMA(0, 0, At, B0); PG8_MMA(0, 1, At, B1); PG8_BAR; PG8_SCHED;
	s_setprio 1
	s_waitcnt lgkmcnt(0)
	v_mfma_f32_16x16x32_bf16 v[104:107], v[142:145], v[194:197], 0
	v_mfma_f32_16x16x32_bf16 v[76:79], v[150:153], v[194:197], 0
	v_mfma_f32_16x16x32_bf16 v[100:103], v[142:145], v[202:205], 0
	v_mfma_f32_16x16x32_bf16 v[72:75], v[150:153], v[202:205], 0
	v_mfma_f32_16x16x32_bf16 v[92:95], v[142:145], v[210:213], 0
	v_mfma_f32_16x16x32_bf16 v[64:67], v[150:153], v[210:213], 0
	v_mfma_f32_16x16x32_bf16 v[80:83], v[142:145], v[218:221], 0
	v_mfma_f32_16x16x32_bf16 v[56:59], v[150:153], v[218:221], 0
	v_mfma_f32_16x16x32_bf16 v[104:107], v[146:149], v[198:201], v[104:107]
	v_mfma_f32_16x16x32_bf16 v[76:79], v[154:157], v[198:201], v[76:79]
	v_mfma_f32_16x16x32_bf16 v[100:103], v[146:149], v[206:209], v[100:103]
	v_mfma_f32_16x16x32_bf16 v[72:75], v[154:157], v[206:209], v[72:75]
	v_mfma_f32_16x16x32_bf16 v[92:95], v[146:149], v[214:217], v[92:95]
	v_mfma_f32_16x16x32_bf16 v[64:67], v[154:157], v[214:217], v[64:67]
	v_mfma_f32_16x16x32_bf16 v[80:83], v[146:149], v[224:227], v[80:83]
	v_mfma_f32_16x16x32_bf16 v[56:59], v[154:157], v[224:227], v[56:59]
	s_setprio 0
	s_setprio 1
	v_mfma_f32_16x16x32_bf16 v[44:47], v[158:161], v[194:197], 0
	v_mfma_f32_16x16x32_bf16 v[12:15], v[166:169], v[194:197], 0
	v_mfma_f32_16x16x32_bf16 v[36:39], v[158:161], v[202:205], 0
	v_mfma_f32_16x16x32_bf16 v[8:11], v[166:169], v[202:205], 0
	v_mfma_f32_16x16x32_bf16 v[28:31], v[158:161], v[210:213], 0
	v_mfma_f32_16x16x32_bf16 v[4:7], v[166:169], v[210:213], 0
	v_mfma_f32_16x16x32_bf16 v[20:23], v[158:161], v[218:221], 0
	v_mfma_f32_16x16x32_bf16 v[0:3], v[166:169], v[218:221], 0
	v_mfma_f32_16x16x32_bf16 v[44:47], v[162:165], v[198:201], v[44:47]
	v_mfma_f32_16x16x32_bf16 v[12:15], v[190:193], v[198:201], v[12:15]
	v_mfma_f32_16x16x32_bf16 v[36:39], v[162:165], v[206:209], v[36:39]
	v_mfma_f32_16x16x32_bf16 v[8:11], v[190:193], v[206:209], v[8:11]
	v_mfma_f32_16x16x32_bf16 v[28:31], v[162:165], v[214:217], v[28:31]
	v_mfma_f32_16x16x32_bf16 v[4:7], v[190:193], v[214:217], v[4:7]
	v_mfma_f32_16x16x32_bf16 v[20:23], v[162:165], v[224:227], v[20:23]
	v_mfma_f32_16x16x32_bf16 v[0:3], v[190:193], v[224:227], v[0:3]
	s_setprio 0
	s_barrier
	ds_read_b128 v[142:145], v182
	ds_read_b128 v[146:149], v183
	ds_read_b128 v[150:153], v184
	ds_read_b128 v[154:157], v185
	ds_read_b128 v[158:161], v186
	ds_read_b128 v[162:165], v187
	ds_read_b128 v[166:169], v188
	ds_read_b128 v[190:193], v189
	s_add_u32 s40, s54, 0x40000
	s_addc_u32 s41, s55, 0
	s_mov_b32 m0, s43
	v_lshl_add_u64 v[240:241], s[40:41], 0, v[128:129]
	ds_read_b128 v[194:197], v172 offset:32768
	ds_read_b128 v[198:201], v172 offset:33792
	ds_read_b128 v[202:205], v172 offset:34816
	ds_read_b128 v[206:209], v172 offset:35840
	ds_read_b128 v[210:213], v172 offset:36864
	ds_read_b128 v[214:217], v172 offset:37888
	ds_read_b128 v[218:221], v172 offset:38912
	ds_read_b128 v[224:227], v172 offset:39936
	global_load_lds_dwordx4 v[240:241], off
	s_mov_b32 m0, s56
	v_lshl_add_u64 v[240:241], s[40:41], 0, v[130:131]
	global_load_lds_dwordx4 v[240:241], off
	s_waitcnt vmcnt(8)
	s_waitcnt lgkmcnt(0)
	s_barrier
	s_setprio 1
	s_waitcnt lgkmcnt(0)
	v_mfma_f32_16x16x32_bf16 v[124:127], v[142:145], v[194:197], v[124:127]
	v_mfma_f32_16x16x32_bf16 v[108:111], v[150:153], v[194:197], v[108:111]
	v_mfma_f32_16x16x32_bf16 v[120:123], v[142:145], v[202:205], v[120:123]
	v_mfma_f32_16x16x32_bf16 v[96:99], v[150:153], v[202:205], v[96:99]
	v_mfma_f32_16x16x32_bf16 v[116:119], v[142:145], v[210:213], v[116:119]
	v_mfma_f32_16x16x32_bf16 v[88:91], v[150:153], v[210:213], v[88:91]
	v_mfma_f32_16x16x32_bf16 v[112:115], v[142:145], v[218:221], v[112:115]
	v_mfma_f32_16x16x32_bf16 v[84:87], v[150:153], v[218:221], v[84:87]
	v_mfma_f32_16x16x32_bf16 v[124:127], v[146:149], v[198:201], v[124:127]
	v_mfma_f32_16x16x32_bf16 v[108:111], v[154:157], v[198:201], v[108:111]
	v_mfma_f32_16x16x32_bf16 v[120:123], v[146:149], v[206:209], v[120:123]
	v_mfma_f32_16x16x32_bf16 v[96:99], v[154:157], v[206:209], v[96:99]
	v_mfma_f32_16x16x32_bf16 v[116:119], v[146:149], v[214:217], v[116:119]
	v_mfma_f32_16x16x32_bf16 v[88:91], v[154:157], v[214:217], v[88:91]
	v_mfma_f32_16x16x32_bf16 v[112:115], v[146:149], v[224:227], v[112:115]
	v_mfma_f32_16x16x32_bf16 v[84:87], v[154:157], v[224:227], v[84:87]
	s_setprio 0
	s_setprio 1
	v_mfma_f32_16x16x32_bf16 v[68:71], v[158:161], v[194:197], v[68:71]
	v_mfma_f32_16x16x32_bf16 v[40:43], v[166:169], v[194:197], v[40:43]
	v_mfma_f32_16x16x32_bf16 v[60:63], v[158:161], v[202:205], v[60:63]
	v_mfma_f32_16x16x32_bf16 v[32:35], v[166:169], v[202:205], v[32:35]
	v_mfma_f32_16x16x32_bf16 v[52:55], v[158:161], v[210:213], v[52:55]
	v_mfma_f32_16x16x32_bf16 v[24:27], v[166:169], v[210:213], v[24:27]
	v_mfma_f32_16x16x32_bf16 v[48:51], v[158:161], v[218:221], v[48:51]
	v_mfma_f32_16x16x32_bf16 v[16:19], v[166:169], v[218:221], v[16:19]
	v_mfma_f32_16x16x32_bf16 v[68:71], v[162:165], v[198:201], v[68:71]
	v_mfma_f32_16x16x32_bf16 v[40:43], v[190:193], v[198:201], v[40:43]
	v_mfma_f32_16x16x32_bf16 v[60:63], v[162:165], v[206:209], v[60:63]
	v_mfma_f32_16x16x32_bf16 v[32:35], v[190:193], v[206:209], v[32:35]
	v_mfma_f32_16x16x32_bf16 v[52:55], v[162:165], v[214:217], v[52:55]
	v_mfma_f32_16x16x32_bf16 v[24:27], v[190:193], v[214:217], v[24:27]
	v_mfma_f32_16x16x32_bf16 v[48:51], v[162:165], v[224:227], v[48:51]
	v_mfma_f32_16x16x32_bf16 v[16:19], v[190:193], v[224:227], v[16:19]
	s_setprio 0
	s_barrier
; #define PG8_STAGE(bufoff, gbase, voff) do { _Pragma("unroll") for (int _i = 0; _i < 2; ++_i) \
;         __builtin_amdgcn_global_load_lds((const unsigned*)((const char*)(gbase) + (voff)[_i]), (PG8_LAS unsigned*)(lds + (bufoff) + ldsw + _i * 8192), 16, 0, 0); } while (0)
; #define PG8_LDA(dst, b, h) do { _Pragma("unroll") for (int m = 0; m < 4; ++m) _Pragma("unroll") for (int k = 0; k < 2; ++k) dst[m][k] = *(const PG8_LAS bf16x8*)(lds + PG8_SA(b, h) + aoff + m * 2048 + k * 1024); } while (0)
; #define PG8_LDB(dst, b, h) do { _Pragma("unroll") for (int n = 0; n < 2; ++n) _Pragma("unroll") for (int k = 0; k < 2; ++k) dst[n][k] = *(const PG8_LAS bf16x8*)(lds + PG8_SB(b, h) + boff + n * 2048 + k * 1024); } while (0)
; #define PG8_MMA(ai, bj, At, Bt) do { __builtin_amdgcn_s_setprio(1); _Pragma("unroll") for (int m = 0; m < 4; ++m) _Pragma("unroll") for (int n = 0; n < 2; ++n) _Pragma("unroll") for (int k = 0; k < 2; ++k) \
;         acc[ai][bj][m][n] = __builtin_amdgcn_mfma_f32_16x16x32_bf16(Bt[n][k], At[m][k], acc[ai][bj][m][n], 0, 0, 0); __builtin_amdgcn_s_setprio(0); } while (0)
; #define PG8_WAIT_V(n) asm volatile("s_waitcnt vmcnt(" #n ")" ::: "memory")
; #define PG8_WAIT_L(n) asm volatile("s_waitcnt lgkmcnt(" #n ")" ::: "memory")
; #define PG8_BAR __builtin_amdgcn_s_barrier()
; #define PG8_SCHED __builtin_amdgcn_sched_barrier(0)
; template <class Epi, class Sched, bool ALIGN_EPI = false, bool SP2 = false>
; __device__ __forceinline__ void gemm_phase(PG8_LAS unsigned char* lds, const Gemm g, const Sched& S, const Epi& E) {
;     ...
;             PG8_LDB(B0, 0, 0); PG8_LDB(B1, 0, 1); PG8_SCHED; PG8_LDA(At, 0, 0); PG8_STAGE(PG8_SA(1, 1), a1 + hstep, voffA);
;             PG8_WAIT_V(8); PG8_WAIT_L(0); PG8_BAR; PG8_MMA(0, 0, At, B0); PG8_MMA(0, 1, At, B1); PG8_BAR; PG8_SCHED;
;     ...
;             PG8_LDA(At, 1, 1); PG8_STAGE(PG8_SB(1, 0), b3, voffB); PG8_STAGE(PG8_SB(1, 1), b3 + hstep, voffB); PG8_STAGE(PG8_SA(1, 0), a3, voffA);
;             PG8_WAIT_V(8); PG8_WAIT_L(0); PG8_BAR; PG8_MMA(1, 0, At, B0); PG8_MMA(1, 1, At, B1); PG8_BAR; PG8_SCHED;
	s_mov_b32 m0, s60
	v_lshl_add_u64 v[170:171], v[170:171], 0, s[10:11]
	s_add_u32 s40, s52, 0x40080
	ds_read_b128 v[194:197], v172 offset:49152
	ds_read_b128 v[198:201], v172 offset:50176
	ds_read_b128 v[202:205], v172 offset:51200
	ds_read_b128 v[206:209], v172 offset:52224
	ds_read_b128 v[210:213], v172 offset:53248
	ds_read_b128 v[214:217], v172 offset:54272
	ds_read_b128 v[218:221], v172 offset:55296
	ds_read_b128 v[224:227], v172 offset:56320
	global_load_lds_dwordx4 v[170:171], off
	v_lshl_add_u64 v[170:171], v[228:229], 0, s[10:11]
	s_mov_b32 m0, s61
	s_addc_u32 s41, s53, 0
	global_load_lds_dwordx4 v[170:171], off
	s_mov_b32 m0, s64
	v_lshl_add_u64 v[170:171], s[40:41], 0, v[128:129]
	global_load_lds_dwordx4 v[170:171], off
	s_mov_b32 m0, s65
	v_lshl_add_u64 v[170:171], s[40:41], 0, v[130:131]
	global_load_lds_dwordx4 v[170:171], off
	s_mov_b32 m0, s62
	v_lshl_add_u64 v[170:171], v[236:237], 0, s[10:11]
	global_load_lds_dwordx4 v[170:171], off
	s_mov_b32 m0, s63
	v_lshl_add_u64 v[170:171], v[238:239], 0, s[10:11]
	global_load_lds_dwordx4 v[170:171], off
	s_waitcnt vmcnt(8)
	s_waitcnt lgkmcnt(0)
	s_barrier
	s_setprio 1
	s_waitcnt lgkmcnt(0)
	v_mfma_f32_16x16x32_bf16 v[104:107], v[142:145], v[194:197], v[104:107]
	v_mfma_f32_16x16x32_bf16 v[76:79], v[150:153], v[194:197], v[76:79]
	v_mfma_f32_16x16x32_bf16 v[100:103], v[142:145], v[202:205], v[100:103]
	v_mfma_f32_16x16x32_bf16 v[72:75], v[150:153], v[202:205], v[72:75]
	v_mfma_f32_16x16x32_bf16 v[92:95], v[142:145], v[210:213], v[92:95]
	v_mfma_f32_16x16x32_bf16 v[64:67], v[150:153], v[210:213], v[64:67]
	v_mfma_f32_16x16x32_bf16 v[80:83], v[142:145], v[218:221], v[80:83]
	v_mfma_f32_16x16x32_bf16 v[56:59], v[150:153], v[218:221], v[56:59]
	v_mfma_f32_16x16x32_bf16 v[104:107], v[146:149], v[198:201], v[104:107]
	v_mfma_f32_16x16x32_bf16 v[76:79], v[154:157], v[198:201], v[76:79]
	v_mfma_f32_16x16x32_bf16 v[100:103], v[146:149], v[206:209], v[100:103]
	v_mfma_f32_16x16x32_bf16 v[72:75], v[154:157], v[206:209], v[72:75]
	v_mfma_f32_16x16x32_bf16 v[92:95], v[146:149], v[214:217], v[92:95]
	v_mfma_f32_16x16x32_bf16 v[64:67], v[154:157], v[214:217], v[64:67]
	v_mfma_f32_16x16x32_bf16 v[80:83], v[146:149], v[224:227], v[80:83]
	v_mfma_f32_16x16x32_bf16 v[56:59], v[154:157], v[224:227], v[56:59]
	s_setprio 0
	s_setprio 1
	v_mfma_f32_16x16x32_bf16 v[44:47], v[158:161], v[194:197], v[44:47]
	v_mfma_f32_16x16x32_bf16 v[12:15], v[166:169], v[194:197], v[12:15]
	v_mfma_f32_16x16x32_bf16 v[36:39], v[158:161], v[202:205], v[36:39]
	v_mfma_f32_16x16x32_bf16 v[8:11], v[166:169], v[202:205], v[8:11]
	v_mfma_f32_16x16x32_bf16 v[28:31], v[158:161], v[210:213], v[28:31]
	v_mfma_f32_16x16x32_bf16 v[4:7], v[166:169], v[210:213], v[4:7]
	v_mfma_f32_16x16x32_bf16 v[20:23], v[158:161], v[218:221], v[20:23]
	v_mfma_f32_16x16x32_bf16 v[0:3], v[166:169], v[218:221], v[0:3]
	v_mfma_f32_16x16x32_bf16 v[44:47], v[162:165], v[198:201], v[44:47]
	v_mfma_f32_16x16x32_bf16 v[12:15], v[190:193], v[198:201], v[12:15]
	v_mfma_f32_16x16x32_bf16 v[36:39], v[162:165], v[206:209], v[36:39]
	v_mfma_f32_16x16x32_bf16 v[8:11], v[190:193], v[206:209], v[8:11]
	v_mfma_f32_16x16x32_bf16 v[28:31], v[162:165], v[214:217], v[28:31]
	v_mfma_f32_16x16x32_bf16 v[4:7], v[190:193], v[214:217], v[4:7]
	v_mfma_f32_16x16x32_bf16 v[20:23], v[162:165], v[224:227], v[20:23]
	v_mfma_f32_16x16x32_bf16 v[0:3], v[190:193], v[224:227], v[0:3]
	s_setprio 0
	s_barrier
	s_add_i32 s79, s79, 2
	s_add_u32 s77, s77, 0x100
	s_addc_u32 s78, s78, 0
	s_mov_b64 s[40:41], s[50:51]
.LBB0_1307:
	ds_read_b128 v[142:145], v174
	ds_read_b128 v[146:149], v175
	ds_read_b128 v[150:153], v176
	ds_read_b128 v[154:157], v177
	ds_read_b128 v[158:161], v178
	ds_read_b128 v[162:165], v179
	ds_read_b128 v[166:169], v180
	ds_read_b128 v[190:193], v181
	s_add_u32 s50, s40, 0x100
	s_addc_u32 s51, s41, 0
	s_cmp_eq_u32 s79, 12
	s_cselect_b32 s55, s21, s51
	s_cselect_b32 s54, s37, s50
	s_cselect_b32 s53, s19, s78
	s_cselect_b32 s52, s76, s77
	s_mov_b32 m0, s68
	v_lshl_add_u64 v[170:171], s[40:41], 0, v[134:135]
	ds_read_b128 v[194:197], v172
	ds_read_b128 v[198:201], v172 offset:1024
	ds_read_b128 v[202:205], v172 offset:2048
	ds_read_b128 v[206:209], v172 offset:3072
	ds_read_b128 v[210:213], v172 offset:4096
	ds_read_b128 v[214:217], v172 offset:5120
	ds_read_b128 v[218:221], v172 offset:6144
	ds_read_b128 v[224:227], v172 offset:7168
	global_load_lds_dwordx4 v[170:171], off
	s_mov_b32 m0, s69
	v_lshl_add_u64 v[170:171], s[40:41], 0, v[136:137]
	global_load_lds_dwordx4 v[170:171], off
	s_waitcnt vmcnt(8)
	s_waitcnt lgkmcnt(0)
	s_barrier
; #define PG8_STAGE(bufoff, gbase, voff) do { _Pragma("unroll") for (int _i = 0; _i < 2; ++_i) \
;         __builtin_amdgcn_global_load_lds((const unsigned*)((const char*)(gbase) + (voff)[_i]), (PG8_LAS unsigned*)(lds + (bufoff) + ldsw + _i * 8192), 16, 0, 0); } while (0)
; #define PG8_LDA(dst, b, h) do { _Pragma("unroll") for (int m = 0; m < 4; ++m) _Pragma("unroll") for (int k = 0; k < 2; ++k) dst[m][k] = *(const PG8_LAS bf16x8*)(lds + PG8_SA(b, h) + aoff + m * 2048 + k * 1024); } while (0)
; #define PG8_MMA(ai, bj, At, Bt) do { __builtin_amdgcn_s_setprio(1); _Pragma("unroll") for (int m = 0; m < 4; ++m) _Pragma("unroll") for (int n = 0; n < 2; ++n) _Pragma("unroll") for (int k = 0; k < 2; ++k) \
;         acc[ai][bj][m][n] = __builtin_amdgcn_mfma_f32_16x16x32_bf16(Bt[n][k], At[m][k], acc[ai][bj][m][n], 0, 0, 0); __builtin_amdgcn_s_setprio(0); } while (0)
; #define PG8_WAIT_V(n) asm volatile("s_waitcnt vmcnt(" #n ")" ::: "memory")
; #define PG8_WAIT_L(n) asm volatile("s_waitcnt lgkmcnt(" #n ")" ::: "memory")
; #define PG8_BAR __builtin_amdgcn_s_barrier()
; #define PG8_SCHED __builtin_amdgcn_sched_barrier(0)
; template <class Epi, class Sched, bool ALIGN_EPI = false, bool SP2 = false>
; __device__ __forceinline__ void gemm_phase(PG8_LAS unsigned char* lds, const Gemm g, const Sched& S, const Epi& E) {
;     ...
;             PG8_WAIT_V(8); PG8_WAIT_L(0); PG8_BAR; PG8_MMA(0, 0, At, B0); PG8_MMA(0, 1, At, B1); PG8_BAR; PG8_SCHED;
;             PG8_LDA(At, 0, 1); PG8_STAGE(PG8_SB(0, 0), b2, voffB); PG8_STAGE(PG8_SB(0, 1), b2 + hstep, voffB); PG8_STAGE(PG8_SA(0, 0), a2, voffA);
;             PG8_WAIT_V(8); PG8_WAIT_L(0); PG8_BAR; PG8_MMA(1, 0, At, B0); PG8_MMA(1, 1, At, B1); PG8_BAR; PG8_SCHED;
	s_setprio 1
	s_waitcnt lgkmcnt(0)
	v_mfma_f32_16x16x32_bf16 v[124:127], v[142:145], v[194:197], v[124:127]
	v_mfma_f32_16x16x32_bf16 v[108:111], v[150:153], v[194:197], v[108:111]
	v_mfma_f32_16x16x32_bf16 v[120:123], v[142:145], v[202:205], v[120:123]
	v_mfma_f32_16x16x32_bf16 v[96:99], v[150:153], v[202:205], v[96:99]
	v_mfma_f32_16x16x32_bf16 v[116:119], v[142:145], v[210:213], v[116:119]
	v_mfma_f32_16x16x32_bf16 v[88:91], v[150:153], v[210:213], v[88:91]
	v_mfma_f32_16x16x32_bf16 v[112:115], v[142:145], v[218:221], v[112:115]
	v_mfma_f32_16x16x32_bf16 v[84:87], v[150:153], v[218:221], v[84:87]
	v_mfma_f32_16x16x32_bf16 v[124:127], v[146:149], v[198:201], v[124:127]
	v_mfma_f32_16x16x32_bf16 v[108:111], v[154:157], v[198:201], v[108:111]
	v_mfma_f32_16x16x32_bf16 v[120:123], v[146:149], v[206:209], v[120:123]
	v_mfma_f32_16x16x32_bf16 v[96:99], v[154:157], v[206:209], v[96:99]
	v_mfma_f32_16x16x32_bf16 v[116:119], v[146:149], v[214:217], v[116:119]
	v_mfma_f32_16x16x32_bf16 v[88:91], v[154:157], v[214:217], v[88:91]
	v_mfma_f32_16x16x32_bf16 v[112:115], v[146:149], v[224:227], v[112:115]
	v_mfma_f32_16x16x32_bf16 v[84:87], v[154:157], v[224:227], v[84:87]
	s_setprio 0
	s_setprio 1
	v_mfma_f32_16x16x32_bf16 v[68:71], v[158:161], v[194:197], v[68:71]
	v_mfma_f32_16x16x32_bf16 v[40:43], v[166:169], v[194:197], v[40:43]
	v_mfma_f32_16x16x32_bf16 v[60:63], v[158:161], v[202:205], v[60:63]
	v_mfma_f32_16x16x32_bf16 v[32:35], v[166:169], v[202:205], v[32:35]
	v_mfma_f32_16x16x32_bf16 v[52:55], v[158:161], v[210:213], v[52:55]
	v_mfma_f32_16x16x32_bf16 v[24:27], v[166:169], v[210:213], v[24:27]
	v_mfma_f32_16x16x32_bf16 v[48:51], v[158:161], v[218:221], v[48:51]
	v_mfma_f32_16x16x32_bf16 v[16:19], v[166:169], v[218:221], v[16:19]
	v_mfma_f32_16x16x32_bf16 v[68:71], v[162:165], v[198:201], v[68:71]
	v_mfma_f32_16x16x32_bf16 v[40:43], v[190:193], v[198:201], v[40:43]
	v_mfma_f32_16x16x32_bf16 v[60:63], v[162:165], v[206:209], v[60:63]
	v_mfma_f32_16x16x32_bf16 v[32:35], v[190:193], v[206:209], v[32:35]
	v_mfma_f32_16x16x32_bf16 v[52:55], v[162:165], v[214:217], v[52:55]
	v_mfma_f32_16x16x32_bf16 v[24:27], v[190:193], v[214:217], v[24:27]
	v_mfma_f32_16x16x32_bf16 v[48:51], v[162:165], v[224:227], v[48:51]
	v_mfma_f32_16x16x32_bf16 v[16:19], v[190:193], v[224:227], v[16:19]
	s_setprio 0
	s_barrier
	s_mov_b32 m0, s12
	v_lshl_add_u64 v[170:171], s[52:53], 0, v[128:129]
	s_add_u32 s40, s52, 0x40000
	ds_read_b128 v[194:197], v172 offset:16384
	ds_read_b128 v[198:201], v172 offset:17408
	ds_read_b128 v[202:205], v172 offset:18432
	ds_read_b128 v[206:209], v172 offset:19456
	ds_read_b128 v[210:213], v172 offset:20480
	ds_read_b128 v[214:217], v172 offset:21504
	ds_read_b128 v[218:221], v172 offset:22528
	ds_read_b128 v[224:227], v172 offset:23552
	global_load_lds_dwordx4 v[170:171], off
	v_lshl_add_u64 v[228:229], s[52:53], 0, v[130:131]
	s_mov_b32 m0, s13
	s_addc_u32 s41, s53, 0
	global_load_lds_dwordx4 v[228:229], off
	v_lshl_add_u64 v[236:237], s[40:41], 0, v[128:129]
	s_mov_b32 m0, s14
	v_lshl_add_u64 v[238:239], s[54:55], 0, v[130:131]
	global_load_lds_dwordx4 v[236:237], off
	s_mov_b32 m0, s15
	v_lshl_add_u64 v[236:237], s[40:41], 0, v[130:131]
	global_load_lds_dwordx4 v[236:237], off
	s_mov_b32 m0, s5
	v_lshl_add_u64 v[236:237], s[54:55], 0, v[128:129]
	global_load_lds_dwordx4 v[236:237], off
	s_mov_b32 m0, s39
	s_nop 0
	global_load_lds_dwordx4 v[238:239], off
	s_waitcnt vmcnt(8)
	s_waitcnt lgkmcnt(0)
	s_barrier
	s_setprio 1
	s_waitcnt lgkmcnt(0)
	v_mfma_f32_16x16x32_bf16 v[104:107], v[142:145], v[194:197], v[104:107]
	v_mfma_f32_16x16x32_bf16 v[76:79], v[150:153], v[194:197], v[76:79]
	v_mfma_f32_16x16x32_bf16 v[100:103], v[142:145], v[202:205], v[100:103]
	v_mfma_f32_16x16x32_bf16 v[72:75], v[150:153], v[202:205], v[72:75]
	v_mfma_f32_16x16x32_bf16 v[92:95], v[142:145], v[210:213], v[92:95]
	v_mfma_f32_16x16x32_bf16 v[64:67], v[150:153], v[210:213], v[64:67]
	v_mfma_f32_16x16x32_bf16 v[80:83], v[142:145], v[218:221], v[80:83]
	v_mfma_f32_16x16x32_bf16 v[56:59], v[150:153], v[218:221], v[56:59]
	v_mfma_f32_16x16x32_bf16 v[104:107], v[146:149], v[198:201], v[104:107]
	v_mfma_f32_16x16x32_bf16 v[76:79], v[154:157], v[198:201], v[76:79]
	v_mfma_f32_16x16x32_bf16 v[100:103], v[146:149], v[206:209], v[100:103]
	v_mfma_f32_16x16x32_bf16 v[72:75], v[154:157], v[206:209], v[72:75]
	v_mfma_f32_16x16x32_bf16 v[92:95], v[146:149], v[214:217], v[92:95]
	v_mfma_f32_16x16x32_bf16 v[64:67], v[154:157], v[214:217], v[64:67]
	v_mfma_f32_16x16x32_bf16 v[80:83], v[146:149], v[224:227], v[80:83]
	v_mfma_f32_16x16x32_bf16 v[56:59], v[154:157], v[224:227], v[56:59]
	s_setprio 0
	s_setprio 1
	v_mfma_f32_16x16x32_bf16 v[44:47], v[158:161], v[194:197], v[44:47]
	v_mfma_f32_16x16x32_bf16 v[12:15], v[166:169], v[194:197], v[12:15]
	v_mfma_f32_16x16x32_bf16 v[36:39], v[158:161], v[202:205], v[36:39]
	v_mfma_f32_16x16x32_bf16 v[8:11], v[166:169], v[202:205], v[8:11]
	v_mfma_f32_16x16x32_bf16 v[28:31], v[158:161], v[210:213], v[28:31]
	v_mfma_f32_16x16x32_bf16 v[4:7], v[166:169], v[210:213], v[4:7]
	v_mfma_f32_16x16x32_bf16 v[20:23], v[158:161], v[218:221], v[20:23]
	v_mfma_f32_16x16x32_bf16 v[0:3], v[166:169], v[218:221], v[0:3]
	v_mfma_f32_16x16x32_bf16 v[44:47], v[162:165], v[198:201], v[44:47]
	v_mfma_f32_16x16x32_bf16 v[12:15], v[190:193], v[198:201], v[12:15]
	v_mfma_f32_16x16x32_bf16 v[36:39], v[162:165], v[206:209], v[36:39]
	v_mfma_f32_16x16x32_bf16 v[8:11], v[190:193], v[206:209], v[8:11]
	v_mfma_f32_16x16x32_bf16 v[28:31], v[162:165], v[214:217], v[28:31]
	v_mfma_f32_16x16x32_bf16 v[4:7], v[190:193], v[214:217], v[4:7]
	v_mfma_f32_16x16x32_bf16 v[20:23], v[162:165], v[224:227], v[20:23]
	v_mfma_f32_16x16x32_bf16 v[0:3], v[190:193], v[224:227], v[0:3]
	s_setprio 0
	s_barrier
; #define PG8_STAGE(bufoff, gbase, voff) do { _Pragma("unroll") for (int _i = 0; _i < 2; ++_i) \
;         __builtin_amdgcn_global_load_lds((const unsigned*)((const char*)(gbase) + (voff)[_i]), (PG8_LAS unsigned*)(lds + (bufoff) + ldsw + _i * 8192), 16, 0, 0); } while (0)
; #define PG8_LDA(dst, b, h) do { _Pragma("unroll") for (int m = 0; m < 4; ++m) _Pragma("unroll") for (int k = 0; k < 2; ++k) dst[m][k] = *(const PG8_LAS bf16x8*)(lds + PG8_SA(b, h) + aoff + m * 2048 + k * 1024); } while (0)
; #define PG8_LDB(dst, b, h) do { _Pragma("unroll") for (int n = 0; n < 2; ++n) _Pragma("unroll") for (int k = 0; k < 2; ++k) dst[n][k] = *(const PG8_LAS bf16x8*)(lds + PG8_SB(b, h) + boff + n * 2048 + k * 1024); } while (0)
; #define PG8_MMA(ai, bj, At, Bt) do { __builtin_amdgcn_s_setprio(1); _Pragma("unroll") for (int m = 0; m < 4; ++m) _Pragma("unroll") for (int n = 0; n < 2; ++n) _Pragma("unroll") for (int k = 0; k < 2; ++k) \
;         acc[ai][bj][m][n] = __builtin_amdgcn_mfma_f32_16x16x32_bf16(Bt[n][k], At[m][k], acc[ai][bj][m][n], 0, 0, 0); __builtin_amdgcn_s_setprio(0); } while (0)
; #define PG8_WAIT_V(n) asm volatile("s_waitcnt vmcnt(" #n ")" ::: "memory")
; #define PG8_WAIT_L(n) asm volatile("s_waitcnt lgkmcnt(" #n ")" ::: "memory")
; template <class Epi, class Sched, bool ALIGN_EPI = false, bool SP2 = false>
; __device__ __forceinline__ void gemm_phase(PG8_LAS unsigned char* lds, const Gemm g, const Sched& S, const Epi& E) {
;     ...
;         for (int t = 0; t < nt; t += 2) {
;             const bool last = (t == nt - 2);
;             const char* a1 = cA + (size_t)(t + 1) * kstep;
;             const char* a2 = last ? nA : cA + (size_t)(t + 2) * kstep; const char* b2 = last ? nB : cB + (size_t)(t + 2) * kstep;
;             const char* a3 = a2 + kstep; const char* b3 = b2 + kstep;
;     ...
;             PG8_LDB(B0, 1, 0); PG8_LDB(B1, 1, 1); PG8_SCHED; PG8_LDA(At, 1, 0); PG8_STAGE(PG8_SA(0, 1), a2 + hstep, voffA);
;             PG8_WAIT_V(8); PG8_WAIT_L(0); PG8_BAR; PG8_MMA(0, 0, At, B0); PG8_MMA(0, 1, At, B1); PG8_BAR; PG8_SCHED;
;             PG8_LDA(At, 1, 1); PG8_STAGE(PG8_SB(1, 0), b3, voffB); PG8_STAGE(PG8_SB(1, 1), b3 + hstep, voffB); PG8_STAGE(PG8_SA(1, 0), a3, voffA);
;             PG8_WAIT_V(8); PG8_WAIT_L(0); PG8_BAR; PG8_MMA(1, 0, At, B0); PG8_MMA(1, 1, At, B1); PG8_BAR; PG8_SCHED;
;     ...
;         if constexpr (ALIGN_EPI) { if (wr == 0) PG8_BAR; }
	ds_read_b128 v[142:145], v182
	ds_read_b128 v[146:149], v183
	ds_read_b128 v[150:153], v184
	ds_read_b128 v[154:157], v185
	ds_read_b128 v[158:161], v186
	ds_read_b128 v[162:165], v187
	ds_read_b128 v[166:169], v188
	ds_read_b128 v[190:193], v189
	s_add_u32 s40, s54, 0x40000
	s_addc_u32 s41, s55, 0
	s_mov_b32 m0, s43
	v_lshl_add_u64 v[240:241], s[40:41], 0, v[128:129]
	ds_read_b128 v[194:197], v172 offset:32768
	ds_read_b128 v[198:201], v172 offset:33792
	ds_read_b128 v[202:205], v172 offset:34816
	ds_read_b128 v[206:209], v172 offset:35840
	ds_read_b128 v[210:213], v172 offset:36864
	ds_read_b128 v[214:217], v172 offset:37888
	ds_read_b128 v[218:221], v172 offset:38912
	ds_read_b128 v[224:227], v172 offset:39936
	global_load_lds_dwordx4 v[240:241], off
	s_mov_b32 m0, s56
	v_lshl_add_u64 v[240:241], s[40:41], 0, v[130:131]
	global_load_lds_dwordx4 v[240:241], off
	s_waitcnt vmcnt(8)
	s_waitcnt lgkmcnt(0)
	s_barrier
	s_setprio 1
	s_waitcnt lgkmcnt(0)
	v_mfma_f32_16x16x32_bf16 v[124:127], v[142:145], v[194:197], v[124:127]
	v_mfma_f32_16x16x32_bf16 v[108:111], v[150:153], v[194:197], v[108:111]
	v_mfma_f32_16x16x32_bf16 v[120:123], v[142:145], v[202:205], v[120:123]
	v_mfma_f32_16x16x32_bf16 v[96:99], v[150:153], v[202:205], v[96:99]
	v_mfma_f32_16x16x32_bf16 v[116:119], v[142:145], v[210:213], v[116:119]
	v_mfma_f32_16x16x32_bf16 v[88:91], v[150:153], v[210:213], v[88:91]
	v_mfma_f32_16x16x32_bf16 v[112:115], v[142:145], v[218:221], v[112:115]
	v_mfma_f32_16x16x32_bf16 v[84:87], v[150:153], v[218:221], v[84:87]
	v_mfma_f32_16x16x32_bf16 v[124:127], v[146:149], v[198:201], v[124:127]
	v_mfma_f32_16x16x32_bf16 v[108:111], v[154:157], v[198:201], v[108:111]
	v_mfma_f32_16x16x32_bf16 v[120:123], v[146:149], v[206:209], v[120:123]
	v_mfma_f32_16x16x32_bf16 v[96:99], v[154:157], v[206:209], v[96:99]
	v_mfma_f32_16x16x32_bf16 v[116:119], v[146:149], v[214:217], v[116:119]
	v_mfma_f32_16x16x32_bf16 v[88:91], v[154:157], v[214:217], v[88:91]
	v_mfma_f32_16x16x32_bf16 v[112:115], v[146:149], v[224:227], v[112:115]
	v_mfma_f32_16x16x32_bf16 v[84:87], v[154:157], v[224:227], v[84:87]
	s_setprio 0
	s_setprio 1
	v_mfma_f32_16x16x32_bf16 v[68:71], v[158:161], v[194:197], v[68:71]
	v_mfma_f32_16x16x32_bf16 v[40:43], v[166:169], v[194:197], v[40:43]
	v_mfma_f32_16x16x32_bf16 v[60:63], v[158:161], v[202:205], v[60:63]
	v_mfma_f32_16x16x32_bf16 v[32:35], v[166:169], v[202:205], v[32:35]
	v_mfma_f32_16x16x32_bf16 v[52:55], v[158:161], v[210:213], v[52:55]
	v_mfma_f32_16x16x32_bf16 v[24:27], v[166:169], v[210:213], v[24:27]
	v_mfma_f32_16x16x32_bf16 v[48:51], v[158:161], v[218:221], v[48:51]
	v_mfma_f32_16x16x32_bf16 v[16:19], v[166:169], v[218:221], v[16:19]
	v_mfma_f32_16x16x32_bf16 v[68:71], v[162:165], v[198:201], v[68:71]
	v_mfma_f32_16x16x32_bf16 v[40:43], v[190:193], v[198:201], v[40:43]
	v_mfma_f32_16x16x32_bf16 v[60:63], v[162:165], v[206:209], v[60:63]
	v_mfma_f32_16x16x32_bf16 v[32:35], v[190:193], v[206:209], v[32:35]
	v_mfma_f32_16x16x32_bf16 v[52:55], v[162:165], v[214:217], v[52:55]
	v_mfma_f32_16x16x32_bf16 v[24:27], v[190:193], v[214:217], v[24:27]
	v_mfma_f32_16x16x32_bf16 v[48:51], v[162:165], v[224:227], v[48:51]
	v_mfma_f32_16x16x32_bf16 v[16:19], v[190:193], v[224:227], v[16:19]
	s_setprio 0
	s_barrier
	s_mov_b32 m0, s60
	v_lshl_add_u64 v[170:171], v[170:171], 0, s[10:11]
	s_add_u32 s40, s52, 0x40080
	ds_read_b128 v[194:197], v172 offset:49152
	ds_read_b128 v[198:201], v172 offset:50176
	ds_read_b128 v[202:205], v172 offset:51200
	ds_read_b128 v[206:209], v172 offset:52224
	ds_read_b128 v[210:213], v172 offset:53248
	ds_read_b128 v[214:217], v172 offset:54272
	ds_read_b128 v[218:221], v172 offset:55296
	ds_read_b128 v[224:227], v172 offset:56320
	global_load_lds_dwordx4 v[170:171], off
	v_lshl_add_u64 v[170:171], v[228:229], 0, s[10:11]
	s_mov_b32 m0, s61
	s_addc_u32 s41, s53, 0
	global_load_lds_dwordx4 v[170:171], off
	s_mov_b32 m0, s64
	v_lshl_add_u64 v[170:171], s[40:41], 0, v[128:129]
	global_load_lds_dwordx4 v[170:171], off
	s_mov_b32 m0, s65
	v_lshl_add_u64 v[170:171], s[40:41], 0, v[130:131]
	global_load_lds_dwordx4 v[170:171], off
	s_mov_b32 m0, s62
	v_lshl_add_u64 v[170:171], v[236:237], 0, s[10:11]
	global_load_lds_dwordx4 v[170:171], off
	s_mov_b32 m0, s63
	v_lshl_add_u64 v[170:171], v[238:239], 0, s[10:11]
	global_load_lds_dwordx4 v[170:171], off
	s_waitcnt vmcnt(8)
	s_waitcnt lgkmcnt(0)
	s_barrier
	s_setprio 1
	s_waitcnt lgkmcnt(0)
	v_mfma_f32_16x16x32_bf16 v[104:107], v[142:145], v[194:197], v[104:107]
	v_mfma_f32_16x16x32_bf16 v[76:79], v[150:153], v[194:197], v[76:79]
	v_mfma_f32_16x16x32_bf16 v[100:103], v[142:145], v[202:205], v[100:103]
	v_mfma_f32_16x16x32_bf16 v[72:75], v[150:153], v[202:205], v[72:75]
	v_mfma_f32_16x16x32_bf16 v[92:95], v[142:145], v[210:213], v[92:95]
	v_mfma_f32_16x16x32_bf16 v[64:67], v[150:153], v[210:213], v[64:67]
	v_mfma_f32_16x16x32_bf16 v[80:83], v[142:145], v[218:221], v[80:83]
	v_mfma_f32_16x16x32_bf16 v[56:59], v[150:153], v[218:221], v[56:59]
	v_mfma_f32_16x16x32_bf16 v[104:107], v[146:149], v[198:201], v[104:107]
	v_mfma_f32_16x16x32_bf16 v[76:79], v[154:157], v[198:201], v[76:79]
	v_mfma_f32_16x16x32_bf16 v[100:103], v[146:149], v[206:209], v[100:103]
	v_mfma_f32_16x16x32_bf16 v[72:75], v[154:157], v[206:209], v[72:75]
	v_mfma_f32_16x16x32_bf16 v[92:95], v[146:149], v[214:217], v[92:95]
	v_mfma_f32_16x16x32_bf16 v[64:67], v[154:157], v[214:217], v[64:67]
	v_mfma_f32_16x16x32_bf16 v[80:83], v[146:149], v[224:227], v[80:83]
	v_mfma_f32_16x16x32_bf16 v[56:59], v[154:157], v[224:227], v[56:59]
	s_setprio 0
	s_setprio 1
	v_mfma_f32_16x16x32_bf16 v[44:47], v[158:161], v[194:197], v[44:47]
	v_mfma_f32_16x16x32_bf16 v[12:15], v[166:169], v[194:197], v[12:15]
	v_mfma_f32_16x16x32_bf16 v[36:39], v[158:161], v[202:205], v[36:39]
	v_mfma_f32_16x16x32_bf16 v[8:11], v[166:169], v[202:205], v[8:11]
	v_mfma_f32_16x16x32_bf16 v[28:31], v[158:161], v[210:213], v[28:31]
	v_mfma_f32_16x16x32_bf16 v[4:7], v[166:169], v[210:213], v[4:7]
	v_mfma_f32_16x16x32_bf16 v[20:23], v[158:161], v[218:221], v[20:23]
	v_mfma_f32_16x16x32_bf16 v[0:3], v[166:169], v[218:221], v[0:3]
	v_mfma_f32_16x16x32_bf16 v[44:47], v[162:165], v[198:201], v[44:47]
	v_mfma_f32_16x16x32_bf16 v[12:15], v[190:193], v[198:201], v[12:15]
	v_mfma_f32_16x16x32_bf16 v[36:39], v[162:165], v[206:209], v[36:39]
	v_mfma_f32_16x16x32_bf16 v[8:11], v[190:193], v[206:209], v[8:11]
	v_mfma_f32_16x16x32_bf16 v[28:31], v[162:165], v[214:217], v[28:31]
	v_mfma_f32_16x16x32_bf16 v[4:7], v[190:193], v[214:217], v[4:7]
	v_mfma_f32_16x16x32_bf16 v[20:23], v[162:165], v[224:227], v[20:23]
	v_mfma_f32_16x16x32_bf16 v[0:3], v[190:193], v[224:227], v[0:3]
	s_setprio 0
	s_barrier
	s_add_i32 s79, s79, 2
	s_add_u32 s77, s77, 0x100
	s_addc_u32 s78, s78, 0
	s_cmp_gt_u32 s79, 13
	s_mov_b64 s[40:41], s[50:51]
	s_cbranch_scc0 .LBB0_1307
	s_and_b64 vcc, exec, s[16:17]
	s_cbranch_vccz .LBB0_1310
	s_barrier

;     __host__ __device__ bool next(int i, Unit& u) const { const int L = i * G + c; if (L >= 16 * nkc) return false; u.kc = L % nkc; const int t = L / nkc; u.pn = t & 3; u.pm = 33 * (t >> 2); return true; }
; #define PG8_STAGE(bufoff, gbase, voff) do { _Pragma("unroll") for (int _i = 0; _i < 2; ++_i) \
;         __builtin_amdgcn_global_load_lds((const unsigned*)((const char*)(gbase) + (voff)[_i]), (PG8_LAS unsigned*)(lds + (bufoff) + ldsw + _i * 8192), 16, 0, 0); } while (0)
; #define PG8_LDA(dst, b, h) do { _Pragma("unroll") for (int m = 0; m < 4; ++m) _Pragma("unroll") for (int k = 0; k < 2; ++k) dst[m][k] = *(const PG8_LAS bf16x8*)(lds + PG8_SA(b, h) + aoff + m * 2048 + k * 1024); } while (0)
; #define PG8_LDB(dst, b, h) do { _Pragma("unroll") for (int n = 0; n < 2; ++n) _Pragma("unroll") for (int k = 0; k < 2; ++k) dst[n][k] = *(const PG8_LAS bf16x8*)(lds + PG8_SB(b, h) + boff + n * 2048 + k * 1024); } while (0)
; #define PG8_BAR __builtin_amdgcn_s_barrier()
; template <class Epi, class Sched, bool ALIGN_EPI = false, bool SP2 = false>
; __device__ __forceinline__ void gemm_phase(PG8_LAS unsigned char* lds, const Gemm g, const Sched& S, const Epi& E) {
;     ...
;         const bool has_next = S.next(ui + 1, nxt);
;         const char* nA = has_next ? (const char*)g.A + (size_t)nxt.pm * tstep + (size_t)nxt.kc * cstep : cA; const char* nB = has_next ? (const char*)g.Bt + (size_t)nxt.pn * tstep + (size_t)nxt.kc * cstep : cB;
;         for (int t = 0; t < nt; t += 2) {
;             const bool last = (t == nt - 2);
;             const char* a1 = cA + (size_t)(t + 1) * kstep;
;             const char* a2 = last ? nA : cA + (size_t)(t + 2) * kstep; const char* b2 = last ? nB : cB + (size_t)(t + 2) * kstep;
;             const char* a3 = a2 + kstep; const char* b3 = b2 + kstep;
;             if (last && has_next) S.a_ready(nxt);
;             if constexpr (SP2) {
;             PG8_LDB(B0, 0, 0); PG8_LDB(B1, 0, 1); PG8_SCHED; PG8_LDA(At, 0, 0); PG8_STAGE(PG8_SA(1, 1), a1 + hstep, voffA);
;             PG8_WAIT_V(8); PG8_WAIT_L(0); PG8_BAR; PG8_MMA(0, 0, At, B0); PG8_MMA(0, 1, At, B1); PG8_BAR; PG8_SCHED;
;             PG8_LDA(At, 0, 1); PG8_STAGE(PG8_SB(0, 0), b2, voffB); PG8_STAGE(PG8_SB(0, 1), b2 + hstep, voffB); PG8_STAGE(PG8_SA(0, 0), a2, voffA);
;             PG8_WAIT_V(8); PG8_WAIT_L(0); PG8_BAR; PG8_MMA(1, 0, At, B0); PG8_MMA(1, 1, At, B1); PG8_BAR; PG8_SCHED;
.LBB0_1437:
	s_ashr_i32 s19, s18, 31
	s_lshl_b64 s[20:21], s[18:19], 19
	s_add_u32 s20, s46, s20
	s_addc_u32 s21, s47, s21
	s_and_b64 s[22:23], s[6:7], exec
	s_cselect_b32 s19, s21, s37
	s_cselect_b32 s66, s20, s36
	s_ashr_i32 s17, s16, 31
	s_lshl_b64 s[22:23], s[16:17], 19
	s_add_u32 s22, s1, s22
	s_addc_u32 s23, s3, s23
	s_and_b64 s[50:51], s[6:7], exec
	s_cselect_b32 s17, s23, s41
	s_cselect_b32 s67, s22, s40
	s_add_u32 s36, s36, 0x40080
	s_addc_u32 s37, s37, 0
	s_add_u32 s68, s40, 0x100
	s_addc_u32 s69, s41, 0
	s_mov_b32 s70, -2
	ds_read_b128 v[166:169], v149
	ds_read_b128 v[170:173], v150
	ds_read_b128 v[174:177], v151
	ds_read_b128 v[178:181], v152
	ds_read_b128 v[182:185], v153
	ds_read_b128 v[186:189], v154
	ds_read_b128 v[190:193], v155
	ds_read_b128 v[194:197], v156
	s_add_u32 s40, s36, 0xfffc0080
	s_addc_u32 s41, s37, -1
	s_cmp_eq_u32 s70, 12
	s_cselect_b32 s51, s19, s41
	s_cselect_b32 s50, s66, s40
	s_cselect_b32 s41, s17, s69
	s_cselect_b32 s40, s67, s68
	s_mov_b32 m0, s63
	v_lshl_add_u64 v[144:145], s[36:37], 0, v[136:137]
	ds_read_b128 v[198:201], v147
	ds_read_b128 v[202:205], v147 offset:1024
	ds_read_b128 v[206:209], v147 offset:2048
	ds_read_b128 v[210:213], v147 offset:3072
	ds_read_b128 v[214:217], v147 offset:4096
	ds_read_b128 v[218:221], v147 offset:5120
	ds_read_b128 v[224:227], v147 offset:6144
	ds_read_b128 v[236:239], v147 offset:7168
	global_load_lds_dwordx4 v[144:145], off
	s_mov_b32 m0, s64
	v_lshl_add_u64 v[144:145], s[36:37], 0, v[138:139]
	global_load_lds_dwordx4 v[144:145], off
	s_waitcnt vmcnt(8)
	s_waitcnt lgkmcnt(0)
	s_barrier
	s_setprio 1
	s_waitcnt lgkmcnt(0)
	v_mfma_f32_16x16x32_bf16 v[124:127], v[166:169], v[198:201], 0
	v_mfma_f32_16x16x32_bf16 v[120:123], v[174:177], v[198:201], 0
	v_mfma_f32_16x16x32_bf16 v[108:111], v[166:169], v[206:209], 0
	v_mfma_f32_16x16x32_bf16 v[104:107], v[174:177], v[206:209], 0
	v_mfma_f32_16x16x32_bf16 v[92:95], v[166:169], v[214:217], 0
	v_mfma_f32_16x16x32_bf16 v[88:91], v[174:177], v[214:217], 0
	v_mfma_f32_16x16x32_bf16 v[76:79], v[166:169], v[224:227], 0
	v_mfma_f32_16x16x32_bf16 v[72:75], v[174:177], v[224:227], 0
	v_mfma_f32_16x16x32_bf16 v[124:127], v[170:173], v[202:205], v[124:127]
	v_mfma_f32_16x16x32_bf16 v[120:123], v[178:181], v[202:205], v[120:123]
	v_mfma_f32_16x16x32_bf16 v[108:111], v[170:173], v[210:213], v[108:111]
	v_mfma_f32_16x16x32_bf16 v[104:107], v[178:181], v[210:213], v[104:107]
	v_mfma_f32_16x16x32_bf16 v[92:95], v[170:173], v[218:221], v[92:95]
	v_mfma_f32_16x16x32_bf16 v[88:91], v[178:181], v[218:221], v[88:91]
	v_mfma_f32_16x16x32_bf16 v[76:79], v[170:173], v[236:239], v[76:79]
	v_mfma_f32_16x16x32_bf16 v[72:75], v[178:181], v[236:239], v[72:75]
	s_setprio 0
	s_setprio 1
	v_mfma_f32_16x16x32_bf16 v[116:119], v[182:185], v[198:201], 0
	v_mfma_f32_16x16x32_bf16 v[112:115], v[190:193], v[198:201], 0
	v_mfma_f32_16x16x32_bf16 v[100:103], v[182:185], v[206:209], 0
	v_mfma_f32_16x16x32_bf16 v[96:99], v[190:193], v[206:209], 0
	v_mfma_f32_16x16x32_bf16 v[84:87], v[182:185], v[214:217], 0
	v_mfma_f32_16x16x32_bf16 v[80:83], v[190:193], v[214:217], 0
	v_mfma_f32_16x16x32_bf16 v[68:71], v[182:185], v[224:227], 0
	v_mfma_f32_16x16x32_bf16 v[64:67], v[190:193], v[224:227], 0
	v_mfma_f32_16x16x32_bf16 v[116:119], v[186:189], v[202:205], v[116:119]
	v_mfma_f32_16x16x32_bf16 v[112:115], v[194:197], v[202:205], v[112:115]
	v_mfma_f32_16x16x32_bf16 v[100:103], v[186:189], v[210:213], v[100:103]
	v_mfma_f32_16x16x32_bf16 v[96:99], v[194:197], v[210:213], v[96:99]
	v_mfma_f32_16x16x32_bf16 v[84:87], v[186:189], v[218:221], v[84:87]
	v_mfma_f32_16x16x32_bf16 v[80:83], v[194:197], v[218:221], v[80:83]
	v_mfma_f32_16x16x32_bf16 v[68:71], v[186:189], v[236:239], v[68:71]
	v_mfma_f32_16x16x32_bf16 v[64:67], v[194:197], v[236:239], v[64:67]
	s_setprio 0
	s_barrier
	s_mov_b32 m0, s15
	v_lshl_add_u64 v[144:145], s[40:41], 0, v[132:133]
	s_add_u32 s72, s40, 0x40000
	ds_read_b128 v[198:201], v147 offset:16384
	ds_read_b128 v[202:205], v147 offset:17408
	ds_read_b128 v[206:209], v147 offset:18432
	ds_read_b128 v[210:213], v147 offset:19456
	ds_read_b128 v[214:217], v147 offset:20480
	ds_read_b128 v[218:221], v147 offset:21504
	ds_read_b128 v[224:227], v147 offset:22528
	ds_read_b128 v[236:239], v147 offset:23552
	global_load_lds_dwordx4 v[144:145], off
	v_lshl_add_u64 v[228:229], s[40:41], 0, v[128:129]
	s_mov_b32 m0, s25
	s_addc_u32 s73, s41, 0
	global_load_lds_dwordx4 v[228:229], off
	v_lshl_add_u64 v[240:241], s[72:73], 0, v[132:133]
	s_mov_b32 m0, s39
	v_lshl_add_u64 v[242:243], s[50:51], 0, v[130:131]
	global_load_lds_dwordx4 v[240:241], off
	s_mov_b32 m0, s43
	v_lshl_add_u64 v[240:241], s[72:73], 0, v[128:129]
	global_load_lds_dwordx4 v[240:241], off
	s_mov_b32 m0, s4
	v_lshl_add_u64 v[240:241], s[50:51], 0, v[134:135]
	global_load_lds_dwordx4 v[240:241], off
	s_mov_b32 m0, s52
	s_nop 0
	global_load_lds_dwordx4 v[242:243], off
	s_waitcnt vmcnt(8)
	s_waitcnt lgkmcnt(0)
	s_barrier
; #define PG8_STAGE(bufoff, gbase, voff) do { _Pragma("unroll") for (int _i = 0; _i < 2; ++_i) \
;         __builtin_amdgcn_global_load_lds((const unsigned*)((const char*)(gbase) + (voff)[_i]), (PG8_LAS unsigned*)(lds + (bufoff) + ldsw + _i * 8192), 16, 0, 0); } while (0)
; #define PG8_LDA(dst, b, h) do { _Pragma("unroll") for (int m = 0; m < 4; ++m) _Pragma("unroll") for (int k = 0; k < 2; ++k) dst[m][k] = *(const PG8_LAS bf16x8*)(lds + PG8_SA(b, h) + aoff + m * 2048 + k * 1024); } while (0)
; #define PG8_LDB(dst, b, h) do { _Pragma("unroll") for (int n = 0; n < 2; ++n) _Pragma("unroll") for (int k = 0; k < 2; ++k) dst[n][k] = *(const PG8_LAS bf16x8*)(lds + PG8_SB(b, h) + boff + n * 2048 + k * 1024); } while (0)
; #define PG8_MMA(ai, bj, At, Bt) do { __builtin_amdgcn_s_setprio(1); _Pragma("unroll") for (int m = 0; m < 4; ++m) _Pragma("unroll") for (int n = 0; n < 2; ++n) _Pragma("unroll") for (int k = 0; k < 2; ++k) \
;         acc[ai][bj][m][n] = __builtin_amdgcn_mfma_f32_16x16x32_bf16(Bt[n][k], At[m][k], acc[ai][bj][m][n], 0, 0, 0); __builtin_amdgcn_s_setprio(0); } while (0)
; #define PG8_WAIT_V(n) asm volatile("s_waitcnt vmcnt(" #n ")" ::: "memory")
; #define PG8_WAIT_L(n) asm volatile("s_waitcnt lgkmcnt(" #n ")" ::: "memory")
; #define PG8_BAR __builtin_amdgcn_s_barrier()
; #define PG8_SCHED __builtin_amdgcn_sched_barrier(0)
; template <class Epi, class Sched, bool ALIGN_EPI = false, bool SP2 = false>
; __device__ __forceinline__ void gemm_phase(PG8_LAS unsigned char* lds, const Gemm g, const Sched& S, const Epi& E) {
;     ...
;             PG8_WAIT_V(8); PG8_WAIT_L(0); PG8_BAR; PG8_MMA(1, 0, At, B0); PG8_MMA(1, 1, At, B1); PG8_BAR; PG8_SCHED;
;             PG8_LDB(B0, 1, 0); PG8_LDB(B1, 1, 1); PG8_SCHED; PG8_LDA(At, 1, 0); PG8_STAGE(PG8_SA(0, 1), a2 + hstep, voffA);
;             PG8_WAIT_V(8); PG8_WAIT_L(0); PG8_BAR; PG8_MMA(0, 0, At, B0); PG8_MMA(0, 1, At, B1); PG8_BAR; PG8_SCHED;
	s_setprio 1
	s_waitcnt lgkmcnt(0)
	v_mfma_f32_16x16x32_bf16 v[60:63], v[166:169], v[198:201], 0
	v_mfma_f32_16x16x32_bf16 v[56:59], v[174:177], v[198:201], 0
	v_mfma_f32_16x16x32_bf16 v[44:47], v[166:169], v[206:209], 0
	v_mfma_f32_16x16x32_bf16 v[40:43], v[174:177], v[206:209], 0
	v_mfma_f32_16x16x32_bf16 v[28:31], v[166:169], v[214:217], 0
	v_mfma_f32_16x16x32_bf16 v[24:27], v[174:177], v[214:217], 0
	v_mfma_f32_16x16x32_bf16 v[12:15], v[166:169], v[224:227], 0
	v_mfma_f32_16x16x32_bf16 v[8:11], v[174:177], v[224:227], 0
	v_mfma_f32_16x16x32_bf16 v[60:63], v[170:173], v[202:205], v[60:63]
	v_mfma_f32_16x16x32_bf16 v[56:59], v[178:181], v[202:205], v[56:59]
	v_mfma_f32_16x16x32_bf16 v[44:47], v[170:173], v[210:213], v[44:47]
	v_mfma_f32_16x16x32_bf16 v[40:43], v[178:181], v[210:213], v[40:43]
	v_mfma_f32_16x16x32_bf16 v[28:31], v[170:173], v[218:221], v[28:31]
	v_mfma_f32_16x16x32_bf16 v[24:27], v[178:181], v[218:221], v[24:27]
	v_mfma_f32_16x16x32_bf16 v[12:15], v[170:173], v[236:239], v[12:15]
	v_mfma_f32_16x16x32_bf16 v[8:11], v[178:181], v[236:239], v[8:11]
	s_setprio 0
	s_setprio 1
	v_mfma_f32_16x16x32_bf16 v[52:55], v[182:185], v[198:201], 0
	v_mfma_f32_16x16x32_bf16 v[48:51], v[190:193], v[198:201], 0
	v_mfma_f32_16x16x32_bf16 v[36:39], v[182:185], v[206:209], 0
	v_mfma_f32_16x16x32_bf16 v[32:35], v[190:193], v[206:209], 0
	v_mfma_f32_16x16x32_bf16 v[20:23], v[182:185], v[214:217], 0
	v_mfma_f32_16x16x32_bf16 v[16:19], v[190:193], v[214:217], 0
	v_mfma_f32_16x16x32_bf16 v[4:7], v[182:185], v[224:227], 0
	v_mfma_f32_16x16x32_bf16 v[0:3], v[190:193], v[224:227], 0
	v_mfma_f32_16x16x32_bf16 v[52:55], v[186:189], v[202:205], v[52:55]
	v_mfma_f32_16x16x32_bf16 v[48:51], v[194:197], v[202:205], v[48:51]
	v_mfma_f32_16x16x32_bf16 v[36:39], v[186:189], v[210:213], v[36:39]
	v_mfma_f32_16x16x32_bf16 v[32:35], v[194:197], v[210:213], v[32:35]
	v_mfma_f32_16x16x32_bf16 v[20:23], v[186:189], v[218:221], v[20:23]
	v_mfma_f32_16x16x32_bf16 v[16:19], v[194:197], v[218:221], v[16:19]
	v_mfma_f32_16x16x32_bf16 v[4:7], v[186:189], v[236:239], v[4:7]
	v_mfma_f32_16x16x32_bf16 v[0:3], v[194:197], v[236:239], v[0:3]
	s_setprio 0
	s_barrier
	ds_read_b128 v[166:169], v157
	ds_read_b128 v[170:173], v158
	ds_read_b128 v[174:177], v159
	ds_read_b128 v[178:181], v160
	ds_read_b128 v[182:185], v161
	ds_read_b128 v[186:189], v162
	ds_read_b128 v[190:193], v163
	ds_read_b128 v[194:197], v164
	s_add_u32 s50, s50, 0x40000
	s_addc_u32 s51, s51, 0
	s_mov_b32 m0, s53
	v_lshl_add_u64 v[244:245], s[50:51], 0, v[134:135]
	ds_read_b128 v[198:201], v147 offset:32768
	ds_read_b128 v[202:205], v147 offset:33792
	ds_read_b128 v[206:209], v147 offset:34816
	ds_read_b128 v[210:213], v147 offset:35840
	ds_read_b128 v[214:217], v147 offset:36864
	ds_read_b128 v[218:221], v147 offset:37888
	ds_read_b128 v[224:227], v147 offset:38912
	ds_read_b128 v[236:239], v147 offset:39936
	global_load_lds_dwordx4 v[244:245], off
	s_mov_b32 m0, s54
	v_lshl_add_u64 v[244:245], s[50:51], 0, v[130:131]
	global_load_lds_dwordx4 v[244:245], off
	s_waitcnt vmcnt(8)
	s_waitcnt lgkmcnt(0)
	s_barrier
	s_setprio 1
	s_waitcnt lgkmcnt(0)
	v_mfma_f32_16x16x32_bf16 v[124:127], v[166:169], v[198:201], v[124:127]
	v_mfma_f32_16x16x32_bf16 v[120:123], v[174:177], v[198:201], v[120:123]
	v_mfma_f32_16x16x32_bf16 v[108:111], v[166:169], v[206:209], v[108:111]
	v_mfma_f32_16x16x32_bf16 v[104:107], v[174:177], v[206:209], v[104:107]
	v_mfma_f32_16x16x32_bf16 v[92:95], v[166:169], v[214:217], v[92:95]
	v_mfma_f32_16x16x32_bf16 v[88:91], v[174:177], v[214:217], v[88:91]
	v_mfma_f32_16x16x32_bf16 v[76:79], v[166:169], v[224:227], v[76:79]
	v_mfma_f32_16x16x32_bf16 v[72:75], v[174:177], v[224:227], v[72:75]
	v_mfma_f32_16x16x32_bf16 v[124:127], v[170:173], v[202:205], v[124:127]
	v_mfma_f32_16x16x32_bf16 v[120:123], v[178:181], v[202:205], v[120:123]
	v_mfma_f32_16x16x32_bf16 v[108:111], v[170:173], v[210:213], v[108:111]
	v_mfma_f32_16x16x32_bf16 v[104:107], v[178:181], v[210:213], v[104:107]
	v_mfma_f32_16x16x32_bf16 v[92:95], v[170:173], v[218:221], v[92:95]
	v_mfma_f32_16x16x32_bf16 v[88:91], v[178:181], v[218:221], v[88:91]
	v_mfma_f32_16x16x32_bf16 v[76:79], v[170:173], v[236:239], v[76:79]
	v_mfma_f32_16x16x32_bf16 v[72:75], v[178:181], v[236:239], v[72:75]
	s_setprio 0
	s_setprio 1
	v_mfma_f32_16x16x32_bf16 v[116:119], v[182:185], v[198:201], v[116:119]
	v_mfma_f32_16x16x32_bf16 v[112:115], v[190:193], v[198:201], v[112:115]
	v_mfma_f32_16x16x32_bf16 v[100:103], v[182:185], v[206:209], v[100:103]
	v_mfma_f32_16x16x32_bf16 v[96:99], v[190:193], v[206:209], v[96:99]
	v_mfma_f32_16x16x32_bf16 v[84:87], v[182:185], v[214:217], v[84:87]
	v_mfma_f32_16x16x32_bf16 v[80:83], v[190:193], v[214:217], v[80:83]
	v_mfma_f32_16x16x32_bf16 v[68:71], v[182:185], v[224:227], v[68:71]
	v_mfma_f32_16x16x32_bf16 v[64:67], v[190:193], v[224:227], v[64:67]
	v_mfma_f32_16x16x32_bf16 v[116:119], v[186:189], v[202:205], v[116:119]
	v_mfma_f32_16x16x32_bf16 v[112:115], v[194:197], v[202:205], v[112:115]
	v_mfma_f32_16x16x32_bf16 v[100:103], v[186:189], v[210:213], v[100:103]
	v_mfma_f32_16x16x32_bf16 v[96:99], v[194:197], v[210:213], v[96:99]
	v_mfma_f32_16x16x32_bf16 v[84:87], v[186:189], v[218:221], v[84:87]
	v_mfma_f32_16x16x32_bf16 v[80:83], v[194:197], v[218:221], v[80:83]
	v_mfma_f32_16x16x32_bf16 v[68:71], v[186:189], v[236:239], v[68:71]
	v_mfma_f32_16x16x32_bf16 v[64:67], v[194:197], v[236:239], v[64:67]
	s_setprio 0
	s_barrier
; #define PG8_STAGE(bufoff, gbase, voff) do { _Pragma("unroll") for (int _i = 0; _i < 2; ++_i) \
;         __builtin_amdgcn_global_load_lds((const unsigned*)((const char*)(gbase) + (voff)[_i]), (PG8_LAS unsigned*)(lds + (bufoff) + ldsw + _i * 8192), 16, 0, 0); } while (0)
; #define PG8_LDA(dst, b, h) do { _Pragma("unroll") for (int m = 0; m < 4; ++m) _Pragma("unroll") for (int k = 0; k < 2; ++k) dst[m][k] = *(const PG8_LAS bf16x8*)(lds + PG8_SA(b, h) + aoff + m * 2048 + k * 1024); } while (0)
; #define PG8_LDB(dst, b, h) do { _Pragma("unroll") for (int n = 0; n < 2; ++n) _Pragma("unroll") for (int k = 0; k < 2; ++k) dst[n][k] = *(const PG8_LAS bf16x8*)(lds + PG8_SB(b, h) + boff + n * 2048 + k * 1024); } while (0)
; #define PG8_MMA(ai, bj, At, Bt) do { __builtin_amdgcn_s_setprio(1); _Pragma("unroll") for (int m = 0; m < 4; ++m) _Pragma("unroll") for (int n = 0; n < 2; ++n) _Pragma("unroll") for (int k = 0; k < 2; ++k) \
;         acc[ai][bj][m][n] = __builtin_amdgcn_mfma_f32_16x16x32_bf16(Bt[n][k], At[m][k], acc[ai][bj][m][n], 0, 0, 0); __builtin_amdgcn_s_setprio(0); } while (0)
; #define PG8_WAIT_V(n) asm volatile("s_waitcnt vmcnt(" #n ")" ::: "memory")
; #define PG8_WAIT_L(n) asm volatile("s_waitcnt lgkmcnt(" #n ")" ::: "memory")
; #define PG8_BAR __builtin_amdgcn_s_barrier()
; #define PG8_SCHED __builtin_amdgcn_sched_barrier(0)
; template <class Epi, class Sched, bool ALIGN_EPI = false, bool SP2 = false>
; __device__ __forceinline__ void gemm_phase(PG8_LAS unsigned char* lds, const Gemm g, const Sched& S, const Epi& E) {
;     ...
;             PG8_LDB(B0, 0, 0); PG8_LDB(B1, 0, 1); PG8_SCHED; PG8_LDA(At, 0, 0); PG8_STAGE(PG8_SA(1, 1), a1 + hstep, voffA);
;             PG8_WAIT_V(8); PG8_WAIT_L(0); PG8_BAR; PG8_MMA(0, 0, At, B0); PG8_MMA(0, 1, At, B1); PG8_BAR; PG8_SCHED;
;     ...
;             PG8_LDA(At, 1, 1); PG8_STAGE(PG8_SB(1, 0), b3, voffB); PG8_STAGE(PG8_SB(1, 1), b3 + hstep, voffB); PG8_STAGE(PG8_SA(1, 0), a3, voffA);
;             PG8_WAIT_V(8); PG8_WAIT_L(0); PG8_BAR; PG8_MMA(1, 0, At, B0); PG8_MMA(1, 1, At, B1); PG8_BAR; PG8_SCHED;
	s_mov_b32 m0, s56
	v_lshl_add_u64 v[144:145], v[144:145], 0, s[10:11]
	s_add_u32 s40, s40, 0x40080
	ds_read_b128 v[198:201], v147 offset:49152
	ds_read_b128 v[202:205], v147 offset:50176
	ds_read_b128 v[206:209], v147 offset:51200
	ds_read_b128 v[210:213], v147 offset:52224
	ds_read_b128 v[214:217], v147 offset:53248
	ds_read_b128 v[218:221], v147 offset:54272
	ds_read_b128 v[224:227], v147 offset:55296
	ds_read_b128 v[236:239], v147 offset:56320
	global_load_lds_dwordx4 v[144:145], off
	v_lshl_add_u64 v[144:145], v[228:229], 0, s[10:11]
	s_mov_b32 m0, s57
	s_addc_u32 s41, s41, 0
	global_load_lds_dwordx4 v[144:145], off
	s_mov_b32 m0, s60
	v_lshl_add_u64 v[144:145], s[40:41], 0, v[132:133]
	global_load_lds_dwordx4 v[144:145], off
	s_mov_b32 m0, s61
	v_lshl_add_u64 v[144:145], s[40:41], 0, v[128:129]
	global_load_lds_dwordx4 v[144:145], off
	s_mov_b32 m0, s58
	v_lshl_add_u64 v[144:145], v[240:241], 0, s[10:11]
	global_load_lds_dwordx4 v[144:145], off
	s_mov_b32 m0, s59
	v_lshl_add_u64 v[144:145], v[242:243], 0, s[10:11]
	global_load_lds_dwordx4 v[144:145], off
	s_waitcnt vmcnt(8)
	s_waitcnt lgkmcnt(0)
	s_barrier
	s_setprio 1
	s_waitcnt lgkmcnt(0)
	v_mfma_f32_16x16x32_bf16 v[60:63], v[166:169], v[198:201], v[60:63]
	v_mfma_f32_16x16x32_bf16 v[56:59], v[174:177], v[198:201], v[56:59]
	v_mfma_f32_16x16x32_bf16 v[44:47], v[166:169], v[206:209], v[44:47]
	v_mfma_f32_16x16x32_bf16 v[40:43], v[174:177], v[206:209], v[40:43]
	v_mfma_f32_16x16x32_bf16 v[28:31], v[166:169], v[214:217], v[28:31]
	v_mfma_f32_16x16x32_bf16 v[24:27], v[174:177], v[214:217], v[24:27]
	v_mfma_f32_16x16x32_bf16 v[12:15], v[166:169], v[224:227], v[12:15]
	v_mfma_f32_16x16x32_bf16 v[8:11], v[174:177], v[224:227], v[8:11]
	v_mfma_f32_16x16x32_bf16 v[60:63], v[170:173], v[202:205], v[60:63]
	v_mfma_f32_16x16x32_bf16 v[56:59], v[178:181], v[202:205], v[56:59]
	v_mfma_f32_16x16x32_bf16 v[44:47], v[170:173], v[210:213], v[44:47]
	v_mfma_f32_16x16x32_bf16 v[40:43], v[178:181], v[210:213], v[40:43]
	v_mfma_f32_16x16x32_bf16 v[28:31], v[170:173], v[218:221], v[28:31]
	v_mfma_f32_16x16x32_bf16 v[24:27], v[178:181], v[218:221], v[24:27]
	v_mfma_f32_16x16x32_bf16 v[12:15], v[170:173], v[236:239], v[12:15]
	v_mfma_f32_16x16x32_bf16 v[8:11], v[178:181], v[236:239], v[8:11]
	s_setprio 0
	s_setprio 1
	v_mfma_f32_16x16x32_bf16 v[52:55], v[182:185], v[198:201], v[52:55]
	v_mfma_f32_16x16x32_bf16 v[48:51], v[190:193], v[198:201], v[48:51]
	v_mfma_f32_16x16x32_bf16 v[36:39], v[182:185], v[206:209], v[36:39]
	v_mfma_f32_16x16x32_bf16 v[32:35], v[190:193], v[206:209], v[32:35]
	v_mfma_f32_16x16x32_bf16 v[20:23], v[182:185], v[214:217], v[20:23]
	v_mfma_f32_16x16x32_bf16 v[16:19], v[190:193], v[214:217], v[16:19]
	v_mfma_f32_16x16x32_bf16 v[4:7], v[182:185], v[224:227], v[4:7]
	v_mfma_f32_16x16x32_bf16 v[0:3], v[190:193], v[224:227], v[0:3]
	v_mfma_f32_16x16x32_bf16 v[52:55], v[186:189], v[202:205], v[52:55]
	v_mfma_f32_16x16x32_bf16 v[48:51], v[194:197], v[202:205], v[48:51]
	v_mfma_f32_16x16x32_bf16 v[36:39], v[186:189], v[210:213], v[36:39]
	v_mfma_f32_16x16x32_bf16 v[32:35], v[194:197], v[210:213], v[32:35]
	v_mfma_f32_16x16x32_bf16 v[20:23], v[186:189], v[218:221], v[20:23]
	v_mfma_f32_16x16x32_bf16 v[16:19], v[194:197], v[218:221], v[16:19]
	v_mfma_f32_16x16x32_bf16 v[4:7], v[186:189], v[236:239], v[4:7]
	v_mfma_f32_16x16x32_bf16 v[0:3], v[194:197], v[236:239], v[0:3]
	s_setprio 0
	s_barrier
	s_add_i32 s70, s70, 2
	s_add_u32 s36, s36, 0x100
	s_addc_u32 s37, s37, 0
	s_add_u32 s68, s68, 0x100
	s_addc_u32 s69, s69, 0
.LBB0_1438:
	ds_read_b128 v[166:169], v149
	ds_read_b128 v[170:173], v150
	ds_read_b128 v[174:177], v151
	ds_read_b128 v[178:181], v152
	ds_read_b128 v[182:185], v153
	ds_read_b128 v[186:189], v154
	ds_read_b128 v[190:193], v155
	ds_read_b128 v[194:197], v156
	s_add_u32 s40, s36, 0xfffc0080
	s_addc_u32 s41, s37, -1
	s_cmp_eq_u32 s70, 12
	s_cselect_b32 s51, s19, s41
	s_cselect_b32 s50, s66, s40
	s_cselect_b32 s41, s17, s69
	s_cselect_b32 s40, s67, s68
	s_mov_b32 m0, s63
	v_lshl_add_u64 v[144:145], s[36:37], 0, v[136:137]
	ds_read_b128 v[198:201], v147
	ds_read_b128 v[202:205], v147 offset:1024
	ds_read_b128 v[206:209], v147 offset:2048
	ds_read_b128 v[210:213], v147 offset:3072
	ds_read_b128 v[214:217], v147 offset:4096
	ds_read_b128 v[218:221], v147 offset:5120
	ds_read_b128 v[224:227], v147 offset:6144
	ds_read_b128 v[236:239], v147 offset:7168
	global_load_lds_dwordx4 v[144:145], off
	s_mov_b32 m0, s64
	v_lshl_add_u64 v[144:145], s[36:37], 0, v[138:139]
	global_load_lds_dwordx4 v[144:145], off
	s_waitcnt vmcnt(8)
	s_waitcnt lgkmcnt(0)
	s_barrier
; #define PG8_STAGE(bufoff, gbase, voff) do { _Pragma("unroll") for (int _i = 0; _i < 2; ++_i) \
;         __builtin_amdgcn_global_load_lds((const unsigned*)((const char*)(gbase) + (voff)[_i]), (PG8_LAS unsigned*)(lds + (bufoff) + ldsw + _i * 8192), 16, 0, 0); } while (0)
; #define PG8_LDA(dst, b, h) do { _Pragma("unroll") for (int m = 0; m < 4; ++m) _Pragma("unroll") for (int k = 0; k < 2; ++k) dst[m][k] = *(const PG8_LAS bf16x8*)(lds + PG8_SA(b, h) + aoff + m * 2048 + k * 1024); } while (0)
; #define PG8_MMA(ai, bj, At, Bt) do { __builtin_amdgcn_s_setprio(1); _Pragma("unroll") for (int m = 0; m < 4; ++m) _Pragma("unroll") for (int n = 0; n < 2; ++n) _Pragma("unroll") for (int k = 0; k < 2; ++k) \
;         acc[ai][bj][m][n] = __builtin_amdgcn_mfma_f32_16x16x32_bf16(Bt[n][k], At[m][k], acc[ai][bj][m][n], 0, 0, 0); __builtin_amdgcn_s_setprio(0); } while (0)
; #define PG8_WAIT_V(n) asm volatile("s_waitcnt vmcnt(" #n ")" ::: "memory")
; #define PG8_WAIT_L(n) asm volatile("s_waitcnt lgkmcnt(" #n ")" ::: "memory")
; #define PG8_BAR __builtin_amdgcn_s_barrier()
; #define PG8_SCHED __builtin_amdgcn_sched_barrier(0)
; template <class Epi, class Sched, bool ALIGN_EPI = false, bool SP2 = false>
; __device__ __forceinline__ void gemm_phase(PG8_LAS unsigned char* lds, const Gemm g, const Sched& S, const Epi& E) {
;     ...
;             PG8_WAIT_V(8); PG8_WAIT_L(0); PG8_BAR; PG8_MMA(0, 0, At, B0); PG8_MMA(0, 1, At, B1); PG8_BAR; PG8_SCHED;
;             PG8_LDA(At, 0, 1); PG8_STAGE(PG8_SB(0, 0), b2, voffB); PG8_STAGE(PG8_SB(0, 1), b2 + hstep, voffB); PG8_STAGE(PG8_SA(0, 0), a2, voffA);
;             PG8_WAIT_V(8); PG8_WAIT_L(0); PG8_BAR; PG8_MMA(1, 0, At, B0); PG8_MMA(1, 1, At, B1); PG8_BAR; PG8_SCHED;
	s_setprio 1
	s_waitcnt lgkmcnt(0)
	v_mfma_f32_16x16x32_bf16 v[124:127], v[166:169], v[198:201], v[124:127]
	v_mfma_f32_16x16x32_bf16 v[120:123], v[174:177], v[198:201], v[120:123]
	v_mfma_f32_16x16x32_bf16 v[108:111], v[166:169], v[206:209], v[108:111]
	v_mfma_f32_16x16x32_bf16 v[104:107], v[174:177], v[206:209], v[104:107]
	v_mfma_f32_16x16x32_bf16 v[92:95], v[166:169], v[214:217], v[92:95]
	v_mfma_f32_16x16x32_bf16 v[88:91], v[174:177], v[214:217], v[88:91]
	v_mfma_f32_16x16x32_bf16 v[76:79], v[166:169], v[224:227], v[76:79]
	v_mfma_f32_16x16x32_bf16 v[72:75], v[174:177], v[224:227], v[72:75]
	v_mfma_f32_16x16x32_bf16 v[124:127], v[170:173], v[202:205], v[124:127]
	v_mfma_f32_16x16x32_bf16 v[120:123], v[178:181], v[202:205], v[120:123]
	v_mfma_f32_16x16x32_bf16 v[108:111], v[170:173], v[210:213], v[108:111]
	v_mfma_f32_16x16x32_bf16 v[104:107], v[178:181], v[210:213], v[104:107]
	v_mfma_f32_16x16x32_bf16 v[92:95], v[170:173], v[218:221], v[92:95]
	v_mfma_f32_16x16x32_bf16 v[88:91], v[178:181], v[218:221], v[88:91]
	v_mfma_f32_16x16x32_bf16 v[76:79], v[170:173], v[236:239], v[76:79]
	v_mfma_f32_16x16x32_bf16 v[72:75], v[178:181], v[236:239], v[72:75]
	s_setprio 0
	s_setprio 1
	v_mfma_f32_16x16x32_bf16 v[116:119], v[182:185], v[198:201], v[116:119]
	v_mfma_f32_16x16x32_bf16 v[112:115], v[190:193], v[198:201], v[112:115]
	v_mfma_f32_16x16x32_bf16 v[100:103], v[182:185], v[206:209], v[100:103]
	v_mfma_f32_16x16x32_bf16 v[96:99], v[190:193], v[206:209], v[96:99]
	v_mfma_f32_16x16x32_bf16 v[84:87], v[182:185], v[214:217], v[84:87]
	v_mfma_f32_16x16x32_bf16 v[80:83], v[190:193], v[214:217], v[80:83]
	v_mfma_f32_16x16x32_bf16 v[68:71], v[182:185], v[224:227], v[68:71]
	v_mfma_f32_16x16x32_bf16 v[64:67], v[190:193], v[224:227], v[64:67]
	v_mfma_f32_16x16x32_bf16 v[116:119], v[186:189], v[202:205], v[116:119]
	v_mfma_f32_16x16x32_bf16 v[112:115], v[194:197], v[202:205], v[112:115]
	v_mfma_f32_16x16x32_bf16 v[100:103], v[186:189], v[210:213], v[100:103]
	v_mfma_f32_16x16x32_bf16 v[96:99], v[194:197], v[210:213], v[96:99]
	v_mfma_f32_16x16x32_bf16 v[84:87], v[186:189], v[218:221], v[84:87]
	v_mfma_f32_16x16x32_bf16 v[80:83], v[194:197], v[218:221], v[80:83]
	v_mfma_f32_16x16x32_bf16 v[68:71], v[186:189], v[236:239], v[68:71]
	v_mfma_f32_16x16x32_bf16 v[64:67], v[194:197], v[236:239], v[64:67]
	s_setprio 0
	s_barrier
	s_mov_b32 m0, s15
	v_lshl_add_u64 v[144:145], s[40:41], 0, v[132:133]
	s_add_u32 s72, s40, 0x40000
	ds_read_b128 v[198:201], v147 offset:16384
	ds_read_b128 v[202:205], v147 offset:17408
	ds_read_b128 v[206:209], v147 offset:18432
	ds_read_b128 v[210:213], v147 offset:19456
	ds_read_b128 v[214:217], v147 offset:20480
	ds_read_b128 v[218:221], v147 offset:21504
	ds_read_b128 v[224:227], v147 offset:22528
	ds_read_b128 v[236:239], v147 offset:23552
	global_load_lds_dwordx4 v[144:145], off
	v_lshl_add_u64 v[228:229], s[40:41], 0, v[128:129]
	s_mov_b32 m0, s25
	s_addc_u32 s73, s41, 0
	global_load_lds_dwordx4 v[228:229], off
	v_lshl_add_u64 v[240:241], s[72:73], 0, v[132:133]
	s_mov_b32 m0, s39
	v_lshl_add_u64 v[242:243], s[50:51], 0, v[130:131]
	global_load_lds_dwordx4 v[240:241], off
	s_mov_b32 m0, s43
	v_lshl_add_u64 v[240:241], s[72:73], 0, v[128:129]
	global_load_lds_dwordx4 v[240:241], off
	s_mov_b32 m0, s4
	v_lshl_add_u64 v[240:241], s[50:51], 0, v[134:135]
	global_load_lds_dwordx4 v[240:241], off
	s_mov_b32 m0, s52
	s_nop 0
	global_load_lds_dwordx4 v[242:243], off
	s_waitcnt vmcnt(8)
	s_waitcnt lgkmcnt(0)
	s_barrier
	s_setprio 1
	s_waitcnt lgkmcnt(0)
	v_mfma_f32_16x16x32_bf16 v[60:63], v[166:169], v[198:201], v[60:63]
	v_mfma_f32_16x16x32_bf16 v[56:59], v[174:177], v[198:201], v[56:59]
	v_mfma_f32_16x16x32_bf16 v[44:47], v[166:169], v[206:209], v[44:47]
	v_mfma_f32_16x16x32_bf16 v[40:43], v[174:177], v[206:209], v[40:43]
	v_mfma_f32_16x16x32_bf16 v[28:31], v[166:169], v[214:217], v[28:31]
	v_mfma_f32_16x16x32_bf16 v[24:27], v[174:177], v[214:217], v[24:27]
	v_mfma_f32_16x16x32_bf16 v[12:15], v[166:169], v[224:227], v[12:15]
	v_mfma_f32_16x16x32_bf16 v[8:11], v[174:177], v[224:227], v[8:11]
	v_mfma_f32_16x16x32_bf16 v[60:63], v[170:173], v[202:205], v[60:63]
	v_mfma_f32_16x16x32_bf16 v[56:59], v[178:181], v[202:205], v[56:59]
	v_mfma_f32_16x16x32_bf16 v[44:47], v[170:173], v[210:213], v[44:47]
	v_mfma_f32_16x16x32_bf16 v[40:43], v[178:181], v[210:213], v[40:43]
	v_mfma_f32_16x16x32_bf16 v[28:31], v[170:173], v[218:221], v[28:31]
	v_mfma_f32_16x16x32_bf16 v[24:27], v[178:181], v[218:221], v[24:27]
	v_mfma_f32_16x16x32_bf16 v[12:15], v[170:173], v[236:239], v[12:15]
	v_mfma_f32_16x16x32_bf16 v[8:11], v[178:181], v[236:239], v[8:11]
	s_setprio 0
	s_setprio 1
	v_mfma_f32_16x16x32_bf16 v[52:55], v[182:185], v[198:201], v[52:55]
	v_mfma_f32_16x16x32_bf16 v[48:51], v[190:193], v[198:201], v[48:51]
	v_mfma_f32_16x16x32_bf16 v[36:39], v[182:185], v[206:209], v[36:39]
	v_mfma_f32_16x16x32_bf16 v[32:35], v[190:193], v[206:209], v[32:35]
	v_mfma_f32_16x16x32_bf16 v[20:23], v[182:185], v[214:217], v[20:23]
	v_mfma_f32_16x16x32_bf16 v[16:19], v[190:193], v[214:217], v[16:19]
	v_mfma_f32_16x16x32_bf16 v[4:7], v[182:185], v[224:227], v[4:7]
	v_mfma_f32_16x16x32_bf16 v[0:3], v[190:193], v[224:227], v[0:3]
	v_mfma_f32_16x16x32_bf16 v[52:55], v[186:189], v[202:205], v[52:55]
	v_mfma_f32_16x16x32_bf16 v[48:51], v[194:197], v[202:205], v[48:51]
	v_mfma_f32_16x16x32_bf16 v[36:39], v[186:189], v[210:213], v[36:39]
	v_mfma_f32_16x16x32_bf16 v[32:35], v[194:197], v[210:213], v[32:35]
	v_mfma_f32_16x16x32_bf16 v[20:23], v[186:189], v[218:221], v[20:23]
	v_mfma_f32_16x16x32_bf16 v[16:19], v[194:197], v[218:221], v[16:19]
	v_mfma_f32_16x16x32_bf16 v[4:7], v[186:189], v[236:239], v[4:7]
	v_mfma_f32_16x16x32_bf16 v[0:3], v[194:197], v[236:239], v[0:3]
	s_setprio 0
	s_barrier
; #define PG8_STAGE(bufoff, gbase, voff) do { _Pragma("unroll") for (int _i = 0; _i < 2; ++_i) \
;         __builtin_amdgcn_global_load_lds((const unsigned*)((const char*)(gbase) + (voff)[_i]), (PG8_LAS unsigned*)(lds + (bufoff) + ldsw + _i * 8192), 16, 0, 0); } while (0)
; #define PG8_LDA(dst, b, h) do { _Pragma("unroll") for (int m = 0; m < 4; ++m) _Pragma("unroll") for (int k = 0; k < 2; ++k) dst[m][k] = *(const PG8_LAS bf16x8*)(lds + PG8_SA(b, h) + aoff + m * 2048 + k * 1024); } while (0)
; #define PG8_LDB(dst, b, h) do { _Pragma("unroll") for (int n = 0; n < 2; ++n) _Pragma("unroll") for (int k = 0; k < 2; ++k) dst[n][k] = *(const PG8_LAS bf16x8*)(lds + PG8_SB(b, h) + boff + n * 2048 + k * 1024); } while (0)
; #define PG8_MMA(ai, bj, At, Bt) do { __builtin_amdgcn_s_setprio(1); _Pragma("unroll") for (int m = 0; m < 4; ++m) _Pragma("unroll") for (int n = 0; n < 2; ++n) _Pragma("unroll") for (int k = 0; k < 2; ++k) \
;         acc[ai][bj][m][n] = __builtin_amdgcn_mfma_f32_16x16x32_bf16(Bt[n][k], At[m][k], acc[ai][bj][m][n], 0, 0, 0); __builtin_amdgcn_s_setprio(0); } while (0)
; #define PG8_WAIT_V(n) asm volatile("s_waitcnt vmcnt(" #n ")" ::: "memory")
; #define PG8_WAIT_L(n) asm volatile("s_waitcnt lgkmcnt(" #n ")" ::: "memory")
; template <class Epi, class Sched, bool ALIGN_EPI = false, bool SP2 = false>
; __device__ __forceinline__ void gemm_phase(PG8_LAS unsigned char* lds, const Gemm g, const Sched& S, const Epi& E) {
;     ...
;         for (int t = 0; t < nt; t += 2) {
;             const bool last = (t == nt - 2);
;             const char* a1 = cA + (size_t)(t + 1) * kstep;
;             const char* a2 = last ? nA : cA + (size_t)(t + 2) * kstep; const char* b2 = last ? nB : cB + (size_t)(t + 2) * kstep;
;             const char* a3 = a2 + kstep; const char* b3 = b2 + kstep;
;     ...
;             PG8_LDB(B0, 1, 0); PG8_LDB(B1, 1, 1); PG8_SCHED; PG8_LDA(At, 1, 0); PG8_STAGE(PG8_SA(0, 1), a2 + hstep, voffA);
;             PG8_WAIT_V(8); PG8_WAIT_L(0); PG8_BAR; PG8_MMA(0, 0, At, B0); PG8_MMA(0, 1, At, B1); PG8_BAR; PG8_SCHED;
;             PG8_LDA(At, 1, 1); PG8_STAGE(PG8_SB(1, 0), b3, voffB); PG8_STAGE(PG8_SB(1, 1), b3 + hstep, voffB); PG8_STAGE(PG8_SA(1, 0), a3, voffA);
;             PG8_WAIT_V(8); PG8_WAIT_L(0); PG8_BAR; PG8_MMA(1, 0, At, B0); PG8_MMA(1, 1, At, B1); PG8_BAR; PG8_SCHED;
;     ...
;         if constexpr (ALIGN_EPI) { if (wr == 0) PG8_BAR; }
	ds_read_b128 v[166:169], v157
	ds_read_b128 v[170:173], v158
	ds_read_b128 v[174:177], v159
	ds_read_b128 v[178:181], v160
	ds_read_b128 v[182:185], v161
	ds_read_b128 v[186:189], v162
	ds_read_b128 v[190:193], v163
	ds_read_b128 v[194:197], v164
	s_add_u32 s50, s50, 0x40000
	s_addc_u32 s51, s51, 0
	s_mov_b32 m0, s53
	v_lshl_add_u64 v[244:245], s[50:51], 0, v[134:135]
	ds_read_b128 v[198:201], v147 offset:32768
	ds_read_b128 v[202:205], v147 offset:33792
	ds_read_b128 v[206:209], v147 offset:34816
	ds_read_b128 v[210:213], v147 offset:35840
	ds_read_b128 v[214:217], v147 offset:36864
	ds_read_b128 v[218:221], v147 offset:37888
	ds_read_b128 v[224:227], v147 offset:38912
	ds_read_b128 v[236:239], v147 offset:39936
	global_load_lds_dwordx4 v[244:245], off
	s_mov_b32 m0, s54
	v_lshl_add_u64 v[244:245], s[50:51], 0, v[130:131]
	global_load_lds_dwordx4 v[244:245], off
	s_waitcnt vmcnt(8)
	s_waitcnt lgkmcnt(0)
	s_barrier
	s_setprio 1
	s_waitcnt lgkmcnt(0)
	v_mfma_f32_16x16x32_bf16 v[124:127], v[166:169], v[198:201], v[124:127]
	v_mfma_f32_16x16x32_bf16 v[120:123], v[174:177], v[198:201], v[120:123]
	v_mfma_f32_16x16x32_bf16 v[108:111], v[166:169], v[206:209], v[108:111]
	v_mfma_f32_16x16x32_bf16 v[104:107], v[174:177], v[206:209], v[104:107]
	v_mfma_f32_16x16x32_bf16 v[92:95], v[166:169], v[214:217], v[92:95]
	v_mfma_f32_16x16x32_bf16 v[88:91], v[174:177], v[214:217], v[88:91]
	v_mfma_f32_16x16x32_bf16 v[76:79], v[166:169], v[224:227], v[76:79]
	v_mfma_f32_16x16x32_bf16 v[72:75], v[174:177], v[224:227], v[72:75]
	v_mfma_f32_16x16x32_bf16 v[124:127], v[170:173], v[202:205], v[124:127]
	v_mfma_f32_16x16x32_bf16 v[120:123], v[178:181], v[202:205], v[120:123]
	v_mfma_f32_16x16x32_bf16 v[108:111], v[170:173], v[210:213], v[108:111]
	v_mfma_f32_16x16x32_bf16 v[104:107], v[178:181], v[210:213], v[104:107]
	v_mfma_f32_16x16x32_bf16 v[92:95], v[170:173], v[218:221], v[92:95]
	v_mfma_f32_16x16x32_bf16 v[88:91], v[178:181], v[218:221], v[88:91]
	v_mfma_f32_16x16x32_bf16 v[76:79], v[170:173], v[236:239], v[76:79]
	v_mfma_f32_16x16x32_bf16 v[72:75], v[178:181], v[236:239], v[72:75]
	s_setprio 0
	s_setprio 1
	v_mfma_f32_16x16x32_bf16 v[116:119], v[182:185], v[198:201], v[116:119]
	v_mfma_f32_16x16x32_bf16 v[112:115], v[190:193], v[198:201], v[112:115]
	v_mfma_f32_16x16x32_bf16 v[100:103], v[182:185], v[206:209], v[100:103]
	v_mfma_f32_16x16x32_bf16 v[96:99], v[190:193], v[206:209], v[96:99]
	v_mfma_f32_16x16x32_bf16 v[84:87], v[182:185], v[214:217], v[84:87]
	v_mfma_f32_16x16x32_bf16 v[80:83], v[190:193], v[214:217], v[80:83]
	v_mfma_f32_16x16x32_bf16 v[68:71], v[182:185], v[224:227], v[68:71]
	v_mfma_f32_16x16x32_bf16 v[64:67], v[190:193], v[224:227], v[64:67]
	v_mfma_f32_16x16x32_bf16 v[116:119], v[186:189], v[202:205], v[116:119]
	v_mfma_f32_16x16x32_bf16 v[112:115], v[194:197], v[202:205], v[112:115]
	v_mfma_f32_16x16x32_bf16 v[100:103], v[186:189], v[210:213], v[100:103]
	v_mfma_f32_16x16x32_bf16 v[96:99], v[194:197], v[210:213], v[96:99]
	v_mfma_f32_16x16x32_bf16 v[84:87], v[186:189], v[218:221], v[84:87]
	v_mfma_f32_16x16x32_bf16 v[80:83], v[194:197], v[218:221], v[80:83]
	v_mfma_f32_16x16x32_bf16 v[68:71], v[186:189], v[236:239], v[68:71]
	v_mfma_f32_16x16x32_bf16 v[64:67], v[194:197], v[236:239], v[64:67]
	s_setprio 0
	s_barrier
	s_mov_b32 m0, s56
	v_lshl_add_u64 v[144:145], v[144:145], 0, s[10:11]
	s_add_u32 s40, s40, 0x40080
	ds_read_b128 v[198:201], v147 offset:49152
	ds_read_b128 v[202:205], v147 offset:50176
	ds_read_b128 v[206:209], v147 offset:51200
	ds_read_b128 v[210:213], v147 offset:52224
	ds_read_b128 v[214:217], v147 offset:53248
	ds_read_b128 v[218:221], v147 offset:54272
	ds_read_b128 v[224:227], v147 offset:55296
	ds_read_b128 v[236:239], v147 offset:56320
	global_load_lds_dwordx4 v[144:145], off
	v_lshl_add_u64 v[144:145], v[228:229], 0, s[10:11]
	s_mov_b32 m0, s57
	s_addc_u32 s41, s41, 0
	global_load_lds_dwordx4 v[144:145], off
	s_mov_b32 m0, s60
	v_lshl_add_u64 v[144:145], s[40:41], 0, v[132:133]
	global_load_lds_dwordx4 v[144:145], off
	s_mov_b32 m0, s61
	v_lshl_add_u64 v[144:145], s[40:41], 0, v[128:129]
	global_load_lds_dwordx4 v[144:145], off
	s_mov_b32 m0, s58
	v_lshl_add_u64 v[144:145], v[240:241], 0, s[10:11]
	global_load_lds_dwordx4 v[144:145], off
	s_mov_b32 m0, s59
	v_lshl_add_u64 v[144:145], v[242:243], 0, s[10:11]
	global_load_lds_dwordx4 v[144:145], off
	s_waitcnt vmcnt(8)
	s_waitcnt lgkmcnt(0)
	s_barrier
	s_setprio 1
	s_waitcnt lgkmcnt(0)
	v_mfma_f32_16x16x32_bf16 v[60:63], v[166:169], v[198:201], v[60:63]
	v_mfma_f32_16x16x32_bf16 v[56:59], v[174:177], v[198:201], v[56:59]
	v_mfma_f32_16x16x32_bf16 v[44:47], v[166:169], v[206:209], v[44:47]
	v_mfma_f32_16x16x32_bf16 v[40:43], v[174:177], v[206:209], v[40:43]
	v_mfma_f32_16x16x32_bf16 v[28:31], v[166:169], v[214:217], v[28:31]
	v_mfma_f32_16x16x32_bf16 v[24:27], v[174:177], v[214:217], v[24:27]
	v_mfma_f32_16x16x32_bf16 v[12:15], v[166:169], v[224:227], v[12:15]
	v_mfma_f32_16x16x32_bf16 v[8:11], v[174:177], v[224:227], v[8:11]
	v_mfma_f32_16x16x32_bf16 v[60:63], v[170:173], v[202:205], v[60:63]
	v_mfma_f32_16x16x32_bf16 v[56:59], v[178:181], v[202:205], v[56:59]
	v_mfma_f32_16x16x32_bf16 v[44:47], v[170:173], v[210:213], v[44:47]
	v_mfma_f32_16x16x32_bf16 v[40:43], v[178:181], v[210:213], v[40:43]
	v_mfma_f32_16x16x32_bf16 v[28:31], v[170:173], v[218:221], v[28:31]
	v_mfma_f32_16x16x32_bf16 v[24:27], v[178:181], v[218:221], v[24:27]
	v_mfma_f32_16x16x32_bf16 v[12:15], v[170:173], v[236:239], v[12:15]
	v_mfma_f32_16x16x32_bf16 v[8:11], v[178:181], v[236:239], v[8:11]
	s_setprio 0
	s_setprio 1
	v_mfma_f32_16x16x32_bf16 v[52:55], v[182:185], v[198:201], v[52:55]
	v_mfma_f32_16x16x32_bf16 v[48:51], v[190:193], v[198:201], v[48:51]
	v_mfma_f32_16x16x32_bf16 v[36:39], v[182:185], v[206:209], v[36:39]
	v_mfma_f32_16x16x32_bf16 v[32:35], v[190:193], v[206:209], v[32:35]
	v_mfma_f32_16x16x32_bf16 v[20:23], v[182:185], v[214:217], v[20:23]
	v_mfma_f32_16x16x32_bf16 v[16:19], v[190:193], v[214:217], v[16:19]
	v_mfma_f32_16x16x32_bf16 v[4:7], v[182:185], v[224:227], v[4:7]
	v_mfma_f32_16x16x32_bf16 v[0:3], v[190:193], v[224:227], v[0:3]
	v_mfma_f32_16x16x32_bf16 v[52:55], v[186:189], v[202:205], v[52:55]
	v_mfma_f32_16x16x32_bf16 v[48:51], v[194:197], v[202:205], v[48:51]
	v_mfma_f32_16x16x32_bf16 v[36:39], v[186:189], v[210:213], v[36:39]
	v_mfma_f32_16x16x32_bf16 v[32:35], v[194:197], v[210:213], v[32:35]
	v_mfma_f32_16x16x32_bf16 v[20:23], v[186:189], v[218:221], v[20:23]
	v_mfma_f32_16x16x32_bf16 v[16:19], v[194:197], v[218:221], v[16:19]
	v_mfma_f32_16x16x32_bf16 v[4:7], v[186:189], v[236:239], v[4:7]
	v_mfma_f32_16x16x32_bf16 v[0:3], v[194:197], v[236:239], v[0:3]
	s_setprio 0
	s_barrier
	s_add_i32 s70, s70, 2
	s_add_u32 s36, s36, 0x100
	s_addc_u32 s37, s37, 0
	s_add_u32 s68, s68, 0x100
	s_addc_u32 s69, s69, 0
	s_cmp_gt_u32 s70, 13
	s_cbranch_scc0 .LBB0_1438
	s_and_b64 vcc, exec, s[12:13]
	s_cbranch_vccz .LBB0_1441
	s_barrier

; #define PG8_STAGE(bufoff, gbase, voff) do { _Pragma("unroll") for (int _i = 0; _i < 2; ++_i) \
;         __builtin_amdgcn_global_load_lds((const unsigned*)((const char*)(gbase) + (voff)[_i]), (PG8_LAS unsigned*)(lds + (bufoff) + ldsw + _i * 8192), 16, 0, 0); } while (0)
; #define PG8_LDA(dst, b, h) do { _Pragma("unroll") for (int m = 0; m < 4; ++m) _Pragma("unroll") for (int k = 0; k < 2; ++k) dst[m][k] = *(const PG8_LAS bf16x8*)(lds + PG8_SA(b, h) + aoff + m * 2048 + k * 1024); } while (0)
; #define PG8_LDB(dst, b, h) do { _Pragma("unroll") for (int n = 0; n < 2; ++n) _Pragma("unroll") for (int k = 0; k < 2; ++k) dst[n][k] = *(const PG8_LAS bf16x8*)(lds + PG8_SB(b, h) + boff + n * 2048 + k * 1024); } while (0)
; #define PG8_MMA(ai, bj, At, Bt) do { __builtin_amdgcn_s_setprio(1); _Pragma("unroll") for (int m = 0; m < 4; ++m) _Pragma("unroll") for (int n = 0; n < 2; ++n) _Pragma("unroll") for (int k = 0; k < 2; ++k) \
;         acc[ai][bj][m][n] = __builtin_amdgcn_mfma_f32_16x16x32_bf16(Bt[n][k], At[m][k], acc[ai][bj][m][n], 0, 0, 0); __builtin_amdgcn_s_setprio(0); } while (0)
; #define PG8_WAIT_V(n) asm volatile("s_waitcnt vmcnt(" #n ")" ::: "memory")
; #define PG8_BAR __builtin_amdgcn_s_barrier()
; template <class Epi, class Sched, bool ALIGN_EPI = false, bool SP2 = false>
; __device__ __forceinline__ void gemm_phase(PG8_LAS unsigned char* lds, const Gemm g, const Sched& S, const Epi& E) {
;     ...
;         for (int t = 0; t < nt; t += 2) {
;             const bool last = (t == nt - 2);
;             const char* a1 = cA + (size_t)(t + 1) * kstep;
;             const char* a2 = last ? nA : cA + (size_t)(t + 2) * kstep; const char* b2 = last ? nB : cB + (size_t)(t + 2) * kstep;
;             const char* a3 = a2 + kstep; const char* b3 = b2 + kstep;
;             if (last && has_next) S.a_ready(nxt);
;             if constexpr (SP2) {
;             PG8_LDB(B0, 0, 0); PG8_LDB(B1, 0, 1); PG8_SCHED; PG8_LDA(At, 0, 0); PG8_STAGE(PG8_SA(1, 1), a1 + hstep, voffA);
;             PG8_WAIT_V(8); PG8_WAIT_L(0); PG8_BAR; PG8_MMA(0, 0, At, B0); PG8_MMA(0, 1, At, B1); PG8_BAR; PG8_SCHED;
;             PG8_LDA(At, 0, 1); PG8_STAGE(PG8_SB(0, 0), b2, voffB); PG8_STAGE(PG8_SB(0, 1), b2 + hstep, voffB); PG8_STAGE(PG8_SA(0, 0), a2, voffA);
;             PG8_WAIT_V(8); PG8_WAIT_L(0); PG8_BAR; PG8_MMA(1, 0, At, B0); PG8_MMA(1, 1, At, B1); PG8_BAR; PG8_SCHED;
.LBB0_1517:
	s_add_u32 s33, s22, 0x100
	s_addc_u32 s72, s23, 0
	s_mov_b32 s73, -2
	ds_read_b128 v[142:145], v174
	ds_read_b128 v[146:149], v175
	ds_read_b128 v[150:153], v176
	ds_read_b128 v[154:157], v177
	ds_read_b128 v[158:161], v178
	ds_read_b128 v[162:165], v179
	ds_read_b128 v[166:169], v180
	ds_read_b128 v[190:193], v181
	s_add_u32 s22, s20, 0x100
	s_addc_u32 s23, s21, 0
	s_cmp_eq_u32 s73, 40
	s_cselect_b32 s37, s5, s23
	s_cselect_b32 s36, s4, s22
	s_cselect_b32 s25, s17, s72
	s_cselect_b32 s24, s16, s33
	s_mov_b32 m0, s62
	v_lshl_add_u64 v[170:171], s[20:21], 0, v[134:135]
	ds_read_b128 v[194:197], v172
	ds_read_b128 v[198:201], v172 offset:1024
	ds_read_b128 v[202:205], v172 offset:2048
	ds_read_b128 v[206:209], v172 offset:3072
	ds_read_b128 v[210:213], v172 offset:4096
	ds_read_b128 v[214:217], v172 offset:5120
	ds_read_b128 v[218:221], v172 offset:6144
	ds_read_b128 v[224:227], v172 offset:7168
	global_load_lds_dwordx4 v[170:171], off
	s_mov_b32 m0, s63
	v_lshl_add_u64 v[170:171], s[20:21], 0, v[136:137]
	global_load_lds_dwordx4 v[170:171], off
	s_waitcnt vmcnt(8)
	s_waitcnt lgkmcnt(0)
	s_barrier
	s_setprio 1
	s_waitcnt lgkmcnt(0)
	v_mfma_f32_16x16x32_bf16 v[124:127], v[142:145], v[194:197], 0
	v_mfma_f32_16x16x32_bf16 v[108:111], v[150:153], v[194:197], 0
	v_mfma_f32_16x16x32_bf16 v[120:123], v[142:145], v[202:205], 0
	v_mfma_f32_16x16x32_bf16 v[96:99], v[150:153], v[202:205], 0
	v_mfma_f32_16x16x32_bf16 v[116:119], v[142:145], v[210:213], 0
	v_mfma_f32_16x16x32_bf16 v[88:91], v[150:153], v[210:213], 0
	v_mfma_f32_16x16x32_bf16 v[112:115], v[142:145], v[218:221], 0
	v_mfma_f32_16x16x32_bf16 v[84:87], v[150:153], v[218:221], 0
	v_mfma_f32_16x16x32_bf16 v[124:127], v[146:149], v[198:201], v[124:127]
	v_mfma_f32_16x16x32_bf16 v[108:111], v[154:157], v[198:201], v[108:111]
	v_mfma_f32_16x16x32_bf16 v[120:123], v[146:149], v[206:209], v[120:123]
	v_mfma_f32_16x16x32_bf16 v[96:99], v[154:157], v[206:209], v[96:99]
	v_mfma_f32_16x16x32_bf16 v[116:119], v[146:149], v[214:217], v[116:119]
	v_mfma_f32_16x16x32_bf16 v[88:91], v[154:157], v[214:217], v[88:91]
	v_mfma_f32_16x16x32_bf16 v[112:115], v[146:149], v[224:227], v[112:115]
	v_mfma_f32_16x16x32_bf16 v[84:87], v[154:157], v[224:227], v[84:87]
	s_setprio 0
	s_setprio 1
	v_mfma_f32_16x16x32_bf16 v[68:71], v[158:161], v[194:197], 0
	v_mfma_f32_16x16x32_bf16 v[40:43], v[166:169], v[194:197], 0
	v_mfma_f32_16x16x32_bf16 v[60:63], v[158:161], v[202:205], 0
	v_mfma_f32_16x16x32_bf16 v[32:35], v[166:169], v[202:205], 0
	v_mfma_f32_16x16x32_bf16 v[52:55], v[158:161], v[210:213], 0
	v_mfma_f32_16x16x32_bf16 v[24:27], v[166:169], v[210:213], 0
	v_mfma_f32_16x16x32_bf16 v[48:51], v[158:161], v[218:221], 0
	v_mfma_f32_16x16x32_bf16 v[16:19], v[166:169], v[218:221], 0
	v_mfma_f32_16x16x32_bf16 v[68:71], v[162:165], v[198:201], v[68:71]
	v_mfma_f32_16x16x32_bf16 v[40:43], v[190:193], v[198:201], v[40:43]
	v_mfma_f32_16x16x32_bf16 v[60:63], v[162:165], v[206:209], v[60:63]
	v_mfma_f32_16x16x32_bf16 v[32:35], v[190:193], v[206:209], v[32:35]
	v_mfma_f32_16x16x32_bf16 v[52:55], v[162:165], v[214:217], v[52:55]
	v_mfma_f32_16x16x32_bf16 v[24:27], v[190:193], v[214:217], v[24:27]
	v_mfma_f32_16x16x32_bf16 v[48:51], v[162:165], v[224:227], v[48:51]
	v_mfma_f32_16x16x32_bf16 v[16:19], v[190:193], v[224:227], v[16:19]
	s_setprio 0
	s_barrier
	s_mov_b32 m0, s39
	v_lshl_add_u64 v[170:171], s[24:25], 0, v[128:129]
	s_add_u32 s20, s24, 0xb0000
	ds_read_b128 v[194:197], v172 offset:16384
	ds_read_b128 v[198:201], v172 offset:17408
	ds_read_b128 v[202:205], v172 offset:18432
	ds_read_b128 v[206:209], v172 offset:19456
	ds_read_b128 v[210:213], v172 offset:20480
	ds_read_b128 v[214:217], v172 offset:21504
	ds_read_b128 v[218:221], v172 offset:22528
	ds_read_b128 v[224:227], v172 offset:23552
	global_load_lds_dwordx4 v[170:171], off
	v_lshl_add_u64 v[228:229], s[24:25], 0, v[130:131]
	s_mov_b32 m0, s40
	s_addc_u32 s21, s25, 0
	global_load_lds_dwordx4 v[228:229], off
	v_lshl_add_u64 v[236:237], s[20:21], 0, v[128:129]
	s_mov_b32 m0, s41
	v_lshl_add_u64 v[238:239], s[36:37], 0, v[130:131]
	global_load_lds_dwordx4 v[236:237], off
	s_mov_b32 m0, s43
	v_lshl_add_u64 v[236:237], s[20:21], 0, v[130:131]
	global_load_lds_dwordx4 v[236:237], off
	s_mov_b32 m0, s15
	v_lshl_add_u64 v[236:237], s[36:37], 0, v[128:129]
	global_load_lds_dwordx4 v[236:237], off
	s_mov_b32 m0, s46
	s_nop 0
	global_load_lds_dwordx4 v[238:239], off
	s_waitcnt vmcnt(8)
	s_waitcnt lgkmcnt(0)
	s_barrier
	s_setprio 1
	s_waitcnt lgkmcnt(0)
	v_mfma_f32_16x16x32_bf16 v[104:107], v[142:145], v[194:197], 0
	v_mfma_f32_16x16x32_bf16 v[76:79], v[150:153], v[194:197], 0
	v_mfma_f32_16x16x32_bf16 v[100:103], v[142:145], v[202:205], 0
	v_mfma_f32_16x16x32_bf16 v[72:75], v[150:153], v[202:205], 0
	v_mfma_f32_16x16x32_bf16 v[92:95], v[142:145], v[210:213], 0
	v_mfma_f32_16x16x32_bf16 v[64:67], v[150:153], v[210:213], 0
	v_mfma_f32_16x16x32_bf16 v[80:83], v[142:145], v[218:221], 0
	v_mfma_f32_16x16x32_bf16 v[56:59], v[150:153], v[218:221], 0
	v_mfma_f32_16x16x32_bf16 v[104:107], v[146:149], v[198:201], v[104:107]
	v_mfma_f32_16x16x32_bf16 v[76:79], v[154:157], v[198:201], v[76:79]
	v_mfma_f32_16x16x32_bf16 v[100:103], v[146:149], v[206:209], v[100:103]
	v_mfma_f32_16x16x32_bf16 v[72:75], v[154:157], v[206:209], v[72:75]
	v_mfma_f32_16x16x32_bf16 v[92:95], v[146:149], v[214:217], v[92:95]
	v_mfma_f32_16x16x32_bf16 v[64:67], v[154:157], v[214:217], v[64:67]
	v_mfma_f32_16x16x32_bf16 v[80:83], v[146:149], v[224:227], v[80:83]
	v_mfma_f32_16x16x32_bf16 v[56:59], v[154:157], v[224:227], v[56:59]
	s_setprio 0
	s_setprio 1
	v_mfma_f32_16x16x32_bf16 v[44:47], v[158:161], v[194:197], 0
	v_mfma_f32_16x16x32_bf16 v[12:15], v[166:169], v[194:197], 0
	v_mfma_f32_16x16x32_bf16 v[36:39], v[158:161], v[202:205], 0
	v_mfma_f32_16x16x32_bf16 v[8:11], v[166:169], v[202:205], 0
	v_mfma_f32_16x16x32_bf16 v[28:31], v[158:161], v[210:213], 0
	v_mfma_f32_16x16x32_bf16 v[4:7], v[166:169], v[210:213], 0
	v_mfma_f32_16x16x32_bf16 v[20:23], v[158:161], v[218:221], 0
	v_mfma_f32_16x16x32_bf16 v[0:3], v[166:169], v[218:221], 0
	v_mfma_f32_16x16x32_bf16 v[44:47], v[162:165], v[198:201], v[44:47]
	v_mfma_f32_16x16x32_bf16 v[12:15], v[190:193], v[198:201], v[12:15]
	v_mfma_f32_16x16x32_bf16 v[36:39], v[162:165], v[206:209], v[36:39]
	v_mfma_f32_16x16x32_bf16 v[8:11], v[190:193], v[206:209], v[8:11]
	v_mfma_f32_16x16x32_bf16 v[28:31], v[162:165], v[214:217], v[28:31]
	v_mfma_f32_16x16x32_bf16 v[4:7], v[190:193], v[214:217], v[4:7]
	v_mfma_f32_16x16x32_bf16 v[20:23], v[162:165], v[224:227], v[20:23]
	v_mfma_f32_16x16x32_bf16 v[0:3], v[190:193], v[224:227], v[0:3]
	s_setprio 0
	s_barrier
; #define PG8_STAGE(bufoff, gbase, voff) do { _Pragma("unroll") for (int _i = 0; _i < 2; ++_i) \
;         __builtin_amdgcn_global_load_lds((const unsigned*)((const char*)(gbase) + (voff)[_i]), (PG8_LAS unsigned*)(lds + (bufoff) + ldsw + _i * 8192), 16, 0, 0); } while (0)
; #define PG8_LDA(dst, b, h) do { _Pragma("unroll") for (int m = 0; m < 4; ++m) _Pragma("unroll") for (int k = 0; k < 2; ++k) dst[m][k] = *(const PG8_LAS bf16x8*)(lds + PG8_SA(b, h) + aoff + m * 2048 + k * 1024); } while (0)
; #define PG8_LDB(dst, b, h) do { _Pragma("unroll") for (int n = 0; n < 2; ++n) _Pragma("unroll") for (int k = 0; k < 2; ++k) dst[n][k] = *(const PG8_LAS bf16x8*)(lds + PG8_SB(b, h) + boff + n * 2048 + k * 1024); } while (0)
; #define PG8_MMA(ai, bj, At, Bt) do { __builtin_amdgcn_s_setprio(1); _Pragma("unroll") for (int m = 0; m < 4; ++m) _Pragma("unroll") for (int n = 0; n < 2; ++n) _Pragma("unroll") for (int k = 0; k < 2; ++k) \
;         acc[ai][bj][m][n] = __builtin_amdgcn_mfma_f32_16x16x32_bf16(Bt[n][k], At[m][k], acc[ai][bj][m][n], 0, 0, 0); __builtin_amdgcn_s_setprio(0); } while (0)
; #define PG8_WAIT_V(n) asm volatile("s_waitcnt vmcnt(" #n ")" ::: "memory")
; #define PG8_WAIT_L(n) asm volatile("s_waitcnt lgkmcnt(" #n ")" ::: "memory")
; #define PG8_BAR __builtin_amdgcn_s_barrier()
; #define PG8_SCHED __builtin_amdgcn_sched_barrier(0)
; template <class Epi, class Sched, bool ALIGN_EPI = false, bool SP2 = false>
; __device__ __forceinline__ void gemm_phase(PG8_LAS unsigned char* lds, const Gemm g, const Sched& S, const Epi& E) {
;     ...
;             PG8_LDB(B0, 1, 0); PG8_LDB(B1, 1, 1); PG8_SCHED; PG8_LDA(At, 1, 0); PG8_STAGE(PG8_SA(0, 1), a2 + hstep, voffA);
;             PG8_WAIT_V(8); PG8_WAIT_L(0); PG8_BAR; PG8_MMA(0, 0, At, B0); PG8_MMA(0, 1, At, B1); PG8_BAR; PG8_SCHED;
;             PG8_LDA(At, 1, 1); PG8_STAGE(PG8_SB(1, 0), b3, voffB); PG8_STAGE(PG8_SB(1, 1), b3 + hstep, voffB); PG8_STAGE(PG8_SA(1, 0), a3, voffA);
;             PG8_WAIT_V(8); PG8_WAIT_L(0); PG8_BAR; PG8_MMA(1, 0, At, B0); PG8_MMA(1, 1, At, B1); PG8_BAR; PG8_SCHED;
	ds_read_b128 v[142:145], v182
	ds_read_b128 v[146:149], v183
	ds_read_b128 v[150:153], v184
	ds_read_b128 v[154:157], v185
	ds_read_b128 v[158:161], v186
	ds_read_b128 v[162:165], v187
	ds_read_b128 v[166:169], v188
	ds_read_b128 v[190:193], v189
	s_add_u32 s20, s36, 0xb0000
	s_addc_u32 s21, s37, 0
	s_mov_b32 m0, s47
	v_lshl_add_u64 v[240:241], s[20:21], 0, v[128:129]
	ds_read_b128 v[194:197], v172 offset:32768
	ds_read_b128 v[198:201], v172 offset:33792
	ds_read_b128 v[202:205], v172 offset:34816
	ds_read_b128 v[206:209], v172 offset:35840
	ds_read_b128 v[210:213], v172 offset:36864
	ds_read_b128 v[214:217], v172 offset:37888
	ds_read_b128 v[218:221], v172 offset:38912
	ds_read_b128 v[224:227], v172 offset:39936
	global_load_lds_dwordx4 v[240:241], off
	s_mov_b32 m0, s50
	v_lshl_add_u64 v[240:241], s[20:21], 0, v[130:131]
	global_load_lds_dwordx4 v[240:241], off
	s_waitcnt vmcnt(8)
	s_waitcnt lgkmcnt(0)
	s_barrier
	s_setprio 1
	s_waitcnt lgkmcnt(0)
	v_mfma_f32_16x16x32_bf16 v[124:127], v[142:145], v[194:197], v[124:127]
	v_mfma_f32_16x16x32_bf16 v[108:111], v[150:153], v[194:197], v[108:111]
	v_mfma_f32_16x16x32_bf16 v[120:123], v[142:145], v[202:205], v[120:123]
	v_mfma_f32_16x16x32_bf16 v[96:99], v[150:153], v[202:205], v[96:99]
	v_mfma_f32_16x16x32_bf16 v[116:119], v[142:145], v[210:213], v[116:119]
	v_mfma_f32_16x16x32_bf16 v[88:91], v[150:153], v[210:213], v[88:91]
	v_mfma_f32_16x16x32_bf16 v[112:115], v[142:145], v[218:221], v[112:115]
	v_mfma_f32_16x16x32_bf16 v[84:87], v[150:153], v[218:221], v[84:87]
	v_mfma_f32_16x16x32_bf16 v[124:127], v[146:149], v[198:201], v[124:127]
	v_mfma_f32_16x16x32_bf16 v[108:111], v[154:157], v[198:201], v[108:111]
	v_mfma_f32_16x16x32_bf16 v[120:123], v[146:149], v[206:209], v[120:123]
	v_mfma_f32_16x16x32_bf16 v[96:99], v[154:157], v[206:209], v[96:99]
	v_mfma_f32_16x16x32_bf16 v[116:119], v[146:149], v[214:217], v[116:119]
	v_mfma_f32_16x16x32_bf16 v[88:91], v[154:157], v[214:217], v[88:91]
	v_mfma_f32_16x16x32_bf16 v[112:115], v[146:149], v[224:227], v[112:115]
	v_mfma_f32_16x16x32_bf16 v[84:87], v[154:157], v[224:227], v[84:87]
	s_setprio 0
	s_setprio 1
	v_mfma_f32_16x16x32_bf16 v[68:71], v[158:161], v[194:197], v[68:71]
	v_mfma_f32_16x16x32_bf16 v[40:43], v[166:169], v[194:197], v[40:43]
	v_mfma_f32_16x16x32_bf16 v[60:63], v[158:161], v[202:205], v[60:63]
	v_mfma_f32_16x16x32_bf16 v[32:35], v[166:169], v[202:205], v[32:35]
	v_mfma_f32_16x16x32_bf16 v[52:55], v[158:161], v[210:213], v[52:55]
	v_mfma_f32_16x16x32_bf16 v[24:27], v[166:169], v[210:213], v[24:27]
	v_mfma_f32_16x16x32_bf16 v[48:51], v[158:161], v[218:221], v[48:51]
	v_mfma_f32_16x16x32_bf16 v[16:19], v[166:169], v[218:221], v[16:19]
	v_mfma_f32_16x16x32_bf16 v[68:71], v[162:165], v[198:201], v[68:71]
	v_mfma_f32_16x16x32_bf16 v[40:43], v[190:193], v[198:201], v[40:43]
	v_mfma_f32_16x16x32_bf16 v[60:63], v[162:165], v[206:209], v[60:63]
	v_mfma_f32_16x16x32_bf16 v[32:35], v[190:193], v[206:209], v[32:35]
	v_mfma_f32_16x16x32_bf16 v[52:55], v[162:165], v[214:217], v[52:55]
	v_mfma_f32_16x16x32_bf16 v[24:27], v[190:193], v[214:217], v[24:27]
	v_mfma_f32_16x16x32_bf16 v[48:51], v[162:165], v[224:227], v[48:51]
	v_mfma_f32_16x16x32_bf16 v[16:19], v[190:193], v[224:227], v[16:19]
	s_setprio 0
	s_barrier
	s_mov_b32 m0, s54
	v_lshl_add_u64 v[170:171], v[170:171], 0, s[10:11]
	s_add_u32 s20, s24, 0xb0080
	ds_read_b128 v[194:197], v172 offset:49152
	ds_read_b128 v[198:201], v172 offset:50176
	ds_read_b128 v[202:205], v172 offset:51200
	ds_read_b128 v[206:209], v172 offset:52224
	ds_read_b128 v[210:213], v172 offset:53248
	ds_read_b128 v[214:217], v172 offset:54272
	ds_read_b128 v[218:221], v172 offset:55296
	ds_read_b128 v[224:227], v172 offset:56320
	global_load_lds_dwordx4 v[170:171], off
	v_lshl_add_u64 v[170:171], v[228:229], 0, s[10:11]
	s_mov_b32 m0, s55
	s_addc_u32 s21, s25, 0
	global_load_lds_dwordx4 v[170:171], off
	s_mov_b32 m0, s58
	v_lshl_add_u64 v[170:171], s[20:21], 0, v[128:129]
	global_load_lds_dwordx4 v[170:171], off
	s_mov_b32 m0, s59
	v_lshl_add_u64 v[170:171], s[20:21], 0, v[130:131]
	global_load_lds_dwordx4 v[170:171], off
	s_mov_b32 m0, s56
	v_lshl_add_u64 v[170:171], v[236:237], 0, s[10:11]
	global_load_lds_dwordx4 v[170:171], off
	s_mov_b32 m0, s57
	v_lshl_add_u64 v[170:171], v[238:239], 0, s[10:11]
	global_load_lds_dwordx4 v[170:171], off
	s_waitcnt vmcnt(8)
	s_waitcnt lgkmcnt(0)
	s_barrier
	s_setprio 1
	s_waitcnt lgkmcnt(0)
	v_mfma_f32_16x16x32_bf16 v[104:107], v[142:145], v[194:197], v[104:107]
	v_mfma_f32_16x16x32_bf16 v[76:79], v[150:153], v[194:197], v[76:79]
	v_mfma_f32_16x16x32_bf16 v[100:103], v[142:145], v[202:205], v[100:103]
	v_mfma_f32_16x16x32_bf16 v[72:75], v[150:153], v[202:205], v[72:75]
	v_mfma_f32_16x16x32_bf16 v[92:95], v[142:145], v[210:213], v[92:95]
	v_mfma_f32_16x16x32_bf16 v[64:67], v[150:153], v[210:213], v[64:67]
	v_mfma_f32_16x16x32_bf16 v[80:83], v[142:145], v[218:221], v[80:83]
	v_mfma_f32_16x16x32_bf16 v[56:59], v[150:153], v[218:221], v[56:59]
	v_mfma_f32_16x16x32_bf16 v[104:107], v[146:149], v[198:201], v[104:107]
	v_mfma_f32_16x16x32_bf16 v[76:79], v[154:157], v[198:201], v[76:79]
	v_mfma_f32_16x16x32_bf16 v[100:103], v[146:149], v[206:209], v[100:103]
	v_mfma_f32_16x16x32_bf16 v[72:75], v[154:157], v[206:209], v[72:75]
	v_mfma_f32_16x16x32_bf16 v[92:95], v[146:149], v[214:217], v[92:95]
	v_mfma_f32_16x16x32_bf16 v[64:67], v[154:157], v[214:217], v[64:67]
	v_mfma_f32_16x16x32_bf16 v[80:83], v[146:149], v[224:227], v[80:83]
	v_mfma_f32_16x16x32_bf16 v[56:59], v[154:157], v[224:227], v[56:59]
	s_setprio 0
	s_setprio 1
	v_mfma_f32_16x16x32_bf16 v[44:47], v[158:161], v[194:197], v[44:47]
	v_mfma_f32_16x16x32_bf16 v[12:15], v[166:169], v[194:197], v[12:15]
	v_mfma_f32_16x16x32_bf16 v[36:39], v[158:161], v[202:205], v[36:39]
	v_mfma_f32_16x16x32_bf16 v[8:11], v[166:169], v[202:205], v[8:11]
	v_mfma_f32_16x16x32_bf16 v[28:31], v[158:161], v[210:213], v[28:31]
	v_mfma_f32_16x16x32_bf16 v[4:7], v[166:169], v[210:213], v[4:7]
	v_mfma_f32_16x16x32_bf16 v[20:23], v[158:161], v[218:221], v[20:23]
	v_mfma_f32_16x16x32_bf16 v[0:3], v[166:169], v[218:221], v[0:3]
	v_mfma_f32_16x16x32_bf16 v[44:47], v[162:165], v[198:201], v[44:47]
	v_mfma_f32_16x16x32_bf16 v[12:15], v[190:193], v[198:201], v[12:15]
	v_mfma_f32_16x16x32_bf16 v[36:39], v[162:165], v[206:209], v[36:39]
	v_mfma_f32_16x16x32_bf16 v[8:11], v[190:193], v[206:209], v[8:11]
	v_mfma_f32_16x16x32_bf16 v[28:31], v[162:165], v[214:217], v[28:31]
	v_mfma_f32_16x16x32_bf16 v[4:7], v[190:193], v[214:217], v[4:7]
	v_mfma_f32_16x16x32_bf16 v[20:23], v[162:165], v[224:227], v[20:23]
	v_mfma_f32_16x16x32_bf16 v[0:3], v[190:193], v[224:227], v[0:3]
	s_setprio 0
	s_barrier
	s_add_i32 s73, s73, 2
	s_add_u32 s33, s33, 0x100
	s_addc_u32 s72, s72, 0
	s_mov_b64 s[20:21], s[22:23]
; #define PG8_STAGE(bufoff, gbase, voff) do { _Pragma("unroll") for (int _i = 0; _i < 2; ++_i) \
;         __builtin_amdgcn_global_load_lds((const unsigned*)((const char*)(gbase) + (voff)[_i]), (PG8_LAS unsigned*)(lds + (bufoff) + ldsw + _i * 8192), 16, 0, 0); } while (0)
; #define PG8_LDA(dst, b, h) do { _Pragma("unroll") for (int m = 0; m < 4; ++m) _Pragma("unroll") for (int k = 0; k < 2; ++k) dst[m][k] = *(const PG8_LAS bf16x8*)(lds + PG8_SA(b, h) + aoff + m * 2048 + k * 1024); } while (0)
; #define PG8_LDB(dst, b, h) do { _Pragma("unroll") for (int n = 0; n < 2; ++n) _Pragma("unroll") for (int k = 0; k < 2; ++k) dst[n][k] = *(const PG8_LAS bf16x8*)(lds + PG8_SB(b, h) + boff + n * 2048 + k * 1024); } while (0)
; #define PG8_MMA(ai, bj, At, Bt) do { __builtin_amdgcn_s_setprio(1); _Pragma("unroll") for (int m = 0; m < 4; ++m) _Pragma("unroll") for (int n = 0; n < 2; ++n) _Pragma("unroll") for (int k = 0; k < 2; ++k) \
;         acc[ai][bj][m][n] = __builtin_amdgcn_mfma_f32_16x16x32_bf16(Bt[n][k], At[m][k], acc[ai][bj][m][n], 0, 0, 0); __builtin_amdgcn_s_setprio(0); } while (0)
; #define PG8_WAIT_V(n) asm volatile("s_waitcnt vmcnt(" #n ")" ::: "memory")
; #define PG8_WAIT_L(n) asm volatile("s_waitcnt lgkmcnt(" #n ")" ::: "memory")
; #define PG8_BAR __builtin_amdgcn_s_barrier()
; #define PG8_SCHED __builtin_amdgcn_sched_barrier(0)
; template <class Epi, class Sched, bool ALIGN_EPI = false, bool SP2 = false>
; __device__ __forceinline__ void gemm_phase(PG8_LAS unsigned char* lds, const Gemm g, const Sched& S, const Epi& E) {
;     ...
;             PG8_LDB(B0, 0, 0); PG8_LDB(B1, 0, 1); PG8_SCHED; PG8_LDA(At, 0, 0); PG8_STAGE(PG8_SA(1, 1), a1 + hstep, voffA);
;             PG8_WAIT_V(8); PG8_WAIT_L(0); PG8_BAR; PG8_MMA(0, 0, At, B0); PG8_MMA(0, 1, At, B1); PG8_BAR; PG8_SCHED;
;             PG8_LDA(At, 0, 1); PG8_STAGE(PG8_SB(0, 0), b2, voffB); PG8_STAGE(PG8_SB(0, 1), b2 + hstep, voffB); PG8_STAGE(PG8_SA(0, 0), a2, voffA);
;             PG8_WAIT_V(8); PG8_WAIT_L(0); PG8_BAR; PG8_MMA(1, 0, At, B0); PG8_MMA(1, 1, At, B1); PG8_BAR; PG8_SCHED;
.LBB0_1518:
	ds_read_b128 v[142:145], v174
	ds_read_b128 v[146:149], v175
	ds_read_b128 v[150:153], v176
	ds_read_b128 v[154:157], v177
	ds_read_b128 v[158:161], v178
	ds_read_b128 v[162:165], v179
	ds_read_b128 v[166:169], v180
	ds_read_b128 v[190:193], v181
	s_add_u32 s22, s20, 0x100
	s_addc_u32 s23, s21, 0
	s_cmp_eq_u32 s73, 40
	s_cselect_b32 s37, s5, s23
	s_cselect_b32 s36, s4, s22
	s_cselect_b32 s25, s17, s72
	s_cselect_b32 s24, s16, s33
	s_mov_b32 m0, s62
	v_lshl_add_u64 v[170:171], s[20:21], 0, v[134:135]
	ds_read_b128 v[194:197], v172
	ds_read_b128 v[198:201], v172 offset:1024
	ds_read_b128 v[202:205], v172 offset:2048
	ds_read_b128 v[206:209], v172 offset:3072
	ds_read_b128 v[210:213], v172 offset:4096
	ds_read_b128 v[214:217], v172 offset:5120
	ds_read_b128 v[218:221], v172 offset:6144
	ds_read_b128 v[224:227], v172 offset:7168
	global_load_lds_dwordx4 v[170:171], off
	s_mov_b32 m0, s63
	v_lshl_add_u64 v[170:171], s[20:21], 0, v[136:137]
	global_load_lds_dwordx4 v[170:171], off
	s_waitcnt vmcnt(8)
	s_waitcnt lgkmcnt(0)
	s_barrier
	s_setprio 1
	s_waitcnt lgkmcnt(0)
	v_mfma_f32_16x16x32_bf16 v[124:127], v[142:145], v[194:197], v[124:127]
	v_mfma_f32_16x16x32_bf16 v[108:111], v[150:153], v[194:197], v[108:111]
	v_mfma_f32_16x16x32_bf16 v[120:123], v[142:145], v[202:205], v[120:123]
	v_mfma_f32_16x16x32_bf16 v[96:99], v[150:153], v[202:205], v[96:99]
	v_mfma_f32_16x16x32_bf16 v[116:119], v[142:145], v[210:213], v[116:119]
	v_mfma_f32_16x16x32_bf16 v[88:91], v[150:153], v[210:213], v[88:91]
	v_mfma_f32_16x16x32_bf16 v[112:115], v[142:145], v[218:221], v[112:115]
	v_mfma_f32_16x16x32_bf16 v[84:87], v[150:153], v[218:221], v[84:87]
	v_mfma_f32_16x16x32_bf16 v[124:127], v[146:149], v[198:201], v[124:127]
	v_mfma_f32_16x16x32_bf16 v[108:111], v[154:157], v[198:201], v[108:111]
	v_mfma_f32_16x16x32_bf16 v[120:123], v[146:149], v[206:209], v[120:123]
	v_mfma_f32_16x16x32_bf16 v[96:99], v[154:157], v[206:209], v[96:99]
	v_mfma_f32_16x16x32_bf16 v[116:119], v[146:149], v[214:217], v[116:119]
	v_mfma_f32_16x16x32_bf16 v[88:91], v[154:157], v[214:217], v[88:91]
	v_mfma_f32_16x16x32_bf16 v[112:115], v[146:149], v[224:227], v[112:115]
	v_mfma_f32_16x16x32_bf16 v[84:87], v[154:157], v[224:227], v[84:87]
	s_setprio 0
	s_setprio 1
	v_mfma_f32_16x16x32_bf16 v[68:71], v[158:161], v[194:197], v[68:71]
	v_mfma_f32_16x16x32_bf16 v[40:43], v[166:169], v[194:197], v[40:43]
	v_mfma_f32_16x16x32_bf16 v[60:63], v[158:161], v[202:205], v[60:63]
	v_mfma_f32_16x16x32_bf16 v[32:35], v[166:169], v[202:205], v[32:35]
	v_mfma_f32_16x16x32_bf16 v[52:55], v[158:161], v[210:213], v[52:55]
	v_mfma_f32_16x16x32_bf16 v[24:27], v[166:169], v[210:213], v[24:27]
	v_mfma_f32_16x16x32_bf16 v[48:51], v[158:161], v[218:221], v[48:51]
	v_mfma_f32_16x16x32_bf16 v[16:19], v[166:169], v[218:221], v[16:19]
	v_mfma_f32_16x16x32_bf16 v[68:71], v[162:165], v[198:201], v[68:71]
	v_mfma_f32_16x16x32_bf16 v[40:43], v[190:193], v[198:201], v[40:43]
	v_mfma_f32_16x16x32_bf16 v[60:63], v[162:165], v[206:209], v[60:63]
	v_mfma_f32_16x16x32_bf16 v[32:35], v[190:193], v[206:209], v[32:35]
	v_mfma_f32_16x16x32_bf16 v[52:55], v[162:165], v[214:217], v[52:55]
	v_mfma_f32_16x16x32_bf16 v[24:27], v[190:193], v[214:217], v[24:27]
	v_mfma_f32_16x16x32_bf16 v[48:51], v[162:165], v[224:227], v[48:51]
	v_mfma_f32_16x16x32_bf16 v[16:19], v[190:193], v[224:227], v[16:19]
	s_setprio 0
	s_barrier
	s_mov_b32 m0, s39
	v_lshl_add_u64 v[170:171], s[24:25], 0, v[128:129]
	s_add_u32 s20, s24, 0xb0000
	ds_read_b128 v[194:197], v172 offset:16384
	ds_read_b128 v[198:201], v172 offset:17408
	ds_read_b128 v[202:205], v172 offset:18432
	ds_read_b128 v[206:209], v172 offset:19456
	ds_read_b128 v[210:213], v172 offset:20480
	ds_read_b128 v[214:217], v172 offset:21504
	ds_read_b128 v[218:221], v172 offset:22528
	ds_read_b128 v[224:227], v172 offset:23552
	global_load_lds_dwordx4 v[170:171], off
	v_lshl_add_u64 v[228:229], s[24:25], 0, v[130:131]
	s_mov_b32 m0, s40
	s_addc_u32 s21, s25, 0
	global_load_lds_dwordx4 v[228:229], off
	v_lshl_add_u64 v[236:237], s[20:21], 0, v[128:129]
	s_mov_b32 m0, s41
	v_lshl_add_u64 v[238:239], s[36:37], 0, v[130:131]
	global_load_lds_dwordx4 v[236:237], off
	s_mov_b32 m0, s43
	v_lshl_add_u64 v[236:237], s[20:21], 0, v[130:131]
	global_load_lds_dwordx4 v[236:237], off
	s_mov_b32 m0, s15
	v_lshl_add_u64 v[236:237], s[36:37], 0, v[128:129]
	global_load_lds_dwordx4 v[236:237], off
	s_mov_b32 m0, s46
	s_nop 0
	global_load_lds_dwordx4 v[238:239], off
	s_waitcnt vmcnt(8)
	s_waitcnt lgkmcnt(0)
	s_barrier
; #define PG8_STAGE(bufoff, gbase, voff) do { _Pragma("unroll") for (int _i = 0; _i < 2; ++_i) \
;         __builtin_amdgcn_global_load_lds((const unsigned*)((const char*)(gbase) + (voff)[_i]), (PG8_LAS unsigned*)(lds + (bufoff) + ldsw + _i * 8192), 16, 0, 0); } while (0)
; #define PG8_LDA(dst, b, h) do { _Pragma("unroll") for (int m = 0; m < 4; ++m) _Pragma("unroll") for (int k = 0; k < 2; ++k) dst[m][k] = *(const PG8_LAS bf16x8*)(lds + PG8_SA(b, h) + aoff + m * 2048 + k * 1024); } while (0)
; #define PG8_LDB(dst, b, h) do { _Pragma("unroll") for (int n = 0; n < 2; ++n) _Pragma("unroll") for (int k = 0; k < 2; ++k) dst[n][k] = *(const PG8_LAS bf16x8*)(lds + PG8_SB(b, h) + boff + n * 2048 + k * 1024); } while (0)
; #define PG8_MMA(ai, bj, At, Bt) do { __builtin_amdgcn_s_setprio(1); _Pragma("unroll") for (int m = 0; m < 4; ++m) _Pragma("unroll") for (int n = 0; n < 2; ++n) _Pragma("unroll") for (int k = 0; k < 2; ++k) \
;         acc[ai][bj][m][n] = __builtin_amdgcn_mfma_f32_16x16x32_bf16(Bt[n][k], At[m][k], acc[ai][bj][m][n], 0, 0, 0); __builtin_amdgcn_s_setprio(0); } while (0)
; #define PG8_WAIT_V(n) asm volatile("s_waitcnt vmcnt(" #n ")" ::: "memory")
; #define PG8_WAIT_L(n) asm volatile("s_waitcnt lgkmcnt(" #n ")" ::: "memory")
; #define PG8_BAR __builtin_amdgcn_s_barrier()
; #define PG8_SCHED __builtin_amdgcn_sched_barrier(0)
; template <class Epi, class Sched, bool ALIGN_EPI = false, bool SP2 = false>
; __device__ __forceinline__ void gemm_phase(PG8_LAS unsigned char* lds, const Gemm g, const Sched& S, const Epi& E) {
;     ...
;             PG8_WAIT_V(8); PG8_WAIT_L(0); PG8_BAR; PG8_MMA(1, 0, At, B0); PG8_MMA(1, 1, At, B1); PG8_BAR; PG8_SCHED;
;             PG8_LDB(B0, 1, 0); PG8_LDB(B1, 1, 1); PG8_SCHED; PG8_LDA(At, 1, 0); PG8_STAGE(PG8_SA(0, 1), a2 + hstep, voffA);
;             PG8_WAIT_V(8); PG8_WAIT_L(0); PG8_BAR; PG8_MMA(0, 0, At, B0); PG8_MMA(0, 1, At, B1); PG8_BAR; PG8_SCHED;
	s_setprio 1
	s_waitcnt lgkmcnt(0)
	v_mfma_f32_16x16x32_bf16 v[104:107], v[142:145], v[194:197], v[104:107]
	v_mfma_f32_16x16x32_bf16 v[76:79], v[150:153], v[194:197], v[76:79]
	v_mfma_f32_16x16x32_bf16 v[100:103], v[142:145], v[202:205], v[100:103]
	v_mfma_f32_16x16x32_bf16 v[72:75], v[150:153], v[202:205], v[72:75]
	v_mfma_f32_16x16x32_bf16 v[92:95], v[142:145], v[210:213], v[92:95]
	v_mfma_f32_16x16x32_bf16 v[64:67], v[150:153], v[210:213], v[64:67]
	v_mfma_f32_16x16x32_bf16 v[80:83], v[142:145], v[218:221], v[80:83]
	v_mfma_f32_16x16x32_bf16 v[56:59], v[150:153], v[218:221], v[56:59]
	v_mfma_f32_16x16x32_bf16 v[104:107], v[146:149], v[198:201], v[104:107]
	v_mfma_f32_16x16x32_bf16 v[76:79], v[154:157], v[198:201], v[76:79]
	v_mfma_f32_16x16x32_bf16 v[100:103], v[146:149], v[206:209], v[100:103]
	v_mfma_f32_16x16x32_bf16 v[72:75], v[154:157], v[206:209], v[72:75]
	v_mfma_f32_16x16x32_bf16 v[92:95], v[146:149], v[214:217], v[92:95]
	v_mfma_f32_16x16x32_bf16 v[64:67], v[154:157], v[214:217], v[64:67]
	v_mfma_f32_16x16x32_bf16 v[80:83], v[146:149], v[224:227], v[80:83]
	v_mfma_f32_16x16x32_bf16 v[56:59], v[154:157], v[224:227], v[56:59]
	s_setprio 0
	s_setprio 1
	v_mfma_f32_16x16x32_bf16 v[44:47], v[158:161], v[194:197], v[44:47]
	v_mfma_f32_16x16x32_bf16 v[12:15], v[166:169], v[194:197], v[12:15]
	v_mfma_f32_16x16x32_bf16 v[36:39], v[158:161], v[202:205], v[36:39]
	v_mfma_f32_16x16x32_bf16 v[8:11], v[166:169], v[202:205], v[8:11]
	v_mfma_f32_16x16x32_bf16 v[28:31], v[158:161], v[210:213], v[28:31]
	v_mfma_f32_16x16x32_bf16 v[4:7], v[166:169], v[210:213], v[4:7]
	v_mfma_f32_16x16x32_bf16 v[20:23], v[158:161], v[218:221], v[20:23]
	v_mfma_f32_16x16x32_bf16 v[0:3], v[166:169], v[218:221], v[0:3]
	v_mfma_f32_16x16x32_bf16 v[44:47], v[162:165], v[198:201], v[44:47]
	v_mfma_f32_16x16x32_bf16 v[12:15], v[190:193], v[198:201], v[12:15]
	v_mfma_f32_16x16x32_bf16 v[36:39], v[162:165], v[206:209], v[36:39]
	v_mfma_f32_16x16x32_bf16 v[8:11], v[190:193], v[206:209], v[8:11]
	v_mfma_f32_16x16x32_bf16 v[28:31], v[162:165], v[214:217], v[28:31]
	v_mfma_f32_16x16x32_bf16 v[4:7], v[190:193], v[214:217], v[4:7]
	v_mfma_f32_16x16x32_bf16 v[20:23], v[162:165], v[224:227], v[20:23]
	v_mfma_f32_16x16x32_bf16 v[0:3], v[190:193], v[224:227], v[0:3]
	s_setprio 0
	s_barrier
	ds_read_b128 v[142:145], v182
	ds_read_b128 v[146:149], v183
	ds_read_b128 v[150:153], v184
	ds_read_b128 v[154:157], v185
	ds_read_b128 v[158:161], v186
	ds_read_b128 v[162:165], v187
	ds_read_b128 v[166:169], v188
	ds_read_b128 v[190:193], v189
	s_add_u32 s20, s36, 0xb0000
	s_addc_u32 s21, s37, 0
	s_mov_b32 m0, s47
	v_lshl_add_u64 v[240:241], s[20:21], 0, v[128:129]
	ds_read_b128 v[194:197], v172 offset:32768
	ds_read_b128 v[198:201], v172 offset:33792
	ds_read_b128 v[202:205], v172 offset:34816
	ds_read_b128 v[206:209], v172 offset:35840
	ds_read_b128 v[210:213], v172 offset:36864
	ds_read_b128 v[214:217], v172 offset:37888
	ds_read_b128 v[218:221], v172 offset:38912
	ds_read_b128 v[224:227], v172 offset:39936
	global_load_lds_dwordx4 v[240:241], off
	s_mov_b32 m0, s50
	v_lshl_add_u64 v[240:241], s[20:21], 0, v[130:131]
	global_load_lds_dwordx4 v[240:241], off
	s_waitcnt vmcnt(8)
	s_waitcnt lgkmcnt(0)
	s_barrier
	s_setprio 1
	s_waitcnt lgkmcnt(0)
	v_mfma_f32_16x16x32_bf16 v[124:127], v[142:145], v[194:197], v[124:127]
	v_mfma_f32_16x16x32_bf16 v[108:111], v[150:153], v[194:197], v[108:111]
	v_mfma_f32_16x16x32_bf16 v[120:123], v[142:145], v[202:205], v[120:123]
	v_mfma_f32_16x16x32_bf16 v[96:99], v[150:153], v[202:205], v[96:99]
	v_mfma_f32_16x16x32_bf16 v[116:119], v[142:145], v[210:213], v[116:119]
	v_mfma_f32_16x16x32_bf16 v[88:91], v[150:153], v[210:213], v[88:91]
	v_mfma_f32_16x16x32_bf16 v[112:115], v[142:145], v[218:221], v[112:115]
	v_mfma_f32_16x16x32_bf16 v[84:87], v[150:153], v[218:221], v[84:87]
	v_mfma_f32_16x16x32_bf16 v[124:127], v[146:149], v[198:201], v[124:127]
	v_mfma_f32_16x16x32_bf16 v[108:111], v[154:157], v[198:201], v[108:111]
	v_mfma_f32_16x16x32_bf16 v[120:123], v[146:149], v[206:209], v[120:123]
	v_mfma_f32_16x16x32_bf16 v[96:99], v[154:157], v[206:209], v[96:99]
	v_mfma_f32_16x16x32_bf16 v[116:119], v[146:149], v[214:217], v[116:119]
	v_mfma_f32_16x16x32_bf16 v[88:91], v[154:157], v[214:217], v[88:91]
	v_mfma_f32_16x16x32_bf16 v[112:115], v[146:149], v[224:227], v[112:115]
	v_mfma_f32_16x16x32_bf16 v[84:87], v[154:157], v[224:227], v[84:87]
	s_setprio 0
	s_setprio 1
	v_mfma_f32_16x16x32_bf16 v[68:71], v[158:161], v[194:197], v[68:71]
	v_mfma_f32_16x16x32_bf16 v[40:43], v[166:169], v[194:197], v[40:43]
	v_mfma_f32_16x16x32_bf16 v[60:63], v[158:161], v[202:205], v[60:63]
	v_mfma_f32_16x16x32_bf16 v[32:35], v[166:169], v[202:205], v[32:35]
	v_mfma_f32_16x16x32_bf16 v[52:55], v[158:161], v[210:213], v[52:55]
	v_mfma_f32_16x16x32_bf16 v[24:27], v[166:169], v[210:213], v[24:27]
	v_mfma_f32_16x16x32_bf16 v[48:51], v[158:161], v[218:221], v[48:51]
	v_mfma_f32_16x16x32_bf16 v[16:19], v[166:169], v[218:221], v[16:19]
	v_mfma_f32_16x16x32_bf16 v[68:71], v[162:165], v[198:201], v[68:71]
	v_mfma_f32_16x16x32_bf16 v[40:43], v[190:193], v[198:201], v[40:43]
	v_mfma_f32_16x16x32_bf16 v[60:63], v[162:165], v[206:209], v[60:63]
	v_mfma_f32_16x16x32_bf16 v[32:35], v[190:193], v[206:209], v[32:35]
	v_mfma_f32_16x16x32_bf16 v[52:55], v[162:165], v[214:217], v[52:55]
	v_mfma_f32_16x16x32_bf16 v[24:27], v[190:193], v[214:217], v[24:27]
	v_mfma_f32_16x16x32_bf16 v[48:51], v[162:165], v[224:227], v[48:51]
	v_mfma_f32_16x16x32_bf16 v[16:19], v[190:193], v[224:227], v[16:19]
	s_setprio 0
	s_barrier
; #define PG8_STAGE(bufoff, gbase, voff) do { _Pragma("unroll") for (int _i = 0; _i < 2; ++_i) \
;         __builtin_amdgcn_global_load_lds((const unsigned*)((const char*)(gbase) + (voff)[_i]), (PG8_LAS unsigned*)(lds + (bufoff) + ldsw + _i * 8192), 16, 0, 0); } while (0)
; #define PG8_LDA(dst, b, h) do { _Pragma("unroll") for (int m = 0; m < 4; ++m) _Pragma("unroll") for (int k = 0; k < 2; ++k) dst[m][k] = *(const PG8_LAS bf16x8*)(lds + PG8_SA(b, h) + aoff + m * 2048 + k * 1024); } while (0)
; #define PG8_MMA(ai, bj, At, Bt) do { __builtin_amdgcn_s_setprio(1); _Pragma("unroll") for (int m = 0; m < 4; ++m) _Pragma("unroll") for (int n = 0; n < 2; ++n) _Pragma("unroll") for (int k = 0; k < 2; ++k) \
;         acc[ai][bj][m][n] = __builtin_amdgcn_mfma_f32_16x16x32_bf16(Bt[n][k], At[m][k], acc[ai][bj][m][n], 0, 0, 0); __builtin_amdgcn_s_setprio(0); } while (0)
; #define PG8_WAIT_V(n) asm volatile("s_waitcnt vmcnt(" #n ")" ::: "memory")
; #define PG8_WAIT_L(n) asm volatile("s_waitcnt lgkmcnt(" #n ")" ::: "memory")
; #define PG8_BAR __builtin_amdgcn_s_barrier()
; #define PG8_SCHED __builtin_amdgcn_sched_barrier(0)
; template <class Epi, class Sched, bool ALIGN_EPI = false, bool SP2 = false>
; __device__ __forceinline__ void gemm_phase(PG8_LAS unsigned char* lds, const Gemm g, const Sched& S, const Epi& E) {
;     ...
;         for (int t = 0; t < nt; t += 2) {
;             const bool last = (t == nt - 2);
;             const char* a1 = cA + (size_t)(t + 1) * kstep;
;             const char* a2 = last ? nA : cA + (size_t)(t + 2) * kstep; const char* b2 = last ? nB : cB + (size_t)(t + 2) * kstep;
;             const char* a3 = a2 + kstep; const char* b3 = b2 + kstep;
;     ...
;             PG8_LDA(At, 1, 1); PG8_STAGE(PG8_SB(1, 0), b3, voffB); PG8_STAGE(PG8_SB(1, 1), b3 + hstep, voffB); PG8_STAGE(PG8_SA(1, 0), a3, voffA);
;             PG8_WAIT_V(8); PG8_WAIT_L(0); PG8_BAR; PG8_MMA(1, 0, At, B0); PG8_MMA(1, 1, At, B1); PG8_BAR; PG8_SCHED;
;     ...
;         if constexpr (ALIGN_EPI) { if (wr == 0) PG8_BAR; }
	s_mov_b32 m0, s54
	v_lshl_add_u64 v[170:171], v[170:171], 0, s[10:11]
	s_add_u32 s20, s24, 0xb0080
	ds_read_b128 v[194:197], v172 offset:49152
	ds_read_b128 v[198:201], v172 offset:50176
	ds_read_b128 v[202:205], v172 offset:51200
	ds_read_b128 v[206:209], v172 offset:52224
	ds_read_b128 v[210:213], v172 offset:53248
	ds_read_b128 v[214:217], v172 offset:54272
	ds_read_b128 v[218:221], v172 offset:55296
	ds_read_b128 v[224:227], v172 offset:56320
	global_load_lds_dwordx4 v[170:171], off
	v_lshl_add_u64 v[170:171], v[228:229], 0, s[10:11]
	s_mov_b32 m0, s55
	s_addc_u32 s21, s25, 0
	global_load_lds_dwordx4 v[170:171], off
	s_mov_b32 m0, s58
	v_lshl_add_u64 v[170:171], s[20:21], 0, v[128:129]
	global_load_lds_dwordx4 v[170:171], off
	s_mov_b32 m0, s59
	v_lshl_add_u64 v[170:171], s[20:21], 0, v[130:131]
	global_load_lds_dwordx4 v[170:171], off
	s_mov_b32 m0, s56
	v_lshl_add_u64 v[170:171], v[236:237], 0, s[10:11]
	global_load_lds_dwordx4 v[170:171], off
	s_mov_b32 m0, s57
	v_lshl_add_u64 v[170:171], v[238:239], 0, s[10:11]
	global_load_lds_dwordx4 v[170:171], off
	s_waitcnt vmcnt(8)
	s_waitcnt lgkmcnt(0)
	s_barrier
	s_setprio 1
	s_waitcnt lgkmcnt(0)
	v_mfma_f32_16x16x32_bf16 v[104:107], v[142:145], v[194:197], v[104:107]
	v_mfma_f32_16x16x32_bf16 v[76:79], v[150:153], v[194:197], v[76:79]
	v_mfma_f32_16x16x32_bf16 v[100:103], v[142:145], v[202:205], v[100:103]
	v_mfma_f32_16x16x32_bf16 v[72:75], v[150:153], v[202:205], v[72:75]
	v_mfma_f32_16x16x32_bf16 v[92:95], v[142:145], v[210:213], v[92:95]
	v_mfma_f32_16x16x32_bf16 v[64:67], v[150:153], v[210:213], v[64:67]
	v_mfma_f32_16x16x32_bf16 v[80:83], v[142:145], v[218:221], v[80:83]
	v_mfma_f32_16x16x32_bf16 v[56:59], v[150:153], v[218:221], v[56:59]
	v_mfma_f32_16x16x32_bf16 v[104:107], v[146:149], v[198:201], v[104:107]
	v_mfma_f32_16x16x32_bf16 v[76:79], v[154:157], v[198:201], v[76:79]
	v_mfma_f32_16x16x32_bf16 v[100:103], v[146:149], v[206:209], v[100:103]
	v_mfma_f32_16x16x32_bf16 v[72:75], v[154:157], v[206:209], v[72:75]
	v_mfma_f32_16x16x32_bf16 v[92:95], v[146:149], v[214:217], v[92:95]
	v_mfma_f32_16x16x32_bf16 v[64:67], v[154:157], v[214:217], v[64:67]
	v_mfma_f32_16x16x32_bf16 v[80:83], v[146:149], v[224:227], v[80:83]
	v_mfma_f32_16x16x32_bf16 v[56:59], v[154:157], v[224:227], v[56:59]
	s_setprio 0
	s_setprio 1
	v_mfma_f32_16x16x32_bf16 v[44:47], v[158:161], v[194:197], v[44:47]
	v_mfma_f32_16x16x32_bf16 v[12:15], v[166:169], v[194:197], v[12:15]
	v_mfma_f32_16x16x32_bf16 v[36:39], v[158:161], v[202:205], v[36:39]
	v_mfma_f32_16x16x32_bf16 v[8:11], v[166:169], v[202:205], v[8:11]
	v_mfma_f32_16x16x32_bf16 v[28:31], v[158:161], v[210:213], v[28:31]
	v_mfma_f32_16x16x32_bf16 v[4:7], v[166:169], v[210:213], v[4:7]
	v_mfma_f32_16x16x32_bf16 v[20:23], v[158:161], v[218:221], v[20:23]
	v_mfma_f32_16x16x32_bf16 v[0:3], v[166:169], v[218:221], v[0:3]
	v_mfma_f32_16x16x32_bf16 v[44:47], v[162:165], v[198:201], v[44:47]
	v_mfma_f32_16x16x32_bf16 v[12:15], v[190:193], v[198:201], v[12:15]
	v_mfma_f32_16x16x32_bf16 v[36:39], v[162:165], v[206:209], v[36:39]
	v_mfma_f32_16x16x32_bf16 v[8:11], v[190:193], v[206:209], v[8:11]
	v_mfma_f32_16x16x32_bf16 v[28:31], v[162:165], v[214:217], v[28:31]
	v_mfma_f32_16x16x32_bf16 v[4:7], v[190:193], v[214:217], v[4:7]
	v_mfma_f32_16x16x32_bf16 v[20:23], v[162:165], v[224:227], v[20:23]
	v_mfma_f32_16x16x32_bf16 v[0:3], v[190:193], v[224:227], v[0:3]
	s_setprio 0
	s_barrier
	s_add_i32 s73, s73, 2
	s_add_u32 s33, s33, 0x100
	s_addc_u32 s72, s72, 0
	s_cmp_gt_u32 s73, 41
	s_mov_b64 s[20:21], s[22:23]
	s_cbranch_scc0 .LBB0_1518
	s_and_b64 vcc, exec, s[12:13]
	s_cbranch_vccz .LBB0_1521
	s_barrier
